# GEMM K-loops: no setprio flips + post-MFMA address/m0/loop-counter SALU moved from before the closing barrier to after it
# speedup vs baseline: 1.0146x; 1.0146x over previous
; #define PG8_STAGE(bufoff, gbase, voff) do { _Pragma("unroll") for (int _i = 0; _i < 2; ++_i) \
;         __builtin_amdgcn_global_load_lds((const unsigned*)((const char*)(gbase) + (voff)[_i]), (PG8_LAS unsigned*)(lds + (bufoff) + ldsw + _i * 8192), 16, 0, 0); } while (0)
; #define PG8_LDA(dst, b, h) do { _Pragma("unroll") for (int m = 0; m < 4; ++m) _Pragma("unroll") for (int k = 0; k < 2; ++k) dst[m][k] = *(const PG8_LAS bf16x8*)(lds + PG8_SA(b, h) + aoff + m * 2048 + k * 1024); } while (0)
; #define PG8_LDB(dst, b, h) do { _Pragma("unroll") for (int n = 0; n < 2; ++n) _Pragma("unroll") for (int k = 0; k < 2; ++k) dst[n][k] = *(const PG8_LAS bf16x8*)(lds + PG8_SB(b, h) + boff + n * 2048 + k * 1024); } while (0)
; #define PG8_MMA(ai, bj, At, Bt) do { __builtin_amdgcn_s_setprio(1); _Pragma("unroll") for (int m = 0; m < 4; ++m) _Pragma("unroll") for (int n = 0; n < 2; ++n) _Pragma("unroll") for (int k = 0; k < 2; ++k) \
;         acc[ai][bj][m][n] = __builtin_amdgcn_mfma_f32_16x16x32_bf16(Bt[n][k], At[m][k], acc[ai][bj][m][n], 0, 0, 0); __builtin_amdgcn_s_setprio(0); } while (0)
; #define PG8_WAIT_L(n) asm volatile("s_waitcnt lgkmcnt(" #n ")" ::: "memory")
; #define PG8_BAR __builtin_amdgcn_s_barrier()
; #define PG8_SCHED __builtin_amdgcn_sched_barrier(0)
; template <class Epi, class Sched>
; __device__ __forceinline__ void gemm_phase(PG8_LAS unsigned char* lds, const Gemm g, const Sched& S, const Epi& E) {
;     ...
;             const bool last = (t == nt - 2);
;             const char* a1 = cA + (size_t)(t + 1) * kstep;
;             const char* a2 = last ? nA : cA + (size_t)(t + 2) * kstep; const char* b2 = last ? nB : cB + (size_t)(t + 2) * kstep;
;             const char* a3 = a2 + kstep; const char* b3 = b2 + kstep;
;             if (last && has_next) S.a_ready(nxt);
;             PG8_LDB(B0, 0, 0); PG8_SCHED; PG8_LDA(At, 0, 0); PG8_STAGE(PG8_SA(1, 1), a1 + hstep, voffA);
;             PG8_WAIT_L(8); PG8_BAR; PG8_WAIT_L(0); PG8_MMA(0, 0, At, B0); PG8_BAR; PG8_SCHED;
;             PG8_LDB(B1, 0, 1); PG8_STAGE(PG8_SB(0, 0), b2, voffB);
;             PG8_BAR; PG8_WAIT_L(0); PG8_MMA(0, 1, At, B1); PG8_BAR;
;             PG8_LDA(At, 0, 1); PG8_STAGE(PG8_SA(0, 0), a2, voffA);
;             PG8_BAR; PG8_WAIT_L(0); PG8_MMA(1, 0, At, B0); PG8_BAR; PG8_SCHED;
.LBB0_195:
	ds_read_b128 v[144:147], v151
	ds_read_b128 v[156:159], v151 offset:1024
	ds_read_b128 v[160:163], v151 offset:2048
	ds_read_b128 v[166:169], v151 offset:3072
	s_add_u32 s30, s28, 0xfffc0080
	s_addc_u32 s31, s29, -1
	s_cmp_eq_u32 s58, 12
	s_cselect_b32 s35, s17, s31
	s_cselect_b32 s34, s54, s30
	s_cselect_b32 s31, s15, s57
	s_cselect_b32 s30, s55, s56
	v_lshl_add_u64 v[174:175], s[28:29], 0, v[136:137]
	s_add_i32 m0, s27, 0xc000
	ds_read_b128 v[170:173], v153
	ds_read_b128 v[182:185], v153 offset:1024
	ds_read_b128 v[190:193], v153 offset:2048
	ds_read_b128 v[194:197], v153 offset:3072
	ds_read_b128 v[198:201], v153 offset:4096
	ds_read_b128 v[202:205], v153 offset:5120
	ds_read_b128 v[206:209], v153 offset:6144
	ds_read_b128 v[210:213], v153 offset:7168
	global_load_lds_dwordx4 v[174:175], off
	v_lshl_add_u64 v[174:175], s[28:29], 0, v[138:139]
	s_add_i32 m0, s27, 0xe000
	s_nop 0
	global_load_lds_dwordx4 v[174:175], off
	s_waitcnt lgkmcnt(8)
	s_barrier
	s_waitcnt lgkmcnt(0)
	s_waitcnt lgkmcnt(0)
	v_mfma_f32_16x16x32_bf16 v[124:127], v[144:147], v[170:173], v[124:127]
	v_mfma_f32_16x16x32_bf16 v[120:123], v[160:163], v[170:173], v[120:123]
	v_mfma_f32_16x16x32_bf16 v[108:111], v[144:147], v[190:193], v[108:111]
	v_mfma_f32_16x16x32_bf16 v[104:107], v[160:163], v[190:193], v[104:107]
	v_mfma_f32_16x16x32_bf16 v[92:95], v[144:147], v[198:201], v[92:95]
	v_mfma_f32_16x16x32_bf16 v[88:91], v[160:163], v[198:201], v[88:91]
	v_mfma_f32_16x16x32_bf16 v[76:79], v[144:147], v[206:209], v[76:79]
	v_mfma_f32_16x16x32_bf16 v[72:75], v[160:163], v[206:209], v[72:75]
	v_mfma_f32_16x16x32_bf16 v[124:127], v[156:159], v[182:185], v[124:127]
	v_mfma_f32_16x16x32_bf16 v[120:123], v[166:169], v[182:185], v[120:123]
	v_mfma_f32_16x16x32_bf16 v[108:111], v[156:159], v[194:197], v[108:111]
	v_mfma_f32_16x16x32_bf16 v[104:107], v[166:169], v[194:197], v[104:107]
	v_mfma_f32_16x16x32_bf16 v[92:95], v[156:159], v[202:205], v[92:95]
	v_mfma_f32_16x16x32_bf16 v[88:91], v[166:169], v[202:205], v[88:91]
	v_mfma_f32_16x16x32_bf16 v[76:79], v[156:159], v[210:213], v[76:79]
	v_mfma_f32_16x16x32_bf16 v[72:75], v[166:169], v[210:213], v[72:75]
	s_barrier
	s_add_i32 s59, s50, s40
	v_lshl_add_u64 v[174:175], s[30:31], 0, v[132:133]
	s_mov_b32 m0, s59
	ds_read_b128 v[214:217], v154
	ds_read_b128 v[218:221], v154 offset:1024
	ds_read_b128 v[222:225], v154 offset:2048
	ds_read_b128 v[226:229], v154 offset:3072
	global_load_lds_dwordx4 v[174:175], off
	v_lshl_add_u64 v[178:179], s[30:31], 0, v[128:129]
	s_add_i32 m0, s59, 0x2000
	s_nop 0
	global_load_lds_dwordx4 v[178:179], off
	s_barrier
	s_waitcnt lgkmcnt(0)
	s_waitcnt lgkmcnt(0)
	v_mfma_f32_16x16x32_bf16 v[116:119], v[214:217], v[170:173], v[116:119]
	v_mfma_f32_16x16x32_bf16 v[112:115], v[222:225], v[170:173], v[112:115]
	v_mfma_f32_16x16x32_bf16 v[100:103], v[214:217], v[190:193], v[100:103]
	v_mfma_f32_16x16x32_bf16 v[96:99], v[222:225], v[190:193], v[96:99]
	v_mfma_f32_16x16x32_bf16 v[84:87], v[214:217], v[198:201], v[84:87]
	v_mfma_f32_16x16x32_bf16 v[80:83], v[222:225], v[198:201], v[80:83]
	v_mfma_f32_16x16x32_bf16 v[68:71], v[214:217], v[206:209], v[68:71]
	v_mfma_f32_16x16x32_bf16 v[64:67], v[222:225], v[206:209], v[64:67]
	v_mfma_f32_16x16x32_bf16 v[116:119], v[218:221], v[182:185], v[116:119]
	v_mfma_f32_16x16x32_bf16 v[112:115], v[226:229], v[182:185], v[112:115]
	v_mfma_f32_16x16x32_bf16 v[100:103], v[218:221], v[194:197], v[100:103]
	v_mfma_f32_16x16x32_bf16 v[96:99], v[226:229], v[194:197], v[96:99]
	v_mfma_f32_16x16x32_bf16 v[84:87], v[218:221], v[202:205], v[84:87]
	v_mfma_f32_16x16x32_bf16 v[80:83], v[226:229], v[202:205], v[80:83]
	v_mfma_f32_16x16x32_bf16 v[68:71], v[218:221], v[210:213], v[68:71]
	v_mfma_f32_16x16x32_bf16 v[64:67], v[226:229], v[210:213], v[64:67]
	s_barrier
	s_mov_b32 m0, s27
	v_lshl_add_u64 v[186:187], s[34:35], 0, v[134:135]
	ds_read_b128 v[170:173], v153 offset:16384
	ds_read_b128 v[182:185], v153 offset:17408
	ds_read_b128 v[190:193], v153 offset:18432
	ds_read_b128 v[194:197], v153 offset:19456
	ds_read_b128 v[198:201], v153 offset:20480
	ds_read_b128 v[202:205], v153 offset:21504
	ds_read_b128 v[206:209], v153 offset:22528
	ds_read_b128 v[210:213], v153 offset:23552
	global_load_lds_dwordx4 v[186:187], off
	v_lshl_add_u64 v[230:231], s[34:35], 0, v[130:131]
	s_mov_b32 m0, s43
	s_nop 0
	global_load_lds_dwordx4 v[230:231], off
	s_barrier
	s_waitcnt lgkmcnt(0)
	s_waitcnt lgkmcnt(0)
	v_mfma_f32_16x16x32_bf16 v[60:63], v[144:147], v[170:173], v[60:63]
	v_mfma_f32_16x16x32_bf16 v[56:59], v[160:163], v[170:173], v[56:59]
	v_mfma_f32_16x16x32_bf16 v[44:47], v[144:147], v[190:193], v[44:47]
	v_mfma_f32_16x16x32_bf16 v[40:43], v[160:163], v[190:193], v[40:43]
	v_mfma_f32_16x16x32_bf16 v[28:31], v[144:147], v[198:201], v[28:31]
	v_mfma_f32_16x16x32_bf16 v[24:27], v[160:163], v[198:201], v[24:27]
	v_mfma_f32_16x16x32_bf16 v[12:15], v[144:147], v[206:209], v[12:15]
	v_mfma_f32_16x16x32_bf16 v[8:11], v[160:163], v[206:209], v[8:11]
	v_mfma_f32_16x16x32_bf16 v[60:63], v[156:159], v[182:185], v[60:63]
	v_mfma_f32_16x16x32_bf16 v[56:59], v[166:169], v[182:185], v[56:59]
	v_mfma_f32_16x16x32_bf16 v[44:47], v[156:159], v[194:197], v[44:47]
	v_mfma_f32_16x16x32_bf16 v[40:43], v[166:169], v[194:197], v[40:43]
	v_mfma_f32_16x16x32_bf16 v[28:31], v[156:159], v[202:205], v[28:31]
	v_mfma_f32_16x16x32_bf16 v[24:27], v[166:169], v[202:205], v[24:27]
	v_mfma_f32_16x16x32_bf16 v[12:15], v[156:159], v[210:213], v[12:15]
	v_mfma_f32_16x16x32_bf16 v[8:11], v[166:169], v[210:213], v[8:11]
	s_barrier
; #define PG8_STAGE(bufoff, gbase, voff) do { _Pragma("unroll") for (int _i = 0; _i < 2; ++_i) \
;         __builtin_amdgcn_global_load_lds((const unsigned*)((const char*)(gbase) + (voff)[_i]), (PG8_LAS unsigned*)(lds + (bufoff) + ldsw + _i * 8192), 16, 0, 0); } while (0)
; #define PG8_LDA(dst, b, h) do { _Pragma("unroll") for (int m = 0; m < 4; ++m) _Pragma("unroll") for (int k = 0; k < 2; ++k) dst[m][k] = *(const PG8_LAS bf16x8*)(lds + PG8_SA(b, h) + aoff + m * 2048 + k * 1024); } while (0)
; #define PG8_LDB(dst, b, h) do { _Pragma("unroll") for (int n = 0; n < 2; ++n) _Pragma("unroll") for (int k = 0; k < 2; ++k) dst[n][k] = *(const PG8_LAS bf16x8*)(lds + PG8_SB(b, h) + boff + n * 2048 + k * 1024); } while (0)
; #define PG8_MMA(ai, bj, At, Bt) do { __builtin_amdgcn_s_setprio(1); _Pragma("unroll") for (int m = 0; m < 4; ++m) _Pragma("unroll") for (int n = 0; n < 2; ++n) _Pragma("unroll") for (int k = 0; k < 2; ++k) \
;         acc[ai][bj][m][n] = __builtin_amdgcn_mfma_f32_16x16x32_bf16(Bt[n][k], At[m][k], acc[ai][bj][m][n], 0, 0, 0); __builtin_amdgcn_s_setprio(0); } while (0)
; #define PG8_WAIT_V(n) asm volatile("s_waitcnt vmcnt(" #n ")" ::: "memory")
; #define PG8_WAIT_L(n) asm volatile("s_waitcnt lgkmcnt(" #n ")" ::: "memory")
; #define PG8_BAR __builtin_amdgcn_s_barrier()
; #define PG8_SCHED __builtin_amdgcn_sched_barrier(0)
; template <class Epi, class Sched>
; __device__ __forceinline__ void gemm_phase(PG8_LAS unsigned char* lds, const Gemm g, const Sched& S, const Epi& E) {
;     ...
;             PG8_STAGE(PG8_SB(0, 1), b2 + hstep, voffB);
;             PG8_WAIT_V(6); PG8_BAR; PG8_MMA(1, 1, At, B1); PG8_BAR;
;             PG8_LDB(B0, 1, 0); PG8_SCHED; PG8_LDA(At, 1, 0); PG8_STAGE(PG8_SA(0, 1), a2 + hstep, voffA);
;             PG8_WAIT_L(8); PG8_BAR; PG8_WAIT_L(0); PG8_MMA(0, 0, At, B0); PG8_BAR; PG8_SCHED;
;             PG8_LDB(B1, 1, 1); PG8_STAGE(PG8_SB(1, 0), b3, voffB);
;             PG8_BAR; PG8_WAIT_L(0); PG8_MMA(0, 1, At, B1); PG8_BAR;
;             PG8_LDA(At, 1, 1); PG8_STAGE(PG8_SA(1, 0), a3, voffA);
	s_add_u32 s60, s30, 0x40000
	s_addc_u32 s61, s31, 0
	s_add_i32 s59, s51, s40
	v_lshl_add_u64 v[144:145], s[60:61], 0, v[132:133]
	s_mov_b32 m0, s59
	s_nop 0
	global_load_lds_dwordx4 v[144:145], off
	v_lshl_add_u64 v[144:145], s[60:61], 0, v[128:129]
	s_add_i32 m0, s59, 0x2000
	s_nop 0
	global_load_lds_dwordx4 v[144:145], off
	s_waitcnt vmcnt(6)
	s_barrier
	v_mfma_f32_16x16x32_bf16 v[52:55], v[214:217], v[170:173], v[52:55]
	v_mfma_f32_16x16x32_bf16 v[48:51], v[222:225], v[170:173], v[48:51]
	v_mfma_f32_16x16x32_bf16 v[36:39], v[214:217], v[190:193], v[36:39]
	v_mfma_f32_16x16x32_bf16 v[32:35], v[222:225], v[190:193], v[32:35]
	v_mfma_f32_16x16x32_bf16 v[20:23], v[214:217], v[198:201], v[20:23]
	v_mfma_f32_16x16x32_bf16 v[16:19], v[222:225], v[198:201], v[16:19]
	v_mfma_f32_16x16x32_bf16 v[4:7], v[214:217], v[206:209], v[4:7]
	v_mfma_f32_16x16x32_bf16 v[0:3], v[222:225], v[206:209], v[0:3]
	v_mfma_f32_16x16x32_bf16 v[52:55], v[218:221], v[182:185], v[52:55]
	v_mfma_f32_16x16x32_bf16 v[48:51], v[226:229], v[182:185], v[48:51]
	v_mfma_f32_16x16x32_bf16 v[36:39], v[218:221], v[194:197], v[36:39]
	v_mfma_f32_16x16x32_bf16 v[32:35], v[226:229], v[194:197], v[32:35]
	v_mfma_f32_16x16x32_bf16 v[20:23], v[218:221], v[202:205], v[20:23]
	v_mfma_f32_16x16x32_bf16 v[16:19], v[226:229], v[202:205], v[16:19]
	v_mfma_f32_16x16x32_bf16 v[4:7], v[218:221], v[210:213], v[4:7]
	v_mfma_f32_16x16x32_bf16 v[0:3], v[226:229], v[210:213], v[0:3]
	s_barrier
	s_add_i32 s59, 0, 0x18000
	v_add_u32_e32 v155, s59, v149
	ds_read_b128 v[144:147], v155
	ds_read_b128 v[156:159], v155 offset:1024
	ds_read_b128 v[160:163], v155 offset:2048
	ds_read_b128 v[166:169], v155 offset:3072
	s_add_u32 s34, s34, 0x40000
	s_addc_u32 s35, s35, 0
	s_mov_b32 m0, s44
	v_lshl_add_u64 v[214:215], s[34:35], 0, v[134:135]
	ds_read_b128 v[170:173], v153 offset:32768
	ds_read_b128 v[182:185], v153 offset:33792
	ds_read_b128 v[190:193], v153 offset:34816
	ds_read_b128 v[194:197], v153 offset:35840
	ds_read_b128 v[198:201], v153 offset:36864
	ds_read_b128 v[202:205], v153 offset:37888
	ds_read_b128 v[206:209], v153 offset:38912
	ds_read_b128 v[210:213], v153 offset:39936
	global_load_lds_dwordx4 v[214:215], off
	v_lshl_add_u64 v[214:215], s[34:35], 0, v[130:131]
	s_mov_b32 m0, s45
	s_nop 0
	global_load_lds_dwordx4 v[214:215], off
	s_waitcnt lgkmcnt(8)
	s_barrier
	s_waitcnt lgkmcnt(0)
	s_waitcnt lgkmcnt(0)
	v_mfma_f32_16x16x32_bf16 v[124:127], v[144:147], v[170:173], v[124:127]
	v_mfma_f32_16x16x32_bf16 v[120:123], v[160:163], v[170:173], v[120:123]
	v_mfma_f32_16x16x32_bf16 v[108:111], v[144:147], v[190:193], v[108:111]
	v_mfma_f32_16x16x32_bf16 v[104:107], v[160:163], v[190:193], v[104:107]
	v_mfma_f32_16x16x32_bf16 v[92:95], v[144:147], v[198:201], v[92:95]
	v_mfma_f32_16x16x32_bf16 v[88:91], v[160:163], v[198:201], v[88:91]
	v_mfma_f32_16x16x32_bf16 v[76:79], v[144:147], v[206:209], v[76:79]
	v_mfma_f32_16x16x32_bf16 v[72:75], v[160:163], v[206:209], v[72:75]
	v_mfma_f32_16x16x32_bf16 v[124:127], v[156:159], v[182:185], v[124:127]
	v_mfma_f32_16x16x32_bf16 v[120:123], v[166:169], v[182:185], v[120:123]
	v_mfma_f32_16x16x32_bf16 v[108:111], v[156:159], v[194:197], v[108:111]
	v_mfma_f32_16x16x32_bf16 v[104:107], v[166:169], v[194:197], v[104:107]
	v_mfma_f32_16x16x32_bf16 v[92:95], v[156:159], v[202:205], v[92:95]
	v_mfma_f32_16x16x32_bf16 v[88:91], v[166:169], v[202:205], v[88:91]
	v_mfma_f32_16x16x32_bf16 v[76:79], v[156:159], v[210:213], v[76:79]
	v_mfma_f32_16x16x32_bf16 v[72:75], v[166:169], v[210:213], v[72:75]
	s_barrier
	s_add_i32 s34, 0, 0x1c000
	s_add_i32 s35, s59, s40
	v_add_u32_e32 v155, s34, v149
	v_lshl_add_u64 v[174:175], v[174:175], 0, s[10:11]
	s_mov_b32 m0, s35
	ds_read_b128 v[214:217], v155
	ds_read_b128 v[218:221], v155 offset:1024
	ds_read_b128 v[222:225], v155 offset:2048
	ds_read_b128 v[226:229], v155 offset:3072
	global_load_lds_dwordx4 v[174:175], off
	v_lshl_add_u64 v[174:175], v[178:179], 0, s[10:11]
	s_add_i32 m0, s35, 0x2000
	s_nop 0
	global_load_lds_dwordx4 v[174:175], off
	s_barrier
	s_waitcnt lgkmcnt(0)
	s_waitcnt lgkmcnt(0)
	v_mfma_f32_16x16x32_bf16 v[116:119], v[214:217], v[170:173], v[116:119]
	v_mfma_f32_16x16x32_bf16 v[112:115], v[222:225], v[170:173], v[112:115]
	v_mfma_f32_16x16x32_bf16 v[100:103], v[214:217], v[190:193], v[100:103]
	v_mfma_f32_16x16x32_bf16 v[96:99], v[222:225], v[190:193], v[96:99]
	v_mfma_f32_16x16x32_bf16 v[84:87], v[214:217], v[198:201], v[84:87]
	v_mfma_f32_16x16x32_bf16 v[80:83], v[222:225], v[198:201], v[80:83]
	v_mfma_f32_16x16x32_bf16 v[68:71], v[214:217], v[206:209], v[68:71]
	v_mfma_f32_16x16x32_bf16 v[64:67], v[222:225], v[206:209], v[64:67]
	v_mfma_f32_16x16x32_bf16 v[116:119], v[218:221], v[182:185], v[116:119]
	v_mfma_f32_16x16x32_bf16 v[112:115], v[226:229], v[182:185], v[112:115]
	v_mfma_f32_16x16x32_bf16 v[100:103], v[218:221], v[194:197], v[100:103]
	v_mfma_f32_16x16x32_bf16 v[96:99], v[226:229], v[194:197], v[96:99]
	v_mfma_f32_16x16x32_bf16 v[84:87], v[218:221], v[202:205], v[84:87]
	v_mfma_f32_16x16x32_bf16 v[80:83], v[226:229], v[202:205], v[80:83]
	v_mfma_f32_16x16x32_bf16 v[68:71], v[218:221], v[210:213], v[68:71]
	v_mfma_f32_16x16x32_bf16 v[64:67], v[226:229], v[210:213], v[64:67]
	s_barrier
	s_mov_b32 m0, s47
	v_lshl_add_u64 v[174:175], v[186:187], 0, s[10:11]
	ds_read_b128 v[170:173], v153 offset:49152
	ds_read_b128 v[182:185], v153 offset:50176
	ds_read_b128 v[190:193], v153 offset:51200
	ds_read_b128 v[194:197], v153 offset:52224
	ds_read_b128 v[198:201], v153 offset:53248
	ds_read_b128 v[202:205], v153 offset:54272
	ds_read_b128 v[206:209], v153 offset:55296
	ds_read_b128 v[210:213], v153 offset:56320
	global_load_lds_dwordx4 v[174:175], off
	v_lshl_add_u64 v[174:175], v[230:231], 0, s[10:11]
	s_mov_b32 m0, s48
	s_nop 0
	global_load_lds_dwordx4 v[174:175], off
	s_barrier
; __device__ __forceinline__ unsigned cvt_pk_bf16(float lo, float hi) { unsigned r; asm volatile("v_cvt_pk_bf16_f32 %0, %1, %2" : "=v"(r) : "v"(lo), "v"(hi)); return r; }
; #define PG8_STAGE(bufoff, gbase, voff) do { _Pragma("unroll") for (int _i = 0; _i < 2; ++_i) \
;         __builtin_amdgcn_global_load_lds((const unsigned*)((const char*)(gbase) + (voff)[_i]), (PG8_LAS unsigned*)(lds + (bufoff) + ldsw + _i * 8192), 16, 0, 0); } while (0)
; #define PG8_MMA(ai, bj, At, Bt) do { __builtin_amdgcn_s_setprio(1); _Pragma("unroll") for (int m = 0; m < 4; ++m) _Pragma("unroll") for (int n = 0; n < 2; ++n) _Pragma("unroll") for (int k = 0; k < 2; ++k) \
;         acc[ai][bj][m][n] = __builtin_amdgcn_mfma_f32_16x16x32_bf16(Bt[n][k], At[m][k], acc[ai][bj][m][n], 0, 0, 0); __builtin_amdgcn_s_setprio(0); } while (0)
; #define PG8_WAIT_V(n) asm volatile("s_waitcnt vmcnt(" #n ")" ::: "memory")
; #define PG8_WAIT_L(n) asm volatile("s_waitcnt lgkmcnt(" #n ")" ::: "memory")
; #define PG8_BAR __builtin_amdgcn_s_barrier()
; #define PG8_SCHED __builtin_amdgcn_sched_barrier(0)
;     __device__ __forceinline__ void operator()(const f32x4 (&acc)[2][2][4][2], const Unit& u, int wr, int wc, int fr, int fq) const {
;     ...
;             for (int m = 0; m < 4; ++m) { bf16_t* rowp = O + (size_t)(row0 + ai * HALF + m * 16) * ldc + col0;
;                 f32x4 v0, v1;
; #pragma unroll
;                 for (int j = 0; j < 1; ++j) { v0 = acc[ai][0][m][0] * sigmoid4(acc[ai][0][m][0]) * acc[ai][1][m][0]; v1 = acc[ai][0][m][1] * sigmoid4(acc[ai][0][m][1]) * acc[ai][1][m][1]; }
;                 u32x4 w; w.x = cvt_pk_bf16(v0[0], v0[1]); w.y = cvt_pk_bf16(v0[2], v0[3]); w.z = cvt_pk_bf16(v1[0], v1[1]); w.w = cvt_pk_bf16(v1[2], v1[3]);
;                 *(u32x4*)rowp = w; }
; template <class Epi, class Sched>
; __device__ __forceinline__ void gemm_phase(PG8_LAS unsigned char* lds, const Gemm g, const Sched& S, const Epi& E) {
;     ...
;             PG8_BAR; PG8_WAIT_L(0); PG8_MMA(1, 0, At, B0); PG8_BAR; PG8_SCHED;
;             PG8_STAGE(PG8_SB(1, 1), b3 + hstep, voffB);
;             PG8_WAIT_V(6); PG8_BAR; PG8_MMA(1, 1, At, B1); PG8_BAR;
	s_waitcnt lgkmcnt(0)
	s_waitcnt lgkmcnt(0)
	v_mfma_f32_16x16x32_bf16 v[60:63], v[144:147], v[170:173], v[60:63]
	v_mfma_f32_16x16x32_bf16 v[56:59], v[160:163], v[170:173], v[56:59]
	v_mfma_f32_16x16x32_bf16 v[44:47], v[144:147], v[190:193], v[44:47]
	v_mfma_f32_16x16x32_bf16 v[40:43], v[160:163], v[190:193], v[40:43]
	v_mfma_f32_16x16x32_bf16 v[28:31], v[144:147], v[198:201], v[28:31]
	v_mfma_f32_16x16x32_bf16 v[24:27], v[160:163], v[198:201], v[24:27]
	v_mfma_f32_16x16x32_bf16 v[12:15], v[144:147], v[206:209], v[12:15]
	v_mfma_f32_16x16x32_bf16 v[8:11], v[160:163], v[206:209], v[8:11]
	v_mfma_f32_16x16x32_bf16 v[60:63], v[156:159], v[182:185], v[60:63]
	v_mfma_f32_16x16x32_bf16 v[56:59], v[166:169], v[182:185], v[56:59]
	v_mfma_f32_16x16x32_bf16 v[44:47], v[156:159], v[194:197], v[44:47]
	v_mfma_f32_16x16x32_bf16 v[40:43], v[166:169], v[194:197], v[40:43]
	v_mfma_f32_16x16x32_bf16 v[28:31], v[156:159], v[202:205], v[28:31]
	v_mfma_f32_16x16x32_bf16 v[24:27], v[166:169], v[202:205], v[24:27]
	v_mfma_f32_16x16x32_bf16 v[12:15], v[156:159], v[210:213], v[12:15]
	v_mfma_f32_16x16x32_bf16 v[8:11], v[166:169], v[210:213], v[8:11]
	s_barrier
	s_add_u32 s30, s30, 0x40080
	s_addc_u32 s31, s31, 0
	s_add_i32 s34, s34, s40
	v_lshl_add_u64 v[144:145], s[30:31], 0, v[132:133]
	s_mov_b32 m0, s34
	s_nop 0
	global_load_lds_dwordx4 v[144:145], off
	v_lshl_add_u64 v[144:145], s[30:31], 0, v[128:129]
	s_add_i32 m0, s34, 0x2000
	s_nop 0
	global_load_lds_dwordx4 v[144:145], off
	s_waitcnt vmcnt(6)
	s_barrier
	v_mfma_f32_16x16x32_bf16 v[52:55], v[214:217], v[170:173], v[52:55]
	v_mfma_f32_16x16x32_bf16 v[48:51], v[222:225], v[170:173], v[48:51]
	v_mfma_f32_16x16x32_bf16 v[36:39], v[214:217], v[190:193], v[36:39]
	v_mfma_f32_16x16x32_bf16 v[32:35], v[222:225], v[190:193], v[32:35]
	v_mfma_f32_16x16x32_bf16 v[20:23], v[214:217], v[198:201], v[20:23]
	v_mfma_f32_16x16x32_bf16 v[16:19], v[222:225], v[198:201], v[16:19]
	v_mfma_f32_16x16x32_bf16 v[4:7], v[214:217], v[206:209], v[4:7]
	v_mfma_f32_16x16x32_bf16 v[0:3], v[222:225], v[206:209], v[0:3]
	v_mfma_f32_16x16x32_bf16 v[52:55], v[218:221], v[182:185], v[52:55]
	v_mfma_f32_16x16x32_bf16 v[48:51], v[226:229], v[182:185], v[48:51]
	v_mfma_f32_16x16x32_bf16 v[36:39], v[218:221], v[194:197], v[36:39]
	v_mfma_f32_16x16x32_bf16 v[32:35], v[226:229], v[194:197], v[32:35]
	v_mfma_f32_16x16x32_bf16 v[20:23], v[218:221], v[202:205], v[20:23]
	v_mfma_f32_16x16x32_bf16 v[16:19], v[226:229], v[202:205], v[16:19]
	v_mfma_f32_16x16x32_bf16 v[4:7], v[218:221], v[210:213], v[4:7]
	v_mfma_f32_16x16x32_bf16 v[0:3], v[226:229], v[210:213], v[0:3]
	s_barrier
	s_add_i32 s58, s58, 2
	s_add_u32 s28, s28, 0x100
	s_addc_u32 s29, s29, 0
	s_add_u32 s56, s56, 0x100
	s_addc_u32 s57, s57, 0
	s_cmp_gt_u32 s58, 13
	s_cbranch_scc0 .LBB0_195
	v_max_f32_e32 v144, v124, v124
	v_max_f32_e32 v144, 0xc1a00000, v144
	v_mul_f32_e32 v144, 0xbfb8aa3b, v144
	v_exp_f32_e32 v157, v144
	v_max_f32_e32 v144, v125, v125
	v_max_f32_e32 v144, 0xc1a00000, v144
	v_mul_f32_e32 v144, 0xbfb8aa3b, v144
	v_exp_f32_e32 v156, v144
	v_max_f32_e32 v144, v126, v126
	v_max_f32_e32 v144, 0xc1a00000, v144
	v_mul_f32_e32 v144, 0xbfb8aa3b, v144
	v_exp_f32_e32 v159, v144
	v_max_f32_e32 v144, v127, v127
	v_max_f32_e32 v144, 0xc1a00000, v144
	v_mul_f32_e32 v144, 0xbfb8aa3b, v144
	v_exp_f32_e32 v158, v144
	v_pk_add_f32 v[156:157], v[156:157], 1.0 op_sel_hi:[1,0]
	v_lshl_or_b32 v146, s53, 7, v150
	v_mov_b32_e32 v160, v157
	v_pk_add_f32 v[158:159], v[158:159], 1.0 op_sel_hi:[1,0]
	v_mov_b32_e32 v162, v156
	v_mov_b32_e32 v161, v159
	v_mov_b32_e32 v163, v158
	v_pk_mul_f32 v[160:161], v[160:161], v[162:163]
	v_lshl_add_u32 v155, s26, 8, v148
	v_mul_f32_e32 v162, v160, v161
	v_rcp_f32_e32 v166, v162
	v_ashrrev_i32_e32 v147, 31, v146
	v_mov_b64_e32 v[144:145], s[4:5]
	v_mad_i64_i32 v[162:163], s[28:29], v155, s52, v[144:145]
	v_mul_f32_e32 v160, v160, v166
	v_mul_f32_e32 v164, v161, v166
	v_pk_mul_f32 v[158:159], v[158:159], v[160:161] op_sel_hi:[1,0]
	v_max_f32_e32 v160, v120, v120
	v_max_f32_e32 v166, v122, v122
	v_max_f32_e32 v160, 0xc1a00000, v160
	v_max_f32_e32 v166, 0xc1a00000, v166
	v_mul_f32_e32 v160, 0xbfb8aa3b, v160
	v_mul_f32_e32 v166, 0xbfb8aa3b, v166
	v_exp_f32_e32 v161, v160
	v_max_f32_e32 v160, v121, v121
	v_exp_f32_e32 v167, v166
	v_max_f32_e32 v166, v123, v123
	v_max_f32_e32 v160, 0xc1a00000, v160
	v_max_f32_e32 v166, 0xc1a00000, v166
	v_mul_f32_e32 v160, 0xbfb8aa3b, v160
	v_mul_f32_e32 v166, 0xbfb8aa3b, v166
	v_exp_f32_e32 v160, v160
	v_exp_f32_e32 v166, v166
	v_pk_mul_f32 v[156:157], v[156:157], v[164:165] op_sel_hi:[1,0]
	v_pk_mul_f32 v[126:127], v[126:127], v[158:159]
	v_pk_mul_f32 v[124:125], v[124:125], v[156:157]
	v_pk_add_f32 v[156:157], v[160:161], 1.0 op_sel_hi:[1,0]
	v_pk_add_f32 v[160:161], v[166:167], 1.0 op_sel_hi:[1,0]
	v_mov_b32_e32 v166, v157
	v_mov_b32_e32 v167, v161
	v_mov_b32_e32 v168, v156
	v_mov_b32_e32 v169, v160
	v_pk_mul_f32 v[166:167], v[166:167], v[168:169]
	v_pk_mul_f32 v[118:119], v[126:127], v[118:119]
	v_mul_f32_e32 v164, v166, v167
	v_rcp_f32_e32 v164, v164
	v_pk_mul_f32 v[116:117], v[124:125], v[116:117]
	v_lshlrev_b64 v[146:147], 1, v[146:147]
	v_lshl_add_u64 v[162:163], v[162:163], 0, v[146:147]
	v_mul_f32_e32 v124, v167, v164
	v_mul_f32_e32 v126, v166, v164
	v_pk_mul_f32 v[126:127], v[160:161], v[126:127] op_sel_hi:[1,0]
	v_pk_mul_f32 v[124:125], v[156:157], v[124:125] op_sel_hi:[1,0]
	v_pk_mul_f32 v[122:123], v[122:123], v[126:127]
	v_pk_mul_f32 v[120:121], v[120:121], v[124:125]
	v_pk_mul_f32 v[122:123], v[122:123], v[114:115]
	v_pk_mul_f32 v[114:115], v[120:121], v[112:113]
	v_cvt_pk_bf16_f32 v112, v116, v117
	v_cvt_pk_bf16_f32 v113, v118, v119
; __device__ __forceinline__ unsigned cvt_pk_bf16(float lo, float hi) { unsigned r; asm volatile("v_cvt_pk_bf16_f32 %0, %1, %2" : "=v"(r) : "v"(lo), "v"(hi)); return r; }
; __device__ __forceinline__ f32x4 sigmoid4(f32x4 x) {
;     f32x4 d;
; #pragma unroll
;     for (int j = 0; j < 4; ++j) d[j] = 1.0f + __expf(-fmaxf(x[j], -20.0f));
;     const float p01 = d[0] * d[1], p23 = d[2] * d[3], r = __builtin_amdgcn_rcpf(p01 * p23), r01 = r * p23, r23 = r * p01;
;     return (f32x4){r01 * d[1], r01 * d[0], r23 * d[3], r23 * d[2]};
; }
;     __device__ __forceinline__ void operator()(const f32x4 (&acc)[2][2][4][2], const Unit& u, int wr, int wc, int fr, int fq) const {
;     ...
;             for (int m = 0; m < 4; ++m) { bf16_t* rowp = O + (size_t)(row0 + ai * HALF + m * 16) * ldc + col0;
;                 f32x4 v0, v1;
; #pragma unroll
;                 for (int j = 0; j < 1; ++j) { v0 = acc[ai][0][m][0] * sigmoid4(acc[ai][0][m][0]) * acc[ai][1][m][0]; v1 = acc[ai][0][m][1] * sigmoid4(acc[ai][0][m][1]) * acc[ai][1][m][1]; }
;                 u32x4 w; w.x = cvt_pk_bf16(v0[0], v0[1]); w.y = cvt_pk_bf16(v0[2], v0[3]); w.z = cvt_pk_bf16(v1[0], v1[1]); w.w = cvt_pk_bf16(v1[2], v1[3]);
;                 *(u32x4*)rowp = w; }
	v_max_f32_e32 v116, v108, v108
	v_max_f32_e32 v118, v110, v110
	v_max_f32_e32 v116, 0xc1a00000, v116
	v_max_f32_e32 v118, 0xc1a00000, v118
	v_mul_f32_e32 v116, 0xbfb8aa3b, v116
	v_mul_f32_e32 v118, 0xbfb8aa3b, v118
	v_exp_f32_e32 v117, v116
	v_max_f32_e32 v116, v109, v109
	v_exp_f32_e32 v119, v118
	v_max_f32_e32 v118, v111, v111
	v_max_f32_e32 v116, 0xc1a00000, v116
	v_max_f32_e32 v118, 0xc1a00000, v118
	v_mul_f32_e32 v116, 0xbfb8aa3b, v116
	v_mul_f32_e32 v118, 0xbfb8aa3b, v118
	v_exp_f32_e32 v116, v116
	v_exp_f32_e32 v118, v118
	v_cvt_pk_bf16_f32 v114, v114, v115
	v_cvt_pk_bf16_f32 v115, v122, v123
	global_store_dwordx4 v[162:163], v[112:115], off
	v_or_b32_e32 v120, 16, v155
	s_and_b64 vcc, exec, s[2:3]
	v_pk_add_f32 v[112:113], v[116:117], 1.0 op_sel_hi:[1,0]
	v_pk_add_f32 v[114:115], v[118:119], 1.0 op_sel_hi:[1,0]
	v_mov_b32_e32 v116, v113
	v_mov_b32_e32 v117, v115
	v_mov_b32_e32 v118, v112
	v_mov_b32_e32 v119, v114
	v_pk_mul_f32 v[116:117], v[116:117], v[118:119]
	s_mov_b32 s53, s14
	v_mul_f32_e32 v118, v116, v117
	v_rcp_f32_e32 v121, v118
	v_mad_i64_i32 v[118:119], s[28:29], v120, s52, v[144:145]
	v_lshl_add_u64 v[118:119], v[118:119], 0, v[146:147]
	v_mul_f32_e32 v116, v116, v121
	v_mul_f32_e32 v120, v117, v121
	v_pk_mul_f32 v[114:115], v[114:115], v[116:117] op_sel_hi:[1,0]
	v_max_f32_e32 v116, v104, v104
	v_max_f32_e32 v121, v106, v106
	v_max_f32_e32 v116, 0xc1a00000, v116
	v_max_f32_e32 v121, 0xc1a00000, v121
	v_mul_f32_e32 v116, 0xbfb8aa3b, v116
	v_mul_f32_e32 v121, 0xbfb8aa3b, v121
	v_exp_f32_e32 v117, v116
	v_max_f32_e32 v116, v105, v105
	v_exp_f32_e32 v123, v121
	v_max_f32_e32 v121, v107, v107
	v_max_f32_e32 v116, 0xc1a00000, v116
	v_max_f32_e32 v121, 0xc1a00000, v121
	v_mul_f32_e32 v116, 0xbfb8aa3b, v116
	v_mul_f32_e32 v121, 0xbfb8aa3b, v121
	v_exp_f32_e32 v116, v116
	v_exp_f32_e32 v122, v121
	v_pk_mul_f32 v[112:113], v[112:113], v[120:121] op_sel_hi:[1,0]
	v_pk_mul_f32 v[110:111], v[110:111], v[114:115]
	v_pk_mul_f32 v[108:109], v[108:109], v[112:113]
	v_pk_add_f32 v[112:113], v[116:117], 1.0 op_sel_hi:[1,0]
	v_pk_add_f32 v[116:117], v[122:123], 1.0 op_sel_hi:[1,0]
	v_mov_b32_e32 v120, v113
	v_mov_b32_e32 v121, v117
	v_mov_b32_e32 v122, v112
	v_mov_b32_e32 v123, v116
	v_pk_mul_f32 v[120:121], v[120:121], v[122:123]
	v_pk_mul_f32 v[102:103], v[110:111], v[102:103]
	v_mul_f32_e32 v122, v120, v121
	v_rcp_f32_e32 v122, v122
	v_pk_mul_f32 v[100:101], v[108:109], v[100:101]
	s_mov_b32 s26, s16
	s_mov_b64 s[30:31], s[24:25]
	v_mul_f32_e32 v108, v121, v122
	v_mul_f32_e32 v110, v120, v122
	v_pk_mul_f32 v[110:111], v[116:117], v[110:111] op_sel_hi:[1,0]
	v_pk_mul_f32 v[108:109], v[112:113], v[108:109] op_sel_hi:[1,0]
	v_pk_mul_f32 v[106:107], v[106:107], v[110:111]
	v_pk_mul_f32 v[104:105], v[104:105], v[108:109]
	v_pk_mul_f32 v[106:107], v[106:107], v[98:99]
	v_pk_mul_f32 v[98:99], v[104:105], v[96:97]
	v_cvt_pk_bf16_f32 v96, v100, v101
	v_cvt_pk_bf16_f32 v97, v102, v103
	v_max_f32_e32 v100, v92, v92
	v_max_f32_e32 v102, v94, v94
	v_max_f32_e32 v100, 0xc1a00000, v100
	v_max_f32_e32 v102, 0xc1a00000, v102
	v_mul_f32_e32 v100, 0xbfb8aa3b, v100
	v_mul_f32_e32 v102, 0xbfb8aa3b, v102
	v_exp_f32_e32 v101, v100
	v_max_f32_e32 v100, v93, v93
	v_exp_f32_e32 v103, v102
	v_max_f32_e32 v102, v95, v95
	v_max_f32_e32 v100, 0xc1a00000, v100
	v_max_f32_e32 v102, 0xc1a00000, v102
	v_mul_f32_e32 v100, 0xbfb8aa3b, v100
	v_mul_f32_e32 v102, 0xbfb8aa3b, v102
	v_exp_f32_e32 v100, v100
	v_exp_f32_e32 v102, v102
	v_cvt_pk_bf16_f32 v98, v98, v99
	v_cvt_pk_bf16_f32 v99, v106, v107
	global_store_dwordx4 v[118:119], v[96:99], off
	v_or_b32_e32 v104, 32, v155
	s_nop 0
	v_pk_add_f32 v[96:97], v[100:101], 1.0 op_sel_hi:[1,0]
	v_pk_add_f32 v[98:99], v[102:103], 1.0 op_sel_hi:[1,0]
	v_mov_b32_e32 v100, v97
	v_mov_b32_e32 v101, v99
	v_mov_b32_e32 v102, v96
	v_mov_b32_e32 v103, v98
	v_pk_mul_f32 v[100:101], v[100:101], v[102:103]
	s_nop 0
	v_mul_f32_e32 v102, v100, v101
	v_rcp_f32_e32 v105, v102
	v_mad_i64_i32 v[102:103], s[28:29], v104, s52, v[144:145]
	v_lshl_add_u64 v[102:103], v[102:103], 0, v[146:147]
	v_mul_f32_e32 v100, v100, v105
	v_mul_f32_e32 v104, v101, v105
	v_pk_mul_f32 v[98:99], v[98:99], v[100:101] op_sel_hi:[1,0]
	v_max_f32_e32 v100, v88, v88
	v_max_f32_e32 v105, v90, v90
	v_max_f32_e32 v100, 0xc1a00000, v100
	v_max_f32_e32 v105, 0xc1a00000, v105
	v_mul_f32_e32 v100, 0xbfb8aa3b, v100
	v_mul_f32_e32 v105, 0xbfb8aa3b, v105
	v_exp_f32_e32 v101, v100
	v_max_f32_e32 v100, v89, v89
	v_exp_f32_e32 v107, v105
	v_max_f32_e32 v105, v91, v91
	v_max_f32_e32 v100, 0xc1a00000, v100
	v_max_f32_e32 v105, 0xc1a00000, v105
	v_mul_f32_e32 v100, 0xbfb8aa3b, v100
	v_mul_f32_e32 v105, 0xbfb8aa3b, v105
	v_exp_f32_e32 v100, v100
	v_exp_f32_e32 v106, v105
	v_pk_mul_f32 v[96:97], v[96:97], v[104:105] op_sel_hi:[1,0]
	v_pk_mul_f32 v[94:95], v[94:95], v[98:99]
	v_pk_mul_f32 v[92:93], v[92:93], v[96:97]
	v_pk_add_f32 v[96:97], v[100:101], 1.0 op_sel_hi:[1,0]
	v_pk_add_f32 v[100:101], v[106:107], 1.0 op_sel_hi:[1,0]
	v_mov_b32_e32 v104, v97
	v_mov_b32_e32 v105, v101
	v_mov_b32_e32 v106, v96
	v_mov_b32_e32 v107, v100
	v_pk_mul_f32 v[104:105], v[104:105], v[106:107]
	v_pk_mul_f32 v[86:87], v[94:95], v[86:87]
	v_mul_f32_e32 v106, v104, v105
	v_rcp_f32_e32 v106, v106
	v_pk_mul_f32 v[84:85], v[92:93], v[84:85]
	v_mul_f32_e32 v92, v105, v106
	v_mul_f32_e32 v94, v104, v106
	v_pk_mul_f32 v[94:95], v[100:101], v[94:95] op_sel_hi:[1,0]
	v_pk_mul_f32 v[92:93], v[96:97], v[92:93] op_sel_hi:[1,0]
	v_pk_mul_f32 v[90:91], v[90:91], v[94:95]
	v_pk_mul_f32 v[88:89], v[88:89], v[92:93]
	v_pk_mul_f32 v[90:91], v[90:91], v[82:83]
	v_pk_mul_f32 v[82:83], v[88:89], v[80:81]
	v_cvt_pk_bf16_f32 v80, v84, v85
; __device__ __forceinline__ unsigned cvt_pk_bf16(float lo, float hi) { unsigned r; asm volatile("v_cvt_pk_bf16_f32 %0, %1, %2" : "=v"(r) : "v"(lo), "v"(hi)); return r; }
; __device__ __forceinline__ f32x4 sigmoid4(f32x4 x) {
;     f32x4 d;
; #pragma unroll
;     for (int j = 0; j < 4; ++j) d[j] = 1.0f + __expf(-fmaxf(x[j], -20.0f));
;     const float p01 = d[0] * d[1], p23 = d[2] * d[3], r = __builtin_amdgcn_rcpf(p01 * p23), r01 = r * p23, r23 = r * p01;
;     return (f32x4){r01 * d[1], r01 * d[0], r23 * d[3], r23 * d[2]};
; }
;     __device__ __forceinline__ void operator()(const f32x4 (&acc)[2][2][4][2], const Unit& u, int wr, int wc, int fr, int fq) const {
;     ...
;             for (int m = 0; m < 4; ++m) { bf16_t* rowp = O + (size_t)(row0 + ai * HALF + m * 16) * ldc + col0;
;                 f32x4 v0, v1;
; #pragma unroll
;                 for (int j = 0; j < 1; ++j) { v0 = acc[ai][0][m][0] * sigmoid4(acc[ai][0][m][0]) * acc[ai][1][m][0]; v1 = acc[ai][0][m][1] * sigmoid4(acc[ai][0][m][1]) * acc[ai][1][m][1]; }
;                 u32x4 w; w.x = cvt_pk_bf16(v0[0], v0[1]); w.y = cvt_pk_bf16(v0[2], v0[3]); w.z = cvt_pk_bf16(v1[0], v1[1]); w.w = cvt_pk_bf16(v1[2], v1[3]);
;                 *(u32x4*)rowp = w; }
	v_cvt_pk_bf16_f32 v81, v86, v87
	v_max_f32_e32 v84, v76, v76
	v_max_f32_e32 v86, v78, v78
	v_max_f32_e32 v84, 0xc1a00000, v84
	v_max_f32_e32 v86, 0xc1a00000, v86
	v_mul_f32_e32 v84, 0xbfb8aa3b, v84
	v_mul_f32_e32 v86, 0xbfb8aa3b, v86
	v_exp_f32_e32 v85, v84
	v_max_f32_e32 v84, v77, v77
	v_exp_f32_e32 v87, v86
	v_max_f32_e32 v86, v79, v79
	v_max_f32_e32 v84, 0xc1a00000, v84
	v_max_f32_e32 v86, 0xc1a00000, v86
	v_mul_f32_e32 v84, 0xbfb8aa3b, v84
	v_mul_f32_e32 v86, 0xbfb8aa3b, v86
	v_exp_f32_e32 v84, v84
	v_exp_f32_e32 v86, v86
	v_cvt_pk_bf16_f32 v82, v82, v83
	v_cvt_pk_bf16_f32 v83, v90, v91
	global_store_dwordx4 v[102:103], v[80:83], off
	v_or_b32_e32 v88, 48, v155
	s_nop 0
	v_pk_add_f32 v[80:81], v[84:85], 1.0 op_sel_hi:[1,0]
	v_pk_add_f32 v[82:83], v[86:87], 1.0 op_sel_hi:[1,0]
	v_mov_b32_e32 v84, v81
	v_mov_b32_e32 v85, v83
	v_mov_b32_e32 v86, v80
	v_mov_b32_e32 v87, v82
	v_pk_mul_f32 v[84:85], v[84:85], v[86:87]
	s_nop 0
	v_mul_f32_e32 v86, v84, v85
	v_rcp_f32_e32 v89, v86
	v_mad_i64_i32 v[86:87], s[28:29], v88, s52, v[144:145]
	v_lshl_add_u64 v[86:87], v[86:87], 0, v[146:147]
	v_mul_f32_e32 v84, v84, v89
	v_mul_f32_e32 v88, v85, v89
	v_pk_mul_f32 v[82:83], v[82:83], v[84:85] op_sel_hi:[1,0]
	v_max_f32_e32 v84, v72, v72
	v_max_f32_e32 v89, v74, v74
	v_max_f32_e32 v84, 0xc1a00000, v84
	v_max_f32_e32 v89, 0xc1a00000, v89
	v_mul_f32_e32 v84, 0xbfb8aa3b, v84
	v_mul_f32_e32 v89, 0xbfb8aa3b, v89
	v_exp_f32_e32 v85, v84
	v_max_f32_e32 v84, v73, v73
	v_exp_f32_e32 v91, v89
	v_max_f32_e32 v89, v75, v75
	v_max_f32_e32 v84, 0xc1a00000, v84
	v_max_f32_e32 v89, 0xc1a00000, v89
	v_mul_f32_e32 v84, 0xbfb8aa3b, v84
	v_mul_f32_e32 v89, 0xbfb8aa3b, v89
	v_exp_f32_e32 v84, v84
	v_exp_f32_e32 v90, v89
	v_pk_mul_f32 v[80:81], v[80:81], v[88:89] op_sel_hi:[1,0]
	v_pk_mul_f32 v[78:79], v[78:79], v[82:83]
	v_pk_mul_f32 v[76:77], v[76:77], v[80:81]
	v_pk_add_f32 v[80:81], v[84:85], 1.0 op_sel_hi:[1,0]
	v_pk_add_f32 v[84:85], v[90:91], 1.0 op_sel_hi:[1,0]
	v_mov_b32_e32 v88, v81
	v_mov_b32_e32 v89, v85
	v_mov_b32_e32 v90, v80
	v_mov_b32_e32 v91, v84
	v_pk_mul_f32 v[88:89], v[88:89], v[90:91]
	v_pk_mul_f32 v[70:71], v[78:79], v[70:71]
	v_mul_f32_e32 v90, v88, v89
	v_rcp_f32_e32 v90, v90
	v_pk_mul_f32 v[68:69], v[76:77], v[68:69]
	v_mul_f32_e32 v76, v89, v90
	v_mul_f32_e32 v78, v88, v90
	v_pk_mul_f32 v[78:79], v[84:85], v[78:79] op_sel_hi:[1,0]
	v_pk_mul_f32 v[76:77], v[80:81], v[76:77] op_sel_hi:[1,0]
	v_pk_mul_f32 v[74:75], v[74:75], v[78:79]
	v_pk_mul_f32 v[72:73], v[72:73], v[76:77]
	v_pk_mul_f32 v[74:75], v[74:75], v[66:67]
	v_pk_mul_f32 v[66:67], v[72:73], v[64:65]
	v_cvt_pk_bf16_f32 v64, v68, v69
	v_cvt_pk_bf16_f32 v65, v70, v71
	v_max_f32_e32 v68, v60, v60
	v_max_f32_e32 v70, v62, v62
	v_max_f32_e32 v68, 0xc1a00000, v68
	v_max_f32_e32 v70, 0xc1a00000, v70
	v_mul_f32_e32 v68, 0xbfb8aa3b, v68
	v_mul_f32_e32 v70, 0xbfb8aa3b, v70
	v_exp_f32_e32 v69, v68
	v_max_f32_e32 v68, v61, v61
	v_exp_f32_e32 v71, v70
	v_max_f32_e32 v70, v63, v63
	v_max_f32_e32 v68, 0xc1a00000, v68
	v_max_f32_e32 v70, 0xc1a00000, v70
	v_mul_f32_e32 v68, 0xbfb8aa3b, v68
	v_mul_f32_e32 v70, 0xbfb8aa3b, v70
	v_exp_f32_e32 v68, v68
	v_exp_f32_e32 v70, v70
	v_cvt_pk_bf16_f32 v66, v66, v67
	v_cvt_pk_bf16_f32 v67, v74, v75
	global_store_dwordx4 v[86:87], v[64:67], off
	v_add_u32_e32 v72, 0x80, v155
	s_nop 0
	v_pk_add_f32 v[64:65], v[68:69], 1.0 op_sel_hi:[1,0]
	v_pk_add_f32 v[66:67], v[70:71], 1.0 op_sel_hi:[1,0]
	v_mov_b32_e32 v68, v65
	v_mov_b32_e32 v69, v67
	v_mov_b32_e32 v70, v64
	v_mov_b32_e32 v71, v66
	v_pk_mul_f32 v[68:69], v[68:69], v[70:71]
	s_nop 0
	v_mul_f32_e32 v70, v68, v69
	v_rcp_f32_e32 v73, v70
	v_mad_i64_i32 v[70:71], s[28:29], v72, s52, v[144:145]
	v_lshl_add_u64 v[70:71], v[70:71], 0, v[146:147]
	v_mul_f32_e32 v68, v68, v73
	v_mul_f32_e32 v72, v69, v73
	v_pk_mul_f32 v[66:67], v[66:67], v[68:69] op_sel_hi:[1,0]
	v_max_f32_e32 v68, v56, v56
	v_max_f32_e32 v73, v58, v58
	v_max_f32_e32 v68, 0xc1a00000, v68
	v_max_f32_e32 v73, 0xc1a00000, v73
	v_mul_f32_e32 v68, 0xbfb8aa3b, v68
	v_mul_f32_e32 v73, 0xbfb8aa3b, v73
	v_exp_f32_e32 v69, v68
	v_max_f32_e32 v68, v57, v57
	v_exp_f32_e32 v75, v73
	v_max_f32_e32 v73, v59, v59
	v_max_f32_e32 v68, 0xc1a00000, v68
	v_max_f32_e32 v73, 0xc1a00000, v73
	v_mul_f32_e32 v68, 0xbfb8aa3b, v68
	v_mul_f32_e32 v73, 0xbfb8aa3b, v73
	v_exp_f32_e32 v68, v68
	v_exp_f32_e32 v74, v73
	v_pk_mul_f32 v[64:65], v[64:65], v[72:73] op_sel_hi:[1,0]
	v_pk_mul_f32 v[62:63], v[62:63], v[66:67]
	v_pk_mul_f32 v[60:61], v[60:61], v[64:65]
	v_pk_add_f32 v[64:65], v[68:69], 1.0 op_sel_hi:[1,0]
	v_pk_add_f32 v[68:69], v[74:75], 1.0 op_sel_hi:[1,0]
	v_mov_b32_e32 v72, v65
	v_mov_b32_e32 v73, v69
	v_mov_b32_e32 v74, v64
	v_mov_b32_e32 v75, v68
	v_pk_mul_f32 v[72:73], v[72:73], v[74:75]
	v_pk_mul_f32 v[54:55], v[62:63], v[54:55]
	v_mul_f32_e32 v74, v72, v73
	v_rcp_f32_e32 v74, v74
	v_pk_mul_f32 v[52:53], v[60:61], v[52:53]
	v_mul_f32_e32 v60, v73, v74
	v_mul_f32_e32 v62, v72, v74
	v_pk_mul_f32 v[62:63], v[68:69], v[62:63] op_sel_hi:[1,0]
	v_pk_mul_f32 v[60:61], v[64:65], v[60:61] op_sel_hi:[1,0]
	v_pk_mul_f32 v[58:59], v[58:59], v[62:63]
	v_pk_mul_f32 v[56:57], v[56:57], v[60:61]
	v_pk_mul_f32 v[58:59], v[58:59], v[50:51]
	v_pk_mul_f32 v[50:51], v[56:57], v[48:49]
	v_cvt_pk_bf16_f32 v48, v52, v53
	v_cvt_pk_bf16_f32 v49, v54, v55
	v_max_f32_e32 v52, v44, v44
	v_max_f32_e32 v54, v46, v46
	v_max_f32_e32 v52, 0xc1a00000, v52
	v_max_f32_e32 v54, 0xc1a00000, v54
	v_mul_f32_e32 v52, 0xbfb8aa3b, v52
	v_mul_f32_e32 v54, 0xbfb8aa3b, v54
	v_exp_f32_e32 v53, v52
	v_max_f32_e32 v52, v45, v45
	v_exp_f32_e32 v55, v54
	v_max_f32_e32 v54, v47, v47
	v_max_f32_e32 v52, 0xc1a00000, v52
; __device__ __forceinline__ unsigned cvt_pk_bf16(float lo, float hi) { unsigned r; asm volatile("v_cvt_pk_bf16_f32 %0, %1, %2" : "=v"(r) : "v"(lo), "v"(hi)); return r; }
; __device__ __forceinline__ f32x4 sigmoid4(f32x4 x) {
;     f32x4 d;
; #pragma unroll
;     for (int j = 0; j < 4; ++j) d[j] = 1.0f + __expf(-fmaxf(x[j], -20.0f));
;     const float p01 = d[0] * d[1], p23 = d[2] * d[3], r = __builtin_amdgcn_rcpf(p01 * p23), r01 = r * p23, r23 = r * p01;
;     return (f32x4){r01 * d[1], r01 * d[0], r23 * d[3], r23 * d[2]};
; }
;     __device__ __forceinline__ void operator()(const f32x4 (&acc)[2][2][4][2], const Unit& u, int wr, int wc, int fr, int fq) const {
;     ...
;             for (int m = 0; m < 4; ++m) { bf16_t* rowp = O + (size_t)(row0 + ai * HALF + m * 16) * ldc + col0;
;                 f32x4 v0, v1;
; #pragma unroll
;                 for (int j = 0; j < 1; ++j) { v0 = acc[ai][0][m][0] * sigmoid4(acc[ai][0][m][0]) * acc[ai][1][m][0]; v1 = acc[ai][0][m][1] * sigmoid4(acc[ai][0][m][1]) * acc[ai][1][m][1]; }
;                 u32x4 w; w.x = cvt_pk_bf16(v0[0], v0[1]); w.y = cvt_pk_bf16(v0[2], v0[3]); w.z = cvt_pk_bf16(v1[0], v1[1]); w.w = cvt_pk_bf16(v1[2], v1[3]);
;                 *(u32x4*)rowp = w; }
	v_max_f32_e32 v54, 0xc1a00000, v54
	v_mul_f32_e32 v52, 0xbfb8aa3b, v52
	v_mul_f32_e32 v54, 0xbfb8aa3b, v54
	v_exp_f32_e32 v52, v52
	v_exp_f32_e32 v54, v54
	v_cvt_pk_bf16_f32 v50, v50, v51
	v_cvt_pk_bf16_f32 v51, v58, v59
	global_store_dwordx4 v[70:71], v[48:51], off
	v_add_u32_e32 v56, 0x90, v155
	s_nop 0
	v_pk_add_f32 v[48:49], v[52:53], 1.0 op_sel_hi:[1,0]
	v_pk_add_f32 v[50:51], v[54:55], 1.0 op_sel_hi:[1,0]
	v_mov_b32_e32 v52, v49
	v_mov_b32_e32 v53, v51
	v_mov_b32_e32 v54, v48
	v_mov_b32_e32 v55, v50
	v_pk_mul_f32 v[52:53], v[52:53], v[54:55]
	s_nop 0
	v_mul_f32_e32 v54, v52, v53
	v_rcp_f32_e32 v57, v54
	v_mad_i64_i32 v[54:55], s[28:29], v56, s52, v[144:145]
	v_lshl_add_u64 v[54:55], v[54:55], 0, v[146:147]
	v_mul_f32_e32 v52, v52, v57
	v_mul_f32_e32 v56, v53, v57
	v_pk_mul_f32 v[50:51], v[50:51], v[52:53] op_sel_hi:[1,0]
	v_max_f32_e32 v52, v40, v40
	v_max_f32_e32 v57, v42, v42
	v_max_f32_e32 v52, 0xc1a00000, v52
	v_max_f32_e32 v57, 0xc1a00000, v57
	v_mul_f32_e32 v52, 0xbfb8aa3b, v52
	v_mul_f32_e32 v57, 0xbfb8aa3b, v57
	v_exp_f32_e32 v53, v52
	v_max_f32_e32 v52, v41, v41
	v_exp_f32_e32 v59, v57
	v_max_f32_e32 v57, v43, v43
	v_max_f32_e32 v52, 0xc1a00000, v52
	v_max_f32_e32 v57, 0xc1a00000, v57
	v_mul_f32_e32 v52, 0xbfb8aa3b, v52
	v_mul_f32_e32 v57, 0xbfb8aa3b, v57
	v_exp_f32_e32 v52, v52
	v_exp_f32_e32 v58, v57
	v_pk_mul_f32 v[48:49], v[48:49], v[56:57] op_sel_hi:[1,0]
	v_pk_mul_f32 v[46:47], v[46:47], v[50:51]
	v_pk_mul_f32 v[44:45], v[44:45], v[48:49]
	v_pk_add_f32 v[48:49], v[52:53], 1.0 op_sel_hi:[1,0]
	v_pk_add_f32 v[52:53], v[58:59], 1.0 op_sel_hi:[1,0]
	v_mov_b32_e32 v56, v49
	v_mov_b32_e32 v57, v53
	v_mov_b32_e32 v58, v48
	v_mov_b32_e32 v59, v52
	v_pk_mul_f32 v[56:57], v[56:57], v[58:59]
	v_pk_mul_f32 v[38:39], v[46:47], v[38:39]
	v_mul_f32_e32 v58, v56, v57
	v_rcp_f32_e32 v58, v58
	v_pk_mul_f32 v[36:37], v[44:45], v[36:37]
	v_mul_f32_e32 v44, v57, v58
	v_mul_f32_e32 v46, v56, v58
	v_pk_mul_f32 v[46:47], v[52:53], v[46:47] op_sel_hi:[1,0]
	v_pk_mul_f32 v[44:45], v[48:49], v[44:45] op_sel_hi:[1,0]
	v_pk_mul_f32 v[42:43], v[42:43], v[46:47]
	v_pk_mul_f32 v[40:41], v[40:41], v[44:45]
	v_pk_mul_f32 v[42:43], v[42:43], v[34:35]
	v_pk_mul_f32 v[34:35], v[40:41], v[32:33]
	v_cvt_pk_bf16_f32 v32, v36, v37
	v_cvt_pk_bf16_f32 v33, v38, v39
	v_max_f32_e32 v36, v28, v28
	v_max_f32_e32 v38, v30, v30
	v_max_f32_e32 v36, 0xc1a00000, v36
	v_max_f32_e32 v38, 0xc1a00000, v38
	v_mul_f32_e32 v36, 0xbfb8aa3b, v36
	v_mul_f32_e32 v38, 0xbfb8aa3b, v38
	v_exp_f32_e32 v37, v36
	v_max_f32_e32 v36, v29, v29
	v_exp_f32_e32 v39, v38
	v_max_f32_e32 v38, v31, v31
	v_max_f32_e32 v36, 0xc1a00000, v36
	v_max_f32_e32 v38, 0xc1a00000, v38
	v_mul_f32_e32 v36, 0xbfb8aa3b, v36
	v_mul_f32_e32 v38, 0xbfb8aa3b, v38
	v_exp_f32_e32 v36, v36
	v_exp_f32_e32 v38, v38
	v_cvt_pk_bf16_f32 v34, v34, v35
	v_cvt_pk_bf16_f32 v35, v42, v43
	global_store_dwordx4 v[54:55], v[32:35], off
	v_add_u32_e32 v40, 0xa0, v155
	s_nop 0
	v_pk_add_f32 v[32:33], v[36:37], 1.0 op_sel_hi:[1,0]
	v_pk_add_f32 v[34:35], v[38:39], 1.0 op_sel_hi:[1,0]
	v_mov_b32_e32 v36, v33
	v_mov_b32_e32 v37, v35
	v_mov_b32_e32 v38, v32
	v_mov_b32_e32 v39, v34
	v_pk_mul_f32 v[36:37], v[36:37], v[38:39]
	s_nop 0
	v_mul_f32_e32 v38, v36, v37
	v_rcp_f32_e32 v41, v38
	v_mad_i64_i32 v[38:39], s[28:29], v40, s52, v[144:145]
	v_lshl_add_u64 v[38:39], v[38:39], 0, v[146:147]
	v_mul_f32_e32 v36, v36, v41
	v_mul_f32_e32 v40, v37, v41
	v_pk_mul_f32 v[34:35], v[34:35], v[36:37] op_sel_hi:[1,0]
	v_max_f32_e32 v36, v24, v24
	v_max_f32_e32 v41, v26, v26
	v_max_f32_e32 v36, 0xc1a00000, v36
	v_max_f32_e32 v41, 0xc1a00000, v41
	v_mul_f32_e32 v36, 0xbfb8aa3b, v36
	v_mul_f32_e32 v41, 0xbfb8aa3b, v41
	v_exp_f32_e32 v37, v36
	v_max_f32_e32 v36, v25, v25
	v_exp_f32_e32 v43, v41
	v_max_f32_e32 v41, v27, v27
	v_max_f32_e32 v36, 0xc1a00000, v36
	v_max_f32_e32 v41, 0xc1a00000, v41
	v_mul_f32_e32 v36, 0xbfb8aa3b, v36
; __device__ __forceinline__ unsigned cvt_pk_bf16(float lo, float hi) { unsigned r; asm volatile("v_cvt_pk_bf16_f32 %0, %1, %2" : "=v"(r) : "v"(lo), "v"(hi)); return r; }
; #define PG8_WAIT_V(n) asm volatile("s_waitcnt vmcnt(" #n ")" ::: "memory")
; #define PG8_BAR __builtin_amdgcn_s_barrier()
; __device__ __forceinline__ f32x4 sigmoid4(f32x4 x) {
;     f32x4 d;
; #pragma unroll
;     for (int j = 0; j < 4; ++j) d[j] = 1.0f + __expf(-fmaxf(x[j], -20.0f));
;     const float p01 = d[0] * d[1], p23 = d[2] * d[3], r = __builtin_amdgcn_rcpf(p01 * p23), r01 = r * p23, r23 = r * p01;
;     return (f32x4){r01 * d[1], r01 * d[0], r23 * d[3], r23 * d[2]};
; }
;     __device__ __forceinline__ void operator()(const f32x4 (&acc)[2][2][4][2], const Unit& u, int wr, int wc, int fr, int fq) const {
;     ...
;             for (int m = 0; m < 4; ++m) { bf16_t* rowp = O + (size_t)(row0 + ai * HALF + m * 16) * ldc + col0;
;                 f32x4 v0, v1;
; #pragma unroll
;                 for (int j = 0; j < 1; ++j) { v0 = acc[ai][0][m][0] * sigmoid4(acc[ai][0][m][0]) * acc[ai][1][m][0]; v1 = acc[ai][0][m][1] * sigmoid4(acc[ai][0][m][1]) * acc[ai][1][m][1]; }
;                 u32x4 w; w.x = cvt_pk_bf16(v0[0], v0[1]); w.y = cvt_pk_bf16(v0[2], v0[3]); w.z = cvt_pk_bf16(v1[0], v1[1]); w.w = cvt_pk_bf16(v1[2], v1[3]);
;                 *(u32x4*)rowp = w; }
; template <class Epi, class Sched>
; __device__ __forceinline__ void gemm_phase(PG8_LAS unsigned char* lds, const Gemm g, const Sched& S, const Epi& E) {
;     ...
;         if (!has_next) break;
; #pragma unroll
;         for (int a = 0; a < 2; ++a)
; #pragma unroll
;             for (int b = 0; b < 2; ++b)
; #pragma unroll
;                 for (int m = 0; m < 4; ++m)
; #pragma unroll
;                     for (int n = 0; n < 2; ++n) acc[a][b][m][n] = (f32x4){0.f, 0.f, 0.f, 0.f};
;         cur = nxt; cA = nA; cB = nB; ++ui;
;     }
;     PG8_WAIT_V(0);
;     if (wr == 0) PG8_BAR;
;     PG8_BAR;
	v_mul_f32_e32 v41, 0xbfb8aa3b, v41
	v_exp_f32_e32 v36, v36
	v_exp_f32_e32 v42, v41
	v_pk_mul_f32 v[32:33], v[32:33], v[40:41] op_sel_hi:[1,0]
	v_pk_mul_f32 v[30:31], v[30:31], v[34:35]
	v_pk_mul_f32 v[28:29], v[28:29], v[32:33]
	v_pk_add_f32 v[32:33], v[36:37], 1.0 op_sel_hi:[1,0]
	v_pk_add_f32 v[36:37], v[42:43], 1.0 op_sel_hi:[1,0]
	v_mov_b32_e32 v40, v33
	v_mov_b32_e32 v41, v37
	v_mov_b32_e32 v42, v32
	v_mov_b32_e32 v43, v36
	v_pk_mul_f32 v[40:41], v[40:41], v[42:43]
	v_pk_mul_f32 v[22:23], v[30:31], v[22:23]
	v_mul_f32_e32 v42, v40, v41
	v_rcp_f32_e32 v42, v42
	v_pk_mul_f32 v[20:21], v[28:29], v[20:21]
	v_mul_f32_e32 v28, v41, v42
	v_mul_f32_e32 v30, v40, v42
	v_pk_mul_f32 v[30:31], v[36:37], v[30:31] op_sel_hi:[1,0]
	v_pk_mul_f32 v[28:29], v[32:33], v[28:29] op_sel_hi:[1,0]
	v_pk_mul_f32 v[26:27], v[26:27], v[30:31]
	v_pk_mul_f32 v[24:25], v[24:25], v[28:29]
	v_pk_mul_f32 v[26:27], v[26:27], v[18:19]
	v_pk_mul_f32 v[18:19], v[24:25], v[16:17]
	v_cvt_pk_bf16_f32 v16, v20, v21
	v_cvt_pk_bf16_f32 v17, v22, v23
	v_max_f32_e32 v20, v12, v12
	v_max_f32_e32 v22, v14, v14
	v_max_f32_e32 v20, 0xc1a00000, v20
	v_max_f32_e32 v22, 0xc1a00000, v22
	v_mul_f32_e32 v20, 0xbfb8aa3b, v20
	v_mul_f32_e32 v22, 0xbfb8aa3b, v22
	v_exp_f32_e32 v21, v20
	v_max_f32_e32 v20, v13, v13
	v_exp_f32_e32 v23, v22
	v_max_f32_e32 v22, v15, v15
	v_max_f32_e32 v20, 0xc1a00000, v20
	v_max_f32_e32 v22, 0xc1a00000, v22
	v_mul_f32_e32 v20, 0xbfb8aa3b, v20
	v_mul_f32_e32 v22, 0xbfb8aa3b, v22
	v_exp_f32_e32 v20, v20
	v_exp_f32_e32 v22, v22
	v_cvt_pk_bf16_f32 v18, v18, v19
	v_cvt_pk_bf16_f32 v19, v26, v27
	global_store_dwordx4 v[38:39], v[16:19], off
	v_add_u32_e32 v24, 0xb0, v155
	s_nop 0
	v_pk_add_f32 v[16:17], v[20:21], 1.0 op_sel_hi:[1,0]
	v_pk_add_f32 v[18:19], v[22:23], 1.0 op_sel_hi:[1,0]
	v_mov_b32_e32 v20, v17
	v_mov_b32_e32 v21, v19
	v_mov_b32_e32 v22, v16
	v_mov_b32_e32 v23, v18
	v_pk_mul_f32 v[20:21], v[20:21], v[22:23]
	s_nop 0
	v_mul_f32_e32 v22, v20, v21
	v_rcp_f32_e32 v25, v22
	v_mad_i64_i32 v[22:23], s[28:29], v24, s52, v[144:145]
	v_lshl_add_u64 v[22:23], v[22:23], 0, v[146:147]
	v_mul_f32_e32 v20, v20, v25
	v_mul_f32_e32 v24, v21, v25
	v_pk_mul_f32 v[18:19], v[18:19], v[20:21] op_sel_hi:[1,0]
	v_max_f32_e32 v20, v8, v8
	v_max_f32_e32 v25, v10, v10
	v_max_f32_e32 v20, 0xc1a00000, v20
	v_max_f32_e32 v25, 0xc1a00000, v25
	v_mul_f32_e32 v20, 0xbfb8aa3b, v20
	v_mul_f32_e32 v25, 0xbfb8aa3b, v25
	v_exp_f32_e32 v21, v20
	v_max_f32_e32 v20, v9, v9
	v_exp_f32_e32 v27, v25
	v_max_f32_e32 v25, v11, v11
	v_max_f32_e32 v20, 0xc1a00000, v20
	v_max_f32_e32 v25, 0xc1a00000, v25
	v_mul_f32_e32 v20, 0xbfb8aa3b, v20
	v_mul_f32_e32 v25, 0xbfb8aa3b, v25
	v_exp_f32_e32 v20, v20
	v_exp_f32_e32 v26, v25
	v_pk_mul_f32 v[16:17], v[16:17], v[24:25] op_sel_hi:[1,0]
	v_pk_mul_f32 v[14:15], v[14:15], v[18:19]
	v_pk_mul_f32 v[12:13], v[12:13], v[16:17]
	v_pk_add_f32 v[16:17], v[20:21], 1.0 op_sel_hi:[1,0]
	v_pk_add_f32 v[20:21], v[26:27], 1.0 op_sel_hi:[1,0]
	v_mov_b32_e32 v24, v17
	v_mov_b32_e32 v25, v21
	v_mov_b32_e32 v26, v16
	v_mov_b32_e32 v27, v20
	v_pk_mul_f32 v[24:25], v[24:25], v[26:27]
	v_pk_mul_f32 v[6:7], v[14:15], v[6:7]
	v_mul_f32_e32 v26, v24, v25
	v_rcp_f32_e32 v26, v26
	v_pk_mul_f32 v[4:5], v[12:13], v[4:5]
	s_mov_b64 s[28:29], s[18:19]
	v_mul_f32_e32 v12, v25, v26
	v_mul_f32_e32 v14, v24, v26
	v_pk_mul_f32 v[14:15], v[20:21], v[14:15] op_sel_hi:[1,0]
	v_pk_mul_f32 v[12:13], v[16:17], v[12:13] op_sel_hi:[1,0]
	v_pk_mul_f32 v[10:11], v[10:11], v[14:15]
	v_pk_mul_f32 v[8:9], v[8:9], v[12:13]
	v_pk_mul_f32 v[10:11], v[10:11], v[2:3]
	v_pk_mul_f32 v[2:3], v[8:9], v[0:1]
	v_cvt_pk_bf16_f32 v0, v4, v5
	v_cvt_pk_bf16_f32 v1, v6, v7
	s_nop 0
	v_cvt_pk_bf16_f32 v2, v2, v3
	v_cvt_pk_bf16_f32 v3, v10, v11
	global_store_dwordx4 v[22:23], v[0:3], off
	s_cbranch_vccz .LBB0_192
	s_waitcnt vmcnt(0)
	s_cmpk_gt_u32 s37, 0xff
	s_cbranch_scc1 .LBB0_199
	s_barrier

; #define PG8_STAGE(bufoff, gbase, voff) do { _Pragma("unroll") for (int _i = 0; _i < 2; ++_i) \
;         __builtin_amdgcn_global_load_lds((const unsigned*)((const char*)(gbase) + (voff)[_i]), (PG8_LAS unsigned*)(lds + (bufoff) + ldsw + _i * 8192), 16, 0, 0); } while (0)
; #define PG8_LDA(dst, b, h) do { _Pragma("unroll") for (int m = 0; m < 4; ++m) _Pragma("unroll") for (int k = 0; k < 2; ++k) dst[m][k] = *(const PG8_LAS bf16x8*)(lds + PG8_SA(b, h) + aoff + m * 2048 + k * 1024); } while (0)
; #define PG8_LDB(dst, b, h) do { _Pragma("unroll") for (int n = 0; n < 2; ++n) _Pragma("unroll") for (int k = 0; k < 2; ++k) dst[n][k] = *(const PG8_LAS bf16x8*)(lds + PG8_SB(b, h) + boff + n * 2048 + k * 1024); } while (0)
; #define PG8_MMA(ai, bj, At, Bt) do { __builtin_amdgcn_s_setprio(1); _Pragma("unroll") for (int m = 0; m < 4; ++m) _Pragma("unroll") for (int n = 0; n < 2; ++n) _Pragma("unroll") for (int k = 0; k < 2; ++k) \
;         acc[ai][bj][m][n] = __builtin_amdgcn_mfma_f32_16x16x32_bf16(Bt[n][k], At[m][k], acc[ai][bj][m][n], 0, 0, 0); __builtin_amdgcn_s_setprio(0); } while (0)
; #define PG8_WAIT_L(n) asm volatile("s_waitcnt lgkmcnt(" #n ")" ::: "memory")
; #define PG8_BAR __builtin_amdgcn_s_barrier()
; #define PG8_SCHED __builtin_amdgcn_sched_barrier(0)
; template <class Epi, class Sched>
; __device__ __forceinline__ void gemm_phase(PG8_LAS unsigned char* lds, const Gemm g, const Sched& S, const Epi& E) {
;     ...
;             const bool last = (t == nt - 2);
;             const char* a1 = cA + (size_t)(t + 1) * kstep;
;             const char* a2 = last ? nA : cA + (size_t)(t + 2) * kstep; const char* b2 = last ? nB : cB + (size_t)(t + 2) * kstep;
;             const char* a3 = a2 + kstep; const char* b3 = b2 + kstep;
;             if (last && has_next) S.a_ready(nxt);
;             PG8_LDB(B0, 0, 0); PG8_SCHED; PG8_LDA(At, 0, 0); PG8_STAGE(PG8_SA(1, 1), a1 + hstep, voffA);
;             PG8_WAIT_L(8); PG8_BAR; PG8_WAIT_L(0); PG8_MMA(0, 0, At, B0); PG8_BAR; PG8_SCHED;
;             PG8_LDB(B1, 0, 1); PG8_STAGE(PG8_SB(0, 0), b2, voffB);
;             PG8_BAR; PG8_WAIT_L(0); PG8_MMA(0, 1, At, B1); PG8_BAR;
;             PG8_LDA(At, 0, 1); PG8_STAGE(PG8_SA(0, 0), a2, voffA);
;             PG8_BAR; PG8_WAIT_L(0); PG8_MMA(1, 0, At, B0); PG8_BAR; PG8_SCHED;
.LBB0_286:
	ds_read_b128 v[154:157], v149
	ds_read_b128 v[158:161], v149 offset:1024
	ds_read_b128 v[166:169], v149 offset:2048
	ds_read_b128 v[170:173], v149 offset:3072
	s_add_u32 s24, s22, 0x100
	s_addc_u32 s25, s23, 0
	s_cmp_eq_u32 s57, 40
	s_cselect_b32 s29, s1, s25
	s_cselect_b32 s28, s0, s24
	s_cselect_b32 s27, s5, s56
	s_cselect_b32 s26, s4, s55
	v_lshl_add_u64 v[144:145], s[22:23], 0, v[136:137]
	s_add_i32 m0, s38, 0xc000
	ds_read_b128 v[182:185], v150
	ds_read_b128 v[190:193], v150 offset:1024
	ds_read_b128 v[194:197], v150 offset:2048
	ds_read_b128 v[198:201], v150 offset:3072
	ds_read_b128 v[202:205], v150 offset:4096
	ds_read_b128 v[206:209], v150 offset:5120
	ds_read_b128 v[210:213], v150 offset:6144
	ds_read_b128 v[214:217], v150 offset:7168
	global_load_lds_dwordx4 v[144:145], off
	v_lshl_add_u64 v[144:145], s[22:23], 0, v[138:139]
	s_add_i32 m0, s38, 0xe000
	s_nop 0
	global_load_lds_dwordx4 v[144:145], off
	s_waitcnt lgkmcnt(8)
	s_barrier
	s_waitcnt lgkmcnt(0)
	s_waitcnt lgkmcnt(0)
	v_mfma_f32_16x16x32_bf16 v[124:127], v[154:157], v[182:185], v[124:127]
	v_mfma_f32_16x16x32_bf16 v[120:123], v[166:169], v[182:185], v[120:123]
	v_mfma_f32_16x16x32_bf16 v[108:111], v[154:157], v[194:197], v[108:111]
	v_mfma_f32_16x16x32_bf16 v[104:107], v[166:169], v[194:197], v[104:107]
	v_mfma_f32_16x16x32_bf16 v[92:95], v[154:157], v[202:205], v[92:95]
	v_mfma_f32_16x16x32_bf16 v[88:91], v[166:169], v[202:205], v[88:91]
	v_mfma_f32_16x16x32_bf16 v[76:79], v[154:157], v[210:213], v[76:79]
	v_mfma_f32_16x16x32_bf16 v[72:75], v[166:169], v[210:213], v[72:75]
	v_mfma_f32_16x16x32_bf16 v[124:127], v[158:161], v[190:193], v[124:127]
	v_mfma_f32_16x16x32_bf16 v[120:123], v[170:173], v[190:193], v[120:123]
	v_mfma_f32_16x16x32_bf16 v[108:111], v[158:161], v[198:201], v[108:111]
	v_mfma_f32_16x16x32_bf16 v[104:107], v[170:173], v[198:201], v[104:107]
	v_mfma_f32_16x16x32_bf16 v[92:95], v[158:161], v[206:209], v[92:95]
	v_mfma_f32_16x16x32_bf16 v[88:91], v[170:173], v[206:209], v[88:91]
	v_mfma_f32_16x16x32_bf16 v[76:79], v[158:161], v[214:217], v[76:79]
	v_mfma_f32_16x16x32_bf16 v[72:75], v[170:173], v[214:217], v[72:75]
	s_barrier
	s_add_i32 s22, s46, s37
	v_lshl_add_u64 v[144:145], s[26:27], 0, v[130:131]
	s_mov_b32 m0, s22
	ds_read_b128 v[218:221], v151
	ds_read_b128 v[222:225], v151 offset:1024
	ds_read_b128 v[226:229], v151 offset:2048
	ds_read_b128 v[230:233], v151 offset:3072
	global_load_lds_dwordx4 v[144:145], off
	v_lshl_add_u64 v[162:163], s[26:27], 0, v[134:135]
	s_add_i32 m0, s22, 0x2000
	s_nop 0
	global_load_lds_dwordx4 v[162:163], off
	s_barrier
	s_waitcnt lgkmcnt(0)
	s_waitcnt lgkmcnt(0)
	v_mfma_f32_16x16x32_bf16 v[116:119], v[218:221], v[182:185], v[116:119]
	v_mfma_f32_16x16x32_bf16 v[112:115], v[226:229], v[182:185], v[112:115]
	v_mfma_f32_16x16x32_bf16 v[100:103], v[218:221], v[194:197], v[100:103]
	v_mfma_f32_16x16x32_bf16 v[96:99], v[226:229], v[194:197], v[96:99]
	v_mfma_f32_16x16x32_bf16 v[84:87], v[218:221], v[202:205], v[84:87]
	v_mfma_f32_16x16x32_bf16 v[80:83], v[226:229], v[202:205], v[80:83]
	v_mfma_f32_16x16x32_bf16 v[68:71], v[218:221], v[210:213], v[68:71]
	v_mfma_f32_16x16x32_bf16 v[64:67], v[226:229], v[210:213], v[64:67]
	v_mfma_f32_16x16x32_bf16 v[116:119], v[222:225], v[190:193], v[116:119]
	v_mfma_f32_16x16x32_bf16 v[112:115], v[230:233], v[190:193], v[112:115]
	v_mfma_f32_16x16x32_bf16 v[100:103], v[222:225], v[198:201], v[100:103]
	v_mfma_f32_16x16x32_bf16 v[96:99], v[230:233], v[198:201], v[96:99]
	v_mfma_f32_16x16x32_bf16 v[84:87], v[222:225], v[206:209], v[84:87]
	v_mfma_f32_16x16x32_bf16 v[80:83], v[230:233], v[206:209], v[80:83]
	v_mfma_f32_16x16x32_bf16 v[68:71], v[222:225], v[214:217], v[68:71]
	v_mfma_f32_16x16x32_bf16 v[64:67], v[230:233], v[214:217], v[64:67]
	s_barrier
	s_mov_b32 m0, s38
	v_lshl_add_u64 v[174:175], s[28:29], 0, v[128:129]
	ds_read_b128 v[182:185], v150 offset:16384
	ds_read_b128 v[190:193], v150 offset:17408
	ds_read_b128 v[194:197], v150 offset:18432
	ds_read_b128 v[198:201], v150 offset:19456
	ds_read_b128 v[202:205], v150 offset:20480
	ds_read_b128 v[206:209], v150 offset:21504
	ds_read_b128 v[210:213], v150 offset:22528
	ds_read_b128 v[214:217], v150 offset:23552
	global_load_lds_dwordx4 v[174:175], off
	v_lshl_add_u64 v[178:179], s[28:29], 0, v[132:133]
	s_mov_b32 m0, s39
	s_nop 0
	global_load_lds_dwordx4 v[178:179], off
	s_barrier
	s_waitcnt lgkmcnt(0)
	s_waitcnt lgkmcnt(0)
	v_mfma_f32_16x16x32_bf16 v[60:63], v[154:157], v[182:185], v[60:63]
	v_mfma_f32_16x16x32_bf16 v[56:59], v[166:169], v[182:185], v[56:59]
	v_mfma_f32_16x16x32_bf16 v[48:51], v[154:157], v[194:197], v[48:51]
	v_mfma_f32_16x16x32_bf16 v[40:43], v[166:169], v[194:197], v[40:43]
	v_mfma_f32_16x16x32_bf16 v[32:35], v[154:157], v[202:205], v[32:35]
	v_mfma_f32_16x16x32_bf16 v[24:27], v[166:169], v[202:205], v[24:27]
	v_mfma_f32_16x16x32_bf16 v[16:19], v[154:157], v[210:213], v[16:19]
	v_mfma_f32_16x16x32_bf16 v[8:11], v[166:169], v[210:213], v[8:11]
	v_mfma_f32_16x16x32_bf16 v[60:63], v[158:161], v[190:193], v[60:63]
	v_mfma_f32_16x16x32_bf16 v[56:59], v[170:173], v[190:193], v[56:59]
	v_mfma_f32_16x16x32_bf16 v[48:51], v[158:161], v[198:201], v[48:51]
	v_mfma_f32_16x16x32_bf16 v[40:43], v[170:173], v[198:201], v[40:43]
	v_mfma_f32_16x16x32_bf16 v[32:35], v[158:161], v[206:209], v[32:35]
	v_mfma_f32_16x16x32_bf16 v[24:27], v[170:173], v[206:209], v[24:27]
	v_mfma_f32_16x16x32_bf16 v[16:19], v[158:161], v[214:217], v[16:19]
	v_mfma_f32_16x16x32_bf16 v[8:11], v[170:173], v[214:217], v[8:11]
	s_barrier
; #define PG8_STAGE(bufoff, gbase, voff) do { _Pragma("unroll") for (int _i = 0; _i < 2; ++_i) \
;         __builtin_amdgcn_global_load_lds((const unsigned*)((const char*)(gbase) + (voff)[_i]), (PG8_LAS unsigned*)(lds + (bufoff) + ldsw + _i * 8192), 16, 0, 0); } while (0)
; #define PG8_LDA(dst, b, h) do { _Pragma("unroll") for (int m = 0; m < 4; ++m) _Pragma("unroll") for (int k = 0; k < 2; ++k) dst[m][k] = *(const PG8_LAS bf16x8*)(lds + PG8_SA(b, h) + aoff + m * 2048 + k * 1024); } while (0)
; #define PG8_LDB(dst, b, h) do { _Pragma("unroll") for (int n = 0; n < 2; ++n) _Pragma("unroll") for (int k = 0; k < 2; ++k) dst[n][k] = *(const PG8_LAS bf16x8*)(lds + PG8_SB(b, h) + boff + n * 2048 + k * 1024); } while (0)
; #define PG8_MMA(ai, bj, At, Bt) do { __builtin_amdgcn_s_setprio(1); _Pragma("unroll") for (int m = 0; m < 4; ++m) _Pragma("unroll") for (int n = 0; n < 2; ++n) _Pragma("unroll") for (int k = 0; k < 2; ++k) \
;         acc[ai][bj][m][n] = __builtin_amdgcn_mfma_f32_16x16x32_bf16(Bt[n][k], At[m][k], acc[ai][bj][m][n], 0, 0, 0); __builtin_amdgcn_s_setprio(0); } while (0)
; #define PG8_WAIT_V(n) asm volatile("s_waitcnt vmcnt(" #n ")" ::: "memory")
; #define PG8_WAIT_L(n) asm volatile("s_waitcnt lgkmcnt(" #n ")" ::: "memory")
; #define PG8_BAR __builtin_amdgcn_s_barrier()
; #define PG8_SCHED __builtin_amdgcn_sched_barrier(0)
; template <class Epi, class Sched>
; __device__ __forceinline__ void gemm_phase(PG8_LAS unsigned char* lds, const Gemm g, const Sched& S, const Epi& E) {
;     ...
;             PG8_STAGE(PG8_SB(0, 1), b2 + hstep, voffB);
;             PG8_WAIT_V(6); PG8_BAR; PG8_MMA(1, 1, At, B1); PG8_BAR;
;             PG8_LDB(B0, 1, 0); PG8_SCHED; PG8_LDA(At, 1, 0); PG8_STAGE(PG8_SA(0, 1), a2 + hstep, voffA);
;             PG8_WAIT_L(8); PG8_BAR; PG8_WAIT_L(0); PG8_MMA(0, 0, At, B0); PG8_BAR; PG8_SCHED;
;             PG8_LDB(B1, 1, 1); PG8_STAGE(PG8_SB(1, 0), b3, voffB);
;             PG8_BAR; PG8_WAIT_L(0); PG8_MMA(0, 1, At, B1); PG8_BAR;
;             PG8_LDA(At, 1, 1); PG8_STAGE(PG8_SA(1, 0), a3, voffA);
	s_add_u32 s22, s26, 0xb0000
	s_addc_u32 s23, s27, 0
	s_add_i32 s58, s47, s37
	v_lshl_add_u64 v[154:155], s[22:23], 0, v[130:131]
	s_mov_b32 m0, s58
	s_nop 0
	global_load_lds_dwordx4 v[154:155], off
	v_lshl_add_u64 v[154:155], s[22:23], 0, v[134:135]
	s_add_i32 m0, s58, 0x2000
	s_nop 0
	global_load_lds_dwordx4 v[154:155], off
	s_waitcnt vmcnt(6)
	s_barrier
	v_mfma_f32_16x16x32_bf16 v[52:55], v[218:221], v[182:185], v[52:55]
	v_mfma_f32_16x16x32_bf16 v[44:47], v[226:229], v[182:185], v[44:47]
	v_mfma_f32_16x16x32_bf16 v[36:39], v[218:221], v[194:197], v[36:39]
	v_mfma_f32_16x16x32_bf16 v[28:31], v[226:229], v[194:197], v[28:31]
	v_mfma_f32_16x16x32_bf16 v[20:23], v[218:221], v[202:205], v[20:23]
	v_mfma_f32_16x16x32_bf16 v[12:15], v[226:229], v[202:205], v[12:15]
	v_mfma_f32_16x16x32_bf16 v[4:7], v[218:221], v[210:213], v[4:7]
	v_mfma_f32_16x16x32_bf16 v[0:3], v[226:229], v[210:213], v[0:3]
	v_mfma_f32_16x16x32_bf16 v[52:55], v[222:225], v[190:193], v[52:55]
	v_mfma_f32_16x16x32_bf16 v[44:47], v[230:233], v[190:193], v[44:47]
	v_mfma_f32_16x16x32_bf16 v[36:39], v[222:225], v[198:201], v[36:39]
	v_mfma_f32_16x16x32_bf16 v[28:31], v[230:233], v[198:201], v[28:31]
	v_mfma_f32_16x16x32_bf16 v[20:23], v[222:225], v[206:209], v[20:23]
	v_mfma_f32_16x16x32_bf16 v[12:15], v[230:233], v[206:209], v[12:15]
	v_mfma_f32_16x16x32_bf16 v[4:7], v[222:225], v[214:217], v[4:7]
	v_mfma_f32_16x16x32_bf16 v[0:3], v[230:233], v[214:217], v[0:3]
	s_barrier
	s_add_i32 s58, 0, 0x18000
	v_add_u32_e32 v153, s58, v147
	ds_read_b128 v[154:157], v153
	ds_read_b128 v[158:161], v153 offset:1024
	ds_read_b128 v[166:169], v153 offset:2048
	ds_read_b128 v[170:173], v153 offset:3072
	s_add_u32 s22, s28, 0xb0000
	s_addc_u32 s23, s29, 0
	s_mov_b32 m0, s40
	v_lshl_add_u64 v[186:187], s[22:23], 0, v[128:129]
	ds_read_b128 v[182:185], v150 offset:32768
	ds_read_b128 v[190:193], v150 offset:33792
	ds_read_b128 v[194:197], v150 offset:34816
	ds_read_b128 v[198:201], v150 offset:35840
	ds_read_b128 v[202:205], v150 offset:36864
	ds_read_b128 v[206:209], v150 offset:37888
	ds_read_b128 v[210:213], v150 offset:38912
	ds_read_b128 v[214:217], v150 offset:39936
	global_load_lds_dwordx4 v[186:187], off
	v_lshl_add_u64 v[186:187], s[22:23], 0, v[132:133]
	s_mov_b32 m0, s41
	s_nop 0
	global_load_lds_dwordx4 v[186:187], off
	s_waitcnt lgkmcnt(8)
	s_barrier
	s_waitcnt lgkmcnt(0)
	s_waitcnt lgkmcnt(0)
	v_mfma_f32_16x16x32_bf16 v[124:127], v[154:157], v[182:185], v[124:127]
	v_mfma_f32_16x16x32_bf16 v[120:123], v[166:169], v[182:185], v[120:123]
	v_mfma_f32_16x16x32_bf16 v[108:111], v[154:157], v[194:197], v[108:111]
	v_mfma_f32_16x16x32_bf16 v[104:107], v[166:169], v[194:197], v[104:107]
	v_mfma_f32_16x16x32_bf16 v[92:95], v[154:157], v[202:205], v[92:95]
	v_mfma_f32_16x16x32_bf16 v[88:91], v[166:169], v[202:205], v[88:91]
	v_mfma_f32_16x16x32_bf16 v[76:79], v[154:157], v[210:213], v[76:79]
	v_mfma_f32_16x16x32_bf16 v[72:75], v[166:169], v[210:213], v[72:75]
	v_mfma_f32_16x16x32_bf16 v[124:127], v[158:161], v[190:193], v[124:127]
	v_mfma_f32_16x16x32_bf16 v[120:123], v[170:173], v[190:193], v[120:123]
	v_mfma_f32_16x16x32_bf16 v[108:111], v[158:161], v[198:201], v[108:111]
	v_mfma_f32_16x16x32_bf16 v[104:107], v[170:173], v[198:201], v[104:107]
	v_mfma_f32_16x16x32_bf16 v[92:95], v[158:161], v[206:209], v[92:95]
	v_mfma_f32_16x16x32_bf16 v[88:91], v[170:173], v[206:209], v[88:91]
	v_mfma_f32_16x16x32_bf16 v[76:79], v[158:161], v[214:217], v[76:79]
	v_mfma_f32_16x16x32_bf16 v[72:75], v[170:173], v[214:217], v[72:75]
	s_barrier
	s_add_i32 s28, 0, 0x1c000
	s_add_i32 s22, s58, s37
	v_add_u32_e32 v153, s28, v147
	v_lshl_add_u64 v[144:145], v[144:145], 0, s[14:15]
	s_mov_b32 m0, s22
	ds_read_b128 v[218:221], v153
	ds_read_b128 v[222:225], v153 offset:1024
	ds_read_b128 v[226:229], v153 offset:2048
	ds_read_b128 v[230:233], v153 offset:3072
	global_load_lds_dwordx4 v[144:145], off
	v_lshl_add_u64 v[144:145], v[162:163], 0, s[14:15]
	s_add_i32 m0, s22, 0x2000
	s_nop 0
	global_load_lds_dwordx4 v[144:145], off
	s_barrier
	s_waitcnt lgkmcnt(0)
	s_waitcnt lgkmcnt(0)
	v_mfma_f32_16x16x32_bf16 v[116:119], v[218:221], v[182:185], v[116:119]
	v_mfma_f32_16x16x32_bf16 v[112:115], v[226:229], v[182:185], v[112:115]
	v_mfma_f32_16x16x32_bf16 v[100:103], v[218:221], v[194:197], v[100:103]
	v_mfma_f32_16x16x32_bf16 v[96:99], v[226:229], v[194:197], v[96:99]
	v_mfma_f32_16x16x32_bf16 v[84:87], v[218:221], v[202:205], v[84:87]
	v_mfma_f32_16x16x32_bf16 v[80:83], v[226:229], v[202:205], v[80:83]
	v_mfma_f32_16x16x32_bf16 v[68:71], v[218:221], v[210:213], v[68:71]
	v_mfma_f32_16x16x32_bf16 v[64:67], v[226:229], v[210:213], v[64:67]
	v_mfma_f32_16x16x32_bf16 v[116:119], v[222:225], v[190:193], v[116:119]
	v_mfma_f32_16x16x32_bf16 v[112:115], v[230:233], v[190:193], v[112:115]
	v_mfma_f32_16x16x32_bf16 v[100:103], v[222:225], v[198:201], v[100:103]
	v_mfma_f32_16x16x32_bf16 v[96:99], v[230:233], v[198:201], v[96:99]
	v_mfma_f32_16x16x32_bf16 v[84:87], v[222:225], v[206:209], v[84:87]
	v_mfma_f32_16x16x32_bf16 v[80:83], v[230:233], v[206:209], v[80:83]
	v_mfma_f32_16x16x32_bf16 v[68:71], v[222:225], v[214:217], v[68:71]
	v_mfma_f32_16x16x32_bf16 v[64:67], v[230:233], v[214:217], v[64:67]
	s_barrier
	s_mov_b32 m0, s43
	v_lshl_add_u64 v[144:145], v[174:175], 0, s[14:15]
	ds_read_b128 v[182:185], v150 offset:49152
	ds_read_b128 v[190:193], v150 offset:50176
	ds_read_b128 v[194:197], v150 offset:51200
	ds_read_b128 v[198:201], v150 offset:52224
	ds_read_b128 v[202:205], v150 offset:53248
	ds_read_b128 v[206:209], v150 offset:54272
	ds_read_b128 v[210:213], v150 offset:55296
	ds_read_b128 v[214:217], v150 offset:56320
	global_load_lds_dwordx4 v[144:145], off
	v_lshl_add_u64 v[144:145], v[178:179], 0, s[14:15]
	s_mov_b32 m0, s44
	s_nop 0
	global_load_lds_dwordx4 v[144:145], off
	s_barrier
; __device__ __forceinline__ unsigned cvt_pk_bf16(float lo, float hi) { unsigned r; asm volatile("v_cvt_pk_bf16_f32 %0, %1, %2" : "=v"(r) : "v"(lo), "v"(hi)); return r; }
; __device__ __forceinline__ float flogsig16(float x) { return (fminf(x, 0.f) - __logf(1.0f + __expf(-fabsf(x)))) * 0.0625f; }
; #define PG8_WAIT_V(n) asm volatile("s_waitcnt vmcnt(" #n ")" ::: "memory")
; #define PG8_WAIT_L(n) asm volatile("s_waitcnt lgkmcnt(" #n ")" ::: "memory")
;     __device__ __forceinline__ void operator()(const f32x4 (&acc)[2][2][4][2], const Unit& u, int wr, int wc, int fr, int fq) const {
;     ...
;         const int row0 = u.pm * BM + wr * 64 + fr, col0 = u.pn * BM + wc * 32 + 8 * fq, bcol0 = wc * 32 + 8 * fq;
;         f32x4 bv[2][2];
; #pragma unroll
;         for (int bj = 0; bj < 2; ++bj)
; #pragma unroll
;             for (int n = 0; n < 2; ++n) bv[bj][n] = bias ? *(const f32x4*)(bias + bcol0 + bj * HALF + 4 * n) : (f32x4){0.f, 0.f, 0.f, 0.f};
; #pragma unroll
;         for (int ai = 0; ai < 2; ++ai)
; #pragma unroll
;             for (int m = 0; m < 4; ++m) { bf16_t* rowp = O + (size_t)(row0 + ai * HALF + m * 16) * ldc + col0;
; #pragma unroll
;                 for (int bj = 0; bj < 2; ++bj) { f32x4 v0 = acc[ai][bj][m][0] + bv[bj][0], v1 = acc[ai][bj][m][1] + bv[bj][1];
;                     if (act == 1) {
; #pragma unroll
;                         for (int j = 0; j < 1; ++j) { v0 = v0 * sigmoid4(v0); v1 = v1 * sigmoid4(v1); } }
;                     else if (act == 2) {
; #pragma unroll
;                         for (int j = 0; j < 1; ++j) { v0 = sigmoid4(v0); v1 = sigmoid4(v1); } }
;                     else if (act == 3) {
; #pragma unroll
;                         for (int j = 0; j < 4; ++j) { v0[j] = flogsig16(v0[j]); v1[j] = flogsig16(v1[j]); } }
;                     u32x4 w; w.x = cvt_pk_bf16(v0[0], v0[1]); w.y = cvt_pk_bf16(v0[2], v0[3]); w.z = cvt_pk_bf16(v1[0], v1[1]); w.w = cvt_pk_bf16(v1[2], v1[3]);
;                     *(u32x4*)(rowp + bj * HALF) = w; } }
; template <class Epi, class Sched>
; __device__ __forceinline__ void gemm_phase(PG8_LAS unsigned char* lds, const Gemm g, const Sched& S, const Epi& E) {
;     ...
;             PG8_BAR; PG8_WAIT_L(0); PG8_MMA(1, 0, At, B0); PG8_BAR; PG8_SCHED;
;             PG8_STAGE(PG8_SB(1, 1), b3 + hstep, voffB);
;             PG8_WAIT_V(6); PG8_BAR; PG8_MMA(1, 1, At, B1); PG8_BAR;
	s_waitcnt lgkmcnt(0)
	s_waitcnt lgkmcnt(0)
	v_mfma_f32_16x16x32_bf16 v[60:63], v[154:157], v[182:185], v[60:63]
	v_mfma_f32_16x16x32_bf16 v[56:59], v[166:169], v[182:185], v[56:59]
	v_mfma_f32_16x16x32_bf16 v[48:51], v[154:157], v[194:197], v[48:51]
	v_mfma_f32_16x16x32_bf16 v[40:43], v[166:169], v[194:197], v[40:43]
	v_mfma_f32_16x16x32_bf16 v[32:35], v[154:157], v[202:205], v[32:35]
	v_mfma_f32_16x16x32_bf16 v[24:27], v[166:169], v[202:205], v[24:27]
	v_mfma_f32_16x16x32_bf16 v[16:19], v[154:157], v[210:213], v[16:19]
	v_mfma_f32_16x16x32_bf16 v[8:11], v[166:169], v[210:213], v[8:11]
	v_mfma_f32_16x16x32_bf16 v[60:63], v[158:161], v[190:193], v[60:63]
	v_mfma_f32_16x16x32_bf16 v[56:59], v[170:173], v[190:193], v[56:59]
	v_mfma_f32_16x16x32_bf16 v[48:51], v[158:161], v[198:201], v[48:51]
	v_mfma_f32_16x16x32_bf16 v[40:43], v[170:173], v[198:201], v[40:43]
	v_mfma_f32_16x16x32_bf16 v[32:35], v[158:161], v[206:209], v[32:35]
	v_mfma_f32_16x16x32_bf16 v[24:27], v[170:173], v[206:209], v[24:27]
	v_mfma_f32_16x16x32_bf16 v[16:19], v[158:161], v[214:217], v[16:19]
	v_mfma_f32_16x16x32_bf16 v[8:11], v[170:173], v[214:217], v[8:11]
	s_barrier
	s_add_u32 s22, s26, 0xb0080
	s_addc_u32 s23, s27, 0
	s_add_i32 s26, s28, s37
	v_lshl_add_u64 v[144:145], s[22:23], 0, v[130:131]
	s_mov_b32 m0, s26
	s_nop 0
	global_load_lds_dwordx4 v[144:145], off
	v_lshl_add_u64 v[144:145], s[22:23], 0, v[134:135]
	s_add_i32 m0, s26, 0x2000
	s_nop 0
	global_load_lds_dwordx4 v[144:145], off
	s_waitcnt vmcnt(6)
	s_barrier
	v_mfma_f32_16x16x32_bf16 v[52:55], v[218:221], v[182:185], v[52:55]
	v_mfma_f32_16x16x32_bf16 v[44:47], v[226:229], v[182:185], v[44:47]
	v_mfma_f32_16x16x32_bf16 v[36:39], v[218:221], v[194:197], v[36:39]
	v_mfma_f32_16x16x32_bf16 v[28:31], v[226:229], v[194:197], v[28:31]
	v_mfma_f32_16x16x32_bf16 v[20:23], v[218:221], v[202:205], v[20:23]
	v_mfma_f32_16x16x32_bf16 v[12:15], v[226:229], v[202:205], v[12:15]
	v_mfma_f32_16x16x32_bf16 v[4:7], v[218:221], v[210:213], v[4:7]
	v_mfma_f32_16x16x32_bf16 v[0:3], v[226:229], v[210:213], v[0:3]
	v_mfma_f32_16x16x32_bf16 v[52:55], v[222:225], v[190:193], v[52:55]
	v_mfma_f32_16x16x32_bf16 v[44:47], v[230:233], v[190:193], v[44:47]
	v_mfma_f32_16x16x32_bf16 v[36:39], v[222:225], v[198:201], v[36:39]
	v_mfma_f32_16x16x32_bf16 v[28:31], v[230:233], v[198:201], v[28:31]
	v_mfma_f32_16x16x32_bf16 v[20:23], v[222:225], v[206:209], v[20:23]
	v_mfma_f32_16x16x32_bf16 v[12:15], v[230:233], v[206:209], v[12:15]
	v_mfma_f32_16x16x32_bf16 v[4:7], v[222:225], v[214:217], v[4:7]
	v_mfma_f32_16x16x32_bf16 v[0:3], v[230:233], v[214:217], v[0:3]
	s_add_i32 s57, s57, 2
	s_add_u32 s55, s55, 0x100
	s_addc_u32 s56, s56, 0
	s_cmp_gt_u32 s57, 41
	s_mov_b64 s[22:23], s[24:25]
	s_barrier
	s_cbranch_scc0 .LBB0_286
	v_lshl_add_u32 v154, s53, 8, v146
	v_lshl_or_b32 v144, s54, 8, v148
	v_ashrrev_i32_e32 v155, 31, v154
	v_ashrrev_i32_e32 v145, 31, v144
	v_lshlrev_b64 v[156:157], 11, v[154:155]
	v_lshl_add_u64 v[156:157], s[10:11], 0, v[156:157]
	v_lshlrev_b64 v[158:159], 1, v[144:145]
	v_lshl_add_u64 v[144:145], v[156:157], 0, v[158:159]
	v_pk_add_f32 v[126:127], v[126:127], 0 op_sel_hi:[1,0]
	v_pk_add_f32 v[124:125], v[124:125], 0 op_sel_hi:[1,0]
	v_pk_add_f32 v[156:157], v[122:123], 0 op_sel_hi:[1,0]
	v_pk_add_f32 v[122:123], v[120:121], 0 op_sel_hi:[1,0]
	v_cvt_pk_bf16_f32 v120, v124, v125
	v_cvt_pk_bf16_f32 v121, v126, v127
	v_pk_add_f32 v[116:117], v[116:117], 0 op_sel_hi:[1,0]
	v_cvt_pk_bf16_f32 v122, v122, v123
	v_cvt_pk_bf16_f32 v123, v156, v157
	global_store_dwordx4 v[144:145], v[120:123], off
	v_pk_add_f32 v[118:119], v[118:119], 0 op_sel_hi:[1,0]
	v_pk_add_f32 v[110:111], v[110:111], 0 op_sel_hi:[1,0]
	v_pk_add_f32 v[120:121], v[114:115], 0 op_sel_hi:[1,0]
	v_pk_add_f32 v[114:115], v[112:113], 0 op_sel_hi:[1,0]
	v_cvt_pk_bf16_f32 v112, v116, v117
	v_cvt_pk_bf16_f32 v113, v118, v119
	v_pk_add_f32 v[108:109], v[108:109], 0 op_sel_hi:[1,0]
	v_cvt_pk_bf16_f32 v114, v114, v115
	v_cvt_pk_bf16_f32 v115, v120, v121
	global_store_dwordx4 v[144:145], v[112:115], off offset:256
	v_pk_add_f32 v[100:101], v[100:101], 0 op_sel_hi:[1,0]
	v_pk_add_f32 v[102:103], v[102:103], 0 op_sel_hi:[1,0]
	v_or_b32_e32 v112, 16, v154
	v_ashrrev_i32_e32 v113, 31, v112
	v_lshlrev_b64 v[112:113], 11, v[112:113]
	v_lshl_add_u64 v[112:113], s[10:11], 0, v[112:113]
	v_lshl_add_u64 v[112:113], v[112:113], 0, v[158:159]
	v_pk_add_f32 v[114:115], v[106:107], 0 op_sel_hi:[1,0]
	v_pk_add_f32 v[106:107], v[104:105], 0 op_sel_hi:[1,0]
	v_cvt_pk_bf16_f32 v104, v108, v109
	v_cvt_pk_bf16_f32 v105, v110, v111
	v_pk_add_f32 v[94:95], v[94:95], 0 op_sel_hi:[1,0]
	v_cvt_pk_bf16_f32 v106, v106, v107
	v_cvt_pk_bf16_f32 v107, v114, v115
	global_store_dwordx4 v[112:113], v[104:107], off
	v_pk_add_f32 v[92:93], v[92:93], 0 op_sel_hi:[1,0]
	v_pk_add_f32 v[84:85], v[84:85], 0 op_sel_hi:[1,0]
	v_pk_add_f32 v[104:105], v[98:99], 0 op_sel_hi:[1,0]
	v_pk_add_f32 v[98:99], v[96:97], 0 op_sel_hi:[1,0]
	v_cvt_pk_bf16_f32 v96, v100, v101
	v_cvt_pk_bf16_f32 v97, v102, v103
	v_pk_add_f32 v[86:87], v[86:87], 0 op_sel_hi:[1,0]
	v_cvt_pk_bf16_f32 v98, v98, v99
	v_cvt_pk_bf16_f32 v99, v104, v105
	global_store_dwordx4 v[112:113], v[96:99], off offset:256
	v_pk_add_f32 v[78:79], v[78:79], 0 op_sel_hi:[1,0]
	v_pk_add_f32 v[76:77], v[76:77], 0 op_sel_hi:[1,0]
	v_or_b32_e32 v96, 32, v154
	v_ashrrev_i32_e32 v97, 31, v96
	v_lshlrev_b64 v[96:97], 11, v[96:97]
	v_lshl_add_u64 v[96:97], s[10:11], 0, v[96:97]
	v_lshl_add_u64 v[96:97], v[96:97], 0, v[158:159]
; __device__ __forceinline__ unsigned cvt_pk_bf16(float lo, float hi) { unsigned r; asm volatile("v_cvt_pk_bf16_f32 %0, %1, %2" : "=v"(r) : "v"(lo), "v"(hi)); return r; }
; __device__ __forceinline__ float flogsig16(float x) { return (fminf(x, 0.f) - __logf(1.0f + __expf(-fabsf(x)))) * 0.0625f; }
; #define PG8_WAIT_V(n) asm volatile("s_waitcnt vmcnt(" #n ")" ::: "memory")
; #define PG8_BAR __builtin_amdgcn_s_barrier()
;     __device__ __forceinline__ void operator()(const f32x4 (&acc)[2][2][4][2], const Unit& u, int wr, int wc, int fr, int fq) const {
;     ...
;             for (int m = 0; m < 4; ++m) { bf16_t* rowp = O + (size_t)(row0 + ai * HALF + m * 16) * ldc + col0;
; #pragma unroll
;                 for (int bj = 0; bj < 2; ++bj) { f32x4 v0 = acc[ai][bj][m][0] + bv[bj][0], v1 = acc[ai][bj][m][1] + bv[bj][1];
;                     if (act == 1) {
; #pragma unroll
;                         for (int j = 0; j < 1; ++j) { v0 = v0 * sigmoid4(v0); v1 = v1 * sigmoid4(v1); } }
;                     else if (act == 2) {
; #pragma unroll
;                         for (int j = 0; j < 1; ++j) { v0 = sigmoid4(v0); v1 = sigmoid4(v1); } }
;                     else if (act == 3) {
; #pragma unroll
;                         for (int j = 0; j < 4; ++j) { v0[j] = flogsig16(v0[j]); v1[j] = flogsig16(v1[j]); } }
;                     u32x4 w; w.x = cvt_pk_bf16(v0[0], v0[1]); w.y = cvt_pk_bf16(v0[2], v0[3]); w.z = cvt_pk_bf16(v1[0], v1[1]); w.w = cvt_pk_bf16(v1[2], v1[3]);
;                     *(u32x4*)(rowp + bj * HALF) = w; } }
; template <class Epi, class Sched>
; __device__ __forceinline__ void gemm_phase(PG8_LAS unsigned char* lds, const Gemm g, const Sched& S, const Epi& E) {
;     ...
;         if constexpr (!Epi::AFTER_DRAIN) { E(acc, cur, wr, wc, fr, fq); S.done(cur); }
;         if (!has_next) break;
; #pragma unroll
;         for (int a = 0; a < 2; ++a)
; #pragma unroll
;             for (int b = 0; b < 2; ++b)
; #pragma unroll
;                 for (int m = 0; m < 4; ++m)
; #pragma unroll
;                     for (int n = 0; n < 2; ++n) acc[a][b][m][n] = (f32x4){0.f, 0.f, 0.f, 0.f};
;         cur = nxt; cA = nA; cB = nB; ++ui;
;     }
;     PG8_WAIT_V(0);
;     if (wr == 0) PG8_BAR;
;     PG8_BAR;
	v_pk_add_f32 v[98:99], v[90:91], 0 op_sel_hi:[1,0]
	v_pk_add_f32 v[90:91], v[88:89], 0 op_sel_hi:[1,0]
	v_cvt_pk_bf16_f32 v88, v92, v93
	v_cvt_pk_bf16_f32 v89, v94, v95
	v_pk_add_f32 v[70:71], v[70:71], 0 op_sel_hi:[1,0]
	v_cvt_pk_bf16_f32 v90, v90, v91
	v_cvt_pk_bf16_f32 v91, v98, v99
	global_store_dwordx4 v[96:97], v[88:91], off
	v_pk_add_f32 v[68:69], v[68:69], 0 op_sel_hi:[1,0]
	s_mov_b64 s[22:23], 0x40000
	v_pk_add_f32 v[88:89], v[82:83], 0 op_sel_hi:[1,0]
	v_pk_add_f32 v[82:83], v[80:81], 0 op_sel_hi:[1,0]
	v_cvt_pk_bf16_f32 v80, v84, v85
	v_cvt_pk_bf16_f32 v81, v86, v87
	v_pk_add_f32 v[60:61], v[60:61], 0 op_sel_hi:[1,0]
	v_cvt_pk_bf16_f32 v82, v82, v83
	v_cvt_pk_bf16_f32 v83, v88, v89
	global_store_dwordx4 v[96:97], v[80:83], off offset:256
	v_pk_add_f32 v[62:63], v[62:63], 0 op_sel_hi:[1,0]
	v_pk_add_f32 v[54:55], v[54:55], 0 op_sel_hi:[1,0]
	v_or_b32_e32 v80, 48, v154
	v_ashrrev_i32_e32 v81, 31, v80
	v_lshlrev_b64 v[80:81], 11, v[80:81]
	v_lshl_add_u64 v[80:81], s[10:11], 0, v[80:81]
	v_lshl_add_u64 v[80:81], v[80:81], 0, v[158:159]
	v_pk_add_f32 v[82:83], v[74:75], 0 op_sel_hi:[1,0]
	v_pk_add_f32 v[74:75], v[72:73], 0 op_sel_hi:[1,0]
	v_cvt_pk_bf16_f32 v72, v76, v77
	v_cvt_pk_bf16_f32 v73, v78, v79
	v_pk_add_f32 v[52:53], v[52:53], 0 op_sel_hi:[1,0]
	v_cvt_pk_bf16_f32 v74, v74, v75
	v_cvt_pk_bf16_f32 v75, v82, v83
	global_store_dwordx4 v[80:81], v[72:75], off
	v_pk_add_f32 v[48:49], v[48:49], 0 op_sel_hi:[1,0]
	v_pk_add_f32 v[38:39], v[38:39], 0 op_sel_hi:[1,0]
	v_pk_add_f32 v[72:73], v[66:67], 0 op_sel_hi:[1,0]
	v_pk_add_f32 v[66:67], v[64:65], 0 op_sel_hi:[1,0]
	v_cvt_pk_bf16_f32 v64, v68, v69
	v_cvt_pk_bf16_f32 v65, v70, v71
	v_pk_add_f32 v[36:37], v[36:37], 0 op_sel_hi:[1,0]
	v_cvt_pk_bf16_f32 v66, v66, v67
	v_cvt_pk_bf16_f32 v67, v72, v73
	global_store_dwordx4 v[80:81], v[64:67], off offset:256
	v_pk_add_f32 v[32:33], v[32:33], 0 op_sel_hi:[1,0]
	v_pk_add_f32 v[22:23], v[22:23], 0 op_sel_hi:[1,0]
	v_lshl_add_u64 v[64:65], v[144:145], 0, s[22:23]
	s_mov_b32 s22, 0x40000
	v_pk_add_f32 v[66:67], v[58:59], 0 op_sel_hi:[1,0]
	v_pk_add_f32 v[58:59], v[56:57], 0 op_sel_hi:[1,0]
	v_cvt_pk_bf16_f32 v56, v60, v61
	v_add_co_u32_e32 v60, vcc, s22, v144
	v_cvt_pk_bf16_f32 v57, v62, v63
	v_cvt_pk_bf16_f32 v58, v58, v59
	v_cvt_pk_bf16_f32 v59, v66, v67
	s_mov_b64 s[22:23], 0x48000
	s_nop 0
	v_addc_co_u32_e32 v61, vcc, 0, v145, vcc
	global_store_dwordx4 v[60:61], v[56:59], off
	v_pk_add_f32 v[20:21], v[20:21], 0 op_sel_hi:[1,0]
	v_pk_add_f32 v[16:17], v[16:17], 0 op_sel_hi:[1,0]
	v_pk_add_f32 v[56:57], v[46:47], 0 op_sel_hi:[1,0]
	v_pk_add_f32 v[46:47], v[44:45], 0 op_sel_hi:[1,0]
	v_cvt_pk_bf16_f32 v44, v52, v53
	v_cvt_pk_bf16_f32 v45, v54, v55
	s_mov_b32 s54, s51
	v_cvt_pk_bf16_f32 v46, v46, v47
	v_cvt_pk_bf16_f32 v47, v56, v57
	global_store_dwordx4 v[64:65], v[44:47], off offset:256
	s_mov_b32 s53, s52
	s_mov_b64 s[24:25], s[4:5]
	v_pk_add_f32 v[46:47], v[50:51], 0 op_sel_hi:[1,0]
	v_pk_add_f32 v[50:51], v[42:43], 0 op_sel_hi:[1,0]
	v_pk_add_f32 v[42:43], v[40:41], 0 op_sel_hi:[1,0]
	v_cvt_pk_bf16_f32 v40, v48, v49
	v_cvt_pk_bf16_f32 v41, v46, v47
	v_add_co_u32_e32 v46, vcc, s48, v144
	v_cvt_pk_bf16_f32 v42, v42, v43
	v_cvt_pk_bf16_f32 v43, v50, v51
	v_lshl_add_u64 v[44:45], v[144:145], 0, s[22:23]
	s_nop 0
	v_addc_co_u32_e32 v47, vcc, 0, v145, vcc
	global_store_dwordx4 v[46:47], v[40:43], off
	s_mov_b64 s[22:23], s[0:1]
	v_pk_add_f32 v[6:7], v[6:7], 0 op_sel_hi:[1,0]
	v_pk_add_f32 v[40:41], v[30:31], 0 op_sel_hi:[1,0]
	v_pk_add_f32 v[30:31], v[28:29], 0 op_sel_hi:[1,0]
	v_cvt_pk_bf16_f32 v28, v36, v37
	v_cvt_pk_bf16_f32 v29, v38, v39
	v_pk_add_f32 v[4:5], v[4:5], 0 op_sel_hi:[1,0]
	v_cvt_pk_bf16_f32 v30, v30, v31
	v_cvt_pk_bf16_f32 v31, v40, v41
	global_store_dwordx4 v[44:45], v[28:31], off offset:256
	s_nop 1
	v_pk_add_f32 v[30:31], v[34:35], 0 op_sel_hi:[1,0]
	v_pk_add_f32 v[34:35], v[26:27], 0 op_sel_hi:[1,0]
	v_pk_add_f32 v[26:27], v[24:25], 0 op_sel_hi:[1,0]
	v_cvt_pk_bf16_f32 v24, v32, v33
	v_cvt_pk_bf16_f32 v25, v30, v31
	v_add_co_u32_e32 v30, vcc, s49, v144
	v_cvt_pk_bf16_f32 v26, v26, v27
	v_cvt_pk_bf16_f32 v27, v34, v35
	v_lshl_add_u64 v[28:29], v[144:145], 0, s[16:17]
	s_nop 0
	v_addc_co_u32_e32 v31, vcc, 0, v145, vcc
	global_store_dwordx4 v[30:31], v[24:27], off
	s_nop 1
	v_pk_add_f32 v[24:25], v[14:15], 0 op_sel_hi:[1,0]
	v_pk_add_f32 v[14:15], v[12:13], 0 op_sel_hi:[1,0]
	v_cvt_pk_bf16_f32 v12, v20, v21
	v_cvt_pk_bf16_f32 v13, v22, v23
	s_nop 0
	v_cvt_pk_bf16_f32 v14, v14, v15
	v_cvt_pk_bf16_f32 v15, v24, v25
	global_store_dwordx4 v[28:29], v[12:15], off offset:256
	s_nop 1
	v_pk_add_f32 v[14:15], v[18:19], 0 op_sel_hi:[1,0]
	v_pk_add_f32 v[18:19], v[10:11], 0 op_sel_hi:[1,0]
	v_pk_add_f32 v[10:11], v[8:9], 0 op_sel_hi:[1,0]
	v_cvt_pk_bf16_f32 v8, v16, v17
	v_cvt_pk_bf16_f32 v9, v14, v15
	v_add_co_u32_e32 v14, vcc, s50, v144
	v_lshl_add_u64 v[12:13], v[144:145], 0, s[18:19]
	s_nop 0
	v_addc_co_u32_e32 v15, vcc, 0, v145, vcc
	v_cvt_pk_bf16_f32 v10, v10, v11
	v_cvt_pk_bf16_f32 v11, v18, v19
	global_store_dwordx4 v[14:15], v[8:11], off
	s_and_b64 vcc, exec, s[2:3]
	s_nop 0
	v_pk_add_f32 v[8:9], v[2:3], 0 op_sel_hi:[1,0]
	v_pk_add_f32 v[2:3], v[0:1], 0 op_sel_hi:[1,0]
	v_cvt_pk_bf16_f32 v0, v4, v5
	v_cvt_pk_bf16_f32 v1, v6, v7
	s_nop 0
	v_cvt_pk_bf16_f32 v2, v2, v3
	v_cvt_pk_bf16_f32 v3, v8, v9
	global_store_dwordx4 v[12:13], v[0:3], off offset:256
	s_cbranch_vccz .LBB0_275
	s_waitcnt vmcnt(0)
	s_cmpk_gt_u32 s31, 0xff
	s_cbranch_scc1 .LBB0_290
	s_barrier

; #define PG8_STAGE(bufoff, gbase, voff) do { _Pragma("unroll") for (int _i = 0; _i < 2; ++_i) \
;         __builtin_amdgcn_global_load_lds((const unsigned*)((const char*)(gbase) + (voff)[_i]), (PG8_LAS unsigned*)(lds + (bufoff) + ldsw + _i * 8192), 16, 0, 0); } while (0)
; #define PG8_LDA(dst, b, h) do { _Pragma("unroll") for (int m = 0; m < 4; ++m) _Pragma("unroll") for (int k = 0; k < 2; ++k) dst[m][k] = *(const PG8_LAS bf16x8*)(lds + PG8_SA(b, h) + aoff + m * 2048 + k * 1024); } while (0)
; #define PG8_LDB(dst, b, h) do { _Pragma("unroll") for (int n = 0; n < 2; ++n) _Pragma("unroll") for (int k = 0; k < 2; ++k) dst[n][k] = *(const PG8_LAS bf16x8*)(lds + PG8_SB(b, h) + boff + n * 2048 + k * 1024); } while (0)
; #define PG8_MMA(ai, bj, At, Bt) do { __builtin_amdgcn_s_setprio(1); _Pragma("unroll") for (int m = 0; m < 4; ++m) _Pragma("unroll") for (int n = 0; n < 2; ++n) _Pragma("unroll") for (int k = 0; k < 2; ++k) \
;         acc[ai][bj][m][n] = __builtin_amdgcn_mfma_f32_16x16x32_bf16(Bt[n][k], At[m][k], acc[ai][bj][m][n], 0, 0, 0); __builtin_amdgcn_s_setprio(0); } while (0)
; #define PG8_WAIT_L(n) asm volatile("s_waitcnt lgkmcnt(" #n ")" ::: "memory")
; #define PG8_BAR __builtin_amdgcn_s_barrier()
; #define PG8_SCHED __builtin_amdgcn_sched_barrier(0)
; template <class Epi, class Sched>
; __device__ __forceinline__ void gemm_phase(PG8_LAS unsigned char* lds, const Gemm g, const Sched& S, const Epi& E) {
;     ...
;             const bool last = (t == nt - 2);
;             const char* a1 = cA + (size_t)(t + 1) * kstep;
;             const char* a2 = last ? nA : cA + (size_t)(t + 2) * kstep; const char* b2 = last ? nB : cB + (size_t)(t + 2) * kstep;
;             const char* a3 = a2 + kstep; const char* b3 = b2 + kstep;
;             if (last && has_next) S.a_ready(nxt);
;             PG8_LDB(B0, 0, 0); PG8_SCHED; PG8_LDA(At, 0, 0); PG8_STAGE(PG8_SA(1, 1), a1 + hstep, voffA);
;             PG8_WAIT_L(8); PG8_BAR; PG8_WAIT_L(0); PG8_MMA(0, 0, At, B0); PG8_BAR; PG8_SCHED;
;             PG8_LDB(B1, 0, 1); PG8_STAGE(PG8_SB(0, 0), b2, voffB);
;             PG8_BAR; PG8_WAIT_L(0); PG8_MMA(0, 1, At, B1); PG8_BAR;
;             PG8_LDA(At, 0, 1); PG8_STAGE(PG8_SA(0, 0), a2, voffA);
;             PG8_BAR; PG8_WAIT_L(0); PG8_MMA(1, 0, At, B0); PG8_BAR; PG8_SCHED;
.LBB0_416:
	ds_read_b128 v[24:27], v186
	ds_read_b128 v[28:31], v186 offset:1024
	ds_read_b128 v[40:43], v186 offset:2048
	ds_read_b128 v[44:47], v186 offset:3072
	s_add_u32 s4, s0, 0xfffc0080
	s_addc_u32 s5, s1, -1
	s_cmp_eq_u32 s53, 12
	s_cselect_b32 s29, s7, s5
	s_cselect_b32 s28, s10, s4
	s_cselect_b32 s5, s19, s52
	s_cselect_b32 s4, s21, s51
	v_lshl_add_u64 v[174:175], s[0:1], 0, v[166:167]
	s_add_i32 m0, s27, 0xc000
	ds_read_b128 v[144:147], v187
	ds_read_b128 v[148:151], v187 offset:1024
	ds_read_b128 v[182:185], v187 offset:2048
	ds_read_b128 v[192:195], v187 offset:3072
	ds_read_b128 v[196:199], v187 offset:4096
	ds_read_b128 v[200:203], v187 offset:5120
	ds_read_b128 v[204:207], v187 offset:6144
	ds_read_b128 v[208:211], v187 offset:7168
	global_load_lds_dwordx4 v[174:175], off
	v_lshl_add_u64 v[174:175], s[0:1], 0, v[168:169]
	s_add_i32 m0, s27, 0xe000
	s_nop 0
	global_load_lds_dwordx4 v[174:175], off
	s_waitcnt lgkmcnt(8)
	s_barrier
	s_waitcnt lgkmcnt(0)
	s_waitcnt lgkmcnt(0)
	v_mfma_f32_16x16x32_bf16 v[140:143], v[24:27], v[144:147], v[140:143]
	v_mfma_f32_16x16x32_bf16 v[136:139], v[40:43], v[144:147], v[136:139]
	v_mfma_f32_16x16x32_bf16 v[124:127], v[24:27], v[182:185], v[124:127]
	v_mfma_f32_16x16x32_bf16 v[120:123], v[40:43], v[182:185], v[120:123]
	v_mfma_f32_16x16x32_bf16 v[108:111], v[24:27], v[196:199], v[108:111]
	v_mfma_f32_16x16x32_bf16 v[104:107], v[40:43], v[196:199], v[104:107]
	v_mfma_f32_16x16x32_bf16 v[92:95], v[24:27], v[204:207], v[92:95]
	v_mfma_f32_16x16x32_bf16 v[88:91], v[40:43], v[204:207], v[88:91]
	v_mfma_f32_16x16x32_bf16 v[140:143], v[28:31], v[148:151], v[140:143]
	v_mfma_f32_16x16x32_bf16 v[136:139], v[44:47], v[148:151], v[136:139]
	v_mfma_f32_16x16x32_bf16 v[124:127], v[28:31], v[192:195], v[124:127]
	v_mfma_f32_16x16x32_bf16 v[120:123], v[44:47], v[192:195], v[120:123]
	v_mfma_f32_16x16x32_bf16 v[108:111], v[28:31], v[200:203], v[108:111]
	v_mfma_f32_16x16x32_bf16 v[104:107], v[44:47], v[200:203], v[104:107]
	v_mfma_f32_16x16x32_bf16 v[92:95], v[28:31], v[208:211], v[92:95]
	v_mfma_f32_16x16x32_bf16 v[88:91], v[44:47], v[208:211], v[88:91]
	s_barrier
	s_add_i32 s54, s43, s35
	v_lshl_add_u64 v[174:175], s[4:5], 0, v[156:157]
	s_mov_b32 m0, s54
	ds_read_b128 v[212:215], v189
	ds_read_b128 v[216:219], v189 offset:1024
	ds_read_b128 v[220:223], v189 offset:2048
	ds_read_b128 v[224:227], v189 offset:3072
	global_load_lds_dwordx4 v[174:175], off
	v_lshl_add_u64 v[228:229], s[4:5], 0, v[160:161]
	s_add_i32 m0, s54, 0x2000
	s_nop 0
	global_load_lds_dwordx4 v[228:229], off
	s_barrier
	s_waitcnt lgkmcnt(0)
	s_waitcnt lgkmcnt(0)
	v_mfma_f32_16x16x32_bf16 v[132:135], v[212:215], v[144:147], v[132:135]
	v_mfma_f32_16x16x32_bf16 v[128:131], v[220:223], v[144:147], v[128:131]
	v_mfma_f32_16x16x32_bf16 v[116:119], v[212:215], v[182:185], v[116:119]
	v_mfma_f32_16x16x32_bf16 v[112:115], v[220:223], v[182:185], v[112:115]
	v_mfma_f32_16x16x32_bf16 v[100:103], v[212:215], v[196:199], v[100:103]
	v_mfma_f32_16x16x32_bf16 v[96:99], v[220:223], v[196:199], v[96:99]
	v_mfma_f32_16x16x32_bf16 v[84:87], v[212:215], v[204:207], v[84:87]
	v_mfma_f32_16x16x32_bf16 v[80:83], v[220:223], v[204:207], v[80:83]
	v_mfma_f32_16x16x32_bf16 v[132:135], v[216:219], v[148:151], v[132:135]
	v_mfma_f32_16x16x32_bf16 v[128:131], v[224:227], v[148:151], v[128:131]
	v_mfma_f32_16x16x32_bf16 v[116:119], v[216:219], v[192:195], v[116:119]
	v_mfma_f32_16x16x32_bf16 v[112:115], v[224:227], v[192:195], v[112:115]
	v_mfma_f32_16x16x32_bf16 v[100:103], v[216:219], v[200:203], v[100:103]
	v_mfma_f32_16x16x32_bf16 v[96:99], v[224:227], v[200:203], v[96:99]
	v_mfma_f32_16x16x32_bf16 v[84:87], v[216:219], v[208:211], v[84:87]
	v_mfma_f32_16x16x32_bf16 v[80:83], v[224:227], v[208:211], v[80:83]
	s_barrier
	s_mov_b32 m0, s27
	v_lshl_add_u64 v[230:231], s[28:29], 0, v[154:155]
	ds_read_b128 v[144:147], v187 offset:16384
	ds_read_b128 v[148:151], v187 offset:17408
	ds_read_b128 v[182:185], v187 offset:18432
	ds_read_b128 v[192:195], v187 offset:19456
	ds_read_b128 v[196:199], v187 offset:20480
	ds_read_b128 v[200:203], v187 offset:21504
	ds_read_b128 v[204:207], v187 offset:22528
	ds_read_b128 v[208:211], v187 offset:23552
	global_load_lds_dwordx4 v[230:231], off
	v_lshl_add_u64 v[232:233], s[28:29], 0, v[158:159]
	s_mov_b32 m0, s36
	s_nop 0
	global_load_lds_dwordx4 v[232:233], off
	s_barrier
	s_waitcnt lgkmcnt(0)
	s_waitcnt lgkmcnt(0)
	v_mfma_f32_16x16x32_bf16 v[76:79], v[24:27], v[144:147], v[76:79]
	v_mfma_f32_16x16x32_bf16 v[72:75], v[40:43], v[144:147], v[72:75]
	v_mfma_f32_16x16x32_bf16 v[60:63], v[24:27], v[182:185], v[60:63]
	v_mfma_f32_16x16x32_bf16 v[56:59], v[40:43], v[182:185], v[56:59]
	v_mfma_f32_16x16x32_bf16 v[36:39], v[24:27], v[196:199], v[36:39]
	v_mfma_f32_16x16x32_bf16 v[32:35], v[40:43], v[196:199], v[32:35]
	v_mfma_f32_16x16x32_bf16 v[12:15], v[24:27], v[204:207], v[12:15]
	v_mfma_f32_16x16x32_bf16 v[8:11], v[40:43], v[204:207], v[8:11]
	v_mfma_f32_16x16x32_bf16 v[76:79], v[28:31], v[148:151], v[76:79]
	v_mfma_f32_16x16x32_bf16 v[72:75], v[44:47], v[148:151], v[72:75]
	v_mfma_f32_16x16x32_bf16 v[60:63], v[28:31], v[192:195], v[60:63]
	v_mfma_f32_16x16x32_bf16 v[56:59], v[44:47], v[192:195], v[56:59]
	v_mfma_f32_16x16x32_bf16 v[36:39], v[28:31], v[200:203], v[36:39]
	v_mfma_f32_16x16x32_bf16 v[32:35], v[44:47], v[200:203], v[32:35]
	v_mfma_f32_16x16x32_bf16 v[12:15], v[28:31], v[208:211], v[12:15]
	v_mfma_f32_16x16x32_bf16 v[8:11], v[44:47], v[208:211], v[8:11]
	s_barrier
; #define PG8_STAGE(bufoff, gbase, voff) do { _Pragma("unroll") for (int _i = 0; _i < 2; ++_i) \
;         __builtin_amdgcn_global_load_lds((const unsigned*)((const char*)(gbase) + (voff)[_i]), (PG8_LAS unsigned*)(lds + (bufoff) + ldsw + _i * 8192), 16, 0, 0); } while (0)
; #define PG8_LDA(dst, b, h) do { _Pragma("unroll") for (int m = 0; m < 4; ++m) _Pragma("unroll") for (int k = 0; k < 2; ++k) dst[m][k] = *(const PG8_LAS bf16x8*)(lds + PG8_SA(b, h) + aoff + m * 2048 + k * 1024); } while (0)
; #define PG8_LDB(dst, b, h) do { _Pragma("unroll") for (int n = 0; n < 2; ++n) _Pragma("unroll") for (int k = 0; k < 2; ++k) dst[n][k] = *(const PG8_LAS bf16x8*)(lds + PG8_SB(b, h) + boff + n * 2048 + k * 1024); } while (0)
; #define PG8_MMA(ai, bj, At, Bt) do { __builtin_amdgcn_s_setprio(1); _Pragma("unroll") for (int m = 0; m < 4; ++m) _Pragma("unroll") for (int n = 0; n < 2; ++n) _Pragma("unroll") for (int k = 0; k < 2; ++k) \
;         acc[ai][bj][m][n] = __builtin_amdgcn_mfma_f32_16x16x32_bf16(Bt[n][k], At[m][k], acc[ai][bj][m][n], 0, 0, 0); __builtin_amdgcn_s_setprio(0); } while (0)
; #define PG8_WAIT_V(n) asm volatile("s_waitcnt vmcnt(" #n ")" ::: "memory")
; #define PG8_WAIT_L(n) asm volatile("s_waitcnt lgkmcnt(" #n ")" ::: "memory")
; #define PG8_BAR __builtin_amdgcn_s_barrier()
; #define PG8_SCHED __builtin_amdgcn_sched_barrier(0)
; template <class Epi, class Sched>
; __device__ __forceinline__ void gemm_phase(PG8_LAS unsigned char* lds, const Gemm g, const Sched& S, const Epi& E) {
;     ...
;             PG8_STAGE(PG8_SB(0, 1), b2 + hstep, voffB);
;             PG8_WAIT_V(6); PG8_BAR; PG8_MMA(1, 1, At, B1); PG8_BAR;
;             PG8_LDB(B0, 1, 0); PG8_SCHED; PG8_LDA(At, 1, 0); PG8_STAGE(PG8_SA(0, 1), a2 + hstep, voffA);
;             PG8_WAIT_L(8); PG8_BAR; PG8_WAIT_L(0); PG8_MMA(0, 0, At, B0); PG8_BAR; PG8_SCHED;
;             PG8_LDB(B1, 1, 1); PG8_STAGE(PG8_SB(1, 0), b3, voffB);
;             PG8_BAR; PG8_WAIT_L(0); PG8_MMA(0, 1, At, B1); PG8_BAR;
	s_add_u32 s54, s4, 0x40000
	s_addc_u32 s55, s5, 0
	s_add_i32 s56, s44, s35
	v_lshl_add_u64 v[24:25], s[54:55], 0, v[156:157]
	s_mov_b32 m0, s56
	s_nop 0
	global_load_lds_dwordx4 v[24:25], off
	v_lshl_add_u64 v[24:25], s[54:55], 0, v[160:161]
	s_add_i32 m0, s56, 0x2000
	s_nop 0
	global_load_lds_dwordx4 v[24:25], off
	s_waitcnt vmcnt(6)
	s_barrier
	v_mfma_f32_16x16x32_bf16 v[20:23], v[212:215], v[196:199], v[20:23]
	v_mfma_f32_16x16x32_bf16 v[16:19], v[220:223], v[196:199], v[16:19]
	v_mfma_f32_16x16x32_bf16 v[4:7], v[212:215], v[204:207], v[4:7]
	v_mfma_f32_16x16x32_bf16 v[0:3], v[220:223], v[204:207], v[0:3]
	v_mfma_f32_16x16x32_bf16 v[24:27], v[212:215], v[144:147], v[68:71]
	v_mfma_f32_16x16x32_bf16 v[28:31], v[220:223], v[144:147], v[64:67]
	v_mfma_f32_16x16x32_bf16 v[40:43], v[212:215], v[182:185], v[52:55]
	v_mfma_f32_16x16x32_bf16 v[44:47], v[220:223], v[182:185], v[48:51]
	v_mfma_f32_16x16x32_bf16 v[20:23], v[216:219], v[200:203], v[20:23]
	v_mfma_f32_16x16x32_bf16 v[16:19], v[224:227], v[200:203], v[16:19]
	v_mfma_f32_16x16x32_bf16 v[4:7], v[216:219], v[208:211], v[4:7]
	v_mfma_f32_16x16x32_bf16 v[0:3], v[224:227], v[208:211], v[0:3]
	v_mfma_f32_16x16x32_bf16 v[24:27], v[216:219], v[148:151], v[24:27]
	v_mfma_f32_16x16x32_bf16 v[28:31], v[224:227], v[148:151], v[28:31]
	v_mfma_f32_16x16x32_bf16 v[40:43], v[216:219], v[192:195], v[40:43]
	v_mfma_f32_16x16x32_bf16 v[44:47], v[224:227], v[192:195], v[44:47]
	s_barrier
	s_add_i32 s54, 0, 0x18000
	v_add_u32_e32 v68, s54, v179
	ds_read_b128 v[48:51], v68
	ds_read_b128 v[52:55], v68 offset:1024
	ds_read_b128 v[64:67], v68 offset:2048
	ds_read_b128 v[68:71], v68 offset:3072
	s_add_u32 s28, s28, 0x40000
	s_addc_u32 s29, s29, 0
	s_mov_b32 m0, s37
	v_lshl_add_u64 v[212:213], s[28:29], 0, v[154:155]
	ds_read_b128 v[144:147], v187 offset:32768
	ds_read_b128 v[148:151], v187 offset:33792
	ds_read_b128 v[182:185], v187 offset:34816
	ds_read_b128 v[192:195], v187 offset:35840
	ds_read_b128 v[196:199], v187 offset:36864
	ds_read_b128 v[200:203], v187 offset:37888
	ds_read_b128 v[204:207], v187 offset:38912
	ds_read_b128 v[208:211], v187 offset:39936
	global_load_lds_dwordx4 v[212:213], off
	v_lshl_add_u64 v[212:213], s[28:29], 0, v[158:159]
	s_mov_b32 m0, s38
	s_nop 0
	global_load_lds_dwordx4 v[212:213], off
	s_waitcnt lgkmcnt(8)
	s_barrier
	s_waitcnt lgkmcnt(0)
	s_waitcnt lgkmcnt(0)
	v_mfma_f32_16x16x32_bf16 v[140:143], v[48:51], v[144:147], v[140:143]
	v_mfma_f32_16x16x32_bf16 v[136:139], v[64:67], v[144:147], v[136:139]
	v_mfma_f32_16x16x32_bf16 v[124:127], v[48:51], v[182:185], v[124:127]
	v_mfma_f32_16x16x32_bf16 v[120:123], v[64:67], v[182:185], v[120:123]
	v_mfma_f32_16x16x32_bf16 v[108:111], v[48:51], v[196:199], v[108:111]
	v_mfma_f32_16x16x32_bf16 v[104:107], v[64:67], v[196:199], v[104:107]
	v_mfma_f32_16x16x32_bf16 v[92:95], v[48:51], v[204:207], v[92:95]
	v_mfma_f32_16x16x32_bf16 v[88:91], v[64:67], v[204:207], v[88:91]
	v_mfma_f32_16x16x32_bf16 v[140:143], v[52:55], v[148:151], v[140:143]
	v_mfma_f32_16x16x32_bf16 v[136:139], v[68:71], v[148:151], v[136:139]
	v_mfma_f32_16x16x32_bf16 v[124:127], v[52:55], v[192:195], v[124:127]
	v_mfma_f32_16x16x32_bf16 v[120:123], v[68:71], v[192:195], v[120:123]
	v_mfma_f32_16x16x32_bf16 v[108:111], v[52:55], v[200:203], v[108:111]
	v_mfma_f32_16x16x32_bf16 v[104:107], v[68:71], v[200:203], v[104:107]
	v_mfma_f32_16x16x32_bf16 v[92:95], v[52:55], v[208:211], v[92:95]
	v_mfma_f32_16x16x32_bf16 v[88:91], v[68:71], v[208:211], v[88:91]
	s_barrier
	s_add_i32 s28, 0, 0x1c000
	s_add_i32 s29, s54, s35
	v_add_u32_e32 v162, s28, v179
	v_lshl_add_u64 v[174:175], v[174:175], 0, s[14:15]
	s_mov_b32 m0, s29
	ds_read_b128 v[212:215], v162
	ds_read_b128 v[216:219], v162 offset:1024
	ds_read_b128 v[220:223], v162 offset:2048
	ds_read_b128 v[224:227], v162 offset:3072
	global_load_lds_dwordx4 v[174:175], off
	v_lshl_add_u64 v[174:175], v[228:229], 0, s[14:15]
	s_add_i32 m0, s29, 0x2000
	s_nop 0
	global_load_lds_dwordx4 v[174:175], off
	s_barrier
	s_waitcnt lgkmcnt(0)
	s_waitcnt lgkmcnt(0)
	v_mfma_f32_16x16x32_bf16 v[132:135], v[212:215], v[144:147], v[132:135]
	v_mfma_f32_16x16x32_bf16 v[128:131], v[220:223], v[144:147], v[128:131]
	v_mfma_f32_16x16x32_bf16 v[116:119], v[212:215], v[182:185], v[116:119]
	v_mfma_f32_16x16x32_bf16 v[112:115], v[220:223], v[182:185], v[112:115]
	v_mfma_f32_16x16x32_bf16 v[100:103], v[212:215], v[196:199], v[100:103]
	v_mfma_f32_16x16x32_bf16 v[96:99], v[220:223], v[196:199], v[96:99]
	v_mfma_f32_16x16x32_bf16 v[84:87], v[212:215], v[204:207], v[84:87]
	v_mfma_f32_16x16x32_bf16 v[80:83], v[220:223], v[204:207], v[80:83]
	v_mfma_f32_16x16x32_bf16 v[132:135], v[216:219], v[148:151], v[132:135]
	v_mfma_f32_16x16x32_bf16 v[128:131], v[224:227], v[148:151], v[128:131]
	v_mfma_f32_16x16x32_bf16 v[116:119], v[216:219], v[192:195], v[116:119]
	v_mfma_f32_16x16x32_bf16 v[112:115], v[224:227], v[192:195], v[112:115]
	v_mfma_f32_16x16x32_bf16 v[100:103], v[216:219], v[200:203], v[100:103]
	v_mfma_f32_16x16x32_bf16 v[96:99], v[224:227], v[200:203], v[96:99]
	v_mfma_f32_16x16x32_bf16 v[84:87], v[216:219], v[208:211], v[84:87]
	v_mfma_f32_16x16x32_bf16 v[80:83], v[224:227], v[208:211], v[80:83]
	s_barrier
; #define PG8_STAGE(bufoff, gbase, voff) do { _Pragma("unroll") for (int _i = 0; _i < 2; ++_i) \
;         __builtin_amdgcn_global_load_lds((const unsigned*)((const char*)(gbase) + (voff)[_i]), (PG8_LAS unsigned*)(lds + (bufoff) + ldsw + _i * 8192), 16, 0, 0); } while (0)
; #define PG8_LDA(dst, b, h) do { _Pragma("unroll") for (int m = 0; m < 4; ++m) _Pragma("unroll") for (int k = 0; k < 2; ++k) dst[m][k] = *(const PG8_LAS bf16x8*)(lds + PG8_SA(b, h) + aoff + m * 2048 + k * 1024); } while (0)
; #define PG8_LDB(dst, b, h) do { _Pragma("unroll") for (int n = 0; n < 2; ++n) _Pragma("unroll") for (int k = 0; k < 2; ++k) dst[n][k] = *(const PG8_LAS bf16x8*)(lds + PG8_SB(b, h) + boff + n * 2048 + k * 1024); } while (0)
; #define PG8_MMA(ai, bj, At, Bt) do { __builtin_amdgcn_s_setprio(1); _Pragma("unroll") for (int m = 0; m < 4; ++m) _Pragma("unroll") for (int n = 0; n < 2; ++n) _Pragma("unroll") for (int k = 0; k < 2; ++k) \
;         acc[ai][bj][m][n] = __builtin_amdgcn_mfma_f32_16x16x32_bf16(Bt[n][k], At[m][k], acc[ai][bj][m][n], 0, 0, 0); __builtin_amdgcn_s_setprio(0); } while (0)
;     __device__ __forceinline__ void operator()(const f32x4 (&acc)[2][2][4][2], const Unit& u, int wr, int wc, int fr, int fq) const {
;     ...
;         if (mode == 1) { if (u.pn >= 8 && u.pn < 12) act = 1; else if (u.pn >= 12) { act = 3; bias = (u.pn >= 14) ? bias_b + (u.pn - 14) * 256 : bias_f + (u.pn - 12) * 256; } }
;         else if (mode == 2) { if (u.pn >= 6) act = 2; }
;         const int row0 = u.pm * BM + wr * 64 + fr, col0 = u.pn * BM + wc * 32 + 8 * fq, bcol0 = wc * 32 + 8 * fq;
;         f32x4 bv[2][2];
; #pragma unroll
;         for (int bj = 0; bj < 2; ++bj)
; #pragma unroll
;             for (int n = 0; n < 2; ++n) bv[bj][n] = bias ? *(const f32x4*)(bias + bcol0 + bj * HALF + 4 * n) : (f32x4){0.f, 0.f, 0.f, 0.f};
; template <class Epi, class Sched>
; __device__ __forceinline__ void gemm_phase(PG8_LAS unsigned char* lds, const Gemm g, const Sched& S, const Epi& E) {
;     ...
;             PG8_LDB(B1, 1, 1); PG8_STAGE(PG8_SB(1, 0), b3, voffB);
;             PG8_BAR; PG8_WAIT_L(0); PG8_MMA(0, 1, At, B1); PG8_BAR;
;             PG8_LDA(At, 1, 1); PG8_STAGE(PG8_SA(1, 0), a3, voffA);
;             PG8_BAR; PG8_WAIT_L(0); PG8_MMA(1, 0, At, B0); PG8_BAR; PG8_SCHED;
;             PG8_STAGE(PG8_SB(1, 1), b3 + hstep, voffB);
;             PG8_WAIT_V(6); PG8_BAR; PG8_MMA(1, 1, At, B1); PG8_BAR;
	s_mov_b32 m0, s39
	v_lshl_add_u64 v[174:175], v[230:231], 0, s[14:15]
	ds_read_b128 v[144:147], v187 offset:49152
	ds_read_b128 v[148:151], v187 offset:50176
	ds_read_b128 v[182:185], v187 offset:51200
	ds_read_b128 v[192:195], v187 offset:52224
	ds_read_b128 v[196:199], v187 offset:53248
	ds_read_b128 v[200:203], v187 offset:54272
	ds_read_b128 v[204:207], v187 offset:55296
	ds_read_b128 v[208:211], v187 offset:56320
	global_load_lds_dwordx4 v[174:175], off
	v_lshl_add_u64 v[174:175], v[232:233], 0, s[14:15]
	s_mov_b32 m0, s40
	s_nop 0
	global_load_lds_dwordx4 v[174:175], off
	s_barrier
	s_waitcnt lgkmcnt(0)
	s_waitcnt lgkmcnt(0)
	v_mfma_f32_16x16x32_bf16 v[76:79], v[48:51], v[144:147], v[76:79]
	v_mfma_f32_16x16x32_bf16 v[72:75], v[64:67], v[144:147], v[72:75]
	v_mfma_f32_16x16x32_bf16 v[60:63], v[48:51], v[182:185], v[60:63]
	v_mfma_f32_16x16x32_bf16 v[56:59], v[64:67], v[182:185], v[56:59]
	v_mfma_f32_16x16x32_bf16 v[36:39], v[48:51], v[196:199], v[36:39]
	v_mfma_f32_16x16x32_bf16 v[32:35], v[64:67], v[196:199], v[32:35]
	v_mfma_f32_16x16x32_bf16 v[12:15], v[48:51], v[204:207], v[12:15]
	v_mfma_f32_16x16x32_bf16 v[8:11], v[64:67], v[204:207], v[8:11]
	v_mfma_f32_16x16x32_bf16 v[76:79], v[52:55], v[148:151], v[76:79]
	v_mfma_f32_16x16x32_bf16 v[72:75], v[68:71], v[148:151], v[72:75]
	v_mfma_f32_16x16x32_bf16 v[60:63], v[52:55], v[192:195], v[60:63]
	v_mfma_f32_16x16x32_bf16 v[56:59], v[68:71], v[192:195], v[56:59]
	v_mfma_f32_16x16x32_bf16 v[36:39], v[52:55], v[200:203], v[36:39]
	v_mfma_f32_16x16x32_bf16 v[32:35], v[68:71], v[200:203], v[32:35]
	v_mfma_f32_16x16x32_bf16 v[12:15], v[52:55], v[208:211], v[12:15]
	v_mfma_f32_16x16x32_bf16 v[8:11], v[68:71], v[208:211], v[8:11]
	s_barrier
	s_add_u32 s4, s4, 0x40080
	s_addc_u32 s5, s5, 0
	s_add_i32 s28, s28, s35
	v_lshl_add_u64 v[48:49], s[4:5], 0, v[156:157]
	s_mov_b32 m0, s28
	s_nop 0
	global_load_lds_dwordx4 v[48:49], off
	v_lshl_add_u64 v[48:49], s[4:5], 0, v[160:161]
	s_add_i32 m0, s28, 0x2000
	s_nop 0
	global_load_lds_dwordx4 v[48:49], off
	s_waitcnt vmcnt(6)
	s_barrier
	v_mfma_f32_16x16x32_bf16 v[24:27], v[212:215], v[144:147], v[24:27]
	v_mfma_f32_16x16x32_bf16 v[68:71], v[216:219], v[148:151], v[24:27]
	v_mfma_f32_16x16x32_bf16 v[24:27], v[220:223], v[144:147], v[28:31]
	v_mfma_f32_16x16x32_bf16 v[64:67], v[224:227], v[148:151], v[24:27]
	v_mfma_f32_16x16x32_bf16 v[24:27], v[212:215], v[182:185], v[40:43]
	v_mfma_f32_16x16x32_bf16 v[52:55], v[216:219], v[192:195], v[24:27]
	v_mfma_f32_16x16x32_bf16 v[24:27], v[220:223], v[182:185], v[44:47]
	v_mfma_f32_16x16x32_bf16 v[20:23], v[212:215], v[196:199], v[20:23]
	v_mfma_f32_16x16x32_bf16 v[16:19], v[220:223], v[196:199], v[16:19]
	v_mfma_f32_16x16x32_bf16 v[4:7], v[212:215], v[204:207], v[4:7]
	v_mfma_f32_16x16x32_bf16 v[0:3], v[220:223], v[204:207], v[0:3]
	v_mfma_f32_16x16x32_bf16 v[48:51], v[224:227], v[192:195], v[24:27]
	v_mfma_f32_16x16x32_bf16 v[20:23], v[216:219], v[200:203], v[20:23]
	v_mfma_f32_16x16x32_bf16 v[16:19], v[224:227], v[200:203], v[16:19]
	v_mfma_f32_16x16x32_bf16 v[4:7], v[216:219], v[208:211], v[4:7]
	v_mfma_f32_16x16x32_bf16 v[0:3], v[224:227], v[208:211], v[0:3]
	s_barrier
	s_add_i32 s53, s53, 2
	s_add_u32 s0, s0, 0x100
	s_addc_u32 s1, s1, 0
	s_add_u32 s51, s51, 0x100
	s_addc_u32 s52, s52, 0
	s_cmp_gt_u32 s53, 13
	s_cbranch_scc0 .LBB0_416
	s_cmp_gt_i32 s26, 11
	s_cselect_b64 s[4:5], -1, 0
	s_cmp_lt_i32 s26, 12
	s_mov_b64 s[0:1], 0
	s_cbranch_scc1 .LBB0_422
	s_lshl_b32 s10, s26, 8
	s_cmp_lt_u32 s26, 14
	s_mov_b64 s[28:29], -1
	s_cbranch_scc0 .LBB0_420
	s_lshl_b64 s[0:1], s[10:11], 2
	v_readlane_b32 s52, v245, 0
	v_readlane_b32 s53, v245, 1
	s_add_u32 s0, s52, s0
	s_addc_u32 s1, s53, s1
	s_add_u32 s0, s0, 0xffffd000
	v_readlane_b32 s54, v245, 2
	v_readlane_b32 s55, v245, 3
	v_readlane_b32 s56, v245, 4
	v_readlane_b32 s57, v245, 5
	v_readlane_b32 s58, v245, 6
	v_readlane_b32 s59, v245, 7
	v_readlane_b32 s60, v245, 8
	v_readlane_b32 s61, v245, 9
	v_readlane_b32 s62, v245, 10
	v_readlane_b32 s63, v245, 11
	v_readlane_b32 s64, v245, 12
	v_readlane_b32 s65, v245, 13
	v_readlane_b32 s66, v245, 14
	v_readlane_b32 s67, v245, 15
	s_addc_u32 s1, s1, -1
	s_mov_b64 s[28:29], 0

; #define PG8_STAGE(bufoff, gbase, voff) do { _Pragma("unroll") for (int _i = 0; _i < 2; ++_i) \
;         __builtin_amdgcn_global_load_lds((const unsigned*)((const char*)(gbase) + (voff)[_i]), (PG8_LAS unsigned*)(lds + (bufoff) + ldsw + _i * 8192), 16, 0, 0); } while (0)
; #define PG8_LDA(dst, b, h) do { _Pragma("unroll") for (int m = 0; m < 4; ++m) _Pragma("unroll") for (int k = 0; k < 2; ++k) dst[m][k] = *(const PG8_LAS bf16x8*)(lds + PG8_SA(b, h) + aoff + m * 2048 + k * 1024); } while (0)
; #define PG8_LDB(dst, b, h) do { _Pragma("unroll") for (int n = 0; n < 2; ++n) _Pragma("unroll") for (int k = 0; k < 2; ++k) dst[n][k] = *(const PG8_LAS bf16x8*)(lds + PG8_SB(b, h) + boff + n * 2048 + k * 1024); } while (0)
; #define PG8_MMA(ai, bj, At, Bt) do { __builtin_amdgcn_s_setprio(1); _Pragma("unroll") for (int m = 0; m < 4; ++m) _Pragma("unroll") for (int n = 0; n < 2; ++n) _Pragma("unroll") for (int k = 0; k < 2; ++k) \
;         acc[ai][bj][m][n] = __builtin_amdgcn_mfma_f32_16x16x32_bf16(Bt[n][k], At[m][k], acc[ai][bj][m][n], 0, 0, 0); __builtin_amdgcn_s_setprio(0); } while (0)
; #define PG8_BAR __builtin_amdgcn_s_barrier()
; template <class Epi, class Sched>
; __device__ __forceinline__ void gemm_phase(PG8_LAS unsigned char* lds, const Gemm g, const Sched& S, const Epi& E) {
;     ...
;             const bool last = (t == nt - 2);
;             const char* a1 = cA + (size_t)(t + 1) * kstep;
;             const char* a2 = last ? nA : cA + (size_t)(t + 2) * kstep; const char* b2 = last ? nB : cB + (size_t)(t + 2) * kstep;
;             const char* a3 = a2 + kstep; const char* b3 = b2 + kstep;
;             if (last && has_next) S.a_ready(nxt);
;             PG8_LDB(B0, 0, 0); PG8_SCHED; PG8_LDA(At, 0, 0); PG8_STAGE(PG8_SA(1, 1), a1 + hstep, voffA);
;             PG8_WAIT_L(8); PG8_BAR; PG8_WAIT_L(0); PG8_MMA(0, 0, At, B0); PG8_BAR; PG8_SCHED;
;             PG8_LDB(B1, 0, 1); PG8_STAGE(PG8_SB(0, 0), b2, voffB);
;             PG8_BAR; PG8_WAIT_L(0); PG8_MMA(0, 1, At, B1); PG8_BAR;
;             PG8_LDA(At, 0, 1); PG8_STAGE(PG8_SA(0, 0), a2, voffA);
;             PG8_BAR; PG8_WAIT_L(0); PG8_MMA(1, 0, At, B0); PG8_BAR; PG8_SCHED;
;             PG8_STAGE(PG8_SB(0, 1), b2 + hstep, voffB);
;             PG8_WAIT_V(6); PG8_BAR; PG8_MMA(1, 1, At, B1); PG8_BAR;
;             PG8_LDB(B0, 1, 0); PG8_SCHED; PG8_LDA(At, 1, 0); PG8_STAGE(PG8_SA(0, 1), a2 + hstep, voffA);
.LBB0_724:
	ds_read_b128 v[144:147], v151
	ds_read_b128 v[156:159], v151 offset:1024
	ds_read_b128 v[160:163], v151 offset:2048
	ds_read_b128 v[166:169], v151 offset:3072
	s_add_u32 s20, s18, 0xfffc0080
	s_addc_u32 s21, s19, -1
	s_cmp_eq_u32 s48, 12
	s_cselect_b32 s23, s5, s21
	s_cselect_b32 s22, s11, s20
	s_cselect_b32 s21, s9, s47
	s_cselect_b32 s20, s45, s46
	v_lshl_add_u64 v[174:175], s[18:19], 0, v[136:137]
	s_add_i32 m0, s17, 0xc000
	ds_read_b128 v[170:173], v153
	ds_read_b128 v[182:185], v153 offset:1024
	ds_read_b128 v[190:193], v153 offset:2048
	ds_read_b128 v[194:197], v153 offset:3072
	ds_read_b128 v[198:201], v153 offset:4096
	ds_read_b128 v[202:205], v153 offset:5120
	ds_read_b128 v[206:209], v153 offset:6144
	ds_read_b128 v[210:213], v153 offset:7168
	global_load_lds_dwordx4 v[174:175], off
	v_lshl_add_u64 v[174:175], s[18:19], 0, v[138:139]
	s_add_i32 m0, s17, 0xe000
	s_nop 0
	global_load_lds_dwordx4 v[174:175], off
	s_waitcnt lgkmcnt(8)
	s_barrier
	s_waitcnt lgkmcnt(0)
	s_waitcnt lgkmcnt(0)
	v_mfma_f32_16x16x32_bf16 v[124:127], v[144:147], v[170:173], v[124:127]
	v_mfma_f32_16x16x32_bf16 v[120:123], v[160:163], v[170:173], v[120:123]
	v_mfma_f32_16x16x32_bf16 v[108:111], v[144:147], v[190:193], v[108:111]
	v_mfma_f32_16x16x32_bf16 v[104:107], v[160:163], v[190:193], v[104:107]
	v_mfma_f32_16x16x32_bf16 v[92:95], v[144:147], v[198:201], v[92:95]
	v_mfma_f32_16x16x32_bf16 v[88:91], v[160:163], v[198:201], v[88:91]
	v_mfma_f32_16x16x32_bf16 v[76:79], v[144:147], v[206:209], v[76:79]
	v_mfma_f32_16x16x32_bf16 v[72:75], v[160:163], v[206:209], v[72:75]
	v_mfma_f32_16x16x32_bf16 v[124:127], v[156:159], v[182:185], v[124:127]
	v_mfma_f32_16x16x32_bf16 v[120:123], v[166:169], v[182:185], v[120:123]
	v_mfma_f32_16x16x32_bf16 v[108:111], v[156:159], v[194:197], v[108:111]
	v_mfma_f32_16x16x32_bf16 v[104:107], v[166:169], v[194:197], v[104:107]
	v_mfma_f32_16x16x32_bf16 v[92:95], v[156:159], v[202:205], v[92:95]
	v_mfma_f32_16x16x32_bf16 v[88:91], v[166:169], v[202:205], v[88:91]
	v_mfma_f32_16x16x32_bf16 v[76:79], v[156:159], v[210:213], v[76:79]
	v_mfma_f32_16x16x32_bf16 v[72:75], v[166:169], v[210:213], v[72:75]
	s_barrier
	s_add_i32 s49, s42, s30
	v_lshl_add_u64 v[174:175], s[20:21], 0, v[130:131]
	s_mov_b32 m0, s49
	ds_read_b128 v[214:217], v154
	ds_read_b128 v[218:221], v154 offset:1024
	ds_read_b128 v[222:225], v154 offset:2048
	ds_read_b128 v[226:229], v154 offset:3072
	global_load_lds_dwordx4 v[174:175], off
	v_lshl_add_u64 v[186:187], s[20:21], 0, v[134:135]
	s_add_i32 m0, s49, 0x2000
	s_nop 0
	global_load_lds_dwordx4 v[186:187], off
	s_barrier
	s_waitcnt lgkmcnt(0)
	s_waitcnt lgkmcnt(0)
	v_mfma_f32_16x16x32_bf16 v[116:119], v[214:217], v[170:173], v[116:119]
	v_mfma_f32_16x16x32_bf16 v[112:115], v[222:225], v[170:173], v[112:115]
	v_mfma_f32_16x16x32_bf16 v[100:103], v[214:217], v[190:193], v[100:103]
	v_mfma_f32_16x16x32_bf16 v[96:99], v[222:225], v[190:193], v[96:99]
	v_mfma_f32_16x16x32_bf16 v[84:87], v[214:217], v[198:201], v[84:87]
	v_mfma_f32_16x16x32_bf16 v[80:83], v[222:225], v[198:201], v[80:83]
	v_mfma_f32_16x16x32_bf16 v[68:71], v[214:217], v[206:209], v[68:71]
	v_mfma_f32_16x16x32_bf16 v[64:67], v[222:225], v[206:209], v[64:67]
	v_mfma_f32_16x16x32_bf16 v[116:119], v[218:221], v[182:185], v[116:119]
	v_mfma_f32_16x16x32_bf16 v[112:115], v[226:229], v[182:185], v[112:115]
	v_mfma_f32_16x16x32_bf16 v[100:103], v[218:221], v[194:197], v[100:103]
	v_mfma_f32_16x16x32_bf16 v[96:99], v[226:229], v[194:197], v[96:99]
	v_mfma_f32_16x16x32_bf16 v[84:87], v[218:221], v[202:205], v[84:87]
	v_mfma_f32_16x16x32_bf16 v[80:83], v[226:229], v[202:205], v[80:83]
	v_mfma_f32_16x16x32_bf16 v[68:71], v[218:221], v[210:213], v[68:71]
	v_mfma_f32_16x16x32_bf16 v[64:67], v[226:229], v[210:213], v[64:67]
	s_barrier
	s_mov_b32 m0, s17
	v_lshl_add_u64 v[230:231], s[22:23], 0, v[128:129]
	ds_read_b128 v[170:173], v153 offset:16384
	ds_read_b128 v[182:185], v153 offset:17408
	ds_read_b128 v[190:193], v153 offset:18432
	ds_read_b128 v[194:197], v153 offset:19456
	ds_read_b128 v[198:201], v153 offset:20480
	ds_read_b128 v[202:205], v153 offset:21504
	ds_read_b128 v[206:209], v153 offset:22528
	ds_read_b128 v[210:213], v153 offset:23552
	global_load_lds_dwordx4 v[230:231], off
	v_lshl_add_u64 v[232:233], s[22:23], 0, v[132:133]
	s_mov_b32 m0, s31
	s_nop 0
	global_load_lds_dwordx4 v[232:233], off
	s_barrier
	s_waitcnt lgkmcnt(0)
	s_waitcnt lgkmcnt(0)
	v_mfma_f32_16x16x32_bf16 v[60:63], v[144:147], v[170:173], v[60:63]
	v_mfma_f32_16x16x32_bf16 v[56:59], v[160:163], v[170:173], v[56:59]
	v_mfma_f32_16x16x32_bf16 v[44:47], v[144:147], v[190:193], v[44:47]
	v_mfma_f32_16x16x32_bf16 v[40:43], v[160:163], v[190:193], v[40:43]
	v_mfma_f32_16x16x32_bf16 v[28:31], v[144:147], v[198:201], v[28:31]
	v_mfma_f32_16x16x32_bf16 v[24:27], v[160:163], v[198:201], v[24:27]
	v_mfma_f32_16x16x32_bf16 v[12:15], v[144:147], v[206:209], v[12:15]
	v_mfma_f32_16x16x32_bf16 v[8:11], v[160:163], v[206:209], v[8:11]
	v_mfma_f32_16x16x32_bf16 v[60:63], v[156:159], v[182:185], v[60:63]
	v_mfma_f32_16x16x32_bf16 v[56:59], v[166:169], v[182:185], v[56:59]
	v_mfma_f32_16x16x32_bf16 v[44:47], v[156:159], v[194:197], v[44:47]
	v_mfma_f32_16x16x32_bf16 v[40:43], v[166:169], v[194:197], v[40:43]
	v_mfma_f32_16x16x32_bf16 v[28:31], v[156:159], v[202:205], v[28:31]
	v_mfma_f32_16x16x32_bf16 v[24:27], v[166:169], v[202:205], v[24:27]
	v_mfma_f32_16x16x32_bf16 v[12:15], v[156:159], v[210:213], v[12:15]
	v_mfma_f32_16x16x32_bf16 v[8:11], v[166:169], v[210:213], v[8:11]
	s_barrier
; #define PG8_STAGE(bufoff, gbase, voff) do { _Pragma("unroll") for (int _i = 0; _i < 2; ++_i) \
;         __builtin_amdgcn_global_load_lds((const unsigned*)((const char*)(gbase) + (voff)[_i]), (PG8_LAS unsigned*)(lds + (bufoff) + ldsw + _i * 8192), 16, 0, 0); } while (0)
; #define PG8_LDA(dst, b, h) do { _Pragma("unroll") for (int m = 0; m < 4; ++m) _Pragma("unroll") for (int k = 0; k < 2; ++k) dst[m][k] = *(const PG8_LAS bf16x8*)(lds + PG8_SA(b, h) + aoff + m * 2048 + k * 1024); } while (0)
; #define PG8_LDB(dst, b, h) do { _Pragma("unroll") for (int n = 0; n < 2; ++n) _Pragma("unroll") for (int k = 0; k < 2; ++k) dst[n][k] = *(const PG8_LAS bf16x8*)(lds + PG8_SB(b, h) + boff + n * 2048 + k * 1024); } while (0)
; #define PG8_MMA(ai, bj, At, Bt) do { __builtin_amdgcn_s_setprio(1); _Pragma("unroll") for (int m = 0; m < 4; ++m) _Pragma("unroll") for (int n = 0; n < 2; ++n) _Pragma("unroll") for (int k = 0; k < 2; ++k) \
;         acc[ai][bj][m][n] = __builtin_amdgcn_mfma_f32_16x16x32_bf16(Bt[n][k], At[m][k], acc[ai][bj][m][n], 0, 0, 0); __builtin_amdgcn_s_setprio(0); } while (0)
; #define PG8_WAIT_V(n) asm volatile("s_waitcnt vmcnt(" #n ")" ::: "memory")
; #define PG8_WAIT_L(n) asm volatile("s_waitcnt lgkmcnt(" #n ")" ::: "memory")
; #define PG8_BAR __builtin_amdgcn_s_barrier()
; #define PG8_SCHED __builtin_amdgcn_sched_barrier(0)
; template <class Epi, class Sched>
; __device__ __forceinline__ void gemm_phase(PG8_LAS unsigned char* lds, const Gemm g, const Sched& S, const Epi& E) {
;     ...
;             PG8_STAGE(PG8_SB(0, 1), b2 + hstep, voffB);
;             PG8_WAIT_V(6); PG8_BAR; PG8_MMA(1, 1, At, B1); PG8_BAR;
;             PG8_LDB(B0, 1, 0); PG8_SCHED; PG8_LDA(At, 1, 0); PG8_STAGE(PG8_SA(0, 1), a2 + hstep, voffA);
;             PG8_WAIT_L(8); PG8_BAR; PG8_WAIT_L(0); PG8_MMA(0, 0, At, B0); PG8_BAR; PG8_SCHED;
;             PG8_LDB(B1, 1, 1); PG8_STAGE(PG8_SB(1, 0), b3, voffB);
;             PG8_BAR; PG8_WAIT_L(0); PG8_MMA(0, 1, At, B1); PG8_BAR;
;             PG8_LDA(At, 1, 1); PG8_STAGE(PG8_SA(1, 0), a3, voffA);
	s_add_u32 s50, s20, 0x40000
	s_addc_u32 s51, s21, 0
	s_add_i32 s49, s43, s30
	v_lshl_add_u64 v[144:145], s[50:51], 0, v[130:131]
	s_mov_b32 m0, s49
	s_nop 0
	global_load_lds_dwordx4 v[144:145], off
	v_lshl_add_u64 v[144:145], s[50:51], 0, v[134:135]
	s_add_i32 m0, s49, 0x2000
	s_nop 0
	global_load_lds_dwordx4 v[144:145], off
	s_waitcnt vmcnt(6)
	s_barrier
	v_mfma_f32_16x16x32_bf16 v[52:55], v[214:217], v[170:173], v[52:55]
	v_mfma_f32_16x16x32_bf16 v[48:51], v[222:225], v[170:173], v[48:51]
	v_mfma_f32_16x16x32_bf16 v[36:39], v[214:217], v[190:193], v[36:39]
	v_mfma_f32_16x16x32_bf16 v[32:35], v[222:225], v[190:193], v[32:35]
	v_mfma_f32_16x16x32_bf16 v[20:23], v[214:217], v[198:201], v[20:23]
	v_mfma_f32_16x16x32_bf16 v[16:19], v[222:225], v[198:201], v[16:19]
	v_mfma_f32_16x16x32_bf16 v[4:7], v[214:217], v[206:209], v[4:7]
	v_mfma_f32_16x16x32_bf16 v[0:3], v[222:225], v[206:209], v[0:3]
	v_mfma_f32_16x16x32_bf16 v[52:55], v[218:221], v[182:185], v[52:55]
	v_mfma_f32_16x16x32_bf16 v[48:51], v[226:229], v[182:185], v[48:51]
	v_mfma_f32_16x16x32_bf16 v[36:39], v[218:221], v[194:197], v[36:39]
	v_mfma_f32_16x16x32_bf16 v[32:35], v[226:229], v[194:197], v[32:35]
	v_mfma_f32_16x16x32_bf16 v[20:23], v[218:221], v[202:205], v[20:23]
	v_mfma_f32_16x16x32_bf16 v[16:19], v[226:229], v[202:205], v[16:19]
	v_mfma_f32_16x16x32_bf16 v[4:7], v[218:221], v[210:213], v[4:7]
	v_mfma_f32_16x16x32_bf16 v[0:3], v[226:229], v[210:213], v[0:3]
	s_barrier
	s_add_i32 s49, 0, 0x18000
	v_add_u32_e32 v155, s49, v149
	ds_read_b128 v[144:147], v155
	ds_read_b128 v[156:159], v155 offset:1024
	ds_read_b128 v[160:163], v155 offset:2048
	ds_read_b128 v[166:169], v155 offset:3072
	s_add_u32 s22, s22, 0x40000
	s_addc_u32 s23, s23, 0
	s_mov_b32 m0, s34
	v_lshl_add_u64 v[214:215], s[22:23], 0, v[128:129]
	ds_read_b128 v[170:173], v153 offset:32768
	ds_read_b128 v[182:185], v153 offset:33792
	ds_read_b128 v[190:193], v153 offset:34816
	ds_read_b128 v[194:197], v153 offset:35840
	ds_read_b128 v[198:201], v153 offset:36864
	ds_read_b128 v[202:205], v153 offset:37888
	ds_read_b128 v[206:209], v153 offset:38912
	ds_read_b128 v[210:213], v153 offset:39936
	global_load_lds_dwordx4 v[214:215], off
	v_lshl_add_u64 v[214:215], s[22:23], 0, v[132:133]
	s_mov_b32 m0, s35
	s_nop 0
	global_load_lds_dwordx4 v[214:215], off
	s_waitcnt lgkmcnt(8)
	s_barrier
	s_waitcnt lgkmcnt(0)
	s_waitcnt lgkmcnt(0)
	v_mfma_f32_16x16x32_bf16 v[124:127], v[144:147], v[170:173], v[124:127]
	v_mfma_f32_16x16x32_bf16 v[120:123], v[160:163], v[170:173], v[120:123]
	v_mfma_f32_16x16x32_bf16 v[108:111], v[144:147], v[190:193], v[108:111]
	v_mfma_f32_16x16x32_bf16 v[104:107], v[160:163], v[190:193], v[104:107]
	v_mfma_f32_16x16x32_bf16 v[92:95], v[144:147], v[198:201], v[92:95]
	v_mfma_f32_16x16x32_bf16 v[88:91], v[160:163], v[198:201], v[88:91]
	v_mfma_f32_16x16x32_bf16 v[76:79], v[144:147], v[206:209], v[76:79]
	v_mfma_f32_16x16x32_bf16 v[72:75], v[160:163], v[206:209], v[72:75]
	v_mfma_f32_16x16x32_bf16 v[124:127], v[156:159], v[182:185], v[124:127]
	v_mfma_f32_16x16x32_bf16 v[120:123], v[166:169], v[182:185], v[120:123]
	v_mfma_f32_16x16x32_bf16 v[108:111], v[156:159], v[194:197], v[108:111]
	v_mfma_f32_16x16x32_bf16 v[104:107], v[166:169], v[194:197], v[104:107]
	v_mfma_f32_16x16x32_bf16 v[92:95], v[156:159], v[202:205], v[92:95]
	v_mfma_f32_16x16x32_bf16 v[88:91], v[166:169], v[202:205], v[88:91]
	v_mfma_f32_16x16x32_bf16 v[76:79], v[156:159], v[210:213], v[76:79]
	v_mfma_f32_16x16x32_bf16 v[72:75], v[166:169], v[210:213], v[72:75]
	s_barrier
	s_add_i32 s22, 0, 0x1c000
	s_add_i32 s23, s49, s30
	v_add_u32_e32 v155, s22, v149
	v_lshl_add_u64 v[174:175], v[174:175], 0, s[6:7]
	s_mov_b32 m0, s23
	ds_read_b128 v[214:217], v155
	ds_read_b128 v[218:221], v155 offset:1024
	ds_read_b128 v[222:225], v155 offset:2048
	ds_read_b128 v[226:229], v155 offset:3072
	global_load_lds_dwordx4 v[174:175], off
	v_lshl_add_u64 v[174:175], v[186:187], 0, s[6:7]
	s_add_i32 m0, s23, 0x2000
	s_nop 0
	global_load_lds_dwordx4 v[174:175], off
	s_barrier
	s_waitcnt lgkmcnt(0)
	s_waitcnt lgkmcnt(0)
	v_mfma_f32_16x16x32_bf16 v[116:119], v[214:217], v[170:173], v[116:119]
	v_mfma_f32_16x16x32_bf16 v[112:115], v[222:225], v[170:173], v[112:115]
	v_mfma_f32_16x16x32_bf16 v[100:103], v[214:217], v[190:193], v[100:103]
	v_mfma_f32_16x16x32_bf16 v[96:99], v[222:225], v[190:193], v[96:99]
	v_mfma_f32_16x16x32_bf16 v[84:87], v[214:217], v[198:201], v[84:87]
	v_mfma_f32_16x16x32_bf16 v[80:83], v[222:225], v[198:201], v[80:83]
	v_mfma_f32_16x16x32_bf16 v[68:71], v[214:217], v[206:209], v[68:71]
	v_mfma_f32_16x16x32_bf16 v[64:67], v[222:225], v[206:209], v[64:67]
	v_mfma_f32_16x16x32_bf16 v[116:119], v[218:221], v[182:185], v[116:119]
	v_mfma_f32_16x16x32_bf16 v[112:115], v[226:229], v[182:185], v[112:115]
	v_mfma_f32_16x16x32_bf16 v[100:103], v[218:221], v[194:197], v[100:103]
	v_mfma_f32_16x16x32_bf16 v[96:99], v[226:229], v[194:197], v[96:99]
	v_mfma_f32_16x16x32_bf16 v[84:87], v[218:221], v[202:205], v[84:87]
	v_mfma_f32_16x16x32_bf16 v[80:83], v[226:229], v[202:205], v[80:83]
	v_mfma_f32_16x16x32_bf16 v[68:71], v[218:221], v[210:213], v[68:71]
	v_mfma_f32_16x16x32_bf16 v[64:67], v[226:229], v[210:213], v[64:67]
	s_barrier
	s_mov_b32 m0, s37
	v_lshl_add_u64 v[174:175], v[230:231], 0, s[6:7]
	ds_read_b128 v[170:173], v153 offset:49152
	ds_read_b128 v[182:185], v153 offset:50176
	ds_read_b128 v[190:193], v153 offset:51200
	ds_read_b128 v[194:197], v153 offset:52224
	ds_read_b128 v[198:201], v153 offset:53248
	ds_read_b128 v[202:205], v153 offset:54272
	ds_read_b128 v[206:209], v153 offset:55296
	ds_read_b128 v[210:213], v153 offset:56320
	global_load_lds_dwordx4 v[174:175], off
	v_lshl_add_u64 v[174:175], v[232:233], 0, s[6:7]
	s_mov_b32 m0, s38
	s_nop 0
	global_load_lds_dwordx4 v[174:175], off
	s_barrier
; #define PG8_STAGE(bufoff, gbase, voff) do { _Pragma("unroll") for (int _i = 0; _i < 2; ++_i) \
;         __builtin_amdgcn_global_load_lds((const unsigned*)((const char*)(gbase) + (voff)[_i]), (PG8_LAS unsigned*)(lds + (bufoff) + ldsw + _i * 8192), 16, 0, 0); } while (0)
; #define PG8_MMA(ai, bj, At, Bt) do { __builtin_amdgcn_s_setprio(1); _Pragma("unroll") for (int m = 0; m < 4; ++m) _Pragma("unroll") for (int n = 0; n < 2; ++n) _Pragma("unroll") for (int k = 0; k < 2; ++k) \
;         acc[ai][bj][m][n] = __builtin_amdgcn_mfma_f32_16x16x32_bf16(Bt[n][k], At[m][k], acc[ai][bj][m][n], 0, 0, 0); __builtin_amdgcn_s_setprio(0); } while (0)
; #define PG8_WAIT_V(n) asm volatile("s_waitcnt vmcnt(" #n ")" ::: "memory")
; #define PG8_WAIT_L(n) asm volatile("s_waitcnt lgkmcnt(" #n ")" ::: "memory")
; #define PG8_BAR __builtin_amdgcn_s_barrier()
; #define PG8_SCHED __builtin_amdgcn_sched_barrier(0)
; __device__ __forceinline__ f32x4 sigmoid4(f32x4 x) {
;     f32x4 d;
; #pragma unroll
;     for (int j = 0; j < 4; ++j) d[j] = 1.0f + __expf(-fmaxf(x[j], -20.0f));
;     const float p01 = d[0] * d[1], p23 = d[2] * d[3], r = __builtin_amdgcn_rcpf(p01 * p23), r01 = r * p23, r23 = r * p01;
;     return (f32x4){r01 * d[1], r01 * d[0], r23 * d[3], r23 * d[2]};
; }
; template <class Epi, class Sched>
; __device__ __forceinline__ void gemm_phase(PG8_LAS unsigned char* lds, const Gemm g, const Sched& S, const Epi& E) {
;     ...
;             PG8_BAR; PG8_WAIT_L(0); PG8_MMA(1, 0, At, B0); PG8_BAR; PG8_SCHED;
;             PG8_STAGE(PG8_SB(1, 1), b3 + hstep, voffB);
;             PG8_WAIT_V(6); PG8_BAR; PG8_MMA(1, 1, At, B1); PG8_BAR;
	s_waitcnt lgkmcnt(0)
	s_waitcnt lgkmcnt(0)
	v_mfma_f32_16x16x32_bf16 v[60:63], v[144:147], v[170:173], v[60:63]
	v_mfma_f32_16x16x32_bf16 v[56:59], v[160:163], v[170:173], v[56:59]
	v_mfma_f32_16x16x32_bf16 v[44:47], v[144:147], v[190:193], v[44:47]
	v_mfma_f32_16x16x32_bf16 v[40:43], v[160:163], v[190:193], v[40:43]
	v_mfma_f32_16x16x32_bf16 v[28:31], v[144:147], v[198:201], v[28:31]
	v_mfma_f32_16x16x32_bf16 v[24:27], v[160:163], v[198:201], v[24:27]
	v_mfma_f32_16x16x32_bf16 v[12:15], v[144:147], v[206:209], v[12:15]
	v_mfma_f32_16x16x32_bf16 v[8:11], v[160:163], v[206:209], v[8:11]
	v_mfma_f32_16x16x32_bf16 v[60:63], v[156:159], v[182:185], v[60:63]
	v_mfma_f32_16x16x32_bf16 v[56:59], v[166:169], v[182:185], v[56:59]
	v_mfma_f32_16x16x32_bf16 v[44:47], v[156:159], v[194:197], v[44:47]
	v_mfma_f32_16x16x32_bf16 v[40:43], v[166:169], v[194:197], v[40:43]
	v_mfma_f32_16x16x32_bf16 v[28:31], v[156:159], v[202:205], v[28:31]
	v_mfma_f32_16x16x32_bf16 v[24:27], v[166:169], v[202:205], v[24:27]
	v_mfma_f32_16x16x32_bf16 v[12:15], v[156:159], v[210:213], v[12:15]
	v_mfma_f32_16x16x32_bf16 v[8:11], v[166:169], v[210:213], v[8:11]
	s_barrier
	s_add_u32 s20, s20, 0x40080
	s_addc_u32 s21, s21, 0
	s_add_i32 s22, s22, s30
	v_lshl_add_u64 v[144:145], s[20:21], 0, v[130:131]
	s_mov_b32 m0, s22
	s_nop 0
	global_load_lds_dwordx4 v[144:145], off
	v_lshl_add_u64 v[144:145], s[20:21], 0, v[134:135]
	s_add_i32 m0, s22, 0x2000
	s_nop 0
	global_load_lds_dwordx4 v[144:145], off
	s_waitcnt vmcnt(6)
	s_barrier
	v_mfma_f32_16x16x32_bf16 v[52:55], v[214:217], v[170:173], v[52:55]
	v_mfma_f32_16x16x32_bf16 v[48:51], v[222:225], v[170:173], v[48:51]
	v_mfma_f32_16x16x32_bf16 v[36:39], v[214:217], v[190:193], v[36:39]
	v_mfma_f32_16x16x32_bf16 v[32:35], v[222:225], v[190:193], v[32:35]
	v_mfma_f32_16x16x32_bf16 v[20:23], v[214:217], v[198:201], v[20:23]
	v_mfma_f32_16x16x32_bf16 v[16:19], v[222:225], v[198:201], v[16:19]
	v_mfma_f32_16x16x32_bf16 v[4:7], v[214:217], v[206:209], v[4:7]
	v_mfma_f32_16x16x32_bf16 v[0:3], v[222:225], v[206:209], v[0:3]
	v_mfma_f32_16x16x32_bf16 v[52:55], v[218:221], v[182:185], v[52:55]
	v_mfma_f32_16x16x32_bf16 v[48:51], v[226:229], v[182:185], v[48:51]
	v_mfma_f32_16x16x32_bf16 v[36:39], v[218:221], v[194:197], v[36:39]
	v_mfma_f32_16x16x32_bf16 v[32:35], v[226:229], v[194:197], v[32:35]
	v_mfma_f32_16x16x32_bf16 v[20:23], v[218:221], v[202:205], v[20:23]
	v_mfma_f32_16x16x32_bf16 v[16:19], v[226:229], v[202:205], v[16:19]
	v_mfma_f32_16x16x32_bf16 v[4:7], v[218:221], v[210:213], v[4:7]
	v_mfma_f32_16x16x32_bf16 v[0:3], v[226:229], v[210:213], v[0:3]
	s_barrier
	s_add_i32 s48, s48, 2
	s_add_u32 s18, s18, 0x100
	s_addc_u32 s19, s19, 0
	s_add_u32 s46, s46, 0x100
	s_addc_u32 s47, s47, 0
	s_cmp_gt_u32 s48, 13
	s_cbranch_scc0 .LBB0_724
	s_cmp_gt_i32 s4, 5
	s_cselect_b64 s[18:19], -1, 0
	s_cmp_lt_i32 s4, 6
	v_pk_add_f32 v[144:145], v[126:127], 0 op_sel_hi:[1,0]
	v_pk_add_f32 v[146:147], v[124:125], 0 op_sel_hi:[1,0]
	v_pk_add_f32 v[124:125], v[122:123], 0 op_sel_hi:[1,0]
	v_pk_add_f32 v[126:127], v[120:121], 0 op_sel_hi:[1,0]
	s_cbranch_scc1 .LBB0_727
	v_max_f32_e32 v122, v144, v144
	v_max_f32_e32 v122, 0xc1a00000, v122
	v_mul_f32_e32 v122, 0xbfb8aa3b, v122
	v_max_f32_e32 v120, v146, v146
	v_max_f32_e32 v121, v147, v147
	v_exp_f32_e32 v123, v122
	v_max_f32_e32 v122, v145, v145
	v_max_f32_e32 v120, 0xc1a00000, v120
	v_max_f32_e32 v121, 0xc1a00000, v121
	v_max_f32_e32 v122, 0xc1a00000, v122
	v_mul_f32_e32 v120, 0xbfb8aa3b, v120
	v_mul_f32_e32 v121, 0xbfb8aa3b, v121
	v_mul_f32_e32 v122, 0xbfb8aa3b, v122
	v_exp_f32_e32 v120, v120
	v_exp_f32_e32 v121, v121
	v_exp_f32_e32 v122, v122
	v_max_f32_e32 v124, v124, v124
	v_max_f32_e32 v124, 0xc1a00000, v124
	v_pk_add_f32 v[120:121], v[120:121], 1.0 op_sel_hi:[1,0]
	v_pk_add_f32 v[122:123], v[122:123], 1.0 op_sel_hi:[1,0]
	v_mov_b32_e32 v144, v120
	v_mov_b32_e32 v145, v123
	v_pk_mov_b32 v[146:147], v[120:121], v[122:123] op_sel:[1,0]
	v_mul_f32_e32 v124, 0xbfb8aa3b, v124
	v_pk_mul_f32 v[144:145], v[144:145], v[146:147]
	v_max_f32_e32 v126, v126, v126
	v_max_f32_e32 v127, v127, v127
	v_exp_f32_e32 v147, v124
	v_max_f32_e32 v124, v125, v125
	v_max_f32_e32 v126, 0xc1a00000, v126
	v_max_f32_e32 v127, 0xc1a00000, v127
	v_max_f32_e32 v124, 0xc1a00000, v124
	v_mul_f32_e32 v146, v144, v145
	v_mul_f32_e32 v126, 0xbfb8aa3b, v126
	v_mul_f32_e32 v127, 0xbfb8aa3b, v127
	v_mul_f32_e32 v124, 0xbfb8aa3b, v124
	v_rcp_f32_e32 v155, v146
	v_exp_f32_e32 v126, v126
	v_exp_f32_e32 v127, v127
	v_exp_f32_e32 v146, v124
	v_mul_f32_e32 v124, v145, v155
	v_mul_f32_e32 v144, v144, v155
	v_pk_add_f32 v[126:127], v[126:127], 1.0 op_sel_hi:[1,0]
	v_pk_add_f32 v[156:157], v[146:147], 1.0 op_sel_hi:[1,0]
	v_mov_b32_e32 v146, v126
	v_mov_b32_e32 v147, v157
	v_pk_mov_b32 v[158:159], v[126:127], v[156:157] op_sel:[1,0]
	v_pk_mul_f32 v[144:145], v[122:123], v[144:145] op_sel_hi:[1,0]
	v_pk_mul_f32 v[158:159], v[146:147], v[158:159]
	s_nop 0
	v_mul_f32_e32 v125, v158, v159
	v_rcp_f32_e32 v125, v125
	s_nop 0
	v_pk_mul_f32 v[146:147], v[120:121], v[124:125] op_sel:[1,0] op_sel_hi:[0,0]
	v_mul_f32_e32 v120, v159, v125
	v_mul_f32_e32 v122, v158, v125
	v_pk_mul_f32 v[124:125], v[156:157], v[122:123] op_sel_hi:[1,0]
	v_pk_mul_f32 v[126:127], v[126:127], v[120:121] op_sel:[1,0] op_sel_hi:[0,0]

; #define PG8_STAGE(bufoff, gbase, voff) do { _Pragma("unroll") for (int _i = 0; _i < 2; ++_i) \
;         __builtin_amdgcn_global_load_lds((const unsigned*)((const char*)(gbase) + (voff)[_i]), (PG8_LAS unsigned*)(lds + (bufoff) + ldsw + _i * 8192), 16, 0, 0); } while (0)
; #define PG8_LDA(dst, b, h) do { _Pragma("unroll") for (int m = 0; m < 4; ++m) _Pragma("unroll") for (int k = 0; k < 2; ++k) dst[m][k] = *(const PG8_LAS bf16x8*)(lds + PG8_SA(b, h) + aoff + m * 2048 + k * 1024); } while (0)
; #define PG8_LDB(dst, b, h) do { _Pragma("unroll") for (int n = 0; n < 2; ++n) _Pragma("unroll") for (int k = 0; k < 2; ++k) dst[n][k] = *(const PG8_LAS bf16x8*)(lds + PG8_SB(b, h) + boff + n * 2048 + k * 1024); } while (0)
; #define PG8_MMA(ai, bj, At, Bt) do { __builtin_amdgcn_s_setprio(1); _Pragma("unroll") for (int m = 0; m < 4; ++m) _Pragma("unroll") for (int n = 0; n < 2; ++n) _Pragma("unroll") for (int k = 0; k < 2; ++k) \
;         acc[ai][bj][m][n] = __builtin_amdgcn_mfma_f32_16x16x32_bf16(Bt[n][k], At[m][k], acc[ai][bj][m][n], 0, 0, 0); __builtin_amdgcn_s_setprio(0); } while (0)
; #define PG8_WAIT_L(n) asm volatile("s_waitcnt lgkmcnt(" #n ")" ::: "memory")
; #define PG8_BAR __builtin_amdgcn_s_barrier()
; #define PG8_SCHED __builtin_amdgcn_sched_barrier(0)
; template <class Epi, class Sched>
; __device__ __forceinline__ void gemm_phase(PG8_LAS unsigned char* lds, const Gemm g, const Sched& S, const Epi& E) {
;     ...
;             const bool last = (t == nt - 2);
;             const char* a1 = cA + (size_t)(t + 1) * kstep;
;             const char* a2 = last ? nA : cA + (size_t)(t + 2) * kstep; const char* b2 = last ? nB : cB + (size_t)(t + 2) * kstep;
;             const char* a3 = a2 + kstep; const char* b3 = b2 + kstep;
;             if (last && has_next) S.a_ready(nxt);
;             PG8_LDB(B0, 0, 0); PG8_SCHED; PG8_LDA(At, 0, 0); PG8_STAGE(PG8_SA(1, 1), a1 + hstep, voffA);
;             PG8_WAIT_L(8); PG8_BAR; PG8_WAIT_L(0); PG8_MMA(0, 0, At, B0); PG8_BAR; PG8_SCHED;
;             PG8_LDB(B1, 0, 1); PG8_STAGE(PG8_SB(0, 0), b2, voffB);
;             PG8_BAR; PG8_WAIT_L(0); PG8_MMA(0, 1, At, B1); PG8_BAR;
;             PG8_LDA(At, 0, 1); PG8_STAGE(PG8_SA(0, 0), a2, voffA);
;             PG8_BAR; PG8_WAIT_L(0); PG8_MMA(1, 0, At, B0); PG8_BAR; PG8_SCHED;
.LBB0_991:
	ds_read_b128 v[144:147], v153
	ds_read_b128 v[156:159], v153 offset:1024
	ds_read_b128 v[160:163], v153 offset:2048
	ds_read_b128 v[164:167], v153 offset:3072
	s_add_u32 s20, s18, 0xfffc0080
	s_addc_u32 s21, s19, -1
	s_cmp_eq_u32 s47, 12
	s_cselect_b32 s23, s11, s21
	s_cselect_b32 s22, s43, s20
	s_cselect_b32 s21, s9, s46
	s_cselect_b32 s20, s44, s45
	v_lshl_add_u64 v[148:149], s[18:19], 0, v[136:137]
	s_add_i32 m0, s17, 0xc000
	ds_read_b128 v[168:171], v154
	ds_read_b128 v[172:175], v154 offset:1024
	ds_read_b128 v[182:185], v154 offset:2048
	ds_read_b128 v[190:193], v154 offset:3072
	ds_read_b128 v[194:197], v154 offset:4096
	ds_read_b128 v[198:201], v154 offset:5120
	ds_read_b128 v[202:205], v154 offset:6144
	ds_read_b128 v[206:209], v154 offset:7168
	global_load_lds_dwordx4 v[148:149], off
	v_lshl_add_u64 v[148:149], s[18:19], 0, v[138:139]
	s_add_i32 m0, s17, 0xe000
	s_nop 0
	global_load_lds_dwordx4 v[148:149], off
	s_waitcnt lgkmcnt(8)
	s_barrier
	s_waitcnt lgkmcnt(0)
	s_waitcnt lgkmcnt(0)
	v_mfma_f32_16x16x32_bf16 v[124:127], v[144:147], v[168:171], v[124:127]
	v_mfma_f32_16x16x32_bf16 v[120:123], v[160:163], v[168:171], v[120:123]
	v_mfma_f32_16x16x32_bf16 v[112:115], v[144:147], v[182:185], v[112:115]
	v_mfma_f32_16x16x32_bf16 v[104:107], v[160:163], v[182:185], v[104:107]
	v_mfma_f32_16x16x32_bf16 v[96:99], v[144:147], v[194:197], v[96:99]
	v_mfma_f32_16x16x32_bf16 v[88:91], v[160:163], v[194:197], v[88:91]
	v_mfma_f32_16x16x32_bf16 v[80:83], v[144:147], v[202:205], v[80:83]
	v_mfma_f32_16x16x32_bf16 v[72:75], v[160:163], v[202:205], v[72:75]
	v_mfma_f32_16x16x32_bf16 v[124:127], v[156:159], v[172:175], v[124:127]
	v_mfma_f32_16x16x32_bf16 v[120:123], v[164:167], v[172:175], v[120:123]
	v_mfma_f32_16x16x32_bf16 v[112:115], v[156:159], v[190:193], v[112:115]
	v_mfma_f32_16x16x32_bf16 v[104:107], v[164:167], v[190:193], v[104:107]
	v_mfma_f32_16x16x32_bf16 v[96:99], v[156:159], v[198:201], v[96:99]
	v_mfma_f32_16x16x32_bf16 v[88:91], v[164:167], v[198:201], v[88:91]
	v_mfma_f32_16x16x32_bf16 v[80:83], v[156:159], v[206:209], v[80:83]
	v_mfma_f32_16x16x32_bf16 v[72:75], v[164:167], v[206:209], v[72:75]
	s_barrier
	s_add_i32 s48, s39, s29
	v_lshl_add_u64 v[148:149], s[20:21], 0, v[130:131]
	s_mov_b32 m0, s48
	ds_read_b128 v[210:213], v155
	ds_read_b128 v[214:217], v155 offset:1024
	ds_read_b128 v[218:221], v155 offset:2048
	ds_read_b128 v[222:225], v155 offset:3072
	global_load_lds_dwordx4 v[148:149], off
	v_lshl_add_u64 v[186:187], s[20:21], 0, v[134:135]
	s_add_i32 m0, s48, 0x2000
	s_nop 0
	global_load_lds_dwordx4 v[186:187], off
	s_barrier
	s_waitcnt lgkmcnt(0)
	s_waitcnt lgkmcnt(0)
	v_mfma_f32_16x16x32_bf16 v[116:119], v[210:213], v[168:171], v[116:119]
	v_mfma_f32_16x16x32_bf16 v[108:111], v[218:221], v[168:171], v[108:111]
	v_mfma_f32_16x16x32_bf16 v[100:103], v[210:213], v[182:185], v[100:103]
	v_mfma_f32_16x16x32_bf16 v[92:95], v[218:221], v[182:185], v[92:95]
	v_mfma_f32_16x16x32_bf16 v[84:87], v[210:213], v[194:197], v[84:87]
	v_mfma_f32_16x16x32_bf16 v[76:79], v[218:221], v[194:197], v[76:79]
	v_mfma_f32_16x16x32_bf16 v[68:71], v[210:213], v[202:205], v[68:71]
	v_mfma_f32_16x16x32_bf16 v[64:67], v[218:221], v[202:205], v[64:67]
	v_mfma_f32_16x16x32_bf16 v[116:119], v[214:217], v[172:175], v[116:119]
	v_mfma_f32_16x16x32_bf16 v[108:111], v[222:225], v[172:175], v[108:111]
	v_mfma_f32_16x16x32_bf16 v[100:103], v[214:217], v[190:193], v[100:103]
	v_mfma_f32_16x16x32_bf16 v[92:95], v[222:225], v[190:193], v[92:95]
	v_mfma_f32_16x16x32_bf16 v[84:87], v[214:217], v[198:201], v[84:87]
	v_mfma_f32_16x16x32_bf16 v[76:79], v[222:225], v[198:201], v[76:79]
	v_mfma_f32_16x16x32_bf16 v[68:71], v[214:217], v[206:209], v[68:71]
	v_mfma_f32_16x16x32_bf16 v[64:67], v[222:225], v[206:209], v[64:67]
	s_barrier
	s_mov_b32 m0, s17
	v_lshl_add_u64 v[226:227], s[22:23], 0, v[128:129]
	ds_read_b128 v[168:171], v154 offset:16384
	ds_read_b128 v[172:175], v154 offset:17408
	ds_read_b128 v[182:185], v154 offset:18432
	ds_read_b128 v[190:193], v154 offset:19456
	ds_read_b128 v[194:197], v154 offset:20480
	ds_read_b128 v[198:201], v154 offset:21504
	ds_read_b128 v[202:205], v154 offset:22528
	ds_read_b128 v[206:209], v154 offset:23552
	global_load_lds_dwordx4 v[226:227], off
	v_lshl_add_u64 v[228:229], s[22:23], 0, v[132:133]
	s_mov_b32 m0, s30
	s_nop 0
	global_load_lds_dwordx4 v[228:229], off
	s_barrier
	s_waitcnt lgkmcnt(0)
	s_waitcnt lgkmcnt(0)
	v_mfma_f32_16x16x32_bf16 v[60:63], v[144:147], v[168:171], v[60:63]
	v_mfma_f32_16x16x32_bf16 v[56:59], v[160:163], v[168:171], v[56:59]
	v_mfma_f32_16x16x32_bf16 v[48:51], v[144:147], v[182:185], v[48:51]
	v_mfma_f32_16x16x32_bf16 v[40:43], v[160:163], v[182:185], v[40:43]
	v_mfma_f32_16x16x32_bf16 v[32:35], v[144:147], v[194:197], v[32:35]
	v_mfma_f32_16x16x32_bf16 v[24:27], v[160:163], v[194:197], v[24:27]
	v_mfma_f32_16x16x32_bf16 v[16:19], v[144:147], v[202:205], v[16:19]
	v_mfma_f32_16x16x32_bf16 v[8:11], v[160:163], v[202:205], v[8:11]
	v_mfma_f32_16x16x32_bf16 v[60:63], v[156:159], v[172:175], v[60:63]
	v_mfma_f32_16x16x32_bf16 v[56:59], v[164:167], v[172:175], v[56:59]
	v_mfma_f32_16x16x32_bf16 v[48:51], v[156:159], v[190:193], v[48:51]
	v_mfma_f32_16x16x32_bf16 v[40:43], v[164:167], v[190:193], v[40:43]
	v_mfma_f32_16x16x32_bf16 v[32:35], v[156:159], v[198:201], v[32:35]
	v_mfma_f32_16x16x32_bf16 v[24:27], v[164:167], v[198:201], v[24:27]
	v_mfma_f32_16x16x32_bf16 v[16:19], v[156:159], v[206:209], v[16:19]
	v_mfma_f32_16x16x32_bf16 v[8:11], v[164:167], v[206:209], v[8:11]
	s_barrier
; #define PG8_STAGE(bufoff, gbase, voff) do { _Pragma("unroll") for (int _i = 0; _i < 2; ++_i) \
;         __builtin_amdgcn_global_load_lds((const unsigned*)((const char*)(gbase) + (voff)[_i]), (PG8_LAS unsigned*)(lds + (bufoff) + ldsw + _i * 8192), 16, 0, 0); } while (0)
; #define PG8_LDA(dst, b, h) do { _Pragma("unroll") for (int m = 0; m < 4; ++m) _Pragma("unroll") for (int k = 0; k < 2; ++k) dst[m][k] = *(const PG8_LAS bf16x8*)(lds + PG8_SA(b, h) + aoff + m * 2048 + k * 1024); } while (0)
; #define PG8_LDB(dst, b, h) do { _Pragma("unroll") for (int n = 0; n < 2; ++n) _Pragma("unroll") for (int k = 0; k < 2; ++k) dst[n][k] = *(const PG8_LAS bf16x8*)(lds + PG8_SB(b, h) + boff + n * 2048 + k * 1024); } while (0)
; #define PG8_MMA(ai, bj, At, Bt) do { __builtin_amdgcn_s_setprio(1); _Pragma("unroll") for (int m = 0; m < 4; ++m) _Pragma("unroll") for (int n = 0; n < 2; ++n) _Pragma("unroll") for (int k = 0; k < 2; ++k) \
;         acc[ai][bj][m][n] = __builtin_amdgcn_mfma_f32_16x16x32_bf16(Bt[n][k], At[m][k], acc[ai][bj][m][n], 0, 0, 0); __builtin_amdgcn_s_setprio(0); } while (0)
; #define PG8_WAIT_V(n) asm volatile("s_waitcnt vmcnt(" #n ")" ::: "memory")
; #define PG8_WAIT_L(n) asm volatile("s_waitcnt lgkmcnt(" #n ")" ::: "memory")
; #define PG8_BAR __builtin_amdgcn_s_barrier()
; #define PG8_SCHED __builtin_amdgcn_sched_barrier(0)
; template <class Epi, class Sched>
; __device__ __forceinline__ void gemm_phase(PG8_LAS unsigned char* lds, const Gemm g, const Sched& S, const Epi& E) {
;     ...
;             PG8_STAGE(PG8_SB(0, 1), b2 + hstep, voffB);
;             PG8_WAIT_V(6); PG8_BAR; PG8_MMA(1, 1, At, B1); PG8_BAR;
;             PG8_LDB(B0, 1, 0); PG8_SCHED; PG8_LDA(At, 1, 0); PG8_STAGE(PG8_SA(0, 1), a2 + hstep, voffA);
;             PG8_WAIT_L(8); PG8_BAR; PG8_WAIT_L(0); PG8_MMA(0, 0, At, B0); PG8_BAR; PG8_SCHED;
;             PG8_LDB(B1, 1, 1); PG8_STAGE(PG8_SB(1, 0), b3, voffB);
;             PG8_BAR; PG8_WAIT_L(0); PG8_MMA(0, 1, At, B1); PG8_BAR;
;             PG8_LDA(At, 1, 1); PG8_STAGE(PG8_SA(1, 0), a3, voffA);
	s_add_u32 s48, s20, 0x40000
	s_addc_u32 s49, s21, 0
	s_add_i32 s50, s40, s29
	v_lshl_add_u64 v[144:145], s[48:49], 0, v[130:131]
	s_mov_b32 m0, s50
	s_nop 0
	global_load_lds_dwordx4 v[144:145], off
	v_lshl_add_u64 v[144:145], s[48:49], 0, v[134:135]
	s_add_i32 m0, s50, 0x2000
	s_nop 0
	global_load_lds_dwordx4 v[144:145], off
	s_waitcnt vmcnt(6)
	s_barrier
	v_mfma_f32_16x16x32_bf16 v[52:55], v[210:213], v[168:171], v[52:55]
	v_mfma_f32_16x16x32_bf16 v[44:47], v[218:221], v[168:171], v[44:47]
	v_mfma_f32_16x16x32_bf16 v[36:39], v[210:213], v[182:185], v[36:39]
	v_mfma_f32_16x16x32_bf16 v[28:31], v[218:221], v[182:185], v[28:31]
	v_mfma_f32_16x16x32_bf16 v[20:23], v[210:213], v[194:197], v[20:23]
	v_mfma_f32_16x16x32_bf16 v[12:15], v[218:221], v[194:197], v[12:15]
	v_mfma_f32_16x16x32_bf16 v[4:7], v[210:213], v[202:205], v[4:7]
	v_mfma_f32_16x16x32_bf16 v[0:3], v[218:221], v[202:205], v[0:3]
	v_mfma_f32_16x16x32_bf16 v[52:55], v[214:217], v[172:175], v[52:55]
	v_mfma_f32_16x16x32_bf16 v[44:47], v[222:225], v[172:175], v[44:47]
	v_mfma_f32_16x16x32_bf16 v[36:39], v[214:217], v[190:193], v[36:39]
	v_mfma_f32_16x16x32_bf16 v[28:31], v[222:225], v[190:193], v[28:31]
	v_mfma_f32_16x16x32_bf16 v[20:23], v[214:217], v[198:201], v[20:23]
	v_mfma_f32_16x16x32_bf16 v[12:15], v[222:225], v[198:201], v[12:15]
	v_mfma_f32_16x16x32_bf16 v[4:7], v[214:217], v[206:209], v[4:7]
	v_mfma_f32_16x16x32_bf16 v[0:3], v[222:225], v[206:209], v[0:3]
	s_barrier
	s_add_i32 s48, 0, 0x18000
	v_add_u32_e32 v164, s48, v151
	ds_read_b128 v[144:147], v164
	ds_read_b128 v[156:159], v164 offset:1024
	ds_read_b128 v[160:163], v164 offset:2048
	ds_read_b128 v[164:167], v164 offset:3072
	s_add_u32 s22, s22, 0x40000
	s_addc_u32 s23, s23, 0
	s_mov_b32 m0, s31
	v_lshl_add_u64 v[210:211], s[22:23], 0, v[128:129]
	ds_read_b128 v[168:171], v154 offset:32768
	ds_read_b128 v[172:175], v154 offset:33792
	ds_read_b128 v[182:185], v154 offset:34816
	ds_read_b128 v[190:193], v154 offset:35840
	ds_read_b128 v[194:197], v154 offset:36864
	ds_read_b128 v[198:201], v154 offset:37888
	ds_read_b128 v[202:205], v154 offset:38912
	ds_read_b128 v[206:209], v154 offset:39936
	global_load_lds_dwordx4 v[210:211], off
	v_lshl_add_u64 v[210:211], s[22:23], 0, v[132:133]
	s_mov_b32 m0, s34
	s_nop 0
	global_load_lds_dwordx4 v[210:211], off
	s_waitcnt lgkmcnt(8)
	s_barrier
	s_waitcnt lgkmcnt(0)
	s_waitcnt lgkmcnt(0)
	v_mfma_f32_16x16x32_bf16 v[124:127], v[144:147], v[168:171], v[124:127]
	v_mfma_f32_16x16x32_bf16 v[120:123], v[160:163], v[168:171], v[120:123]
	v_mfma_f32_16x16x32_bf16 v[112:115], v[144:147], v[182:185], v[112:115]
	v_mfma_f32_16x16x32_bf16 v[104:107], v[160:163], v[182:185], v[104:107]
	v_mfma_f32_16x16x32_bf16 v[96:99], v[144:147], v[194:197], v[96:99]
	v_mfma_f32_16x16x32_bf16 v[88:91], v[160:163], v[194:197], v[88:91]
	v_mfma_f32_16x16x32_bf16 v[80:83], v[144:147], v[202:205], v[80:83]
	v_mfma_f32_16x16x32_bf16 v[72:75], v[160:163], v[202:205], v[72:75]
	v_mfma_f32_16x16x32_bf16 v[124:127], v[156:159], v[172:175], v[124:127]
	v_mfma_f32_16x16x32_bf16 v[120:123], v[164:167], v[172:175], v[120:123]
	v_mfma_f32_16x16x32_bf16 v[112:115], v[156:159], v[190:193], v[112:115]
	v_mfma_f32_16x16x32_bf16 v[104:107], v[164:167], v[190:193], v[104:107]
	v_mfma_f32_16x16x32_bf16 v[96:99], v[156:159], v[198:201], v[96:99]
	v_mfma_f32_16x16x32_bf16 v[88:91], v[164:167], v[198:201], v[88:91]
	v_mfma_f32_16x16x32_bf16 v[80:83], v[156:159], v[206:209], v[80:83]
	v_mfma_f32_16x16x32_bf16 v[72:75], v[164:167], v[206:209], v[72:75]
	s_barrier
	s_add_i32 s22, 0, 0x1c000
	s_add_i32 s23, s48, s29
	v_add_u32_e32 v179, s22, v151
	v_lshl_add_u64 v[148:149], v[148:149], 0, s[6:7]
	s_mov_b32 m0, s23
	ds_read_b128 v[210:213], v179
	ds_read_b128 v[214:217], v179 offset:1024
	ds_read_b128 v[218:221], v179 offset:2048
	ds_read_b128 v[222:225], v179 offset:3072
	global_load_lds_dwordx4 v[148:149], off
	v_lshl_add_u64 v[148:149], v[186:187], 0, s[6:7]
	s_add_i32 m0, s23, 0x2000
	s_nop 0
	global_load_lds_dwordx4 v[148:149], off
	s_barrier
	s_waitcnt lgkmcnt(0)
	s_waitcnt lgkmcnt(0)
	v_mfma_f32_16x16x32_bf16 v[116:119], v[210:213], v[168:171], v[116:119]
	v_mfma_f32_16x16x32_bf16 v[108:111], v[218:221], v[168:171], v[108:111]
	v_mfma_f32_16x16x32_bf16 v[100:103], v[210:213], v[182:185], v[100:103]
	v_mfma_f32_16x16x32_bf16 v[92:95], v[218:221], v[182:185], v[92:95]
	v_mfma_f32_16x16x32_bf16 v[84:87], v[210:213], v[194:197], v[84:87]
	v_mfma_f32_16x16x32_bf16 v[76:79], v[218:221], v[194:197], v[76:79]
	v_mfma_f32_16x16x32_bf16 v[68:71], v[210:213], v[202:205], v[68:71]
	v_mfma_f32_16x16x32_bf16 v[64:67], v[218:221], v[202:205], v[64:67]
	v_mfma_f32_16x16x32_bf16 v[116:119], v[214:217], v[172:175], v[116:119]
	v_mfma_f32_16x16x32_bf16 v[108:111], v[222:225], v[172:175], v[108:111]
	v_mfma_f32_16x16x32_bf16 v[100:103], v[214:217], v[190:193], v[100:103]
	v_mfma_f32_16x16x32_bf16 v[92:95], v[222:225], v[190:193], v[92:95]
	v_mfma_f32_16x16x32_bf16 v[84:87], v[214:217], v[198:201], v[84:87]
	v_mfma_f32_16x16x32_bf16 v[76:79], v[222:225], v[198:201], v[76:79]
	v_mfma_f32_16x16x32_bf16 v[68:71], v[214:217], v[206:209], v[68:71]
	v_mfma_f32_16x16x32_bf16 v[64:67], v[222:225], v[206:209], v[64:67]
	s_barrier
	s_mov_b32 m0, s36
	v_lshl_add_u64 v[148:149], v[226:227], 0, s[6:7]
	ds_read_b128 v[168:171], v154 offset:49152
	ds_read_b128 v[172:175], v154 offset:50176
	ds_read_b128 v[182:185], v154 offset:51200
	ds_read_b128 v[190:193], v154 offset:52224
	ds_read_b128 v[194:197], v154 offset:53248
	ds_read_b128 v[198:201], v154 offset:54272
	ds_read_b128 v[202:205], v154 offset:55296
	ds_read_b128 v[206:209], v154 offset:56320
	global_load_lds_dwordx4 v[148:149], off
	v_lshl_add_u64 v[148:149], v[228:229], 0, s[6:7]
	s_mov_b32 m0, s37
	s_nop 0
	global_load_lds_dwordx4 v[148:149], off
	s_barrier
; __device__ __forceinline__ unsigned cvt_pk_bf16(float lo, float hi) { unsigned r; asm volatile("v_cvt_pk_bf16_f32 %0, %1, %2" : "=v"(r) : "v"(lo), "v"(hi)); return r; }
; __device__ __forceinline__ float bf_lo(unsigned u) { return __uint_as_float(u << 16); }
; __device__ __forceinline__ float bf_hi(unsigned u) { return __uint_as_float(u & 0xffff0000u); }
; #define PG8_STAGE(bufoff, gbase, voff) do { _Pragma("unroll") for (int _i = 0; _i < 2; ++_i) \
;         __builtin_amdgcn_global_load_lds((const unsigned*)((const char*)(gbase) + (voff)[_i]), (PG8_LAS unsigned*)(lds + (bufoff) + ldsw + _i * 8192), 16, 0, 0); } while (0)
; #define PG8_WAIT_V(n) asm volatile("s_waitcnt vmcnt(" #n ")" ::: "memory")
; #define PG8_BAR __builtin_amdgcn_s_barrier()
;     __device__ __forceinline__ void operator()(const f32x4 (&acc)[2][2][4][2], const Unit& u, int wr, int wc, int fr, int fq) const {
;     ...
;             for (int m = 0; m < 4; ++m) { const size_t r = (size_t)(row0 + ai * HALF + m * 16); bf16_t* rowp = O + r * ldc + col0; const bf16_t* gp = G + r * ldg + col0;
; #pragma unroll
;                 for (int bj = 0; bj < 2; ++bj) { const u32x4 gw = *(const u32x4*)(gp + bj * HALF);
;                     f32x4 v0 = acc[ai][bj][m][0], v1 = acc[ai][bj][m][1];
;                     v0[0] *= bf_lo(gw.x); v0[1] *= bf_hi(gw.x); v0[2] *= bf_lo(gw.y); v0[3] *= bf_hi(gw.y);
;                     v1[0] *= bf_lo(gw.z); v1[1] *= bf_hi(gw.z); v1[2] *= bf_lo(gw.w); v1[3] *= bf_hi(gw.w);
;                     if (ACCUM) { const u32x4 pw = *(const u32x4*)(rowp + bj * HALF);
;                         v0[0] += bf_lo(pw.x); v0[1] += bf_hi(pw.x); v0[2] += bf_lo(pw.y); v0[3] += bf_hi(pw.y);
;                         v1[0] += bf_lo(pw.z); v1[1] += bf_hi(pw.z); v1[2] += bf_lo(pw.w); v1[3] += bf_hi(pw.w); }
;                     u32x4 w; w.x = cvt_pk_bf16(v0[0], v0[1]); w.y = cvt_pk_bf16(v0[2], v0[3]); w.z = cvt_pk_bf16(v1[0], v1[1]); w.w = cvt_pk_bf16(v1[2], v1[3]);
;                     *(u32x4*)(rowp + bj * HALF) = w; } }
; template <class Epi, class Sched>
; __device__ __forceinline__ void gemm_phase(PG8_LAS unsigned char* lds, const Gemm g, const Sched& S, const Epi& E) {
;     ...
;             PG8_BAR; PG8_WAIT_L(0); PG8_MMA(1, 0, At, B0); PG8_BAR; PG8_SCHED;
;             PG8_STAGE(PG8_SB(1, 1), b3 + hstep, voffB);
;             PG8_WAIT_V(6); PG8_BAR; PG8_MMA(1, 1, At, B1); PG8_BAR;
	s_waitcnt lgkmcnt(0)
	s_waitcnt lgkmcnt(0)
	v_mfma_f32_16x16x32_bf16 v[60:63], v[144:147], v[168:171], v[60:63]
	v_mfma_f32_16x16x32_bf16 v[56:59], v[160:163], v[168:171], v[56:59]
	v_mfma_f32_16x16x32_bf16 v[48:51], v[144:147], v[182:185], v[48:51]
	v_mfma_f32_16x16x32_bf16 v[40:43], v[160:163], v[182:185], v[40:43]
	v_mfma_f32_16x16x32_bf16 v[32:35], v[144:147], v[194:197], v[32:35]
	v_mfma_f32_16x16x32_bf16 v[24:27], v[160:163], v[194:197], v[24:27]
	v_mfma_f32_16x16x32_bf16 v[16:19], v[144:147], v[202:205], v[16:19]
	v_mfma_f32_16x16x32_bf16 v[8:11], v[160:163], v[202:205], v[8:11]
	v_mfma_f32_16x16x32_bf16 v[60:63], v[156:159], v[172:175], v[60:63]
	v_mfma_f32_16x16x32_bf16 v[56:59], v[164:167], v[172:175], v[56:59]
	v_mfma_f32_16x16x32_bf16 v[48:51], v[156:159], v[190:193], v[48:51]
	v_mfma_f32_16x16x32_bf16 v[40:43], v[164:167], v[190:193], v[40:43]
	v_mfma_f32_16x16x32_bf16 v[32:35], v[156:159], v[198:201], v[32:35]
	v_mfma_f32_16x16x32_bf16 v[24:27], v[164:167], v[198:201], v[24:27]
	v_mfma_f32_16x16x32_bf16 v[16:19], v[156:159], v[206:209], v[16:19]
	v_mfma_f32_16x16x32_bf16 v[8:11], v[164:167], v[206:209], v[8:11]
	s_barrier
	s_add_u32 s20, s20, 0x40080
	s_addc_u32 s21, s21, 0
	s_add_i32 s22, s22, s29
	v_lshl_add_u64 v[144:145], s[20:21], 0, v[130:131]
	s_mov_b32 m0, s22
	s_nop 0
	global_load_lds_dwordx4 v[144:145], off
	v_lshl_add_u64 v[144:145], s[20:21], 0, v[134:135]
	s_add_i32 m0, s22, 0x2000
	s_nop 0
	global_load_lds_dwordx4 v[144:145], off
	s_waitcnt vmcnt(6)
	s_barrier
	v_mfma_f32_16x16x32_bf16 v[52:55], v[210:213], v[168:171], v[52:55]
	v_mfma_f32_16x16x32_bf16 v[44:47], v[218:221], v[168:171], v[44:47]
	v_mfma_f32_16x16x32_bf16 v[36:39], v[210:213], v[182:185], v[36:39]
	v_mfma_f32_16x16x32_bf16 v[28:31], v[218:221], v[182:185], v[28:31]
	v_mfma_f32_16x16x32_bf16 v[20:23], v[210:213], v[194:197], v[20:23]
	v_mfma_f32_16x16x32_bf16 v[12:15], v[218:221], v[194:197], v[12:15]
	v_mfma_f32_16x16x32_bf16 v[4:7], v[210:213], v[202:205], v[4:7]
	v_mfma_f32_16x16x32_bf16 v[0:3], v[218:221], v[202:205], v[0:3]
	v_mfma_f32_16x16x32_bf16 v[52:55], v[214:217], v[172:175], v[52:55]
	v_mfma_f32_16x16x32_bf16 v[44:47], v[222:225], v[172:175], v[44:47]
	v_mfma_f32_16x16x32_bf16 v[36:39], v[214:217], v[190:193], v[36:39]
	v_mfma_f32_16x16x32_bf16 v[28:31], v[222:225], v[190:193], v[28:31]
	v_mfma_f32_16x16x32_bf16 v[20:23], v[214:217], v[198:201], v[20:23]
	v_mfma_f32_16x16x32_bf16 v[12:15], v[222:225], v[198:201], v[12:15]
	v_mfma_f32_16x16x32_bf16 v[4:7], v[214:217], v[206:209], v[4:7]
	v_mfma_f32_16x16x32_bf16 v[0:3], v[222:225], v[206:209], v[0:3]
	s_barrier
	s_add_i32 s47, s47, 2
	s_add_u32 s18, s18, 0x100
	s_addc_u32 s19, s19, 0
	s_add_u32 s45, s45, 0x100
	s_addc_u32 s46, s46, 0
	s_cmp_gt_u32 s47, 13
	s_cbranch_scc0 .LBB0_991
	v_lshl_or_b32 v144, s42, 8, v152
	v_lshl_add_u32 v146, s16, 8, v150
	v_ashrrev_i32_e32 v145, 31, v144
	v_mov_b64_e32 v[148:149], s[4:5]
	v_lshlrev_b64 v[144:145], 1, v[144:145]
	v_mad_i64_i32 v[156:157], s[18:19], v146, s41, v[148:149]
	v_lshl_add_u64 v[160:161], v[156:157], 0, v[144:145]
	global_load_dwordx4 v[156:159], v[160:161], off offset:3072
	s_and_b64 vcc, exec, s[2:3]
	s_mov_b32 s42, s8
	s_mov_b32 s16, s10
	s_mov_b64 s[20:21], s[14:15]
	s_waitcnt vmcnt(0)
	v_lshlrev_b32_e32 v147, 16, v156
	v_and_b32_e32 v156, 0xffff0000, v156
	v_lshlrev_b32_e32 v162, 16, v157
	v_and_b32_e32 v157, 0xffff0000, v157
	v_lshlrev_b32_e32 v164, 16, v159
	v_and_b32_e32 v159, 0xffff0000, v159
	v_lshlrev_b32_e32 v163, 16, v158
	v_and_b32_e32 v158, 0xffff0000, v158
	v_mul_f32_e32 v124, v124, v147
	v_mul_f32_e32 v125, v125, v156
	v_mul_f32_e32 v126, v126, v162
	v_mul_f32_e32 v127, v127, v157
	v_mul_f32_e32 v123, v123, v159
	v_mul_f32_e32 v147, v120, v163
	v_mul_f32_e32 v156, v121, v158
	v_mul_f32_e32 v157, v122, v164
	v_cvt_pk_bf16_f32 v120, v124, v125
	v_cvt_pk_bf16_f32 v121, v126, v127
	v_cvt_pk_bf16_f32 v122, v147, v156
	v_cvt_pk_bf16_f32 v123, v157, v123
	global_load_dwordx4 v[124:127], v[160:161], off offset:3328
	v_ashrrev_i32_e32 v147, 31, v146
	v_lshlrev_b64 v[158:159], 11, v[146:147]
	v_lshl_add_u64 v[158:159], s[0:1], 0, v[158:159]
	v_or_b32_e32 v156, 16, v146
	v_lshl_add_u64 v[158:159], v[158:159], 0, v[144:145]
	v_mad_i64_i32 v[160:161], s[18:19], v156, s41, v[148:149]
	global_store_dwordx4 v[158:159], v[120:123], off
	v_lshl_add_u64 v[160:161], v[160:161], 0, v[144:145]
	v_ashrrev_i32_e32 v157, 31, v156
	s_waitcnt vmcnt(0)
	v_lshlrev_b32_e32 v120, 16, v124
	v_and_b32_e32 v121, 0xffff0000, v124
	v_lshlrev_b32_e32 v122, 16, v125
	v_and_b32_e32 v123, 0xffff0000, v125
	v_lshlrev_b32_e32 v124, 16, v126
	v_and_b32_e32 v125, 0xffff0000, v126
	v_lshlrev_b32_e32 v126, 16, v127
	v_and_b32_e32 v127, 0xffff0000, v127
	v_mul_f32_e32 v116, v116, v120
	v_mul_f32_e32 v117, v117, v121
	v_mul_f32_e32 v118, v118, v122
	v_mul_f32_e32 v119, v119, v123
	v_mul_f32_e32 v111, v111, v127
	v_mul_f32_e32 v120, v108, v124
	v_mul_f32_e32 v121, v109, v125
	v_mul_f32_e32 v122, v110, v126
	v_cvt_pk_bf16_f32 v108, v116, v117
	v_cvt_pk_bf16_f32 v109, v118, v119
	v_cvt_pk_bf16_f32 v110, v120, v121
	v_cvt_pk_bf16_f32 v111, v122, v111
	global_load_dwordx4 v[116:119], v[160:161], off offset:3072
	s_nop 0
	global_store_dwordx4 v[158:159], v[108:111], off offset:256
	s_waitcnt vmcnt(0)
; __device__ __forceinline__ unsigned cvt_pk_bf16(float lo, float hi) { unsigned r; asm volatile("v_cvt_pk_bf16_f32 %0, %1, %2" : "=v"(r) : "v"(lo), "v"(hi)); return r; }
; __device__ __forceinline__ float bf_lo(unsigned u) { return __uint_as_float(u << 16); }
; __device__ __forceinline__ float bf_hi(unsigned u) { return __uint_as_float(u & 0xffff0000u); }
;     __device__ __forceinline__ void operator()(const f32x4 (&acc)[2][2][4][2], const Unit& u, int wr, int wc, int fr, int fq) const {
;     ...
;             for (int m = 0; m < 4; ++m) { const size_t r = (size_t)(row0 + ai * HALF + m * 16); bf16_t* rowp = O + r * ldc + col0; const bf16_t* gp = G + r * ldg + col0;
; #pragma unroll
;                 for (int bj = 0; bj < 2; ++bj) { const u32x4 gw = *(const u32x4*)(gp + bj * HALF);
;                     f32x4 v0 = acc[ai][bj][m][0], v1 = acc[ai][bj][m][1];
;                     v0[0] *= bf_lo(gw.x); v0[1] *= bf_hi(gw.x); v0[2] *= bf_lo(gw.y); v0[3] *= bf_hi(gw.y);
;                     v1[0] *= bf_lo(gw.z); v1[1] *= bf_hi(gw.z); v1[2] *= bf_lo(gw.w); v1[3] *= bf_hi(gw.w);
;                     if (ACCUM) { const u32x4 pw = *(const u32x4*)(rowp + bj * HALF);
;                         v0[0] += bf_lo(pw.x); v0[1] += bf_hi(pw.x); v0[2] += bf_lo(pw.y); v0[3] += bf_hi(pw.y);
;                         v1[0] += bf_lo(pw.z); v1[1] += bf_hi(pw.z); v1[2] += bf_lo(pw.w); v1[3] += bf_hi(pw.w); }
;                     u32x4 w; w.x = cvt_pk_bf16(v0[0], v0[1]); w.y = cvt_pk_bf16(v0[2], v0[3]); w.z = cvt_pk_bf16(v1[0], v1[1]); w.w = cvt_pk_bf16(v1[2], v1[3]);
;                     *(u32x4*)(rowp + bj * HALF) = w; } }
	s_nop 0
	v_lshlrev_b32_e32 v108, 16, v116
	v_and_b32_e32 v109, 0xffff0000, v116
	v_lshlrev_b32_e32 v110, 16, v117
	v_and_b32_e32 v111, 0xffff0000, v117
	v_lshlrev_b32_e32 v116, 16, v118
	v_and_b32_e32 v117, 0xffff0000, v118
	v_lshlrev_b32_e32 v118, 16, v119
	v_and_b32_e32 v119, 0xffff0000, v119
	v_mul_f32_e32 v108, v112, v108
	v_mul_f32_e32 v109, v113, v109
	v_mul_f32_e32 v110, v114, v110
	v_mul_f32_e32 v111, v115, v111
	v_mul_f32_e32 v107, v107, v119
	v_mul_f32_e32 v112, v104, v116
	v_mul_f32_e32 v113, v105, v117
	v_mul_f32_e32 v114, v106, v118
	v_cvt_pk_bf16_f32 v104, v108, v109
	v_cvt_pk_bf16_f32 v105, v110, v111
	v_cvt_pk_bf16_f32 v106, v112, v113
	v_cvt_pk_bf16_f32 v107, v114, v107
	global_load_dwordx4 v[108:111], v[160:161], off offset:3328
	v_lshlrev_b64 v[116:117], 11, v[156:157]
	v_lshl_add_u64 v[116:117], s[0:1], 0, v[116:117]
	v_or_b32_e32 v112, 32, v146
	v_lshl_add_u64 v[116:117], v[116:117], 0, v[144:145]
	v_mad_i64_i32 v[114:115], s[18:19], v112, s41, v[148:149]
	global_store_dwordx4 v[116:117], v[104:107], off
	v_lshl_add_u64 v[114:115], v[114:115], 0, v[144:145]
	v_ashrrev_i32_e32 v113, 31, v112
	s_waitcnt vmcnt(0)
	v_lshlrev_b32_e32 v104, 16, v108
	v_and_b32_e32 v105, 0xffff0000, v108
	v_lshlrev_b32_e32 v106, 16, v109
	v_and_b32_e32 v107, 0xffff0000, v109
	v_lshlrev_b32_e32 v108, 16, v110
	v_and_b32_e32 v109, 0xffff0000, v110
	v_lshlrev_b32_e32 v110, 16, v111
	v_and_b32_e32 v111, 0xffff0000, v111
	v_mul_f32_e32 v100, v100, v104
	v_mul_f32_e32 v101, v101, v105
	v_mul_f32_e32 v102, v102, v106
	v_mul_f32_e32 v103, v103, v107
	v_mul_f32_e32 v95, v95, v111
	v_mul_f32_e32 v104, v92, v108
	v_mul_f32_e32 v105, v93, v109
	v_mul_f32_e32 v106, v94, v110
	v_cvt_pk_bf16_f32 v92, v100, v101
	v_cvt_pk_bf16_f32 v93, v102, v103
	v_cvt_pk_bf16_f32 v94, v104, v105
	v_cvt_pk_bf16_f32 v95, v106, v95
	global_load_dwordx4 v[100:103], v[114:115], off offset:3072
	s_nop 0
	global_store_dwordx4 v[116:117], v[92:95], off offset:256
	s_waitcnt vmcnt(0)
	s_nop 0
	v_lshlrev_b32_e32 v92, 16, v100
	v_and_b32_e32 v93, 0xffff0000, v100
	v_lshlrev_b32_e32 v94, 16, v101
	v_and_b32_e32 v95, 0xffff0000, v101
	v_lshlrev_b32_e32 v100, 16, v102
	v_and_b32_e32 v101, 0xffff0000, v102
	v_lshlrev_b32_e32 v102, 16, v103
	v_and_b32_e32 v103, 0xffff0000, v103
	v_mul_f32_e32 v92, v96, v92
	v_mul_f32_e32 v93, v97, v93
	v_mul_f32_e32 v94, v98, v94
	v_mul_f32_e32 v95, v99, v95
	v_mul_f32_e32 v91, v91, v103
	v_mul_f32_e32 v96, v88, v100
	v_mul_f32_e32 v97, v89, v101
	v_mul_f32_e32 v98, v90, v102
	v_cvt_pk_bf16_f32 v88, v92, v93
	v_cvt_pk_bf16_f32 v89, v94, v95
	v_cvt_pk_bf16_f32 v90, v96, v97
	v_cvt_pk_bf16_f32 v91, v98, v91
	global_load_dwordx4 v[92:95], v[114:115], off offset:3328
	v_lshlrev_b64 v[100:101], 11, v[112:113]
	v_lshl_add_u64 v[100:101], s[0:1], 0, v[100:101]
	v_or_b32_e32 v96, 48, v146
	v_lshl_add_u64 v[100:101], v[100:101], 0, v[144:145]
	v_mad_i64_i32 v[98:99], s[18:19], v96, s41, v[148:149]
	global_store_dwordx4 v[100:101], v[88:91], off
	v_lshl_add_u64 v[98:99], v[98:99], 0, v[144:145]
	v_ashrrev_i32_e32 v97, 31, v96
	s_waitcnt vmcnt(0)
	v_lshlrev_b32_e32 v88, 16, v92
	v_and_b32_e32 v89, 0xffff0000, v92
	v_lshlrev_b32_e32 v90, 16, v93
	v_and_b32_e32 v91, 0xffff0000, v93
	v_lshlrev_b32_e32 v92, 16, v94
	v_and_b32_e32 v93, 0xffff0000, v94
	v_lshlrev_b32_e32 v94, 16, v95
	v_and_b32_e32 v95, 0xffff0000, v95
	v_mul_f32_e32 v84, v84, v88
	v_mul_f32_e32 v85, v85, v89
	v_mul_f32_e32 v86, v86, v90
	v_mul_f32_e32 v87, v87, v91
	v_mul_f32_e32 v79, v79, v95
	v_mul_f32_e32 v88, v76, v92
	v_mul_f32_e32 v89, v77, v93
	v_mul_f32_e32 v90, v78, v94
	v_cvt_pk_bf16_f32 v76, v84, v85
	v_cvt_pk_bf16_f32 v77, v86, v87
	v_cvt_pk_bf16_f32 v78, v88, v89
	v_cvt_pk_bf16_f32 v79, v90, v79
	global_load_dwordx4 v[84:87], v[98:99], off offset:3072
	s_nop 0
	global_store_dwordx4 v[100:101], v[76:79], off offset:256
	s_waitcnt vmcnt(0)
	s_nop 0
	v_lshlrev_b32_e32 v76, 16, v84
	v_and_b32_e32 v77, 0xffff0000, v84
	v_lshlrev_b32_e32 v78, 16, v85
	v_and_b32_e32 v79, 0xffff0000, v85
	v_lshlrev_b32_e32 v84, 16, v86
	v_and_b32_e32 v85, 0xffff0000, v86
	v_lshlrev_b32_e32 v86, 16, v87
	v_and_b32_e32 v87, 0xffff0000, v87
	v_mul_f32_e32 v76, v80, v76
	v_mul_f32_e32 v77, v81, v77
	v_mul_f32_e32 v78, v82, v78
	v_mul_f32_e32 v79, v83, v79
	v_mul_f32_e32 v75, v75, v87
	v_mul_f32_e32 v80, v72, v84
	v_mul_f32_e32 v81, v73, v85
	v_mul_f32_e32 v82, v74, v86
	v_cvt_pk_bf16_f32 v72, v76, v77
	v_cvt_pk_bf16_f32 v73, v78, v79
	v_cvt_pk_bf16_f32 v74, v80, v81
	v_cvt_pk_bf16_f32 v75, v82, v75
	global_load_dwordx4 v[76:79], v[98:99], off offset:3328
	v_lshlrev_b64 v[84:85], 11, v[96:97]
	v_lshl_add_u64 v[84:85], s[0:1], 0, v[84:85]
	v_add_u32_e32 v80, 0x80, v146
	v_lshl_add_u64 v[84:85], v[84:85], 0, v[144:145]
	v_mad_i64_i32 v[82:83], s[18:19], v80, s41, v[148:149]
	global_store_dwordx4 v[84:85], v[72:75], off
	v_lshl_add_u64 v[82:83], v[82:83], 0, v[144:145]
	v_ashrrev_i32_e32 v81, 31, v80
	s_waitcnt vmcnt(0)
	v_lshlrev_b32_e32 v72, 16, v76
	v_and_b32_e32 v73, 0xffff0000, v76
	v_lshlrev_b32_e32 v74, 16, v77
	v_and_b32_e32 v75, 0xffff0000, v77
	v_lshlrev_b32_e32 v76, 16, v78
	v_and_b32_e32 v77, 0xffff0000, v78
	v_lshlrev_b32_e32 v78, 16, v79
	v_and_b32_e32 v79, 0xffff0000, v79
	v_mul_f32_e32 v68, v68, v72
	v_mul_f32_e32 v69, v69, v73
	v_mul_f32_e32 v70, v70, v74
	v_mul_f32_e32 v71, v71, v75
	v_mul_f32_e32 v67, v67, v79
	v_mul_f32_e32 v72, v64, v76
	v_mul_f32_e32 v73, v65, v77
	v_mul_f32_e32 v74, v66, v78
	v_cvt_pk_bf16_f32 v64, v68, v69
	v_cvt_pk_bf16_f32 v65, v70, v71
	v_cvt_pk_bf16_f32 v66, v72, v73
	v_cvt_pk_bf16_f32 v67, v74, v67
	global_load_dwordx4 v[68:71], v[82:83], off offset:3072
	s_nop 0
	global_store_dwordx4 v[84:85], v[64:67], off offset:256
	s_waitcnt vmcnt(0)
; __device__ __forceinline__ unsigned cvt_pk_bf16(float lo, float hi) { unsigned r; asm volatile("v_cvt_pk_bf16_f32 %0, %1, %2" : "=v"(r) : "v"(lo), "v"(hi)); return r; }
; __device__ __forceinline__ float bf_lo(unsigned u) { return __uint_as_float(u << 16); }
; __device__ __forceinline__ float bf_hi(unsigned u) { return __uint_as_float(u & 0xffff0000u); }
;     __device__ __forceinline__ void operator()(const f32x4 (&acc)[2][2][4][2], const Unit& u, int wr, int wc, int fr, int fq) const {
;     ...
;             for (int m = 0; m < 4; ++m) { const size_t r = (size_t)(row0 + ai * HALF + m * 16); bf16_t* rowp = O + r * ldc + col0; const bf16_t* gp = G + r * ldg + col0;
; #pragma unroll
;                 for (int bj = 0; bj < 2; ++bj) { const u32x4 gw = *(const u32x4*)(gp + bj * HALF);
;                     f32x4 v0 = acc[ai][bj][m][0], v1 = acc[ai][bj][m][1];
;                     v0[0] *= bf_lo(gw.x); v0[1] *= bf_hi(gw.x); v0[2] *= bf_lo(gw.y); v0[3] *= bf_hi(gw.y);
;                     v1[0] *= bf_lo(gw.z); v1[1] *= bf_hi(gw.z); v1[2] *= bf_lo(gw.w); v1[3] *= bf_hi(gw.w);
;                     if (ACCUM) { const u32x4 pw = *(const u32x4*)(rowp + bj * HALF);
;                         v0[0] += bf_lo(pw.x); v0[1] += bf_hi(pw.x); v0[2] += bf_lo(pw.y); v0[3] += bf_hi(pw.y);
;                         v1[0] += bf_lo(pw.z); v1[1] += bf_hi(pw.z); v1[2] += bf_lo(pw.w); v1[3] += bf_hi(pw.w); }
;                     u32x4 w; w.x = cvt_pk_bf16(v0[0], v0[1]); w.y = cvt_pk_bf16(v0[2], v0[3]); w.z = cvt_pk_bf16(v1[0], v1[1]); w.w = cvt_pk_bf16(v1[2], v1[3]);
;                     *(u32x4*)(rowp + bj * HALF) = w; } }
	s_nop 0
	v_lshlrev_b32_e32 v64, 16, v68
	v_and_b32_e32 v65, 0xffff0000, v68
	v_lshlrev_b32_e32 v66, 16, v69
	v_and_b32_e32 v67, 0xffff0000, v69
	v_lshlrev_b32_e32 v68, 16, v70
	v_and_b32_e32 v69, 0xffff0000, v70
	v_lshlrev_b32_e32 v70, 16, v71
	v_and_b32_e32 v71, 0xffff0000, v71
	v_mul_f32_e32 v60, v60, v64
	v_mul_f32_e32 v61, v61, v65
	v_mul_f32_e32 v62, v62, v66
	v_mul_f32_e32 v63, v63, v67
	v_mul_f32_e32 v59, v59, v71
	v_mul_f32_e32 v64, v56, v68
	v_mul_f32_e32 v65, v57, v69
	v_mul_f32_e32 v66, v58, v70
	v_cvt_pk_bf16_f32 v56, v60, v61
	v_cvt_pk_bf16_f32 v57, v62, v63
	v_cvt_pk_bf16_f32 v58, v64, v65
	v_cvt_pk_bf16_f32 v59, v66, v59
	global_load_dwordx4 v[60:63], v[82:83], off offset:3328
	v_lshlrev_b64 v[68:69], 11, v[80:81]
	v_lshl_add_u64 v[68:69], s[0:1], 0, v[68:69]
	v_add_u32_e32 v64, 0x90, v146
	v_lshl_add_u64 v[68:69], v[68:69], 0, v[144:145]
	v_mad_i64_i32 v[66:67], s[18:19], v64, s41, v[148:149]
	global_store_dwordx4 v[68:69], v[56:59], off
	v_lshl_add_u64 v[66:67], v[66:67], 0, v[144:145]
	v_ashrrev_i32_e32 v65, 31, v64
	s_waitcnt vmcnt(0)
	v_lshlrev_b32_e32 v56, 16, v60
	v_and_b32_e32 v57, 0xffff0000, v60
	v_lshlrev_b32_e32 v58, 16, v61
	v_and_b32_e32 v59, 0xffff0000, v61
	v_lshlrev_b32_e32 v60, 16, v62
	v_and_b32_e32 v61, 0xffff0000, v62
	v_lshlrev_b32_e32 v62, 16, v63
	v_and_b32_e32 v63, 0xffff0000, v63
	v_mul_f32_e32 v52, v52, v56
	v_mul_f32_e32 v53, v53, v57
	v_mul_f32_e32 v54, v54, v58
	v_mul_f32_e32 v55, v55, v59
	v_mul_f32_e32 v47, v47, v63
	v_mul_f32_e32 v56, v44, v60
	v_mul_f32_e32 v57, v45, v61
	v_mul_f32_e32 v58, v46, v62
	v_cvt_pk_bf16_f32 v44, v52, v53
	v_cvt_pk_bf16_f32 v45, v54, v55
	v_cvt_pk_bf16_f32 v46, v56, v57
	v_cvt_pk_bf16_f32 v47, v58, v47
	global_load_dwordx4 v[52:55], v[66:67], off offset:3072
	s_nop 0
	global_store_dwordx4 v[68:69], v[44:47], off offset:256
	s_waitcnt vmcnt(0)
	s_nop 0
	v_lshlrev_b32_e32 v44, 16, v52
	v_and_b32_e32 v45, 0xffff0000, v52
	v_lshlrev_b32_e32 v46, 16, v53
	v_and_b32_e32 v47, 0xffff0000, v53
	v_lshlrev_b32_e32 v52, 16, v54
	v_and_b32_e32 v53, 0xffff0000, v54
	v_lshlrev_b32_e32 v54, 16, v55
	v_and_b32_e32 v55, 0xffff0000, v55
	v_mul_f32_e32 v44, v48, v44
	v_mul_f32_e32 v45, v49, v45
	v_mul_f32_e32 v46, v50, v46
	v_mul_f32_e32 v47, v51, v47
	v_mul_f32_e32 v43, v43, v55
	v_mul_f32_e32 v48, v40, v52
	v_mul_f32_e32 v49, v41, v53
	v_mul_f32_e32 v50, v42, v54
	v_cvt_pk_bf16_f32 v40, v44, v45
	v_cvt_pk_bf16_f32 v41, v46, v47
	v_cvt_pk_bf16_f32 v42, v48, v49
	v_cvt_pk_bf16_f32 v43, v50, v43
	global_load_dwordx4 v[44:47], v[66:67], off offset:3328
	v_lshlrev_b64 v[52:53], 11, v[64:65]
	v_lshl_add_u64 v[52:53], s[0:1], 0, v[52:53]
	v_add_u32_e32 v48, 0xa0, v146
	v_lshl_add_u64 v[52:53], v[52:53], 0, v[144:145]
	v_mad_i64_i32 v[50:51], s[18:19], v48, s41, v[148:149]
	global_store_dwordx4 v[52:53], v[40:43], off
	v_lshl_add_u64 v[50:51], v[50:51], 0, v[144:145]
	v_ashrrev_i32_e32 v49, 31, v48
	s_waitcnt vmcnt(0)
	v_lshlrev_b32_e32 v40, 16, v44
	v_and_b32_e32 v41, 0xffff0000, v44
	v_lshlrev_b32_e32 v42, 16, v45
	v_and_b32_e32 v43, 0xffff0000, v45
	v_lshlrev_b32_e32 v44, 16, v46
	v_and_b32_e32 v45, 0xffff0000, v46
	v_lshlrev_b32_e32 v46, 16, v47
	v_and_b32_e32 v47, 0xffff0000, v47
	v_mul_f32_e32 v36, v36, v40
	v_mul_f32_e32 v37, v37, v41
	v_mul_f32_e32 v38, v38, v42
	v_mul_f32_e32 v39, v39, v43
	v_mul_f32_e32 v31, v31, v47
	v_mul_f32_e32 v40, v28, v44
	v_mul_f32_e32 v41, v29, v45
	v_mul_f32_e32 v42, v30, v46
	v_cvt_pk_bf16_f32 v28, v36, v37
	v_cvt_pk_bf16_f32 v29, v38, v39
	v_cvt_pk_bf16_f32 v30, v40, v41
	v_cvt_pk_bf16_f32 v31, v42, v31
	global_load_dwordx4 v[36:39], v[50:51], off offset:3072
	s_nop 0
	global_store_dwordx4 v[52:53], v[28:31], off offset:256
	s_waitcnt vmcnt(0)
; __device__ __forceinline__ unsigned cvt_pk_bf16(float lo, float hi) { unsigned r; asm volatile("v_cvt_pk_bf16_f32 %0, %1, %2" : "=v"(r) : "v"(lo), "v"(hi)); return r; }
; __device__ __forceinline__ float bf_lo(unsigned u) { return __uint_as_float(u << 16); }
; __device__ __forceinline__ float bf_hi(unsigned u) { return __uint_as_float(u & 0xffff0000u); }
; #define PG8_WAIT_V(n) asm volatile("s_waitcnt vmcnt(" #n ")" ::: "memory")
; #define PG8_BAR __builtin_amdgcn_s_barrier()
;     __device__ __forceinline__ void operator()(const f32x4 (&acc)[2][2][4][2], const Unit& u, int wr, int wc, int fr, int fq) const {
;     ...
;             for (int m = 0; m < 4; ++m) { const size_t r = (size_t)(row0 + ai * HALF + m * 16); bf16_t* rowp = O + r * ldc + col0; const bf16_t* gp = G + r * ldg + col0;
; #pragma unroll
;                 for (int bj = 0; bj < 2; ++bj) { const u32x4 gw = *(const u32x4*)(gp + bj * HALF);
;                     f32x4 v0 = acc[ai][bj][m][0], v1 = acc[ai][bj][m][1];
;                     v0[0] *= bf_lo(gw.x); v0[1] *= bf_hi(gw.x); v0[2] *= bf_lo(gw.y); v0[3] *= bf_hi(gw.y);
;                     v1[0] *= bf_lo(gw.z); v1[1] *= bf_hi(gw.z); v1[2] *= bf_lo(gw.w); v1[3] *= bf_hi(gw.w);
;                     if (ACCUM) { const u32x4 pw = *(const u32x4*)(rowp + bj * HALF);
;                         v0[0] += bf_lo(pw.x); v0[1] += bf_hi(pw.x); v0[2] += bf_lo(pw.y); v0[3] += bf_hi(pw.y);
;                         v1[0] += bf_lo(pw.z); v1[1] += bf_hi(pw.z); v1[2] += bf_lo(pw.w); v1[3] += bf_hi(pw.w); }
;                     u32x4 w; w.x = cvt_pk_bf16(v0[0], v0[1]); w.y = cvt_pk_bf16(v0[2], v0[3]); w.z = cvt_pk_bf16(v1[0], v1[1]); w.w = cvt_pk_bf16(v1[2], v1[3]);
;                     *(u32x4*)(rowp + bj * HALF) = w; } }
; template <class Epi, class Sched>
; __device__ __forceinline__ void gemm_phase(PG8_LAS unsigned char* lds, const Gemm g, const Sched& S, const Epi& E) {
;     ...
;         if (!has_next) break;
; #pragma unroll
;         for (int a = 0; a < 2; ++a)
; #pragma unroll
;             for (int b = 0; b < 2; ++b)
; #pragma unroll
;                 for (int m = 0; m < 4; ++m)
; #pragma unroll
;                     for (int n = 0; n < 2; ++n) acc[a][b][m][n] = (f32x4){0.f, 0.f, 0.f, 0.f};
;         cur = nxt; cA = nA; cB = nB; ++ui;
;     }
;     PG8_WAIT_V(0);
;     if (wr == 0) PG8_BAR;
;     PG8_BAR;
	s_nop 0
	v_lshlrev_b32_e32 v28, 16, v36
	v_and_b32_e32 v29, 0xffff0000, v36
	v_lshlrev_b32_e32 v30, 16, v37
	v_and_b32_e32 v31, 0xffff0000, v37
	v_lshlrev_b32_e32 v36, 16, v38
	v_and_b32_e32 v37, 0xffff0000, v38
	v_lshlrev_b32_e32 v38, 16, v39
	v_and_b32_e32 v39, 0xffff0000, v39
	v_mul_f32_e32 v28, v32, v28
	v_mul_f32_e32 v29, v33, v29
	v_mul_f32_e32 v30, v34, v30
	v_mul_f32_e32 v31, v35, v31
	v_mul_f32_e32 v27, v27, v39
	v_mul_f32_e32 v32, v24, v36
	v_mul_f32_e32 v33, v25, v37
	v_mul_f32_e32 v34, v26, v38
	v_cvt_pk_bf16_f32 v24, v28, v29
	v_cvt_pk_bf16_f32 v25, v30, v31
	v_cvt_pk_bf16_f32 v26, v32, v33
	v_cvt_pk_bf16_f32 v27, v34, v27
	global_load_dwordx4 v[28:31], v[50:51], off offset:3328
	v_lshlrev_b64 v[36:37], 11, v[48:49]
	v_lshl_add_u64 v[36:37], s[0:1], 0, v[36:37]
	v_add_u32_e32 v32, 0xb0, v146
	v_lshl_add_u64 v[36:37], v[36:37], 0, v[144:145]
	v_mad_i64_i32 v[34:35], s[18:19], v32, s41, v[148:149]
	global_store_dwordx4 v[36:37], v[24:27], off
	v_lshl_add_u64 v[34:35], v[34:35], 0, v[144:145]
	v_ashrrev_i32_e32 v33, 31, v32
	s_mov_b64 s[18:19], s[12:13]
	s_waitcnt vmcnt(0)
	v_lshlrev_b32_e32 v24, 16, v28
	v_and_b32_e32 v25, 0xffff0000, v28
	v_lshlrev_b32_e32 v26, 16, v29
	v_and_b32_e32 v27, 0xffff0000, v29
	v_lshlrev_b32_e32 v28, 16, v30
	v_and_b32_e32 v29, 0xffff0000, v30
	v_lshlrev_b32_e32 v30, 16, v31
	v_and_b32_e32 v31, 0xffff0000, v31
	v_mul_f32_e32 v20, v20, v24
	v_mul_f32_e32 v21, v21, v25
	v_mul_f32_e32 v22, v22, v26
	v_mul_f32_e32 v23, v23, v27
	v_mul_f32_e32 v15, v15, v31
	v_mul_f32_e32 v24, v12, v28
	v_mul_f32_e32 v25, v13, v29
	v_mul_f32_e32 v26, v14, v30
	v_cvt_pk_bf16_f32 v12, v20, v21
	v_cvt_pk_bf16_f32 v13, v22, v23
	v_cvt_pk_bf16_f32 v14, v24, v25
	v_cvt_pk_bf16_f32 v15, v26, v15
	global_load_dwordx4 v[20:23], v[34:35], off offset:3072
	s_nop 0
	global_store_dwordx4 v[36:37], v[12:15], off offset:256
	s_waitcnt vmcnt(0)
	s_nop 0
	v_lshlrev_b32_e32 v12, 16, v20
	v_and_b32_e32 v13, 0xffff0000, v20
	v_lshlrev_b32_e32 v14, 16, v21
	v_and_b32_e32 v15, 0xffff0000, v21
	v_lshlrev_b32_e32 v20, 16, v22
	v_and_b32_e32 v21, 0xffff0000, v22
	v_lshlrev_b32_e32 v22, 16, v23
	v_and_b32_e32 v23, 0xffff0000, v23
	v_mul_f32_e32 v12, v16, v12
	v_mul_f32_e32 v13, v17, v13
	v_mul_f32_e32 v14, v18, v14
	v_mul_f32_e32 v15, v19, v15
	v_mul_f32_e32 v11, v11, v23
	v_mul_f32_e32 v16, v8, v20
	v_mul_f32_e32 v17, v9, v21
	v_mul_f32_e32 v18, v10, v22
	v_cvt_pk_bf16_f32 v8, v12, v13
	v_cvt_pk_bf16_f32 v9, v14, v15
	v_cvt_pk_bf16_f32 v10, v16, v17
	v_cvt_pk_bf16_f32 v11, v18, v11
	global_load_dwordx4 v[12:15], v[34:35], off offset:3328
	v_lshlrev_b64 v[16:17], 11, v[32:33]
	v_lshl_add_u64 v[16:17], s[0:1], 0, v[16:17]
	v_lshl_add_u64 v[16:17], v[16:17], 0, v[144:145]
	global_store_dwordx4 v[16:17], v[8:11], off
	s_waitcnt vmcnt(0)
	s_nop 0
	v_lshlrev_b32_e32 v8, 16, v12
	v_and_b32_e32 v9, 0xffff0000, v12
	v_lshlrev_b32_e32 v10, 16, v13
	v_and_b32_e32 v11, 0xffff0000, v13
	v_lshlrev_b32_e32 v12, 16, v14
	v_and_b32_e32 v13, 0xffff0000, v14
	v_lshlrev_b32_e32 v14, 16, v15
	v_and_b32_e32 v15, 0xffff0000, v15
	v_mul_f32_e32 v3, v3, v15
	v_mul_f32_e32 v4, v4, v8
	v_mul_f32_e32 v5, v5, v9
	v_mul_f32_e32 v6, v6, v10
	v_mul_f32_e32 v7, v7, v11
	v_mul_f32_e32 v8, v0, v12
	v_mul_f32_e32 v9, v1, v13
	v_mul_f32_e32 v10, v2, v14
	v_cvt_pk_bf16_f32 v0, v4, v5
	v_cvt_pk_bf16_f32 v1, v6, v7
	v_cvt_pk_bf16_f32 v2, v8, v9
	v_cvt_pk_bf16_f32 v3, v10, v3
	global_store_dwordx4 v[16:17], v[0:3], off offset:256
	s_cbranch_vccz .LBB0_984
	s_waitcnt vmcnt(0)
	s_cmpk_gt_u32 s25, 0xff
	s_cbranch_scc1 .LBB0_995
	s_barrier

; #define PG8_STAGE(bufoff, gbase, voff) do { _Pragma("unroll") for (int _i = 0; _i < 2; ++_i) \
;         __builtin_amdgcn_global_load_lds((const unsigned*)((const char*)(gbase) + (voff)[_i]), (PG8_LAS unsigned*)(lds + (bufoff) + ldsw + _i * 8192), 16, 0, 0); } while (0)
; #define PG8_LDA(dst, b, h) do { _Pragma("unroll") for (int m = 0; m < 4; ++m) _Pragma("unroll") for (int k = 0; k < 2; ++k) dst[m][k] = *(const PG8_LAS bf16x8*)(lds + PG8_SA(b, h) + aoff + m * 2048 + k * 1024); } while (0)
; #define PG8_LDB(dst, b, h) do { _Pragma("unroll") for (int n = 0; n < 2; ++n) _Pragma("unroll") for (int k = 0; k < 2; ++k) dst[n][k] = *(const PG8_LAS bf16x8*)(lds + PG8_SB(b, h) + boff + n * 2048 + k * 1024); } while (0)
; #define PG8_MMA(ai, bj, At, Bt) do { __builtin_amdgcn_s_setprio(1); _Pragma("unroll") for (int m = 0; m < 4; ++m) _Pragma("unroll") for (int n = 0; n < 2; ++n) _Pragma("unroll") for (int k = 0; k < 2; ++k) \
;         acc[ai][bj][m][n] = __builtin_amdgcn_mfma_f32_16x16x32_bf16(Bt[n][k], At[m][k], acc[ai][bj][m][n], 0, 0, 0); __builtin_amdgcn_s_setprio(0); } while (0)
; #define PG8_WAIT_L(n) asm volatile("s_waitcnt lgkmcnt(" #n ")" ::: "memory")
; #define PG8_BAR __builtin_amdgcn_s_barrier()
; #define PG8_SCHED __builtin_amdgcn_sched_barrier(0)
; template <class Epi, class Sched>
; __device__ __forceinline__ void gemm_phase(PG8_LAS unsigned char* lds, const Gemm g, const Sched& S, const Epi& E) {
;     ...
;             const bool last = (t == nt - 2);
;             const char* a1 = cA + (size_t)(t + 1) * kstep;
;             const char* a2 = last ? nA : cA + (size_t)(t + 2) * kstep; const char* b2 = last ? nB : cB + (size_t)(t + 2) * kstep;
;             const char* a3 = a2 + kstep; const char* b3 = b2 + kstep;
;             if (last && has_next) S.a_ready(nxt);
;             PG8_LDB(B0, 0, 0); PG8_SCHED; PG8_LDA(At, 0, 0); PG8_STAGE(PG8_SA(1, 1), a1 + hstep, voffA);
;             PG8_WAIT_L(8); PG8_BAR; PG8_WAIT_L(0); PG8_MMA(0, 0, At, B0); PG8_BAR; PG8_SCHED;
;             PG8_LDB(B1, 0, 1); PG8_STAGE(PG8_SB(0, 0), b2, voffB);
;             PG8_BAR; PG8_WAIT_L(0); PG8_MMA(0, 1, At, B1); PG8_BAR;
;             PG8_LDA(At, 0, 1); PG8_STAGE(PG8_SA(0, 0), a2, voffA);
;             PG8_BAR; PG8_WAIT_L(0); PG8_MMA(1, 0, At, B0); PG8_BAR; PG8_SCHED;
.LBB0_1011:
	ds_read_b128 v[144:147], v153
	ds_read_b128 v[156:159], v153 offset:1024
	ds_read_b128 v[160:163], v153 offset:2048
	ds_read_b128 v[164:167], v153 offset:3072
	s_add_u32 s20, s18, 0xfffc0080
	s_addc_u32 s21, s19, -1
	s_cmp_eq_u32 s47, 12
	s_cselect_b32 s23, s11, s21
	s_cselect_b32 s22, s43, s20
	s_cselect_b32 s21, s9, s46
	s_cselect_b32 s20, s44, s45
	v_lshl_add_u64 v[148:149], s[18:19], 0, v[136:137]
	s_add_i32 m0, s17, 0xc000
	ds_read_b128 v[168:171], v154
	ds_read_b128 v[172:175], v154 offset:1024
	ds_read_b128 v[182:185], v154 offset:2048
	ds_read_b128 v[190:193], v154 offset:3072
	ds_read_b128 v[194:197], v154 offset:4096
	ds_read_b128 v[198:201], v154 offset:5120
	ds_read_b128 v[202:205], v154 offset:6144
	ds_read_b128 v[206:209], v154 offset:7168
	global_load_lds_dwordx4 v[148:149], off
	v_lshl_add_u64 v[148:149], s[18:19], 0, v[138:139]
	s_add_i32 m0, s17, 0xe000
	s_nop 0
	global_load_lds_dwordx4 v[148:149], off
	s_waitcnt lgkmcnt(8)
	s_barrier
	s_waitcnt lgkmcnt(0)
	s_waitcnt lgkmcnt(0)
	v_mfma_f32_16x16x32_bf16 v[124:127], v[144:147], v[168:171], v[124:127]
	v_mfma_f32_16x16x32_bf16 v[120:123], v[160:163], v[168:171], v[120:123]
	v_mfma_f32_16x16x32_bf16 v[108:111], v[144:147], v[182:185], v[108:111]
	v_mfma_f32_16x16x32_bf16 v[104:107], v[160:163], v[182:185], v[104:107]
	v_mfma_f32_16x16x32_bf16 v[92:95], v[144:147], v[194:197], v[92:95]
	v_mfma_f32_16x16x32_bf16 v[88:91], v[160:163], v[194:197], v[88:91]
	v_mfma_f32_16x16x32_bf16 v[76:79], v[144:147], v[202:205], v[76:79]
	v_mfma_f32_16x16x32_bf16 v[72:75], v[160:163], v[202:205], v[72:75]
	v_mfma_f32_16x16x32_bf16 v[124:127], v[156:159], v[172:175], v[124:127]
	v_mfma_f32_16x16x32_bf16 v[120:123], v[164:167], v[172:175], v[120:123]
	v_mfma_f32_16x16x32_bf16 v[108:111], v[156:159], v[190:193], v[108:111]
	v_mfma_f32_16x16x32_bf16 v[104:107], v[164:167], v[190:193], v[104:107]
	v_mfma_f32_16x16x32_bf16 v[92:95], v[156:159], v[198:201], v[92:95]
	v_mfma_f32_16x16x32_bf16 v[88:91], v[164:167], v[198:201], v[88:91]
	v_mfma_f32_16x16x32_bf16 v[76:79], v[156:159], v[206:209], v[76:79]
	v_mfma_f32_16x16x32_bf16 v[72:75], v[164:167], v[206:209], v[72:75]
	s_barrier
	s_add_i32 s48, s39, s29
	v_lshl_add_u64 v[148:149], s[20:21], 0, v[130:131]
	s_mov_b32 m0, s48
	ds_read_b128 v[210:213], v155
	ds_read_b128 v[214:217], v155 offset:1024
	ds_read_b128 v[218:221], v155 offset:2048
	ds_read_b128 v[222:225], v155 offset:3072
	global_load_lds_dwordx4 v[148:149], off
	v_lshl_add_u64 v[186:187], s[20:21], 0, v[134:135]
	s_add_i32 m0, s48, 0x2000
	s_nop 0
	global_load_lds_dwordx4 v[186:187], off
	s_barrier
	s_waitcnt lgkmcnt(0)
	s_waitcnt lgkmcnt(0)
	v_mfma_f32_16x16x32_bf16 v[116:119], v[210:213], v[168:171], v[116:119]
	v_mfma_f32_16x16x32_bf16 v[112:115], v[218:221], v[168:171], v[112:115]
	v_mfma_f32_16x16x32_bf16 v[100:103], v[210:213], v[182:185], v[100:103]
	v_mfma_f32_16x16x32_bf16 v[96:99], v[218:221], v[182:185], v[96:99]
	v_mfma_f32_16x16x32_bf16 v[84:87], v[210:213], v[194:197], v[84:87]
	v_mfma_f32_16x16x32_bf16 v[80:83], v[218:221], v[194:197], v[80:83]
	v_mfma_f32_16x16x32_bf16 v[68:71], v[210:213], v[202:205], v[68:71]
	v_mfma_f32_16x16x32_bf16 v[64:67], v[218:221], v[202:205], v[64:67]
	v_mfma_f32_16x16x32_bf16 v[116:119], v[214:217], v[172:175], v[116:119]
	v_mfma_f32_16x16x32_bf16 v[112:115], v[222:225], v[172:175], v[112:115]
	v_mfma_f32_16x16x32_bf16 v[100:103], v[214:217], v[190:193], v[100:103]
	v_mfma_f32_16x16x32_bf16 v[96:99], v[222:225], v[190:193], v[96:99]
	v_mfma_f32_16x16x32_bf16 v[84:87], v[214:217], v[198:201], v[84:87]
	v_mfma_f32_16x16x32_bf16 v[80:83], v[222:225], v[198:201], v[80:83]
	v_mfma_f32_16x16x32_bf16 v[68:71], v[214:217], v[206:209], v[68:71]
	v_mfma_f32_16x16x32_bf16 v[64:67], v[222:225], v[206:209], v[64:67]
	s_barrier
	s_mov_b32 m0, s17
	v_lshl_add_u64 v[226:227], s[22:23], 0, v[128:129]
	ds_read_b128 v[168:171], v154 offset:16384
	ds_read_b128 v[172:175], v154 offset:17408
	ds_read_b128 v[182:185], v154 offset:18432
	ds_read_b128 v[190:193], v154 offset:19456
	ds_read_b128 v[194:197], v154 offset:20480
	ds_read_b128 v[198:201], v154 offset:21504
	ds_read_b128 v[202:205], v154 offset:22528
	ds_read_b128 v[206:209], v154 offset:23552
	global_load_lds_dwordx4 v[226:227], off
	v_lshl_add_u64 v[228:229], s[22:23], 0, v[132:133]
	s_mov_b32 m0, s30
	s_nop 0
	global_load_lds_dwordx4 v[228:229], off
	s_barrier
	s_waitcnt lgkmcnt(0)
	s_waitcnt lgkmcnt(0)
	v_mfma_f32_16x16x32_bf16 v[60:63], v[144:147], v[168:171], v[60:63]
	v_mfma_f32_16x16x32_bf16 v[56:59], v[160:163], v[168:171], v[56:59]
	v_mfma_f32_16x16x32_bf16 v[44:47], v[144:147], v[182:185], v[44:47]
	v_mfma_f32_16x16x32_bf16 v[40:43], v[160:163], v[182:185], v[40:43]
	v_mfma_f32_16x16x32_bf16 v[28:31], v[144:147], v[194:197], v[28:31]
	v_mfma_f32_16x16x32_bf16 v[24:27], v[160:163], v[194:197], v[24:27]
	v_mfma_f32_16x16x32_bf16 v[12:15], v[144:147], v[202:205], v[12:15]
	v_mfma_f32_16x16x32_bf16 v[8:11], v[160:163], v[202:205], v[8:11]
	v_mfma_f32_16x16x32_bf16 v[60:63], v[156:159], v[172:175], v[60:63]
	v_mfma_f32_16x16x32_bf16 v[56:59], v[164:167], v[172:175], v[56:59]
	v_mfma_f32_16x16x32_bf16 v[44:47], v[156:159], v[190:193], v[44:47]
	v_mfma_f32_16x16x32_bf16 v[40:43], v[164:167], v[190:193], v[40:43]
	v_mfma_f32_16x16x32_bf16 v[28:31], v[156:159], v[198:201], v[28:31]
	v_mfma_f32_16x16x32_bf16 v[24:27], v[164:167], v[198:201], v[24:27]
	v_mfma_f32_16x16x32_bf16 v[12:15], v[156:159], v[206:209], v[12:15]
	v_mfma_f32_16x16x32_bf16 v[8:11], v[164:167], v[206:209], v[8:11]
	s_barrier
; #define PG8_STAGE(bufoff, gbase, voff) do { _Pragma("unroll") for (int _i = 0; _i < 2; ++_i) \
;         __builtin_amdgcn_global_load_lds((const unsigned*)((const char*)(gbase) + (voff)[_i]), (PG8_LAS unsigned*)(lds + (bufoff) + ldsw + _i * 8192), 16, 0, 0); } while (0)
; #define PG8_LDA(dst, b, h) do { _Pragma("unroll") for (int m = 0; m < 4; ++m) _Pragma("unroll") for (int k = 0; k < 2; ++k) dst[m][k] = *(const PG8_LAS bf16x8*)(lds + PG8_SA(b, h) + aoff + m * 2048 + k * 1024); } while (0)
; #define PG8_LDB(dst, b, h) do { _Pragma("unroll") for (int n = 0; n < 2; ++n) _Pragma("unroll") for (int k = 0; k < 2; ++k) dst[n][k] = *(const PG8_LAS bf16x8*)(lds + PG8_SB(b, h) + boff + n * 2048 + k * 1024); } while (0)
; #define PG8_MMA(ai, bj, At, Bt) do { __builtin_amdgcn_s_setprio(1); _Pragma("unroll") for (int m = 0; m < 4; ++m) _Pragma("unroll") for (int n = 0; n < 2; ++n) _Pragma("unroll") for (int k = 0; k < 2; ++k) \
;         acc[ai][bj][m][n] = __builtin_amdgcn_mfma_f32_16x16x32_bf16(Bt[n][k], At[m][k], acc[ai][bj][m][n], 0, 0, 0); __builtin_amdgcn_s_setprio(0); } while (0)
; #define PG8_WAIT_V(n) asm volatile("s_waitcnt vmcnt(" #n ")" ::: "memory")
; #define PG8_WAIT_L(n) asm volatile("s_waitcnt lgkmcnt(" #n ")" ::: "memory")
; #define PG8_BAR __builtin_amdgcn_s_barrier()
; #define PG8_SCHED __builtin_amdgcn_sched_barrier(0)
; template <class Epi, class Sched>
; __device__ __forceinline__ void gemm_phase(PG8_LAS unsigned char* lds, const Gemm g, const Sched& S, const Epi& E) {
;     ...
;             PG8_STAGE(PG8_SB(0, 1), b2 + hstep, voffB);
;             PG8_WAIT_V(6); PG8_BAR; PG8_MMA(1, 1, At, B1); PG8_BAR;
;             PG8_LDB(B0, 1, 0); PG8_SCHED; PG8_LDA(At, 1, 0); PG8_STAGE(PG8_SA(0, 1), a2 + hstep, voffA);
;             PG8_WAIT_L(8); PG8_BAR; PG8_WAIT_L(0); PG8_MMA(0, 0, At, B0); PG8_BAR; PG8_SCHED;
;             PG8_LDB(B1, 1, 1); PG8_STAGE(PG8_SB(1, 0), b3, voffB);
;             PG8_BAR; PG8_WAIT_L(0); PG8_MMA(0, 1, At, B1); PG8_BAR;
;             PG8_LDA(At, 1, 1); PG8_STAGE(PG8_SA(1, 0), a3, voffA);
	s_add_u32 s48, s20, 0x40000
	s_addc_u32 s49, s21, 0
	s_add_i32 s50, s40, s29
	v_lshl_add_u64 v[144:145], s[48:49], 0, v[130:131]
	s_mov_b32 m0, s50
	s_nop 0
	global_load_lds_dwordx4 v[144:145], off
	v_lshl_add_u64 v[144:145], s[48:49], 0, v[134:135]
	s_add_i32 m0, s50, 0x2000
	s_nop 0
	global_load_lds_dwordx4 v[144:145], off
	s_waitcnt vmcnt(6)
	s_barrier
	v_mfma_f32_16x16x32_bf16 v[52:55], v[210:213], v[168:171], v[52:55]
	v_mfma_f32_16x16x32_bf16 v[48:51], v[218:221], v[168:171], v[48:51]
	v_mfma_f32_16x16x32_bf16 v[36:39], v[210:213], v[182:185], v[36:39]
	v_mfma_f32_16x16x32_bf16 v[32:35], v[218:221], v[182:185], v[32:35]
	v_mfma_f32_16x16x32_bf16 v[20:23], v[210:213], v[194:197], v[20:23]
	v_mfma_f32_16x16x32_bf16 v[16:19], v[218:221], v[194:197], v[16:19]
	v_mfma_f32_16x16x32_bf16 v[4:7], v[210:213], v[202:205], v[4:7]
	v_mfma_f32_16x16x32_bf16 v[0:3], v[218:221], v[202:205], v[0:3]
	v_mfma_f32_16x16x32_bf16 v[52:55], v[214:217], v[172:175], v[52:55]
	v_mfma_f32_16x16x32_bf16 v[48:51], v[222:225], v[172:175], v[48:51]
	v_mfma_f32_16x16x32_bf16 v[36:39], v[214:217], v[190:193], v[36:39]
	v_mfma_f32_16x16x32_bf16 v[32:35], v[222:225], v[190:193], v[32:35]
	v_mfma_f32_16x16x32_bf16 v[20:23], v[214:217], v[198:201], v[20:23]
	v_mfma_f32_16x16x32_bf16 v[16:19], v[222:225], v[198:201], v[16:19]
	v_mfma_f32_16x16x32_bf16 v[4:7], v[214:217], v[206:209], v[4:7]
	v_mfma_f32_16x16x32_bf16 v[0:3], v[222:225], v[206:209], v[0:3]
	s_barrier
	s_add_i32 s48, 0, 0x18000
	v_add_u32_e32 v164, s48, v151
	ds_read_b128 v[144:147], v164
	ds_read_b128 v[156:159], v164 offset:1024
	ds_read_b128 v[160:163], v164 offset:2048
	ds_read_b128 v[164:167], v164 offset:3072
	s_add_u32 s22, s22, 0x40000
	s_addc_u32 s23, s23, 0
	s_mov_b32 m0, s31
	v_lshl_add_u64 v[210:211], s[22:23], 0, v[128:129]
	ds_read_b128 v[168:171], v154 offset:32768
	ds_read_b128 v[172:175], v154 offset:33792
	ds_read_b128 v[182:185], v154 offset:34816
	ds_read_b128 v[190:193], v154 offset:35840
	ds_read_b128 v[194:197], v154 offset:36864
	ds_read_b128 v[198:201], v154 offset:37888
	ds_read_b128 v[202:205], v154 offset:38912
	ds_read_b128 v[206:209], v154 offset:39936
	global_load_lds_dwordx4 v[210:211], off
	v_lshl_add_u64 v[210:211], s[22:23], 0, v[132:133]
	s_mov_b32 m0, s34
	s_nop 0
	global_load_lds_dwordx4 v[210:211], off
	s_waitcnt lgkmcnt(8)
	s_barrier
	s_waitcnt lgkmcnt(0)
	s_waitcnt lgkmcnt(0)
	v_mfma_f32_16x16x32_bf16 v[124:127], v[144:147], v[168:171], v[124:127]
	v_mfma_f32_16x16x32_bf16 v[120:123], v[160:163], v[168:171], v[120:123]
	v_mfma_f32_16x16x32_bf16 v[108:111], v[144:147], v[182:185], v[108:111]
	v_mfma_f32_16x16x32_bf16 v[104:107], v[160:163], v[182:185], v[104:107]
	v_mfma_f32_16x16x32_bf16 v[92:95], v[144:147], v[194:197], v[92:95]
	v_mfma_f32_16x16x32_bf16 v[88:91], v[160:163], v[194:197], v[88:91]
	v_mfma_f32_16x16x32_bf16 v[76:79], v[144:147], v[202:205], v[76:79]
	v_mfma_f32_16x16x32_bf16 v[72:75], v[160:163], v[202:205], v[72:75]
	v_mfma_f32_16x16x32_bf16 v[124:127], v[156:159], v[172:175], v[124:127]
	v_mfma_f32_16x16x32_bf16 v[120:123], v[164:167], v[172:175], v[120:123]
	v_mfma_f32_16x16x32_bf16 v[108:111], v[156:159], v[190:193], v[108:111]
	v_mfma_f32_16x16x32_bf16 v[104:107], v[164:167], v[190:193], v[104:107]
	v_mfma_f32_16x16x32_bf16 v[92:95], v[156:159], v[198:201], v[92:95]
	v_mfma_f32_16x16x32_bf16 v[88:91], v[164:167], v[198:201], v[88:91]
	v_mfma_f32_16x16x32_bf16 v[76:79], v[156:159], v[206:209], v[76:79]
	v_mfma_f32_16x16x32_bf16 v[72:75], v[164:167], v[206:209], v[72:75]
	s_barrier
	s_add_i32 s22, 0, 0x1c000
	s_add_i32 s23, s48, s29
	v_add_u32_e32 v179, s22, v151
	v_lshl_add_u64 v[148:149], v[148:149], 0, s[6:7]
	s_mov_b32 m0, s23
	ds_read_b128 v[210:213], v179
	ds_read_b128 v[214:217], v179 offset:1024
	ds_read_b128 v[218:221], v179 offset:2048
	ds_read_b128 v[222:225], v179 offset:3072
	global_load_lds_dwordx4 v[148:149], off
	v_lshl_add_u64 v[148:149], v[186:187], 0, s[6:7]
	s_add_i32 m0, s23, 0x2000
	s_nop 0
	global_load_lds_dwordx4 v[148:149], off
	s_barrier
	s_waitcnt lgkmcnt(0)
	s_waitcnt lgkmcnt(0)
	v_mfma_f32_16x16x32_bf16 v[116:119], v[210:213], v[168:171], v[116:119]
	v_mfma_f32_16x16x32_bf16 v[112:115], v[218:221], v[168:171], v[112:115]
	v_mfma_f32_16x16x32_bf16 v[100:103], v[210:213], v[182:185], v[100:103]
	v_mfma_f32_16x16x32_bf16 v[96:99], v[218:221], v[182:185], v[96:99]
	v_mfma_f32_16x16x32_bf16 v[84:87], v[210:213], v[194:197], v[84:87]
	v_mfma_f32_16x16x32_bf16 v[80:83], v[218:221], v[194:197], v[80:83]
	v_mfma_f32_16x16x32_bf16 v[68:71], v[210:213], v[202:205], v[68:71]
	v_mfma_f32_16x16x32_bf16 v[64:67], v[218:221], v[202:205], v[64:67]
	v_mfma_f32_16x16x32_bf16 v[116:119], v[214:217], v[172:175], v[116:119]
	v_mfma_f32_16x16x32_bf16 v[112:115], v[222:225], v[172:175], v[112:115]
	v_mfma_f32_16x16x32_bf16 v[100:103], v[214:217], v[190:193], v[100:103]
	v_mfma_f32_16x16x32_bf16 v[96:99], v[222:225], v[190:193], v[96:99]
	v_mfma_f32_16x16x32_bf16 v[84:87], v[214:217], v[198:201], v[84:87]
	v_mfma_f32_16x16x32_bf16 v[80:83], v[222:225], v[198:201], v[80:83]
	v_mfma_f32_16x16x32_bf16 v[68:71], v[214:217], v[206:209], v[68:71]
	v_mfma_f32_16x16x32_bf16 v[64:67], v[222:225], v[206:209], v[64:67]
	s_barrier
	s_mov_b32 m0, s36
	v_lshl_add_u64 v[148:149], v[226:227], 0, s[6:7]
	ds_read_b128 v[168:171], v154 offset:49152
	ds_read_b128 v[172:175], v154 offset:50176
	ds_read_b128 v[182:185], v154 offset:51200
	ds_read_b128 v[190:193], v154 offset:52224
	ds_read_b128 v[194:197], v154 offset:53248
	ds_read_b128 v[198:201], v154 offset:54272
	ds_read_b128 v[202:205], v154 offset:55296
	ds_read_b128 v[206:209], v154 offset:56320
	global_load_lds_dwordx4 v[148:149], off
	v_lshl_add_u64 v[148:149], v[228:229], 0, s[6:7]
	s_mov_b32 m0, s37
	s_nop 0
	global_load_lds_dwordx4 v[148:149], off
	s_barrier
; __device__ __forceinline__ unsigned cvt_pk_bf16(float lo, float hi) { unsigned r; asm volatile("v_cvt_pk_bf16_f32 %0, %1, %2" : "=v"(r) : "v"(lo), "v"(hi)); return r; }
; __device__ __forceinline__ float bf_lo(unsigned u) { return __uint_as_float(u << 16); }
; __device__ __forceinline__ float bf_hi(unsigned u) { return __uint_as_float(u & 0xffff0000u); }
; #define PG8_STAGE(bufoff, gbase, voff) do { _Pragma("unroll") for (int _i = 0; _i < 2; ++_i) \
;         __builtin_amdgcn_global_load_lds((const unsigned*)((const char*)(gbase) + (voff)[_i]), (PG8_LAS unsigned*)(lds + (bufoff) + ldsw + _i * 8192), 16, 0, 0); } while (0)
; #define PG8_WAIT_V(n) asm volatile("s_waitcnt vmcnt(" #n ")" ::: "memory")
; #define PG8_BAR __builtin_amdgcn_s_barrier()
;     __device__ __forceinline__ void operator()(const f32x4 (&acc)[2][2][4][2], const Unit& u, int wr, int wc, int fr, int fq) const {
;     ...
;             for (int m = 0; m < 4; ++m) { const size_t r = (size_t)(row0 + ai * HALF + m * 16); bf16_t* rowp = O + r * ldc + col0; const bf16_t* gp = G + r * ldg + col0;
; #pragma unroll
;                 for (int bj = 0; bj < 2; ++bj) { const u32x4 gw = *(const u32x4*)(gp + bj * HALF);
;                     f32x4 v0 = acc[ai][bj][m][0], v1 = acc[ai][bj][m][1];
;                     v0[0] *= bf_lo(gw.x); v0[1] *= bf_hi(gw.x); v0[2] *= bf_lo(gw.y); v0[3] *= bf_hi(gw.y);
;                     v1[0] *= bf_lo(gw.z); v1[1] *= bf_hi(gw.z); v1[2] *= bf_lo(gw.w); v1[3] *= bf_hi(gw.w);
;                     if (ACCUM) { const u32x4 pw = *(const u32x4*)(rowp + bj * HALF);
;                         v0[0] += bf_lo(pw.x); v0[1] += bf_hi(pw.x); v0[2] += bf_lo(pw.y); v0[3] += bf_hi(pw.y);
;                         v1[0] += bf_lo(pw.z); v1[1] += bf_hi(pw.z); v1[2] += bf_lo(pw.w); v1[3] += bf_hi(pw.w); }
;                     u32x4 w; w.x = cvt_pk_bf16(v0[0], v0[1]); w.y = cvt_pk_bf16(v0[2], v0[3]); w.z = cvt_pk_bf16(v1[0], v1[1]); w.w = cvt_pk_bf16(v1[2], v1[3]);
;                     *(u32x4*)(rowp + bj * HALF) = w; } }
; template <class Epi, class Sched>
; __device__ __forceinline__ void gemm_phase(PG8_LAS unsigned char* lds, const Gemm g, const Sched& S, const Epi& E) {
;     ...
;             PG8_BAR; PG8_WAIT_L(0); PG8_MMA(1, 0, At, B0); PG8_BAR; PG8_SCHED;
;             PG8_STAGE(PG8_SB(1, 1), b3 + hstep, voffB);
;             PG8_WAIT_V(6); PG8_BAR; PG8_MMA(1, 1, At, B1); PG8_BAR;
	s_waitcnt lgkmcnt(0)
	s_waitcnt lgkmcnt(0)
	v_mfma_f32_16x16x32_bf16 v[60:63], v[144:147], v[168:171], v[60:63]
	v_mfma_f32_16x16x32_bf16 v[56:59], v[160:163], v[168:171], v[56:59]
	v_mfma_f32_16x16x32_bf16 v[44:47], v[144:147], v[182:185], v[44:47]
	v_mfma_f32_16x16x32_bf16 v[40:43], v[160:163], v[182:185], v[40:43]
	v_mfma_f32_16x16x32_bf16 v[28:31], v[144:147], v[194:197], v[28:31]
	v_mfma_f32_16x16x32_bf16 v[24:27], v[160:163], v[194:197], v[24:27]
	v_mfma_f32_16x16x32_bf16 v[12:15], v[144:147], v[202:205], v[12:15]
	v_mfma_f32_16x16x32_bf16 v[8:11], v[160:163], v[202:205], v[8:11]
	v_mfma_f32_16x16x32_bf16 v[60:63], v[156:159], v[172:175], v[60:63]
	v_mfma_f32_16x16x32_bf16 v[56:59], v[164:167], v[172:175], v[56:59]
	v_mfma_f32_16x16x32_bf16 v[44:47], v[156:159], v[190:193], v[44:47]
	v_mfma_f32_16x16x32_bf16 v[40:43], v[164:167], v[190:193], v[40:43]
	v_mfma_f32_16x16x32_bf16 v[28:31], v[156:159], v[198:201], v[28:31]
	v_mfma_f32_16x16x32_bf16 v[24:27], v[164:167], v[198:201], v[24:27]
	v_mfma_f32_16x16x32_bf16 v[12:15], v[156:159], v[206:209], v[12:15]
	v_mfma_f32_16x16x32_bf16 v[8:11], v[164:167], v[206:209], v[8:11]
	s_barrier
	s_add_u32 s20, s20, 0x40080
	s_addc_u32 s21, s21, 0
	s_add_i32 s22, s22, s29
	v_lshl_add_u64 v[144:145], s[20:21], 0, v[130:131]
	s_mov_b32 m0, s22
	s_nop 0
	global_load_lds_dwordx4 v[144:145], off
	v_lshl_add_u64 v[144:145], s[20:21], 0, v[134:135]
	s_add_i32 m0, s22, 0x2000
	s_nop 0
	global_load_lds_dwordx4 v[144:145], off
	s_waitcnt vmcnt(6)
	s_barrier
	v_mfma_f32_16x16x32_bf16 v[52:55], v[210:213], v[168:171], v[52:55]
	v_mfma_f32_16x16x32_bf16 v[48:51], v[218:221], v[168:171], v[48:51]
	v_mfma_f32_16x16x32_bf16 v[36:39], v[210:213], v[182:185], v[36:39]
	v_mfma_f32_16x16x32_bf16 v[32:35], v[218:221], v[182:185], v[32:35]
	v_mfma_f32_16x16x32_bf16 v[20:23], v[210:213], v[194:197], v[20:23]
	v_mfma_f32_16x16x32_bf16 v[16:19], v[218:221], v[194:197], v[16:19]
	v_mfma_f32_16x16x32_bf16 v[4:7], v[210:213], v[202:205], v[4:7]
	v_mfma_f32_16x16x32_bf16 v[0:3], v[218:221], v[202:205], v[0:3]
	v_mfma_f32_16x16x32_bf16 v[52:55], v[214:217], v[172:175], v[52:55]
	v_mfma_f32_16x16x32_bf16 v[48:51], v[222:225], v[172:175], v[48:51]
	v_mfma_f32_16x16x32_bf16 v[36:39], v[214:217], v[190:193], v[36:39]
	v_mfma_f32_16x16x32_bf16 v[32:35], v[222:225], v[190:193], v[32:35]
	v_mfma_f32_16x16x32_bf16 v[20:23], v[214:217], v[198:201], v[20:23]
	v_mfma_f32_16x16x32_bf16 v[16:19], v[222:225], v[198:201], v[16:19]
	v_mfma_f32_16x16x32_bf16 v[4:7], v[214:217], v[206:209], v[4:7]
	v_mfma_f32_16x16x32_bf16 v[0:3], v[222:225], v[206:209], v[0:3]
	s_barrier
	s_add_i32 s47, s47, 2
	s_add_u32 s18, s18, 0x100
	s_addc_u32 s19, s19, 0
	s_add_u32 s45, s45, 0x100
	s_addc_u32 s46, s46, 0
	s_cmp_gt_u32 s47, 13
	s_cbranch_scc0 .LBB0_1011
	v_lshl_add_u32 v146, s16, 8, v150
	v_lshl_or_b32 v144, s42, 8, v152
	v_ashrrev_i32_e32 v147, 31, v146
	v_ashrrev_i32_e32 v145, 31, v144
	v_mov_b64_e32 v[148:149], s[4:5]
	v_lshlrev_b64 v[160:161], 11, v[146:147]
	v_lshlrev_b64 v[144:145], 1, v[144:145]
	v_mad_i64_i32 v[156:157], s[18:19], v146, s41, v[148:149]
	v_lshl_add_u64 v[160:161], s[0:1], 0, v[160:161]
	v_lshl_add_u64 v[164:165], v[156:157], 0, v[144:145]
	v_lshl_add_u64 v[166:167], v[160:161], 0, v[144:145]
	global_load_dwordx4 v[156:159], v[164:165], off
	global_load_dwordx4 v[160:163], v[166:167], off
	s_and_b64 vcc, exec, s[2:3]
	s_mov_b32 s42, s8
	s_mov_b32 s16, s10
	s_mov_b64 s[20:21], s[14:15]
	s_waitcnt vmcnt(0)
	v_lshlrev_b32_e32 v147, 16, v156
	v_and_b32_e32 v156, 0xffff0000, v156
	v_lshlrev_b32_e32 v168, 16, v157
	v_and_b32_e32 v157, 0xffff0000, v157
	v_lshlrev_b32_e32 v169, 16, v158
	v_and_b32_e32 v158, 0xffff0000, v158
	v_lshlrev_b32_e32 v170, 16, v159
	v_and_b32_e32 v159, 0xffff0000, v159
	v_lshlrev_b32_e32 v171, 16, v160
	v_and_b32_e32 v160, 0xffff0000, v160
	v_lshlrev_b32_e32 v172, 16, v161
	v_and_b32_e32 v161, 0xffff0000, v161
	v_lshlrev_b32_e32 v173, 16, v162
	v_and_b32_e32 v162, 0xffff0000, v162
	v_lshlrev_b32_e32 v174, 16, v163
	v_and_b32_e32 v163, 0xffff0000, v163
	v_fmac_f32_e32 v171, v124, v147
	v_fmac_f32_e32 v160, v125, v156
	v_fmac_f32_e32 v172, v126, v168
	v_fmac_f32_e32 v161, v127, v157
	v_fmac_f32_e32 v173, v120, v169
	v_fmac_f32_e32 v162, v121, v158
	v_fmac_f32_e32 v174, v122, v170
	v_fmac_f32_e32 v163, v123, v159
	v_cvt_pk_bf16_f32 v120, v171, v160
	v_cvt_pk_bf16_f32 v121, v172, v161
	v_cvt_pk_bf16_f32 v122, v173, v162
	v_cvt_pk_bf16_f32 v123, v174, v163
	global_load_dwordx4 v[124:127], v[164:165], off offset:256
	global_load_dwordx4 v[156:159], v[166:167], off offset:256
	v_or_b32_e32 v160, 16, v146
	global_store_dwordx4 v[166:167], v[120:123], off
	v_mad_i64_i32 v[162:163], s[18:19], v160, s41, v[148:149]
	v_lshl_add_u64 v[162:163], v[162:163], 0, v[144:145]
	s_waitcnt vmcnt(0)
	v_lshlrev_b32_e32 v122, 16, v125
	v_lshlrev_b32_e32 v161, 16, v157
	v_lshlrev_b32_e32 v120, 16, v124
	v_and_b32_e32 v121, 0xffff0000, v124
	v_and_b32_e32 v123, 0xffff0000, v125
	v_lshlrev_b32_e32 v124, 16, v126
	v_and_b32_e32 v125, 0xffff0000, v126
	v_lshlrev_b32_e32 v147, 16, v156
	v_and_b32_e32 v156, 0xffff0000, v156
	v_and_b32_e32 v157, 0xffff0000, v157
	v_lshlrev_b32_e32 v164, 16, v158
	v_and_b32_e32 v158, 0xffff0000, v158
	v_fmac_f32_e32 v161, v118, v122
	v_fmac_f32_e32 v147, v116, v120
	v_fmac_f32_e32 v156, v117, v121
	v_fmac_f32_e32 v157, v119, v123
	v_fmac_f32_e32 v164, v112, v124
	v_fmac_f32_e32 v158, v113, v125
	v_cvt_pk_bf16_f32 v112, v147, v156
	v_cvt_pk_bf16_f32 v113, v161, v157
	v_ashrrev_i32_e32 v161, 31, v160
	v_lshlrev_b64 v[120:121], 11, v[160:161]
	v_lshl_add_u64 v[120:121], s[0:1], 0, v[120:121]
	v_lshlrev_b32_e32 v126, 16, v127
	v_and_b32_e32 v127, 0xffff0000, v127
	v_lshlrev_b32_e32 v165, 16, v159
	v_and_b32_e32 v159, 0xffff0000, v159
	v_lshl_add_u64 v[124:125], v[120:121], 0, v[144:145]
	v_fmac_f32_e32 v165, v114, v126
	v_fmac_f32_e32 v159, v115, v127
	v_cvt_pk_bf16_f32 v114, v164, v158
	v_cvt_pk_bf16_f32 v115, v165, v159
	global_load_dwordx4 v[116:119], v[162:163], off
	global_load_dwordx4 v[120:123], v[124:125], off
	s_waitcnt vmcnt(0)
; __device__ __forceinline__ unsigned cvt_pk_bf16(float lo, float hi) { unsigned r; asm volatile("v_cvt_pk_bf16_f32 %0, %1, %2" : "=v"(r) : "v"(lo), "v"(hi)); return r; }
; __device__ __forceinline__ float bf_lo(unsigned u) { return __uint_as_float(u << 16); }
; __device__ __forceinline__ float bf_hi(unsigned u) { return __uint_as_float(u & 0xffff0000u); }
;     __device__ __forceinline__ void operator()(const f32x4 (&acc)[2][2][4][2], const Unit& u, int wr, int wc, int fr, int fq) const {
;     ...
;             for (int m = 0; m < 4; ++m) { const size_t r = (size_t)(row0 + ai * HALF + m * 16); bf16_t* rowp = O + r * ldc + col0; const bf16_t* gp = G + r * ldg + col0;
; #pragma unroll
;                 for (int bj = 0; bj < 2; ++bj) { const u32x4 gw = *(const u32x4*)(gp + bj * HALF);
;                     f32x4 v0 = acc[ai][bj][m][0], v1 = acc[ai][bj][m][1];
;                     v0[0] *= bf_lo(gw.x); v0[1] *= bf_hi(gw.x); v0[2] *= bf_lo(gw.y); v0[3] *= bf_hi(gw.y);
;                     v1[0] *= bf_lo(gw.z); v1[1] *= bf_hi(gw.z); v1[2] *= bf_lo(gw.w); v1[3] *= bf_hi(gw.w);
;                     if (ACCUM) { const u32x4 pw = *(const u32x4*)(rowp + bj * HALF);
;                         v0[0] += bf_lo(pw.x); v0[1] += bf_hi(pw.x); v0[2] += bf_lo(pw.y); v0[3] += bf_hi(pw.y);
;                         v1[0] += bf_lo(pw.z); v1[1] += bf_hi(pw.z); v1[2] += bf_lo(pw.w); v1[3] += bf_hi(pw.w); }
;                     u32x4 w; w.x = cvt_pk_bf16(v0[0], v0[1]); w.y = cvt_pk_bf16(v0[2], v0[3]); w.z = cvt_pk_bf16(v1[0], v1[1]); w.w = cvt_pk_bf16(v1[2], v1[3]);
;                     *(u32x4*)(rowp + bj * HALF) = w; } }
	v_lshlrev_b32_e32 v126, 16, v120
	global_store_dwordx4 v[166:167], v[112:115], off offset:256
	v_and_b32_e32 v120, 0xffff0000, v120
	v_lshlrev_b32_e32 v127, 16, v121
	v_lshlrev_b32_e32 v112, 16, v116
	v_and_b32_e32 v113, 0xffff0000, v116
	v_lshlrev_b32_e32 v114, 16, v117
	v_and_b32_e32 v115, 0xffff0000, v117
	v_lshlrev_b32_e32 v116, 16, v118
	v_and_b32_e32 v117, 0xffff0000, v118
	v_lshlrev_b32_e32 v118, 16, v119
	v_and_b32_e32 v119, 0xffff0000, v119
	v_and_b32_e32 v121, 0xffff0000, v121
	v_lshlrev_b32_e32 v147, 16, v122
	v_and_b32_e32 v122, 0xffff0000, v122
	v_lshlrev_b32_e32 v156, 16, v123
	v_and_b32_e32 v123, 0xffff0000, v123
	v_fmac_f32_e32 v126, v108, v112
	v_fmac_f32_e32 v120, v109, v113
	v_fmac_f32_e32 v127, v110, v114
	v_fmac_f32_e32 v121, v111, v115
	v_fmac_f32_e32 v147, v104, v116
	v_fmac_f32_e32 v122, v105, v117
	v_fmac_f32_e32 v156, v106, v118
	v_fmac_f32_e32 v123, v107, v119
	v_cvt_pk_bf16_f32 v104, v126, v120
	v_cvt_pk_bf16_f32 v105, v127, v121
	v_cvt_pk_bf16_f32 v106, v147, v122
	v_cvt_pk_bf16_f32 v107, v156, v123
	global_load_dwordx4 v[108:111], v[162:163], off offset:256
	global_load_dwordx4 v[112:115], v[124:125], off offset:256
	v_or_b32_e32 v116, 32, v146
	global_store_dwordx4 v[124:125], v[104:107], off
	v_mad_i64_i32 v[118:119], s[18:19], v116, s41, v[148:149]
	v_lshl_add_u64 v[118:119], v[118:119], 0, v[144:145]
	s_waitcnt vmcnt(0)
	v_lshlrev_b32_e32 v104, 16, v108
	v_lshlrev_b32_e32 v117, 16, v112
	v_and_b32_e32 v105, 0xffff0000, v108
	v_lshlrev_b32_e32 v108, 16, v110
	v_and_b32_e32 v112, 0xffff0000, v112
	v_lshlrev_b32_e32 v121, 16, v114
	v_fmac_f32_e32 v117, v100, v104
	v_fmac_f32_e32 v112, v101, v105
	v_fmac_f32_e32 v121, v96, v108
	v_cvt_pk_bf16_f32 v96, v117, v112
	v_ashrrev_i32_e32 v117, 31, v116
	v_lshlrev_b64 v[104:105], 11, v[116:117]
	v_lshlrev_b32_e32 v106, 16, v109
	v_and_b32_e32 v107, 0xffff0000, v109
	v_and_b32_e32 v109, 0xffff0000, v110
	v_and_b32_e32 v114, 0xffff0000, v114
	v_lshl_add_u64 v[104:105], s[0:1], 0, v[104:105]
	v_lshlrev_b32_e32 v110, 16, v111
	v_and_b32_e32 v111, 0xffff0000, v111
	v_lshlrev_b32_e32 v120, 16, v113
	v_and_b32_e32 v113, 0xffff0000, v113
	v_lshlrev_b32_e32 v122, 16, v115
	v_and_b32_e32 v115, 0xffff0000, v115
	v_fmac_f32_e32 v114, v97, v109
	v_lshl_add_u64 v[108:109], v[104:105], 0, v[144:145]
	v_fmac_f32_e32 v120, v102, v106
	v_fmac_f32_e32 v113, v103, v107
	v_fmac_f32_e32 v122, v98, v110
	v_fmac_f32_e32 v115, v99, v111
	v_cvt_pk_bf16_f32 v97, v120, v113
	v_cvt_pk_bf16_f32 v98, v121, v114
	v_cvt_pk_bf16_f32 v99, v122, v115
	global_load_dwordx4 v[100:103], v[118:119], off
	global_load_dwordx4 v[104:107], v[108:109], off
	s_waitcnt vmcnt(0)
	v_lshlrev_b32_e32 v110, 16, v104
	global_store_dwordx4 v[124:125], v[96:99], off offset:256
	v_and_b32_e32 v104, 0xffff0000, v104
	v_lshlrev_b32_e32 v111, 16, v105
	v_lshlrev_b32_e32 v96, 16, v100
	v_and_b32_e32 v97, 0xffff0000, v100
	v_lshlrev_b32_e32 v98, 16, v101
	v_and_b32_e32 v99, 0xffff0000, v101
	v_lshlrev_b32_e32 v100, 16, v102
	v_and_b32_e32 v101, 0xffff0000, v102
	v_lshlrev_b32_e32 v102, 16, v103
	v_and_b32_e32 v103, 0xffff0000, v103
	v_and_b32_e32 v105, 0xffff0000, v105
	v_lshlrev_b32_e32 v112, 16, v106
	v_and_b32_e32 v106, 0xffff0000, v106
	v_lshlrev_b32_e32 v113, 16, v107
	v_and_b32_e32 v107, 0xffff0000, v107
	v_fmac_f32_e32 v110, v92, v96
	v_fmac_f32_e32 v104, v93, v97
	v_fmac_f32_e32 v111, v94, v98
	v_fmac_f32_e32 v105, v95, v99
	v_fmac_f32_e32 v112, v88, v100
	v_fmac_f32_e32 v106, v89, v101
	v_fmac_f32_e32 v113, v90, v102
	v_fmac_f32_e32 v107, v91, v103
	v_cvt_pk_bf16_f32 v88, v110, v104
	v_cvt_pk_bf16_f32 v89, v111, v105
	v_cvt_pk_bf16_f32 v90, v112, v106
	v_cvt_pk_bf16_f32 v91, v113, v107
	global_load_dwordx4 v[92:95], v[118:119], off offset:256
	global_load_dwordx4 v[96:99], v[108:109], off offset:256
	v_or_b32_e32 v100, 48, v146
	global_store_dwordx4 v[108:109], v[88:91], off
	v_mad_i64_i32 v[102:103], s[18:19], v100, s41, v[148:149]
	v_lshl_add_u64 v[102:103], v[102:103], 0, v[144:145]
	s_waitcnt vmcnt(0)
	v_lshlrev_b32_e32 v88, 16, v92
	v_lshlrev_b32_e32 v101, 16, v96
	v_and_b32_e32 v89, 0xffff0000, v92
	v_lshlrev_b32_e32 v92, 16, v94
	v_and_b32_e32 v96, 0xffff0000, v96
	v_lshlrev_b32_e32 v105, 16, v98
	v_fmac_f32_e32 v101, v84, v88
	v_fmac_f32_e32 v96, v85, v89
	v_fmac_f32_e32 v105, v80, v92
	v_cvt_pk_bf16_f32 v80, v101, v96
	v_ashrrev_i32_e32 v101, 31, v100
	v_lshlrev_b64 v[88:89], 11, v[100:101]
	v_lshlrev_b32_e32 v90, 16, v93
	v_and_b32_e32 v91, 0xffff0000, v93
	v_and_b32_e32 v93, 0xffff0000, v94
	v_and_b32_e32 v98, 0xffff0000, v98
	v_lshl_add_u64 v[88:89], s[0:1], 0, v[88:89]
	v_lshlrev_b32_e32 v94, 16, v95
	v_and_b32_e32 v95, 0xffff0000, v95
	v_lshlrev_b32_e32 v104, 16, v97
	v_and_b32_e32 v97, 0xffff0000, v97
	v_lshlrev_b32_e32 v106, 16, v99
	v_and_b32_e32 v99, 0xffff0000, v99
	v_fmac_f32_e32 v98, v81, v93
	v_lshl_add_u64 v[92:93], v[88:89], 0, v[144:145]
	v_fmac_f32_e32 v104, v86, v90
	v_fmac_f32_e32 v97, v87, v91
	v_fmac_f32_e32 v106, v82, v94
	v_fmac_f32_e32 v99, v83, v95
	v_cvt_pk_bf16_f32 v81, v104, v97
	v_cvt_pk_bf16_f32 v82, v105, v98
	v_cvt_pk_bf16_f32 v83, v106, v99
	global_load_dwordx4 v[84:87], v[102:103], off
	global_load_dwordx4 v[88:91], v[92:93], off
	s_waitcnt vmcnt(0)
; __device__ __forceinline__ unsigned cvt_pk_bf16(float lo, float hi) { unsigned r; asm volatile("v_cvt_pk_bf16_f32 %0, %1, %2" : "=v"(r) : "v"(lo), "v"(hi)); return r; }
; __device__ __forceinline__ float bf_lo(unsigned u) { return __uint_as_float(u << 16); }
; __device__ __forceinline__ float bf_hi(unsigned u) { return __uint_as_float(u & 0xffff0000u); }
;     __device__ __forceinline__ void operator()(const f32x4 (&acc)[2][2][4][2], const Unit& u, int wr, int wc, int fr, int fq) const {
;     ...
;             for (int m = 0; m < 4; ++m) { const size_t r = (size_t)(row0 + ai * HALF + m * 16); bf16_t* rowp = O + r * ldc + col0; const bf16_t* gp = G + r * ldg + col0;
; #pragma unroll
;                 for (int bj = 0; bj < 2; ++bj) { const u32x4 gw = *(const u32x4*)(gp + bj * HALF);
;                     f32x4 v0 = acc[ai][bj][m][0], v1 = acc[ai][bj][m][1];
;                     v0[0] *= bf_lo(gw.x); v0[1] *= bf_hi(gw.x); v0[2] *= bf_lo(gw.y); v0[3] *= bf_hi(gw.y);
;                     v1[0] *= bf_lo(gw.z); v1[1] *= bf_hi(gw.z); v1[2] *= bf_lo(gw.w); v1[3] *= bf_hi(gw.w);
;                     if (ACCUM) { const u32x4 pw = *(const u32x4*)(rowp + bj * HALF);
;                         v0[0] += bf_lo(pw.x); v0[1] += bf_hi(pw.x); v0[2] += bf_lo(pw.y); v0[3] += bf_hi(pw.y);
;                         v1[0] += bf_lo(pw.z); v1[1] += bf_hi(pw.z); v1[2] += bf_lo(pw.w); v1[3] += bf_hi(pw.w); }
;                     u32x4 w; w.x = cvt_pk_bf16(v0[0], v0[1]); w.y = cvt_pk_bf16(v0[2], v0[3]); w.z = cvt_pk_bf16(v1[0], v1[1]); w.w = cvt_pk_bf16(v1[2], v1[3]);
;                     *(u32x4*)(rowp + bj * HALF) = w; } }
	v_lshlrev_b32_e32 v94, 16, v88
	global_store_dwordx4 v[108:109], v[80:83], off offset:256
	v_and_b32_e32 v88, 0xffff0000, v88
	v_lshlrev_b32_e32 v95, 16, v89
	v_lshlrev_b32_e32 v80, 16, v84
	v_and_b32_e32 v81, 0xffff0000, v84
	v_lshlrev_b32_e32 v82, 16, v85
	v_and_b32_e32 v83, 0xffff0000, v85
	v_lshlrev_b32_e32 v84, 16, v86
	v_and_b32_e32 v85, 0xffff0000, v86
	v_lshlrev_b32_e32 v86, 16, v87
	v_and_b32_e32 v87, 0xffff0000, v87
	v_and_b32_e32 v89, 0xffff0000, v89
	v_lshlrev_b32_e32 v96, 16, v90
	v_and_b32_e32 v90, 0xffff0000, v90
	v_lshlrev_b32_e32 v97, 16, v91
	v_and_b32_e32 v91, 0xffff0000, v91
	v_fmac_f32_e32 v94, v76, v80
	v_fmac_f32_e32 v88, v77, v81
	v_fmac_f32_e32 v95, v78, v82
	v_fmac_f32_e32 v89, v79, v83
	v_fmac_f32_e32 v96, v72, v84
	v_fmac_f32_e32 v90, v73, v85
	v_fmac_f32_e32 v97, v74, v86
	v_fmac_f32_e32 v91, v75, v87
	v_cvt_pk_bf16_f32 v72, v94, v88
	v_cvt_pk_bf16_f32 v73, v95, v89
	v_cvt_pk_bf16_f32 v74, v96, v90
	v_cvt_pk_bf16_f32 v75, v97, v91
	global_load_dwordx4 v[76:79], v[102:103], off offset:256
	global_load_dwordx4 v[80:83], v[92:93], off offset:256
	v_add_u32_e32 v84, 0x80, v146
	global_store_dwordx4 v[92:93], v[72:75], off
	v_mad_i64_i32 v[86:87], s[18:19], v84, s41, v[148:149]
	v_lshl_add_u64 v[86:87], v[86:87], 0, v[144:145]
	s_waitcnt vmcnt(0)
	v_lshlrev_b32_e32 v72, 16, v76
	v_lshlrev_b32_e32 v85, 16, v80
	v_and_b32_e32 v73, 0xffff0000, v76
	v_lshlrev_b32_e32 v76, 16, v78
	v_and_b32_e32 v80, 0xffff0000, v80
	v_lshlrev_b32_e32 v89, 16, v82
	v_fmac_f32_e32 v85, v68, v72
	v_fmac_f32_e32 v80, v69, v73
	v_fmac_f32_e32 v89, v64, v76
	v_cvt_pk_bf16_f32 v64, v85, v80
	v_ashrrev_i32_e32 v85, 31, v84
	v_lshlrev_b64 v[72:73], 11, v[84:85]
	v_lshlrev_b32_e32 v74, 16, v77
	v_and_b32_e32 v75, 0xffff0000, v77
	v_and_b32_e32 v77, 0xffff0000, v78
	v_and_b32_e32 v82, 0xffff0000, v82
	v_lshl_add_u64 v[72:73], s[0:1], 0, v[72:73]
	v_lshlrev_b32_e32 v78, 16, v79
	v_and_b32_e32 v79, 0xffff0000, v79
	v_lshlrev_b32_e32 v88, 16, v81
	v_and_b32_e32 v81, 0xffff0000, v81
	v_lshlrev_b32_e32 v90, 16, v83
	v_and_b32_e32 v83, 0xffff0000, v83
	v_fmac_f32_e32 v82, v65, v77
	v_lshl_add_u64 v[76:77], v[72:73], 0, v[144:145]
	v_fmac_f32_e32 v88, v70, v74
	v_fmac_f32_e32 v81, v71, v75
	v_fmac_f32_e32 v90, v66, v78
	v_fmac_f32_e32 v83, v67, v79
	v_cvt_pk_bf16_f32 v65, v88, v81
	v_cvt_pk_bf16_f32 v66, v89, v82
	v_cvt_pk_bf16_f32 v67, v90, v83
	global_load_dwordx4 v[68:71], v[86:87], off
	global_load_dwordx4 v[72:75], v[76:77], off
	s_waitcnt vmcnt(0)
	v_lshlrev_b32_e32 v78, 16, v72
	global_store_dwordx4 v[92:93], v[64:67], off offset:256
	v_and_b32_e32 v72, 0xffff0000, v72
	v_lshlrev_b32_e32 v79, 16, v73
	v_lshlrev_b32_e32 v64, 16, v68
	v_and_b32_e32 v65, 0xffff0000, v68
	v_lshlrev_b32_e32 v66, 16, v69
	v_and_b32_e32 v67, 0xffff0000, v69
	v_lshlrev_b32_e32 v68, 16, v70
	v_and_b32_e32 v69, 0xffff0000, v70
	v_lshlrev_b32_e32 v70, 16, v71
	v_and_b32_e32 v71, 0xffff0000, v71
	v_and_b32_e32 v73, 0xffff0000, v73
	v_lshlrev_b32_e32 v80, 16, v74
	v_and_b32_e32 v74, 0xffff0000, v74
	v_lshlrev_b32_e32 v81, 16, v75
	v_and_b32_e32 v75, 0xffff0000, v75
	v_fmac_f32_e32 v78, v60, v64
	v_fmac_f32_e32 v72, v61, v65
	v_fmac_f32_e32 v79, v62, v66
	v_fmac_f32_e32 v73, v63, v67
	v_fmac_f32_e32 v80, v56, v68
	v_fmac_f32_e32 v74, v57, v69
	v_fmac_f32_e32 v81, v58, v70
	v_fmac_f32_e32 v75, v59, v71
	v_cvt_pk_bf16_f32 v56, v78, v72
	v_cvt_pk_bf16_f32 v57, v79, v73
	v_cvt_pk_bf16_f32 v58, v80, v74
	v_cvt_pk_bf16_f32 v59, v81, v75
	global_load_dwordx4 v[60:63], v[86:87], off offset:256
	global_load_dwordx4 v[64:67], v[76:77], off offset:256
	v_add_u32_e32 v68, 0x90, v146
	global_store_dwordx4 v[76:77], v[56:59], off
	v_mad_i64_i32 v[70:71], s[18:19], v68, s41, v[148:149]
	v_lshl_add_u64 v[70:71], v[70:71], 0, v[144:145]
	s_waitcnt vmcnt(0)
	v_lshlrev_b32_e32 v56, 16, v60
	v_lshlrev_b32_e32 v69, 16, v64
	v_and_b32_e32 v57, 0xffff0000, v60
	v_lshlrev_b32_e32 v60, 16, v62
	v_and_b32_e32 v64, 0xffff0000, v64
	v_lshlrev_b32_e32 v73, 16, v66
	v_fmac_f32_e32 v69, v52, v56
	v_fmac_f32_e32 v64, v53, v57
	v_fmac_f32_e32 v73, v48, v60
	v_cvt_pk_bf16_f32 v48, v69, v64
	v_ashrrev_i32_e32 v69, 31, v68
	v_lshlrev_b64 v[56:57], 11, v[68:69]
	v_lshlrev_b32_e32 v58, 16, v61
	v_and_b32_e32 v59, 0xffff0000, v61
	v_and_b32_e32 v61, 0xffff0000, v62
	v_and_b32_e32 v66, 0xffff0000, v66
	v_lshl_add_u64 v[56:57], s[0:1], 0, v[56:57]
	v_lshlrev_b32_e32 v62, 16, v63
	v_and_b32_e32 v63, 0xffff0000, v63
	v_lshlrev_b32_e32 v72, 16, v65
	v_and_b32_e32 v65, 0xffff0000, v65
	v_lshlrev_b32_e32 v74, 16, v67
	v_and_b32_e32 v67, 0xffff0000, v67
	v_fmac_f32_e32 v66, v49, v61
	v_lshl_add_u64 v[60:61], v[56:57], 0, v[144:145]
	v_fmac_f32_e32 v72, v54, v58
	v_fmac_f32_e32 v65, v55, v59
	v_fmac_f32_e32 v74, v50, v62
	v_fmac_f32_e32 v67, v51, v63
	v_cvt_pk_bf16_f32 v49, v72, v65
	v_cvt_pk_bf16_f32 v50, v73, v66
	v_cvt_pk_bf16_f32 v51, v74, v67
	global_load_dwordx4 v[52:55], v[70:71], off
	global_load_dwordx4 v[56:59], v[60:61], off
	s_waitcnt vmcnt(0)
	v_lshlrev_b32_e32 v62, 16, v56
	global_store_dwordx4 v[76:77], v[48:51], off offset:256
	v_and_b32_e32 v56, 0xffff0000, v56
	v_lshlrev_b32_e32 v63, 16, v57
	v_lshlrev_b32_e32 v48, 16, v52
	v_and_b32_e32 v49, 0xffff0000, v52
	v_lshlrev_b32_e32 v50, 16, v53
	v_and_b32_e32 v51, 0xffff0000, v53
	v_lshlrev_b32_e32 v52, 16, v54
	v_and_b32_e32 v53, 0xffff0000, v54
	v_lshlrev_b32_e32 v54, 16, v55
	v_and_b32_e32 v55, 0xffff0000, v55
	v_and_b32_e32 v57, 0xffff0000, v57
	v_lshlrev_b32_e32 v64, 16, v58
	v_and_b32_e32 v58, 0xffff0000, v58
	v_lshlrev_b32_e32 v65, 16, v59
	v_and_b32_e32 v59, 0xffff0000, v59
	v_fmac_f32_e32 v62, v44, v48
	v_fmac_f32_e32 v56, v45, v49
	v_fmac_f32_e32 v63, v46, v50
	v_fmac_f32_e32 v57, v47, v51
	v_fmac_f32_e32 v64, v40, v52
	v_fmac_f32_e32 v58, v41, v53
	v_fmac_f32_e32 v65, v42, v54
	v_fmac_f32_e32 v59, v43, v55
	v_cvt_pk_bf16_f32 v40, v62, v56
	v_cvt_pk_bf16_f32 v41, v63, v57
	v_cvt_pk_bf16_f32 v42, v64, v58
	v_cvt_pk_bf16_f32 v43, v65, v59
	global_load_dwordx4 v[44:47], v[70:71], off offset:256
	global_load_dwordx4 v[48:51], v[60:61], off offset:256
	v_add_u32_e32 v52, 0xa0, v146
	global_store_dwordx4 v[60:61], v[40:43], off
	v_mad_i64_i32 v[54:55], s[18:19], v52, s41, v[148:149]
	v_lshl_add_u64 v[54:55], v[54:55], 0, v[144:145]
	s_waitcnt vmcnt(0)
; __device__ __forceinline__ unsigned cvt_pk_bf16(float lo, float hi) { unsigned r; asm volatile("v_cvt_pk_bf16_f32 %0, %1, %2" : "=v"(r) : "v"(lo), "v"(hi)); return r; }
; __device__ __forceinline__ float bf_lo(unsigned u) { return __uint_as_float(u << 16); }
; __device__ __forceinline__ float bf_hi(unsigned u) { return __uint_as_float(u & 0xffff0000u); }
; #define PG8_WAIT_V(n) asm volatile("s_waitcnt vmcnt(" #n ")" ::: "memory")
; #define PG8_BAR __builtin_amdgcn_s_barrier()
;     __device__ __forceinline__ void operator()(const f32x4 (&acc)[2][2][4][2], const Unit& u, int wr, int wc, int fr, int fq) const {
;     ...
;             for (int m = 0; m < 4; ++m) { const size_t r = (size_t)(row0 + ai * HALF + m * 16); bf16_t* rowp = O + r * ldc + col0; const bf16_t* gp = G + r * ldg + col0;
; #pragma unroll
;                 for (int bj = 0; bj < 2; ++bj) { const u32x4 gw = *(const u32x4*)(gp + bj * HALF);
;                     f32x4 v0 = acc[ai][bj][m][0], v1 = acc[ai][bj][m][1];
;                     v0[0] *= bf_lo(gw.x); v0[1] *= bf_hi(gw.x); v0[2] *= bf_lo(gw.y); v0[3] *= bf_hi(gw.y);
;                     v1[0] *= bf_lo(gw.z); v1[1] *= bf_hi(gw.z); v1[2] *= bf_lo(gw.w); v1[3] *= bf_hi(gw.w);
;                     if (ACCUM) { const u32x4 pw = *(const u32x4*)(rowp + bj * HALF);
;                         v0[0] += bf_lo(pw.x); v0[1] += bf_hi(pw.x); v0[2] += bf_lo(pw.y); v0[3] += bf_hi(pw.y);
;                         v1[0] += bf_lo(pw.z); v1[1] += bf_hi(pw.z); v1[2] += bf_lo(pw.w); v1[3] += bf_hi(pw.w); }
;                     u32x4 w; w.x = cvt_pk_bf16(v0[0], v0[1]); w.y = cvt_pk_bf16(v0[2], v0[3]); w.z = cvt_pk_bf16(v1[0], v1[1]); w.w = cvt_pk_bf16(v1[2], v1[3]);
;                     *(u32x4*)(rowp + bj * HALF) = w; } }
; template <class Epi, class Sched>
; __device__ __forceinline__ void gemm_phase(PG8_LAS unsigned char* lds, const Gemm g, const Sched& S, const Epi& E) {
;     ...
;         if (!has_next) break;
; #pragma unroll
;         for (int a = 0; a < 2; ++a)
; #pragma unroll
;             for (int b = 0; b < 2; ++b)
; #pragma unroll
;                 for (int m = 0; m < 4; ++m)
; #pragma unroll
;                     for (int n = 0; n < 2; ++n) acc[a][b][m][n] = (f32x4){0.f, 0.f, 0.f, 0.f};
;         cur = nxt; cA = nA; cB = nB; ++ui;
;     }
;     PG8_WAIT_V(0);
;     if (wr == 0) PG8_BAR;
;     PG8_BAR;
	v_lshlrev_b32_e32 v40, 16, v44
	v_lshlrev_b32_e32 v53, 16, v48
	v_and_b32_e32 v41, 0xffff0000, v44
	v_lshlrev_b32_e32 v44, 16, v46
	v_and_b32_e32 v48, 0xffff0000, v48
	v_lshlrev_b32_e32 v57, 16, v50
	v_fmac_f32_e32 v53, v36, v40
	v_fmac_f32_e32 v48, v37, v41
	v_fmac_f32_e32 v57, v32, v44
	v_cvt_pk_bf16_f32 v32, v53, v48
	v_ashrrev_i32_e32 v53, 31, v52
	v_lshlrev_b64 v[40:41], 11, v[52:53]
	v_lshlrev_b32_e32 v42, 16, v45
	v_and_b32_e32 v43, 0xffff0000, v45
	v_and_b32_e32 v45, 0xffff0000, v46
	v_and_b32_e32 v50, 0xffff0000, v50
	v_lshl_add_u64 v[40:41], s[0:1], 0, v[40:41]
	v_lshlrev_b32_e32 v46, 16, v47
	v_and_b32_e32 v47, 0xffff0000, v47
	v_lshlrev_b32_e32 v56, 16, v49
	v_and_b32_e32 v49, 0xffff0000, v49
	v_lshlrev_b32_e32 v58, 16, v51
	v_and_b32_e32 v51, 0xffff0000, v51
	v_fmac_f32_e32 v50, v33, v45
	v_lshl_add_u64 v[44:45], v[40:41], 0, v[144:145]
	v_fmac_f32_e32 v56, v38, v42
	v_fmac_f32_e32 v49, v39, v43
	v_fmac_f32_e32 v58, v34, v46
	v_fmac_f32_e32 v51, v35, v47
	v_cvt_pk_bf16_f32 v33, v56, v49
	v_cvt_pk_bf16_f32 v34, v57, v50
	v_cvt_pk_bf16_f32 v35, v58, v51
	global_load_dwordx4 v[36:39], v[54:55], off
	global_load_dwordx4 v[40:43], v[44:45], off
	s_waitcnt vmcnt(0)
	v_lshlrev_b32_e32 v46, 16, v40
	global_store_dwordx4 v[60:61], v[32:35], off offset:256
	v_and_b32_e32 v40, 0xffff0000, v40
	v_lshlrev_b32_e32 v47, 16, v41
	v_lshlrev_b32_e32 v32, 16, v36
	v_and_b32_e32 v33, 0xffff0000, v36
	v_lshlrev_b32_e32 v34, 16, v37
	v_and_b32_e32 v35, 0xffff0000, v37
	v_lshlrev_b32_e32 v36, 16, v38
	v_and_b32_e32 v37, 0xffff0000, v38
	v_lshlrev_b32_e32 v38, 16, v39
	v_and_b32_e32 v39, 0xffff0000, v39
	v_and_b32_e32 v41, 0xffff0000, v41
	v_lshlrev_b32_e32 v48, 16, v42
	v_and_b32_e32 v42, 0xffff0000, v42
	v_lshlrev_b32_e32 v49, 16, v43
	v_and_b32_e32 v43, 0xffff0000, v43
	v_fmac_f32_e32 v46, v28, v32
	v_fmac_f32_e32 v40, v29, v33
	v_fmac_f32_e32 v47, v30, v34
	v_fmac_f32_e32 v41, v31, v35
	v_fmac_f32_e32 v48, v24, v36
	v_fmac_f32_e32 v42, v25, v37
	v_fmac_f32_e32 v49, v26, v38
	v_fmac_f32_e32 v43, v27, v39
	v_cvt_pk_bf16_f32 v24, v46, v40
	v_cvt_pk_bf16_f32 v25, v47, v41
	v_cvt_pk_bf16_f32 v26, v48, v42
	v_cvt_pk_bf16_f32 v27, v49, v43
	global_load_dwordx4 v[28:31], v[54:55], off offset:256
	global_load_dwordx4 v[32:35], v[44:45], off offset:256
	v_add_u32_e32 v36, 0xb0, v146
	global_store_dwordx4 v[44:45], v[24:27], off
	v_mad_i64_i32 v[38:39], s[18:19], v36, s41, v[148:149]
	v_lshl_add_u64 v[38:39], v[38:39], 0, v[144:145]
	s_mov_b64 s[18:19], s[12:13]
	s_waitcnt vmcnt(0)
	v_lshlrev_b32_e32 v24, 16, v28
	v_lshlrev_b32_e32 v37, 16, v32
	v_and_b32_e32 v25, 0xffff0000, v28
	v_lshlrev_b32_e32 v28, 16, v30
	v_and_b32_e32 v32, 0xffff0000, v32
	v_lshlrev_b32_e32 v41, 16, v34
	v_fmac_f32_e32 v37, v20, v24
	v_fmac_f32_e32 v32, v21, v25
	v_fmac_f32_e32 v41, v16, v28
	v_cvt_pk_bf16_f32 v16, v37, v32
	v_ashrrev_i32_e32 v37, 31, v36
	v_lshlrev_b64 v[24:25], 11, v[36:37]
	v_lshlrev_b32_e32 v26, 16, v29
	v_and_b32_e32 v27, 0xffff0000, v29
	v_and_b32_e32 v29, 0xffff0000, v30
	v_and_b32_e32 v34, 0xffff0000, v34
	v_lshl_add_u64 v[24:25], s[0:1], 0, v[24:25]
	v_lshlrev_b32_e32 v30, 16, v31
	v_and_b32_e32 v31, 0xffff0000, v31
	v_lshlrev_b32_e32 v40, 16, v33
	v_and_b32_e32 v33, 0xffff0000, v33
	v_lshlrev_b32_e32 v42, 16, v35
	v_and_b32_e32 v35, 0xffff0000, v35
	v_fmac_f32_e32 v34, v17, v29
	v_lshl_add_u64 v[28:29], v[24:25], 0, v[144:145]
	v_fmac_f32_e32 v40, v22, v26
	v_fmac_f32_e32 v33, v23, v27
	v_fmac_f32_e32 v42, v18, v30
	v_fmac_f32_e32 v35, v19, v31
	v_cvt_pk_bf16_f32 v17, v40, v33
	v_cvt_pk_bf16_f32 v18, v41, v34
	v_cvt_pk_bf16_f32 v19, v42, v35
	global_load_dwordx4 v[20:23], v[38:39], off
	global_load_dwordx4 v[24:27], v[28:29], off
	s_waitcnt vmcnt(0)
	v_lshlrev_b32_e32 v30, 16, v24
	global_store_dwordx4 v[44:45], v[16:19], off offset:256
	v_and_b32_e32 v24, 0xffff0000, v24
	v_lshlrev_b32_e32 v31, 16, v25
	v_lshlrev_b32_e32 v16, 16, v20
	v_and_b32_e32 v17, 0xffff0000, v20
	v_lshlrev_b32_e32 v18, 16, v21
	v_and_b32_e32 v19, 0xffff0000, v21
	v_lshlrev_b32_e32 v20, 16, v22
	v_and_b32_e32 v21, 0xffff0000, v22
	v_lshlrev_b32_e32 v22, 16, v23
	v_and_b32_e32 v23, 0xffff0000, v23
	v_and_b32_e32 v25, 0xffff0000, v25
	v_lshlrev_b32_e32 v32, 16, v26
	v_and_b32_e32 v26, 0xffff0000, v26
	v_lshlrev_b32_e32 v33, 16, v27
	v_and_b32_e32 v27, 0xffff0000, v27
	v_fmac_f32_e32 v30, v12, v16
	v_fmac_f32_e32 v24, v13, v17
	v_fmac_f32_e32 v31, v14, v18
	v_fmac_f32_e32 v25, v15, v19
	v_fmac_f32_e32 v32, v8, v20
	v_fmac_f32_e32 v26, v9, v21
	v_fmac_f32_e32 v33, v10, v22
	v_fmac_f32_e32 v27, v11, v23
	v_cvt_pk_bf16_f32 v8, v30, v24
	v_cvt_pk_bf16_f32 v9, v31, v25
	v_cvt_pk_bf16_f32 v10, v32, v26
	v_cvt_pk_bf16_f32 v11, v33, v27
	global_load_dwordx4 v[12:15], v[38:39], off offset:256
	global_load_dwordx4 v[16:19], v[28:29], off offset:256
	s_waitcnt vmcnt(0)
	v_lshlrev_b32_e32 v20, 16, v16
	global_store_dwordx4 v[28:29], v[8:11], off
	v_and_b32_e32 v16, 0xffff0000, v16
	v_lshlrev_b32_e32 v21, 16, v17
	v_lshlrev_b32_e32 v8, 16, v12
	v_and_b32_e32 v9, 0xffff0000, v12
	v_lshlrev_b32_e32 v10, 16, v13
	v_and_b32_e32 v11, 0xffff0000, v13
	v_lshlrev_b32_e32 v12, 16, v14
	v_and_b32_e32 v13, 0xffff0000, v14
	v_lshlrev_b32_e32 v14, 16, v15
	v_and_b32_e32 v15, 0xffff0000, v15
	v_and_b32_e32 v17, 0xffff0000, v17
	v_lshlrev_b32_e32 v22, 16, v18
	v_and_b32_e32 v18, 0xffff0000, v18
	v_lshlrev_b32_e32 v23, 16, v19
	v_and_b32_e32 v19, 0xffff0000, v19
	v_fmac_f32_e32 v20, v4, v8
	v_fmac_f32_e32 v16, v5, v9
	v_fmac_f32_e32 v21, v6, v10
	v_fmac_f32_e32 v17, v7, v11
	v_fmac_f32_e32 v22, v0, v12
	v_fmac_f32_e32 v18, v1, v13
	v_fmac_f32_e32 v23, v2, v14
	v_fmac_f32_e32 v19, v3, v15
	v_cvt_pk_bf16_f32 v0, v20, v16
	v_cvt_pk_bf16_f32 v1, v21, v17
	v_cvt_pk_bf16_f32 v2, v22, v18
	v_cvt_pk_bf16_f32 v3, v23, v19
	global_store_dwordx4 v[28:29], v[0:3], off offset:256
	s_cbranch_vccz .LBB0_1004
	s_waitcnt vmcnt(0)
	s_cmpk_gt_u32 s25, 0xff
	s_cbranch_scc1 .LBB0_1015
	s_barrier

; #define PG8_STAGE(bufoff, gbase, voff) do { _Pragma("unroll") for (int _i = 0; _i < 2; ++_i) \
;         __builtin_amdgcn_global_load_lds((const unsigned*)((const char*)(gbase) + (voff)[_i]), (PG8_LAS unsigned*)(lds + (bufoff) + ldsw + _i * 8192), 16, 0, 0); } while (0)
; #define PG8_LDA(dst, b, h) do { _Pragma("unroll") for (int m = 0; m < 4; ++m) _Pragma("unroll") for (int k = 0; k < 2; ++k) dst[m][k] = *(const PG8_LAS bf16x8*)(lds + PG8_SA(b, h) + aoff + m * 2048 + k * 1024); } while (0)
; #define PG8_LDB(dst, b, h) do { _Pragma("unroll") for (int n = 0; n < 2; ++n) _Pragma("unroll") for (int k = 0; k < 2; ++k) dst[n][k] = *(const PG8_LAS bf16x8*)(lds + PG8_SB(b, h) + boff + n * 2048 + k * 1024); } while (0)
; #define PG8_MMA(ai, bj, At, Bt) do { __builtin_amdgcn_s_setprio(1); _Pragma("unroll") for (int m = 0; m < 4; ++m) _Pragma("unroll") for (int n = 0; n < 2; ++n) _Pragma("unroll") for (int k = 0; k < 2; ++k) \
;         acc[ai][bj][m][n] = __builtin_amdgcn_mfma_f32_16x16x32_bf16(Bt[n][k], At[m][k], acc[ai][bj][m][n], 0, 0, 0); __builtin_amdgcn_s_setprio(0); } while (0)
; #define PG8_WAIT_L(n) asm volatile("s_waitcnt lgkmcnt(" #n ")" ::: "memory")
; #define PG8_BAR __builtin_amdgcn_s_barrier()
; #define PG8_SCHED __builtin_amdgcn_sched_barrier(0)
; template <class Epi, class Sched>
; __device__ __forceinline__ void gemm_phase(PG8_LAS unsigned char* lds, const Gemm g, const Sched& S, const Epi& E) {
;     ...
;             const bool last = (t == nt - 2);
;             const char* a1 = cA + (size_t)(t + 1) * kstep;
;             const char* a2 = last ? nA : cA + (size_t)(t + 2) * kstep; const char* b2 = last ? nB : cB + (size_t)(t + 2) * kstep;
;             const char* a3 = a2 + kstep; const char* b3 = b2 + kstep;
;             if (last && has_next) S.a_ready(nxt);
;             PG8_LDB(B0, 0, 0); PG8_SCHED; PG8_LDA(At, 0, 0); PG8_STAGE(PG8_SA(1, 1), a1 + hstep, voffA);
;             PG8_WAIT_L(8); PG8_BAR; PG8_WAIT_L(0); PG8_MMA(0, 0, At, B0); PG8_BAR; PG8_SCHED;
;             PG8_LDB(B1, 0, 1); PG8_STAGE(PG8_SB(0, 0), b2, voffB);
;             PG8_BAR; PG8_WAIT_L(0); PG8_MMA(0, 1, At, B1); PG8_BAR;
;             PG8_LDA(At, 0, 1); PG8_STAGE(PG8_SA(0, 0), a2, voffA);
;             PG8_BAR; PG8_WAIT_L(0); PG8_MMA(1, 0, At, B0); PG8_BAR; PG8_SCHED;
.LBB0_1083:
	ds_read_b128 v[152:155], v149
	ds_read_b128 v[156:159], v149 offset:1024
	ds_read_b128 v[160:163], v149 offset:2048
	ds_read_b128 v[164:167], v149 offset:3072
	s_add_u32 s26, s24, 0xfffc0080
	s_addc_u32 s27, s25, -1
	s_cmp_eq_u32 s56, 12
	s_cselect_b32 s29, s17, s27
	s_cselect_b32 s28, s52, s26
	s_cselect_b32 s27, s15, s55
	s_cselect_b32 s26, s53, s54
	v_lshl_add_u64 v[144:145], s[24:25], 0, v[136:137]
	s_add_i32 m0, s23, 0xc000
	ds_read_b128 v[168:171], v150
	ds_read_b128 v[172:175], v150 offset:1024
	ds_read_b128 v[182:185], v150 offset:2048
	ds_read_b128 v[190:193], v150 offset:3072
	ds_read_b128 v[194:197], v150 offset:4096
	ds_read_b128 v[198:201], v150 offset:5120
	ds_read_b128 v[202:205], v150 offset:6144
	ds_read_b128 v[206:209], v150 offset:7168
	global_load_lds_dwordx4 v[144:145], off
	v_lshl_add_u64 v[144:145], s[24:25], 0, v[138:139]
	s_add_i32 m0, s23, 0xe000
	s_nop 0
	global_load_lds_dwordx4 v[144:145], off
	s_waitcnt lgkmcnt(8)
	s_barrier
	s_waitcnt lgkmcnt(0)
	s_waitcnt lgkmcnt(0)
	v_mfma_f32_16x16x32_bf16 v[124:127], v[152:155], v[168:171], v[124:127]
	v_mfma_f32_16x16x32_bf16 v[120:123], v[160:163], v[168:171], v[120:123]
	v_mfma_f32_16x16x32_bf16 v[108:111], v[152:155], v[182:185], v[108:111]
	v_mfma_f32_16x16x32_bf16 v[104:107], v[160:163], v[182:185], v[104:107]
	v_mfma_f32_16x16x32_bf16 v[92:95], v[152:155], v[194:197], v[92:95]
	v_mfma_f32_16x16x32_bf16 v[88:91], v[160:163], v[194:197], v[88:91]
	v_mfma_f32_16x16x32_bf16 v[76:79], v[152:155], v[202:205], v[76:79]
	v_mfma_f32_16x16x32_bf16 v[72:75], v[160:163], v[202:205], v[72:75]
	v_mfma_f32_16x16x32_bf16 v[124:127], v[156:159], v[172:175], v[124:127]
	v_mfma_f32_16x16x32_bf16 v[120:123], v[164:167], v[172:175], v[120:123]
	v_mfma_f32_16x16x32_bf16 v[108:111], v[156:159], v[190:193], v[108:111]
	v_mfma_f32_16x16x32_bf16 v[104:107], v[164:167], v[190:193], v[104:107]
	v_mfma_f32_16x16x32_bf16 v[92:95], v[156:159], v[198:201], v[92:95]
	v_mfma_f32_16x16x32_bf16 v[88:91], v[164:167], v[198:201], v[88:91]
	v_mfma_f32_16x16x32_bf16 v[76:79], v[156:159], v[206:209], v[76:79]
	v_mfma_f32_16x16x32_bf16 v[72:75], v[164:167], v[206:209], v[72:75]
	s_barrier
	s_add_i32 s57, s45, s37
	v_lshl_add_u64 v[144:145], s[26:27], 0, v[130:131]
	s_mov_b32 m0, s57
	ds_read_b128 v[210:213], v151
	ds_read_b128 v[214:217], v151 offset:1024
	ds_read_b128 v[218:221], v151 offset:2048
	ds_read_b128 v[222:225], v151 offset:3072
	global_load_lds_dwordx4 v[144:145], off
	v_lshl_add_u64 v[186:187], s[26:27], 0, v[134:135]
	s_add_i32 m0, s57, 0x2000
	s_nop 0
	global_load_lds_dwordx4 v[186:187], off
	s_barrier
	s_waitcnt lgkmcnt(0)
	s_waitcnt lgkmcnt(0)
	v_mfma_f32_16x16x32_bf16 v[116:119], v[210:213], v[168:171], v[116:119]
	v_mfma_f32_16x16x32_bf16 v[112:115], v[218:221], v[168:171], v[112:115]
	v_mfma_f32_16x16x32_bf16 v[100:103], v[210:213], v[182:185], v[100:103]
	v_mfma_f32_16x16x32_bf16 v[96:99], v[218:221], v[182:185], v[96:99]
	v_mfma_f32_16x16x32_bf16 v[84:87], v[210:213], v[194:197], v[84:87]
	v_mfma_f32_16x16x32_bf16 v[80:83], v[218:221], v[194:197], v[80:83]
	v_mfma_f32_16x16x32_bf16 v[68:71], v[210:213], v[202:205], v[68:71]
	v_mfma_f32_16x16x32_bf16 v[64:67], v[218:221], v[202:205], v[64:67]
	v_mfma_f32_16x16x32_bf16 v[116:119], v[214:217], v[172:175], v[116:119]
	v_mfma_f32_16x16x32_bf16 v[112:115], v[222:225], v[172:175], v[112:115]
	v_mfma_f32_16x16x32_bf16 v[100:103], v[214:217], v[190:193], v[100:103]
	v_mfma_f32_16x16x32_bf16 v[96:99], v[222:225], v[190:193], v[96:99]
	v_mfma_f32_16x16x32_bf16 v[84:87], v[214:217], v[198:201], v[84:87]
	v_mfma_f32_16x16x32_bf16 v[80:83], v[222:225], v[198:201], v[80:83]
	v_mfma_f32_16x16x32_bf16 v[68:71], v[214:217], v[206:209], v[68:71]
	v_mfma_f32_16x16x32_bf16 v[64:67], v[222:225], v[206:209], v[64:67]
	s_barrier
	s_mov_b32 m0, s23
	v_lshl_add_u64 v[226:227], s[28:29], 0, v[128:129]
	ds_read_b128 v[168:171], v150 offset:16384
	ds_read_b128 v[172:175], v150 offset:17408
	ds_read_b128 v[182:185], v150 offset:18432
	ds_read_b128 v[190:193], v150 offset:19456
	ds_read_b128 v[194:197], v150 offset:20480
	ds_read_b128 v[198:201], v150 offset:21504
	ds_read_b128 v[202:205], v150 offset:22528
	ds_read_b128 v[206:209], v150 offset:23552
	global_load_lds_dwordx4 v[226:227], off
	v_lshl_add_u64 v[228:229], s[28:29], 0, v[132:133]
	s_mov_b32 m0, s38
	s_nop 0
	global_load_lds_dwordx4 v[228:229], off
	s_barrier
	s_waitcnt lgkmcnt(0)
	s_waitcnt lgkmcnt(0)
	v_mfma_f32_16x16x32_bf16 v[60:63], v[152:155], v[168:171], v[60:63]
	v_mfma_f32_16x16x32_bf16 v[56:59], v[160:163], v[168:171], v[56:59]
	v_mfma_f32_16x16x32_bf16 v[48:51], v[152:155], v[182:185], v[48:51]
	v_mfma_f32_16x16x32_bf16 v[40:43], v[160:163], v[182:185], v[40:43]
	v_mfma_f32_16x16x32_bf16 v[32:35], v[152:155], v[194:197], v[32:35]
	v_mfma_f32_16x16x32_bf16 v[24:27], v[160:163], v[194:197], v[24:27]
	v_mfma_f32_16x16x32_bf16 v[16:19], v[152:155], v[202:205], v[16:19]
	v_mfma_f32_16x16x32_bf16 v[8:11], v[160:163], v[202:205], v[8:11]
	v_mfma_f32_16x16x32_bf16 v[60:63], v[156:159], v[172:175], v[60:63]
	v_mfma_f32_16x16x32_bf16 v[56:59], v[164:167], v[172:175], v[56:59]
	v_mfma_f32_16x16x32_bf16 v[48:51], v[156:159], v[190:193], v[48:51]
	v_mfma_f32_16x16x32_bf16 v[40:43], v[164:167], v[190:193], v[40:43]
	v_mfma_f32_16x16x32_bf16 v[32:35], v[156:159], v[198:201], v[32:35]
	v_mfma_f32_16x16x32_bf16 v[24:27], v[164:167], v[198:201], v[24:27]
	v_mfma_f32_16x16x32_bf16 v[16:19], v[156:159], v[206:209], v[16:19]
	v_mfma_f32_16x16x32_bf16 v[8:11], v[164:167], v[206:209], v[8:11]
	s_barrier
; #define PG8_STAGE(bufoff, gbase, voff) do { _Pragma("unroll") for (int _i = 0; _i < 2; ++_i) \
;         __builtin_amdgcn_global_load_lds((const unsigned*)((const char*)(gbase) + (voff)[_i]), (PG8_LAS unsigned*)(lds + (bufoff) + ldsw + _i * 8192), 16, 0, 0); } while (0)
; #define PG8_LDA(dst, b, h) do { _Pragma("unroll") for (int m = 0; m < 4; ++m) _Pragma("unroll") for (int k = 0; k < 2; ++k) dst[m][k] = *(const PG8_LAS bf16x8*)(lds + PG8_SA(b, h) + aoff + m * 2048 + k * 1024); } while (0)
; #define PG8_LDB(dst, b, h) do { _Pragma("unroll") for (int n = 0; n < 2; ++n) _Pragma("unroll") for (int k = 0; k < 2; ++k) dst[n][k] = *(const PG8_LAS bf16x8*)(lds + PG8_SB(b, h) + boff + n * 2048 + k * 1024); } while (0)
; #define PG8_MMA(ai, bj, At, Bt) do { __builtin_amdgcn_s_setprio(1); _Pragma("unroll") for (int m = 0; m < 4; ++m) _Pragma("unroll") for (int n = 0; n < 2; ++n) _Pragma("unroll") for (int k = 0; k < 2; ++k) \
;         acc[ai][bj][m][n] = __builtin_amdgcn_mfma_f32_16x16x32_bf16(Bt[n][k], At[m][k], acc[ai][bj][m][n], 0, 0, 0); __builtin_amdgcn_s_setprio(0); } while (0)
; #define PG8_WAIT_V(n) asm volatile("s_waitcnt vmcnt(" #n ")" ::: "memory")
; #define PG8_WAIT_L(n) asm volatile("s_waitcnt lgkmcnt(" #n ")" ::: "memory")
; #define PG8_BAR __builtin_amdgcn_s_barrier()
; #define PG8_SCHED __builtin_amdgcn_sched_barrier(0)
; template <class Epi, class Sched>
; __device__ __forceinline__ void gemm_phase(PG8_LAS unsigned char* lds, const Gemm g, const Sched& S, const Epi& E) {
;     ...
;             PG8_STAGE(PG8_SB(0, 1), b2 + hstep, voffB);
;             PG8_WAIT_V(6); PG8_BAR; PG8_MMA(1, 1, At, B1); PG8_BAR;
;             PG8_LDB(B0, 1, 0); PG8_SCHED; PG8_LDA(At, 1, 0); PG8_STAGE(PG8_SA(0, 1), a2 + hstep, voffA);
;             PG8_WAIT_L(8); PG8_BAR; PG8_WAIT_L(0); PG8_MMA(0, 0, At, B0); PG8_BAR; PG8_SCHED;
;             PG8_LDB(B1, 1, 1); PG8_STAGE(PG8_SB(1, 0), b3, voffB);
;             PG8_BAR; PG8_WAIT_L(0); PG8_MMA(0, 1, At, B1); PG8_BAR;
;             PG8_LDA(At, 1, 1); PG8_STAGE(PG8_SA(1, 0), a3, voffA);
	s_add_u32 s58, s26, 0x40000
	s_addc_u32 s59, s27, 0
	s_add_i32 s57, s46, s37
	v_lshl_add_u64 v[152:153], s[58:59], 0, v[130:131]
	s_mov_b32 m0, s57
	s_nop 0
	global_load_lds_dwordx4 v[152:153], off
	v_lshl_add_u64 v[152:153], s[58:59], 0, v[134:135]
	s_add_i32 m0, s57, 0x2000
	s_nop 0
	global_load_lds_dwordx4 v[152:153], off
	s_waitcnt vmcnt(6)
	s_barrier
	v_mfma_f32_16x16x32_bf16 v[52:55], v[210:213], v[168:171], v[52:55]
	v_mfma_f32_16x16x32_bf16 v[44:47], v[218:221], v[168:171], v[44:47]
	v_mfma_f32_16x16x32_bf16 v[36:39], v[210:213], v[182:185], v[36:39]
	v_mfma_f32_16x16x32_bf16 v[28:31], v[218:221], v[182:185], v[28:31]
	v_mfma_f32_16x16x32_bf16 v[20:23], v[210:213], v[194:197], v[20:23]
	v_mfma_f32_16x16x32_bf16 v[12:15], v[218:221], v[194:197], v[12:15]
	v_mfma_f32_16x16x32_bf16 v[4:7], v[210:213], v[202:205], v[4:7]
	v_mfma_f32_16x16x32_bf16 v[0:3], v[218:221], v[202:205], v[0:3]
	v_mfma_f32_16x16x32_bf16 v[52:55], v[214:217], v[172:175], v[52:55]
	v_mfma_f32_16x16x32_bf16 v[44:47], v[222:225], v[172:175], v[44:47]
	v_mfma_f32_16x16x32_bf16 v[36:39], v[214:217], v[190:193], v[36:39]
	v_mfma_f32_16x16x32_bf16 v[28:31], v[222:225], v[190:193], v[28:31]
	v_mfma_f32_16x16x32_bf16 v[20:23], v[214:217], v[198:201], v[20:23]
	v_mfma_f32_16x16x32_bf16 v[12:15], v[222:225], v[198:201], v[12:15]
	v_mfma_f32_16x16x32_bf16 v[4:7], v[214:217], v[206:209], v[4:7]
	v_mfma_f32_16x16x32_bf16 v[0:3], v[222:225], v[206:209], v[0:3]
	s_barrier
	s_add_i32 s57, 0, 0x18000
	v_add_u32_e32 v164, s57, v147
	ds_read_b128 v[152:155], v164
	ds_read_b128 v[156:159], v164 offset:1024
	ds_read_b128 v[160:163], v164 offset:2048
	ds_read_b128 v[164:167], v164 offset:3072
	s_add_u32 s28, s28, 0x40000
	s_addc_u32 s29, s29, 0
	s_mov_b32 m0, s39
	v_lshl_add_u64 v[210:211], s[28:29], 0, v[128:129]
	ds_read_b128 v[168:171], v150 offset:32768
	ds_read_b128 v[172:175], v150 offset:33792
	ds_read_b128 v[182:185], v150 offset:34816
	ds_read_b128 v[190:193], v150 offset:35840
	ds_read_b128 v[194:197], v150 offset:36864
	ds_read_b128 v[198:201], v150 offset:37888
	ds_read_b128 v[202:205], v150 offset:38912
	ds_read_b128 v[206:209], v150 offset:39936
	global_load_lds_dwordx4 v[210:211], off
	v_lshl_add_u64 v[210:211], s[28:29], 0, v[132:133]
	s_mov_b32 m0, s40
	s_nop 0
	global_load_lds_dwordx4 v[210:211], off
	s_waitcnt lgkmcnt(8)
	s_barrier
	s_waitcnt lgkmcnt(0)
	s_waitcnt lgkmcnt(0)
	v_mfma_f32_16x16x32_bf16 v[124:127], v[152:155], v[168:171], v[124:127]
	v_mfma_f32_16x16x32_bf16 v[120:123], v[160:163], v[168:171], v[120:123]
	v_mfma_f32_16x16x32_bf16 v[108:111], v[152:155], v[182:185], v[108:111]
	v_mfma_f32_16x16x32_bf16 v[104:107], v[160:163], v[182:185], v[104:107]
	v_mfma_f32_16x16x32_bf16 v[92:95], v[152:155], v[194:197], v[92:95]
	v_mfma_f32_16x16x32_bf16 v[88:91], v[160:163], v[194:197], v[88:91]
	v_mfma_f32_16x16x32_bf16 v[76:79], v[152:155], v[202:205], v[76:79]
	v_mfma_f32_16x16x32_bf16 v[72:75], v[160:163], v[202:205], v[72:75]
	v_mfma_f32_16x16x32_bf16 v[124:127], v[156:159], v[172:175], v[124:127]
	v_mfma_f32_16x16x32_bf16 v[120:123], v[164:167], v[172:175], v[120:123]
	v_mfma_f32_16x16x32_bf16 v[108:111], v[156:159], v[190:193], v[108:111]
	v_mfma_f32_16x16x32_bf16 v[104:107], v[164:167], v[190:193], v[104:107]
	v_mfma_f32_16x16x32_bf16 v[92:95], v[156:159], v[198:201], v[92:95]
	v_mfma_f32_16x16x32_bf16 v[88:91], v[164:167], v[198:201], v[88:91]
	v_mfma_f32_16x16x32_bf16 v[76:79], v[156:159], v[206:209], v[76:79]
	v_mfma_f32_16x16x32_bf16 v[72:75], v[164:167], v[206:209], v[72:75]
	s_barrier
	s_add_i32 s28, 0, 0x1c000
	s_add_i32 s29, s57, s37
	v_add_u32_e32 v179, s28, v147
	v_lshl_add_u64 v[144:145], v[144:145], 0, s[6:7]
	s_mov_b32 m0, s29
	ds_read_b128 v[210:213], v179
	ds_read_b128 v[214:217], v179 offset:1024
	ds_read_b128 v[218:221], v179 offset:2048
	ds_read_b128 v[222:225], v179 offset:3072
	global_load_lds_dwordx4 v[144:145], off
	v_lshl_add_u64 v[144:145], v[186:187], 0, s[6:7]
	s_add_i32 m0, s29, 0x2000
	s_nop 0
	global_load_lds_dwordx4 v[144:145], off
	s_barrier
	s_waitcnt lgkmcnt(0)
	s_waitcnt lgkmcnt(0)
	v_mfma_f32_16x16x32_bf16 v[116:119], v[210:213], v[168:171], v[116:119]
	v_mfma_f32_16x16x32_bf16 v[112:115], v[218:221], v[168:171], v[112:115]
	v_mfma_f32_16x16x32_bf16 v[100:103], v[210:213], v[182:185], v[100:103]
	v_mfma_f32_16x16x32_bf16 v[96:99], v[218:221], v[182:185], v[96:99]
	v_mfma_f32_16x16x32_bf16 v[84:87], v[210:213], v[194:197], v[84:87]
	v_mfma_f32_16x16x32_bf16 v[80:83], v[218:221], v[194:197], v[80:83]
	v_mfma_f32_16x16x32_bf16 v[68:71], v[210:213], v[202:205], v[68:71]
	v_mfma_f32_16x16x32_bf16 v[64:67], v[218:221], v[202:205], v[64:67]
	v_mfma_f32_16x16x32_bf16 v[116:119], v[214:217], v[172:175], v[116:119]
	v_mfma_f32_16x16x32_bf16 v[112:115], v[222:225], v[172:175], v[112:115]
	v_mfma_f32_16x16x32_bf16 v[100:103], v[214:217], v[190:193], v[100:103]
	v_mfma_f32_16x16x32_bf16 v[96:99], v[222:225], v[190:193], v[96:99]
	v_mfma_f32_16x16x32_bf16 v[84:87], v[214:217], v[198:201], v[84:87]
	v_mfma_f32_16x16x32_bf16 v[80:83], v[222:225], v[198:201], v[80:83]
	v_mfma_f32_16x16x32_bf16 v[68:71], v[214:217], v[206:209], v[68:71]
	v_mfma_f32_16x16x32_bf16 v[64:67], v[222:225], v[206:209], v[64:67]
	s_barrier
	s_mov_b32 m0, s42
	v_lshl_add_u64 v[144:145], v[226:227], 0, s[6:7]
	ds_read_b128 v[168:171], v150 offset:49152
	ds_read_b128 v[172:175], v150 offset:50176
	ds_read_b128 v[182:185], v150 offset:51200
	ds_read_b128 v[190:193], v150 offset:52224
	ds_read_b128 v[194:197], v150 offset:53248
	ds_read_b128 v[198:201], v150 offset:54272
	ds_read_b128 v[202:205], v150 offset:55296
	ds_read_b128 v[206:209], v150 offset:56320
	global_load_lds_dwordx4 v[144:145], off
	v_lshl_add_u64 v[144:145], v[228:229], 0, s[6:7]
	s_mov_b32 m0, s43
	s_nop 0
	global_load_lds_dwordx4 v[144:145], off
	s_barrier
; __device__ __forceinline__ unsigned cvt_pk_bf16(float lo, float hi) { unsigned r; asm volatile("v_cvt_pk_bf16_f32 %0, %1, %2" : "=v"(r) : "v"(lo), "v"(hi)); return r; }
; __device__ __forceinline__ float flogsig16(float x) { return (fminf(x, 0.f) - __logf(1.0f + __expf(-fabsf(x)))) * 0.0625f; }
; #define PG8_STAGE(bufoff, gbase, voff) do { _Pragma("unroll") for (int _i = 0; _i < 2; ++_i) \
;         __builtin_amdgcn_global_load_lds((const unsigned*)((const char*)(gbase) + (voff)[_i]), (PG8_LAS unsigned*)(lds + (bufoff) + ldsw + _i * 8192), 16, 0, 0); } while (0)
; #define PG8_WAIT_V(n) asm volatile("s_waitcnt vmcnt(" #n ")" ::: "memory")
; #define PG8_WAIT_L(n) asm volatile("s_waitcnt lgkmcnt(" #n ")" ::: "memory")
; #define PG8_BAR __builtin_amdgcn_s_barrier()
; #define PG8_SCHED __builtin_amdgcn_sched_barrier(0)
;     __device__ __forceinline__ void operator()(const f32x4 (&acc)[2][2][4][2], const Unit& u, int wr, int wc, int fr, int fq) const {
;     ...
;             for (int m = 0; m < 4; ++m) { bf16_t* rowp = O + (size_t)(row0 + ai * HALF + m * 16) * ldc + col0;
; #pragma unroll
;                 for (int bj = 0; bj < 2; ++bj) { f32x4 v0 = acc[ai][bj][m][0] + bv[bj][0], v1 = acc[ai][bj][m][1] + bv[bj][1];
;                     if (act == 1) {
; #pragma unroll
;                         for (int j = 0; j < 1; ++j) { v0 = v0 * sigmoid4(v0); v1 = v1 * sigmoid4(v1); } }
;                     else if (act == 2) {
; #pragma unroll
;                         for (int j = 0; j < 1; ++j) { v0 = sigmoid4(v0); v1 = sigmoid4(v1); } }
;                     else if (act == 3) {
; #pragma unroll
;                         for (int j = 0; j < 4; ++j) { v0[j] = flogsig16(v0[j]); v1[j] = flogsig16(v1[j]); } }
;                     u32x4 w; w.x = cvt_pk_bf16(v0[0], v0[1]); w.y = cvt_pk_bf16(v0[2], v0[3]); w.z = cvt_pk_bf16(v1[0], v1[1]); w.w = cvt_pk_bf16(v1[2], v1[3]);
;                     *(u32x4*)(rowp + bj * HALF) = w; } }
; template <class Epi, class Sched>
; __device__ __forceinline__ void gemm_phase(PG8_LAS unsigned char* lds, const Gemm g, const Sched& S, const Epi& E) {
;     ...
;             PG8_BAR; PG8_WAIT_L(0); PG8_MMA(1, 0, At, B0); PG8_BAR; PG8_SCHED;
;             PG8_STAGE(PG8_SB(1, 1), b3 + hstep, voffB);
;             PG8_WAIT_V(6); PG8_BAR; PG8_MMA(1, 1, At, B1); PG8_BAR;
	s_waitcnt lgkmcnt(0)
	s_waitcnt lgkmcnt(0)
	v_mfma_f32_16x16x32_bf16 v[60:63], v[152:155], v[168:171], v[60:63]
	v_mfma_f32_16x16x32_bf16 v[56:59], v[160:163], v[168:171], v[56:59]
	v_mfma_f32_16x16x32_bf16 v[48:51], v[152:155], v[182:185], v[48:51]
	v_mfma_f32_16x16x32_bf16 v[40:43], v[160:163], v[182:185], v[40:43]
	v_mfma_f32_16x16x32_bf16 v[32:35], v[152:155], v[194:197], v[32:35]
	v_mfma_f32_16x16x32_bf16 v[24:27], v[160:163], v[194:197], v[24:27]
	v_mfma_f32_16x16x32_bf16 v[16:19], v[152:155], v[202:205], v[16:19]
	v_mfma_f32_16x16x32_bf16 v[8:11], v[160:163], v[202:205], v[8:11]
	v_mfma_f32_16x16x32_bf16 v[60:63], v[156:159], v[172:175], v[60:63]
	v_mfma_f32_16x16x32_bf16 v[56:59], v[164:167], v[172:175], v[56:59]
	v_mfma_f32_16x16x32_bf16 v[48:51], v[156:159], v[190:193], v[48:51]
	v_mfma_f32_16x16x32_bf16 v[40:43], v[164:167], v[190:193], v[40:43]
	v_mfma_f32_16x16x32_bf16 v[32:35], v[156:159], v[198:201], v[32:35]
	v_mfma_f32_16x16x32_bf16 v[24:27], v[164:167], v[198:201], v[24:27]
	v_mfma_f32_16x16x32_bf16 v[16:19], v[156:159], v[206:209], v[16:19]
	v_mfma_f32_16x16x32_bf16 v[8:11], v[164:167], v[206:209], v[8:11]
	s_barrier
	s_add_u32 s26, s26, 0x40080
	s_addc_u32 s27, s27, 0
	s_add_i32 s28, s28, s37
	v_lshl_add_u64 v[144:145], s[26:27], 0, v[130:131]
	s_mov_b32 m0, s28
	s_nop 0
	global_load_lds_dwordx4 v[144:145], off
	v_lshl_add_u64 v[144:145], s[26:27], 0, v[134:135]
	s_add_i32 m0, s28, 0x2000
	s_nop 0
	global_load_lds_dwordx4 v[144:145], off
	s_waitcnt vmcnt(6)
	s_barrier
	v_mfma_f32_16x16x32_bf16 v[52:55], v[210:213], v[168:171], v[52:55]
	v_mfma_f32_16x16x32_bf16 v[44:47], v[218:221], v[168:171], v[44:47]
	v_mfma_f32_16x16x32_bf16 v[36:39], v[210:213], v[182:185], v[36:39]
	v_mfma_f32_16x16x32_bf16 v[28:31], v[218:221], v[182:185], v[28:31]
	v_mfma_f32_16x16x32_bf16 v[20:23], v[210:213], v[194:197], v[20:23]
	v_mfma_f32_16x16x32_bf16 v[12:15], v[218:221], v[194:197], v[12:15]
	v_mfma_f32_16x16x32_bf16 v[4:7], v[210:213], v[202:205], v[4:7]
	v_mfma_f32_16x16x32_bf16 v[0:3], v[218:221], v[202:205], v[0:3]
	v_mfma_f32_16x16x32_bf16 v[52:55], v[214:217], v[172:175], v[52:55]
	v_mfma_f32_16x16x32_bf16 v[44:47], v[222:225], v[172:175], v[44:47]
	v_mfma_f32_16x16x32_bf16 v[36:39], v[214:217], v[190:193], v[36:39]
	v_mfma_f32_16x16x32_bf16 v[28:31], v[222:225], v[190:193], v[28:31]
	v_mfma_f32_16x16x32_bf16 v[20:23], v[214:217], v[198:201], v[20:23]
	v_mfma_f32_16x16x32_bf16 v[12:15], v[222:225], v[198:201], v[12:15]
	v_mfma_f32_16x16x32_bf16 v[4:7], v[214:217], v[206:209], v[4:7]
	v_mfma_f32_16x16x32_bf16 v[0:3], v[222:225], v[206:209], v[0:3]
	s_barrier
	s_add_i32 s56, s56, 2
	s_add_u32 s24, s24, 0x100
	s_addc_u32 s25, s25, 0
	s_add_u32 s54, s54, 0x100
	s_addc_u32 s55, s55, 0
	s_cmp_gt_u32 s56, 13
	s_cbranch_scc0 .LBB0_1083
	v_lshl_add_u32 v152, s22, 8, v146
	v_lshl_or_b32 v144, s51, 8, v148
	v_ashrrev_i32_e32 v153, 31, v152
	v_ashrrev_i32_e32 v145, 31, v144
	v_lshlrev_b64 v[154:155], 11, v[152:153]
	v_lshl_add_u64 v[154:155], s[4:5], 0, v[154:155]
	v_lshlrev_b64 v[156:157], 1, v[144:145]
	v_lshl_add_u64 v[144:145], v[154:155], 0, v[156:157]
	v_pk_add_f32 v[126:127], v[126:127], 0 op_sel_hi:[1,0]
	v_pk_add_f32 v[124:125], v[124:125], 0 op_sel_hi:[1,0]
	v_pk_add_f32 v[154:155], v[122:123], 0 op_sel_hi:[1,0]
	v_pk_add_f32 v[122:123], v[120:121], 0 op_sel_hi:[1,0]
	v_cvt_pk_bf16_f32 v120, v124, v125
	v_cvt_pk_bf16_f32 v121, v126, v127
	v_pk_add_f32 v[116:117], v[116:117], 0 op_sel_hi:[1,0]
	v_cvt_pk_bf16_f32 v122, v122, v123
	v_cvt_pk_bf16_f32 v123, v154, v155
	global_store_dwordx4 v[144:145], v[120:123], off
	v_pk_add_f32 v[118:119], v[118:119], 0 op_sel_hi:[1,0]
	v_pk_add_f32 v[110:111], v[110:111], 0 op_sel_hi:[1,0]
	v_pk_add_f32 v[120:121], v[114:115], 0 op_sel_hi:[1,0]
	v_pk_add_f32 v[114:115], v[112:113], 0 op_sel_hi:[1,0]
	v_cvt_pk_bf16_f32 v112, v116, v117
	v_cvt_pk_bf16_f32 v113, v118, v119
	v_pk_add_f32 v[108:109], v[108:109], 0 op_sel_hi:[1,0]
	v_cvt_pk_bf16_f32 v114, v114, v115
	v_cvt_pk_bf16_f32 v115, v120, v121
	global_store_dwordx4 v[144:145], v[112:115], off offset:256
	v_pk_add_f32 v[100:101], v[100:101], 0 op_sel_hi:[1,0]
	v_pk_add_f32 v[102:103], v[102:103], 0 op_sel_hi:[1,0]
	v_or_b32_e32 v112, 16, v152
	v_ashrrev_i32_e32 v113, 31, v112
	v_lshlrev_b64 v[112:113], 11, v[112:113]
	v_lshl_add_u64 v[112:113], s[4:5], 0, v[112:113]
	v_lshl_add_u64 v[112:113], v[112:113], 0, v[156:157]
	v_pk_add_f32 v[114:115], v[106:107], 0 op_sel_hi:[1,0]
	v_pk_add_f32 v[106:107], v[104:105], 0 op_sel_hi:[1,0]
	v_cvt_pk_bf16_f32 v104, v108, v109
	v_cvt_pk_bf16_f32 v105, v110, v111
	v_pk_add_f32 v[94:95], v[94:95], 0 op_sel_hi:[1,0]
	v_cvt_pk_bf16_f32 v106, v106, v107
	v_cvt_pk_bf16_f32 v107, v114, v115
	global_store_dwordx4 v[112:113], v[104:107], off
	v_pk_add_f32 v[92:93], v[92:93], 0 op_sel_hi:[1,0]
	v_pk_add_f32 v[84:85], v[84:85], 0 op_sel_hi:[1,0]
	v_pk_add_f32 v[104:105], v[98:99], 0 op_sel_hi:[1,0]
	v_pk_add_f32 v[98:99], v[96:97], 0 op_sel_hi:[1,0]
	v_cvt_pk_bf16_f32 v96, v100, v101
	v_cvt_pk_bf16_f32 v97, v102, v103
	v_pk_add_f32 v[86:87], v[86:87], 0 op_sel_hi:[1,0]
	v_cvt_pk_bf16_f32 v98, v98, v99
	v_cvt_pk_bf16_f32 v99, v104, v105
	global_store_dwordx4 v[112:113], v[96:99], off offset:256
	v_pk_add_f32 v[78:79], v[78:79], 0 op_sel_hi:[1,0]
	v_pk_add_f32 v[76:77], v[76:77], 0 op_sel_hi:[1,0]
	v_or_b32_e32 v96, 32, v152
	v_ashrrev_i32_e32 v97, 31, v96
	v_lshlrev_b64 v[96:97], 11, v[96:97]
	v_lshl_add_u64 v[96:97], s[4:5], 0, v[96:97]
; __device__ __forceinline__ unsigned cvt_pk_bf16(float lo, float hi) { unsigned r; asm volatile("v_cvt_pk_bf16_f32 %0, %1, %2" : "=v"(r) : "v"(lo), "v"(hi)); return r; }
; __device__ __forceinline__ float flogsig16(float x) { return (fminf(x, 0.f) - __logf(1.0f + __expf(-fabsf(x)))) * 0.0625f; }
; #define PG8_WAIT_V(n) asm volatile("s_waitcnt vmcnt(" #n ")" ::: "memory")
; #define PG8_BAR __builtin_amdgcn_s_barrier()
;     __device__ __forceinline__ void operator()(const f32x4 (&acc)[2][2][4][2], const Unit& u, int wr, int wc, int fr, int fq) const {
;     ...
;             for (int m = 0; m < 4; ++m) { bf16_t* rowp = O + (size_t)(row0 + ai * HALF + m * 16) * ldc + col0;
; #pragma unroll
;                 for (int bj = 0; bj < 2; ++bj) { f32x4 v0 = acc[ai][bj][m][0] + bv[bj][0], v1 = acc[ai][bj][m][1] + bv[bj][1];
;                     if (act == 1) {
; #pragma unroll
;                         for (int j = 0; j < 1; ++j) { v0 = v0 * sigmoid4(v0); v1 = v1 * sigmoid4(v1); } }
;                     else if (act == 2) {
; #pragma unroll
;                         for (int j = 0; j < 1; ++j) { v0 = sigmoid4(v0); v1 = sigmoid4(v1); } }
;                     else if (act == 3) {
; #pragma unroll
;                         for (int j = 0; j < 4; ++j) { v0[j] = flogsig16(v0[j]); v1[j] = flogsig16(v1[j]); } }
;                     u32x4 w; w.x = cvt_pk_bf16(v0[0], v0[1]); w.y = cvt_pk_bf16(v0[2], v0[3]); w.z = cvt_pk_bf16(v1[0], v1[1]); w.w = cvt_pk_bf16(v1[2], v1[3]);
;                     *(u32x4*)(rowp + bj * HALF) = w; } }
; template <class Epi, class Sched>
; __device__ __forceinline__ void gemm_phase(PG8_LAS unsigned char* lds, const Gemm g, const Sched& S, const Epi& E) {
;     ...
;         if (!has_next) break;
; #pragma unroll
;         for (int a = 0; a < 2; ++a)
; #pragma unroll
;             for (int b = 0; b < 2; ++b)
; #pragma unroll
;                 for (int m = 0; m < 4; ++m)
; #pragma unroll
;                     for (int n = 0; n < 2; ++n) acc[a][b][m][n] = (f32x4){0.f, 0.f, 0.f, 0.f};
;         cur = nxt; cA = nA; cB = nB; ++ui;
;     }
;     PG8_WAIT_V(0);
;     if (wr == 0) PG8_BAR;
;     PG8_BAR;
	v_lshl_add_u64 v[96:97], v[96:97], 0, v[156:157]
	v_pk_add_f32 v[98:99], v[90:91], 0 op_sel_hi:[1,0]
	v_pk_add_f32 v[90:91], v[88:89], 0 op_sel_hi:[1,0]
	v_cvt_pk_bf16_f32 v88, v92, v93
	v_cvt_pk_bf16_f32 v89, v94, v95
	v_pk_add_f32 v[70:71], v[70:71], 0 op_sel_hi:[1,0]
	v_cvt_pk_bf16_f32 v90, v90, v91
	v_cvt_pk_bf16_f32 v91, v98, v99
	global_store_dwordx4 v[96:97], v[88:91], off
	v_pk_add_f32 v[68:69], v[68:69], 0 op_sel_hi:[1,0]
	v_pk_add_f32 v[60:61], v[60:61], 0 op_sel_hi:[1,0]
	v_pk_add_f32 v[88:89], v[82:83], 0 op_sel_hi:[1,0]
	v_pk_add_f32 v[82:83], v[80:81], 0 op_sel_hi:[1,0]
	v_cvt_pk_bf16_f32 v80, v84, v85
	v_cvt_pk_bf16_f32 v81, v86, v87
	v_pk_add_f32 v[62:63], v[62:63], 0 op_sel_hi:[1,0]
	v_cvt_pk_bf16_f32 v82, v82, v83
	v_cvt_pk_bf16_f32 v83, v88, v89
	global_store_dwordx4 v[96:97], v[80:83], off offset:256
	v_pk_add_f32 v[54:55], v[54:55], 0 op_sel_hi:[1,0]
	v_pk_add_f32 v[52:53], v[52:53], 0 op_sel_hi:[1,0]
	v_or_b32_e32 v80, 48, v152
	v_ashrrev_i32_e32 v81, 31, v80
	v_lshlrev_b64 v[80:81], 11, v[80:81]
	v_lshl_add_u64 v[80:81], s[4:5], 0, v[80:81]
	v_lshl_add_u64 v[80:81], v[80:81], 0, v[156:157]
	v_pk_add_f32 v[82:83], v[74:75], 0 op_sel_hi:[1,0]
	v_pk_add_f32 v[74:75], v[72:73], 0 op_sel_hi:[1,0]
	v_cvt_pk_bf16_f32 v72, v76, v77
	v_cvt_pk_bf16_f32 v73, v78, v79
	v_pk_add_f32 v[48:49], v[48:49], 0 op_sel_hi:[1,0]
	v_cvt_pk_bf16_f32 v74, v74, v75
	v_cvt_pk_bf16_f32 v75, v82, v83
	global_store_dwordx4 v[80:81], v[72:75], off
	v_pk_add_f32 v[38:39], v[38:39], 0 op_sel_hi:[1,0]
	v_pk_add_f32 v[36:37], v[36:37], 0 op_sel_hi:[1,0]
	v_pk_add_f32 v[72:73], v[66:67], 0 op_sel_hi:[1,0]
	v_pk_add_f32 v[66:67], v[64:65], 0 op_sel_hi:[1,0]
	v_cvt_pk_bf16_f32 v64, v68, v69
	v_cvt_pk_bf16_f32 v65, v70, v71
	v_pk_add_f32 v[32:33], v[32:33], 0 op_sel_hi:[1,0]
	v_cvt_pk_bf16_f32 v66, v66, v67
	v_cvt_pk_bf16_f32 v67, v72, v73
	global_store_dwordx4 v[80:81], v[64:67], off offset:256
	v_pk_add_f32 v[22:23], v[22:23], 0 op_sel_hi:[1,0]
	v_pk_add_f32 v[20:21], v[20:21], 0 op_sel_hi:[1,0]
	v_pk_add_f32 v[66:67], v[58:59], 0 op_sel_hi:[1,0]
	v_pk_add_f32 v[58:59], v[56:57], 0 op_sel_hi:[1,0]
	v_cvt_pk_bf16_f32 v56, v60, v61
	v_add_co_u32_e32 v60, vcc, s47, v144
	v_cvt_pk_bf16_f32 v57, v62, v63
	v_cvt_pk_bf16_f32 v58, v58, v59
	v_cvt_pk_bf16_f32 v59, v66, v67
	v_lshl_add_u64 v[64:65], v[144:145], 0, s[0:1]
	s_nop 0
	v_addc_co_u32_e32 v61, vcc, 0, v145, vcc
	global_store_dwordx4 v[60:61], v[56:59], off
	v_pk_add_f32 v[16:17], v[16:17], 0 op_sel_hi:[1,0]
	s_mov_b32 s51, s14
	v_pk_add_f32 v[56:57], v[46:47], 0 op_sel_hi:[1,0]
	v_pk_add_f32 v[46:47], v[44:45], 0 op_sel_hi:[1,0]
	v_cvt_pk_bf16_f32 v44, v52, v53
	v_cvt_pk_bf16_f32 v45, v54, v55
	s_mov_b32 s22, s16
	v_cvt_pk_bf16_f32 v46, v46, v47
	v_cvt_pk_bf16_f32 v47, v56, v57
	global_store_dwordx4 v[64:65], v[44:47], off offset:256
	s_mov_b64 s[26:27], s[20:21]
	s_mov_b64 s[24:25], s[18:19]
	v_pk_add_f32 v[46:47], v[50:51], 0 op_sel_hi:[1,0]
	v_pk_add_f32 v[50:51], v[42:43], 0 op_sel_hi:[1,0]
	v_pk_add_f32 v[42:43], v[40:41], 0 op_sel_hi:[1,0]
	v_cvt_pk_bf16_f32 v40, v48, v49
	v_cvt_pk_bf16_f32 v41, v46, v47
	v_add_co_u32_e32 v46, vcc, s48, v144
	v_cvt_pk_bf16_f32 v42, v42, v43
	v_cvt_pk_bf16_f32 v43, v50, v51
	v_lshl_add_u64 v[44:45], v[144:145], 0, s[8:9]
	s_nop 0
	v_addc_co_u32_e32 v47, vcc, 0, v145, vcc
	global_store_dwordx4 v[46:47], v[40:43], off
	v_pk_add_f32 v[6:7], v[6:7], 0 op_sel_hi:[1,0]
	v_pk_add_f32 v[4:5], v[4:5], 0 op_sel_hi:[1,0]
	v_pk_add_f32 v[40:41], v[30:31], 0 op_sel_hi:[1,0]
	v_pk_add_f32 v[30:31], v[28:29], 0 op_sel_hi:[1,0]
	v_cvt_pk_bf16_f32 v28, v36, v37
	v_cvt_pk_bf16_f32 v29, v38, v39
	s_nop 0
	v_cvt_pk_bf16_f32 v30, v30, v31
	v_cvt_pk_bf16_f32 v31, v40, v41
	global_store_dwordx4 v[44:45], v[28:31], off offset:256
	s_nop 1
	v_pk_add_f32 v[30:31], v[34:35], 0 op_sel_hi:[1,0]
	v_pk_add_f32 v[34:35], v[26:27], 0 op_sel_hi:[1,0]
	v_pk_add_f32 v[26:27], v[24:25], 0 op_sel_hi:[1,0]
	v_cvt_pk_bf16_f32 v24, v32, v33
	v_cvt_pk_bf16_f32 v25, v30, v31
	v_add_co_u32_e32 v30, vcc, s49, v144
	v_cvt_pk_bf16_f32 v26, v26, v27
	v_cvt_pk_bf16_f32 v27, v34, v35
	v_lshl_add_u64 v[28:29], v[144:145], 0, s[10:11]
	s_nop 0
	v_addc_co_u32_e32 v31, vcc, 0, v145, vcc
	global_store_dwordx4 v[30:31], v[24:27], off
	s_nop 1
	v_pk_add_f32 v[24:25], v[14:15], 0 op_sel_hi:[1,0]
	v_pk_add_f32 v[14:15], v[12:13], 0 op_sel_hi:[1,0]
	v_cvt_pk_bf16_f32 v12, v20, v21
	v_cvt_pk_bf16_f32 v13, v22, v23
	s_nop 0
	v_cvt_pk_bf16_f32 v14, v14, v15
	v_cvt_pk_bf16_f32 v15, v24, v25
	global_store_dwordx4 v[28:29], v[12:15], off offset:256
	s_nop 1
	v_pk_add_f32 v[14:15], v[18:19], 0 op_sel_hi:[1,0]
	v_pk_add_f32 v[18:19], v[10:11], 0 op_sel_hi:[1,0]
	v_pk_add_f32 v[10:11], v[8:9], 0 op_sel_hi:[1,0]
	v_cvt_pk_bf16_f32 v8, v16, v17
	v_cvt_pk_bf16_f32 v9, v14, v15
	v_add_co_u32_e32 v14, vcc, s50, v144
	v_lshl_add_u64 v[12:13], v[144:145], 0, s[12:13]
	s_nop 0
	v_addc_co_u32_e32 v15, vcc, 0, v145, vcc
	v_cvt_pk_bf16_f32 v10, v10, v11
	v_cvt_pk_bf16_f32 v11, v18, v19
	global_store_dwordx4 v[14:15], v[8:11], off
	s_and_b64 vcc, exec, s[2:3]
	s_nop 0
	v_pk_add_f32 v[8:9], v[2:3], 0 op_sel_hi:[1,0]
	v_pk_add_f32 v[2:3], v[0:1], 0 op_sel_hi:[1,0]
	v_cvt_pk_bf16_f32 v0, v4, v5
	v_cvt_pk_bf16_f32 v1, v6, v7
	s_nop 0
	v_cvt_pk_bf16_f32 v2, v2, v3
	v_cvt_pk_bf16_f32 v3, v8, v9
	global_store_dwordx4 v[12:13], v[0:3], off offset:256
	s_cbranch_vccz .LBB0_1076
	s_waitcnt vmcnt(0)
	s_cmpk_gt_u32 s31, 0xff
	s_cbranch_scc1 .LBB0_1087
	s_barrier

; #define PG8_STAGE(bufoff, gbase, voff) do { _Pragma("unroll") for (int _i = 0; _i < 2; ++_i) \
;         __builtin_amdgcn_global_load_lds((const unsigned*)((const char*)(gbase) + (voff)[_i]), (PG8_LAS unsigned*)(lds + (bufoff) + ldsw + _i * 8192), 16, 0, 0); } while (0)
; #define PG8_LDA(dst, b, h) do { _Pragma("unroll") for (int m = 0; m < 4; ++m) _Pragma("unroll") for (int k = 0; k < 2; ++k) dst[m][k] = *(const PG8_LAS bf16x8*)(lds + PG8_SA(b, h) + aoff + m * 2048 + k * 1024); } while (0)
; #define PG8_LDB(dst, b, h) do { _Pragma("unroll") for (int n = 0; n < 2; ++n) _Pragma("unroll") for (int k = 0; k < 2; ++k) dst[n][k] = *(const PG8_LAS bf16x8*)(lds + PG8_SB(b, h) + boff + n * 2048 + k * 1024); } while (0)
; #define PG8_MMA(ai, bj, At, Bt) do { __builtin_amdgcn_s_setprio(1); _Pragma("unroll") for (int m = 0; m < 4; ++m) _Pragma("unroll") for (int n = 0; n < 2; ++n) _Pragma("unroll") for (int k = 0; k < 2; ++k) \
;         acc[ai][bj][m][n] = __builtin_amdgcn_mfma_f32_16x16x32_bf16(Bt[n][k], At[m][k], acc[ai][bj][m][n], 0, 0, 0); __builtin_amdgcn_s_setprio(0); } while (0)
; #define PG8_WAIT_L(n) asm volatile("s_waitcnt lgkmcnt(" #n ")" ::: "memory")
; #define PG8_BAR __builtin_amdgcn_s_barrier()
; #define PG8_SCHED __builtin_amdgcn_sched_barrier(0)
; template <class Epi, class Sched>
; __device__ __forceinline__ void gemm_phase(PG8_LAS unsigned char* lds, const Gemm g, const Sched& S, const Epi& E) {
;     ...
;             const bool last = (t == nt - 2);
;             const char* a1 = cA + (size_t)(t + 1) * kstep;
;             const char* a2 = last ? nA : cA + (size_t)(t + 2) * kstep; const char* b2 = last ? nB : cB + (size_t)(t + 2) * kstep;
;             const char* a3 = a2 + kstep; const char* b3 = b2 + kstep;
;             if (last && has_next) S.a_ready(nxt);
;             PG8_LDB(B0, 0, 0); PG8_SCHED; PG8_LDA(At, 0, 0); PG8_STAGE(PG8_SA(1, 1), a1 + hstep, voffA);
;             PG8_WAIT_L(8); PG8_BAR; PG8_WAIT_L(0); PG8_MMA(0, 0, At, B0); PG8_BAR; PG8_SCHED;
;             PG8_LDB(B1, 0, 1); PG8_STAGE(PG8_SB(0, 0), b2, voffB);
;             PG8_BAR; PG8_WAIT_L(0); PG8_MMA(0, 1, At, B1); PG8_BAR;
;             PG8_LDA(At, 0, 1); PG8_STAGE(PG8_SA(0, 0), a2, voffA);
;             PG8_BAR; PG8_WAIT_L(0); PG8_MMA(1, 0, At, B0); PG8_BAR; PG8_SCHED;
.LBB0_1202:
	ds_read_b128 v[144:147], v151
	ds_read_b128 v[154:157], v151 offset:1024
	ds_read_b128 v[158:161], v151 offset:2048
	ds_read_b128 v[162:165], v151 offset:3072
	s_add_u32 s18, s16, 0xfffc0080
	s_addc_u32 s19, s17, -1
	s_cmp_eq_u32 s46, 12
	s_cselect_b32 s21, s9, s19
	s_cselect_b32 s20, s42, s18
	s_cselect_b32 s19, s7, s45
	s_cselect_b32 s18, s43, s44
	v_lshl_add_u64 v[174:175], s[16:17], 0, v[136:137]
	s_add_i32 m0, s15, 0xc000
	ds_read_b128 v[166:169], v152
	ds_read_b128 v[170:173], v152 offset:1024
	ds_read_b128 v[182:185], v152 offset:2048
	ds_read_b128 v[190:193], v152 offset:3072
	ds_read_b128 v[194:197], v152 offset:4096
	ds_read_b128 v[198:201], v152 offset:5120
	ds_read_b128 v[202:205], v152 offset:6144
	ds_read_b128 v[206:209], v152 offset:7168
	global_load_lds_dwordx4 v[174:175], off
	v_lshl_add_u64 v[174:175], s[16:17], 0, v[138:139]
	s_add_i32 m0, s15, 0xe000
	s_nop 0
	global_load_lds_dwordx4 v[174:175], off
	s_waitcnt lgkmcnt(8)
	s_barrier
	s_waitcnt lgkmcnt(0)
	s_waitcnt lgkmcnt(0)
	v_mfma_f32_16x16x32_bf16 v[124:127], v[144:147], v[166:169], v[124:127]
	v_mfma_f32_16x16x32_bf16 v[120:123], v[158:161], v[166:169], v[120:123]
	v_mfma_f32_16x16x32_bf16 v[108:111], v[144:147], v[182:185], v[108:111]
	v_mfma_f32_16x16x32_bf16 v[104:107], v[158:161], v[182:185], v[104:107]
	v_mfma_f32_16x16x32_bf16 v[92:95], v[144:147], v[194:197], v[92:95]
	v_mfma_f32_16x16x32_bf16 v[88:91], v[158:161], v[194:197], v[88:91]
	v_mfma_f32_16x16x32_bf16 v[76:79], v[144:147], v[202:205], v[76:79]
	v_mfma_f32_16x16x32_bf16 v[72:75], v[158:161], v[202:205], v[72:75]
	v_mfma_f32_16x16x32_bf16 v[124:127], v[154:157], v[170:173], v[124:127]
	v_mfma_f32_16x16x32_bf16 v[120:123], v[162:165], v[170:173], v[120:123]
	v_mfma_f32_16x16x32_bf16 v[108:111], v[154:157], v[190:193], v[108:111]
	v_mfma_f32_16x16x32_bf16 v[104:107], v[162:165], v[190:193], v[104:107]
	v_mfma_f32_16x16x32_bf16 v[92:95], v[154:157], v[198:201], v[92:95]
	v_mfma_f32_16x16x32_bf16 v[88:91], v[162:165], v[198:201], v[88:91]
	v_mfma_f32_16x16x32_bf16 v[76:79], v[154:157], v[206:209], v[76:79]
	v_mfma_f32_16x16x32_bf16 v[72:75], v[162:165], v[206:209], v[72:75]
	s_barrier
	s_add_i32 s47, s38, s26
	v_lshl_add_u64 v[174:175], s[18:19], 0, v[132:133]
	s_mov_b32 m0, s47
	ds_read_b128 v[210:213], v153
	ds_read_b128 v[214:217], v153 offset:1024
	ds_read_b128 v[218:221], v153 offset:2048
	ds_read_b128 v[222:225], v153 offset:3072
	global_load_lds_dwordx4 v[174:175], off
	v_lshl_add_u64 v[186:187], s[18:19], 0, v[128:129]
	s_add_i32 m0, s47, 0x2000
	s_nop 0
	global_load_lds_dwordx4 v[186:187], off
	s_barrier
	s_waitcnt lgkmcnt(0)
	s_waitcnt lgkmcnt(0)
	v_mfma_f32_16x16x32_bf16 v[116:119], v[210:213], v[166:169], v[116:119]
	v_mfma_f32_16x16x32_bf16 v[112:115], v[218:221], v[166:169], v[112:115]
	v_mfma_f32_16x16x32_bf16 v[100:103], v[210:213], v[182:185], v[100:103]
	v_mfma_f32_16x16x32_bf16 v[96:99], v[218:221], v[182:185], v[96:99]
	v_mfma_f32_16x16x32_bf16 v[84:87], v[210:213], v[194:197], v[84:87]
	v_mfma_f32_16x16x32_bf16 v[80:83], v[218:221], v[194:197], v[80:83]
	v_mfma_f32_16x16x32_bf16 v[68:71], v[210:213], v[202:205], v[68:71]
	v_mfma_f32_16x16x32_bf16 v[64:67], v[218:221], v[202:205], v[64:67]
	v_mfma_f32_16x16x32_bf16 v[116:119], v[214:217], v[170:173], v[116:119]
	v_mfma_f32_16x16x32_bf16 v[112:115], v[222:225], v[170:173], v[112:115]
	v_mfma_f32_16x16x32_bf16 v[100:103], v[214:217], v[190:193], v[100:103]
	v_mfma_f32_16x16x32_bf16 v[96:99], v[222:225], v[190:193], v[96:99]
	v_mfma_f32_16x16x32_bf16 v[84:87], v[214:217], v[198:201], v[84:87]
	v_mfma_f32_16x16x32_bf16 v[80:83], v[222:225], v[198:201], v[80:83]
	v_mfma_f32_16x16x32_bf16 v[68:71], v[214:217], v[206:209], v[68:71]
	v_mfma_f32_16x16x32_bf16 v[64:67], v[222:225], v[206:209], v[64:67]
	s_barrier
	s_mov_b32 m0, s15
	v_lshl_add_u64 v[226:227], s[20:21], 0, v[134:135]
	ds_read_b128 v[166:169], v152 offset:16384
	ds_read_b128 v[170:173], v152 offset:17408
	ds_read_b128 v[182:185], v152 offset:18432
	ds_read_b128 v[190:193], v152 offset:19456
	ds_read_b128 v[194:197], v152 offset:20480
	ds_read_b128 v[198:201], v152 offset:21504
	ds_read_b128 v[202:205], v152 offset:22528
	ds_read_b128 v[206:209], v152 offset:23552
	global_load_lds_dwordx4 v[226:227], off
	v_lshl_add_u64 v[228:229], s[20:21], 0, v[130:131]
	s_mov_b32 m0, s29
	s_nop 0
	global_load_lds_dwordx4 v[228:229], off
	s_barrier
	s_waitcnt lgkmcnt(0)
	s_waitcnt lgkmcnt(0)
	v_mfma_f32_16x16x32_bf16 v[60:63], v[144:147], v[166:169], v[60:63]
	v_mfma_f32_16x16x32_bf16 v[56:59], v[158:161], v[166:169], v[56:59]
	v_mfma_f32_16x16x32_bf16 v[44:47], v[144:147], v[182:185], v[44:47]
	v_mfma_f32_16x16x32_bf16 v[40:43], v[158:161], v[182:185], v[40:43]
	v_mfma_f32_16x16x32_bf16 v[28:31], v[144:147], v[194:197], v[28:31]
	v_mfma_f32_16x16x32_bf16 v[24:27], v[158:161], v[194:197], v[24:27]
	v_mfma_f32_16x16x32_bf16 v[12:15], v[144:147], v[202:205], v[12:15]
	v_mfma_f32_16x16x32_bf16 v[8:11], v[158:161], v[202:205], v[8:11]
	v_mfma_f32_16x16x32_bf16 v[60:63], v[154:157], v[170:173], v[60:63]
	v_mfma_f32_16x16x32_bf16 v[56:59], v[162:165], v[170:173], v[56:59]
	v_mfma_f32_16x16x32_bf16 v[44:47], v[154:157], v[190:193], v[44:47]
	v_mfma_f32_16x16x32_bf16 v[40:43], v[162:165], v[190:193], v[40:43]
	v_mfma_f32_16x16x32_bf16 v[28:31], v[154:157], v[198:201], v[28:31]
	v_mfma_f32_16x16x32_bf16 v[24:27], v[162:165], v[198:201], v[24:27]
	v_mfma_f32_16x16x32_bf16 v[12:15], v[154:157], v[206:209], v[12:15]
	v_mfma_f32_16x16x32_bf16 v[8:11], v[162:165], v[206:209], v[8:11]
	s_barrier
; #define PG8_STAGE(bufoff, gbase, voff) do { _Pragma("unroll") for (int _i = 0; _i < 2; ++_i) \
;         __builtin_amdgcn_global_load_lds((const unsigned*)((const char*)(gbase) + (voff)[_i]), (PG8_LAS unsigned*)(lds + (bufoff) + ldsw + _i * 8192), 16, 0, 0); } while (0)
; #define PG8_LDA(dst, b, h) do { _Pragma("unroll") for (int m = 0; m < 4; ++m) _Pragma("unroll") for (int k = 0; k < 2; ++k) dst[m][k] = *(const PG8_LAS bf16x8*)(lds + PG8_SA(b, h) + aoff + m * 2048 + k * 1024); } while (0)
; #define PG8_LDB(dst, b, h) do { _Pragma("unroll") for (int n = 0; n < 2; ++n) _Pragma("unroll") for (int k = 0; k < 2; ++k) dst[n][k] = *(const PG8_LAS bf16x8*)(lds + PG8_SB(b, h) + boff + n * 2048 + k * 1024); } while (0)
; #define PG8_MMA(ai, bj, At, Bt) do { __builtin_amdgcn_s_setprio(1); _Pragma("unroll") for (int m = 0; m < 4; ++m) _Pragma("unroll") for (int n = 0; n < 2; ++n) _Pragma("unroll") for (int k = 0; k < 2; ++k) \
;         acc[ai][bj][m][n] = __builtin_amdgcn_mfma_f32_16x16x32_bf16(Bt[n][k], At[m][k], acc[ai][bj][m][n], 0, 0, 0); __builtin_amdgcn_s_setprio(0); } while (0)
; #define PG8_WAIT_V(n) asm volatile("s_waitcnt vmcnt(" #n ")" ::: "memory")
; #define PG8_WAIT_L(n) asm volatile("s_waitcnt lgkmcnt(" #n ")" ::: "memory")
; #define PG8_BAR __builtin_amdgcn_s_barrier()
; #define PG8_SCHED __builtin_amdgcn_sched_barrier(0)
; template <class Epi, class Sched>
; __device__ __forceinline__ void gemm_phase(PG8_LAS unsigned char* lds, const Gemm g, const Sched& S, const Epi& E) {
;     ...
;             PG8_STAGE(PG8_SB(0, 1), b2 + hstep, voffB);
;             PG8_WAIT_V(6); PG8_BAR; PG8_MMA(1, 1, At, B1); PG8_BAR;
;             PG8_LDB(B0, 1, 0); PG8_SCHED; PG8_LDA(At, 1, 0); PG8_STAGE(PG8_SA(0, 1), a2 + hstep, voffA);
;             PG8_WAIT_L(8); PG8_BAR; PG8_WAIT_L(0); PG8_MMA(0, 0, At, B0); PG8_BAR; PG8_SCHED;
;             PG8_LDB(B1, 1, 1); PG8_STAGE(PG8_SB(1, 0), b3, voffB);
;             PG8_BAR; PG8_WAIT_L(0); PG8_MMA(0, 1, At, B1); PG8_BAR;
;             PG8_LDA(At, 1, 1); PG8_STAGE(PG8_SA(1, 0), a3, voffA);
	s_add_u32 s48, s18, 0x40000
	s_addc_u32 s49, s19, 0
	s_add_i32 s47, s39, s26
	v_lshl_add_u64 v[144:145], s[48:49], 0, v[132:133]
	s_mov_b32 m0, s47
	s_nop 0
	global_load_lds_dwordx4 v[144:145], off
	v_lshl_add_u64 v[144:145], s[48:49], 0, v[128:129]
	s_add_i32 m0, s47, 0x2000
	s_nop 0
	global_load_lds_dwordx4 v[144:145], off
	s_waitcnt vmcnt(6)
	s_barrier
	v_mfma_f32_16x16x32_bf16 v[52:55], v[210:213], v[166:169], v[52:55]
	v_mfma_f32_16x16x32_bf16 v[48:51], v[218:221], v[166:169], v[48:51]
	v_mfma_f32_16x16x32_bf16 v[36:39], v[210:213], v[182:185], v[36:39]
	v_mfma_f32_16x16x32_bf16 v[32:35], v[218:221], v[182:185], v[32:35]
	v_mfma_f32_16x16x32_bf16 v[20:23], v[210:213], v[194:197], v[20:23]
	v_mfma_f32_16x16x32_bf16 v[16:19], v[218:221], v[194:197], v[16:19]
	v_mfma_f32_16x16x32_bf16 v[4:7], v[210:213], v[202:205], v[4:7]
	v_mfma_f32_16x16x32_bf16 v[0:3], v[218:221], v[202:205], v[0:3]
	v_mfma_f32_16x16x32_bf16 v[52:55], v[214:217], v[170:173], v[52:55]
	v_mfma_f32_16x16x32_bf16 v[48:51], v[222:225], v[170:173], v[48:51]
	v_mfma_f32_16x16x32_bf16 v[36:39], v[214:217], v[190:193], v[36:39]
	v_mfma_f32_16x16x32_bf16 v[32:35], v[222:225], v[190:193], v[32:35]
	v_mfma_f32_16x16x32_bf16 v[20:23], v[214:217], v[198:201], v[20:23]
	v_mfma_f32_16x16x32_bf16 v[16:19], v[222:225], v[198:201], v[16:19]
	v_mfma_f32_16x16x32_bf16 v[4:7], v[214:217], v[206:209], v[4:7]
	v_mfma_f32_16x16x32_bf16 v[0:3], v[222:225], v[206:209], v[0:3]
	s_barrier
	s_add_i32 s47, 0, 0x18000
	v_add_u32_e32 v162, s47, v149
	ds_read_b128 v[144:147], v162
	ds_read_b128 v[154:157], v162 offset:1024
	ds_read_b128 v[158:161], v162 offset:2048
	ds_read_b128 v[162:165], v162 offset:3072
	s_add_u32 s20, s20, 0x40000
	s_addc_u32 s21, s21, 0
	s_mov_b32 m0, s30
	v_lshl_add_u64 v[210:211], s[20:21], 0, v[134:135]
	ds_read_b128 v[166:169], v152 offset:32768
	ds_read_b128 v[170:173], v152 offset:33792
	ds_read_b128 v[182:185], v152 offset:34816
	ds_read_b128 v[190:193], v152 offset:35840
	ds_read_b128 v[194:197], v152 offset:36864
	ds_read_b128 v[198:201], v152 offset:37888
	ds_read_b128 v[202:205], v152 offset:38912
	ds_read_b128 v[206:209], v152 offset:39936
	global_load_lds_dwordx4 v[210:211], off
	v_lshl_add_u64 v[210:211], s[20:21], 0, v[130:131]
	s_mov_b32 m0, s31
	s_nop 0
	global_load_lds_dwordx4 v[210:211], off
	s_waitcnt lgkmcnt(8)
	s_barrier
	s_waitcnt lgkmcnt(0)
	s_waitcnt lgkmcnt(0)
	v_mfma_f32_16x16x32_bf16 v[124:127], v[144:147], v[166:169], v[124:127]
	v_mfma_f32_16x16x32_bf16 v[120:123], v[158:161], v[166:169], v[120:123]
	v_mfma_f32_16x16x32_bf16 v[108:111], v[144:147], v[182:185], v[108:111]
	v_mfma_f32_16x16x32_bf16 v[104:107], v[158:161], v[182:185], v[104:107]
	v_mfma_f32_16x16x32_bf16 v[92:95], v[144:147], v[194:197], v[92:95]
	v_mfma_f32_16x16x32_bf16 v[88:91], v[158:161], v[194:197], v[88:91]
	v_mfma_f32_16x16x32_bf16 v[76:79], v[144:147], v[202:205], v[76:79]
	v_mfma_f32_16x16x32_bf16 v[72:75], v[158:161], v[202:205], v[72:75]
	v_mfma_f32_16x16x32_bf16 v[124:127], v[154:157], v[170:173], v[124:127]
	v_mfma_f32_16x16x32_bf16 v[120:123], v[162:165], v[170:173], v[120:123]
	v_mfma_f32_16x16x32_bf16 v[108:111], v[154:157], v[190:193], v[108:111]
	v_mfma_f32_16x16x32_bf16 v[104:107], v[162:165], v[190:193], v[104:107]
	v_mfma_f32_16x16x32_bf16 v[92:95], v[154:157], v[198:201], v[92:95]
	v_mfma_f32_16x16x32_bf16 v[88:91], v[162:165], v[198:201], v[88:91]
	v_mfma_f32_16x16x32_bf16 v[76:79], v[154:157], v[206:209], v[76:79]
	v_mfma_f32_16x16x32_bf16 v[72:75], v[162:165], v[206:209], v[72:75]
	s_barrier
	s_add_i32 s20, 0, 0x1c000
	s_add_i32 s21, s47, s26
	v_add_u32_e32 v179, s20, v149
	v_lshl_add_u64 v[174:175], v[174:175], 0, s[4:5]
	s_mov_b32 m0, s21
	ds_read_b128 v[210:213], v179
	ds_read_b128 v[214:217], v179 offset:1024
	ds_read_b128 v[218:221], v179 offset:2048
	ds_read_b128 v[222:225], v179 offset:3072
	global_load_lds_dwordx4 v[174:175], off
	v_lshl_add_u64 v[174:175], v[186:187], 0, s[4:5]
	s_add_i32 m0, s21, 0x2000
	s_nop 0
	global_load_lds_dwordx4 v[174:175], off
	s_barrier
	s_waitcnt lgkmcnt(0)
	s_waitcnt lgkmcnt(0)
	v_mfma_f32_16x16x32_bf16 v[116:119], v[210:213], v[166:169], v[116:119]
	v_mfma_f32_16x16x32_bf16 v[112:115], v[218:221], v[166:169], v[112:115]
	v_mfma_f32_16x16x32_bf16 v[100:103], v[210:213], v[182:185], v[100:103]
	v_mfma_f32_16x16x32_bf16 v[96:99], v[218:221], v[182:185], v[96:99]
	v_mfma_f32_16x16x32_bf16 v[84:87], v[210:213], v[194:197], v[84:87]
	v_mfma_f32_16x16x32_bf16 v[80:83], v[218:221], v[194:197], v[80:83]
	v_mfma_f32_16x16x32_bf16 v[68:71], v[210:213], v[202:205], v[68:71]
	v_mfma_f32_16x16x32_bf16 v[64:67], v[218:221], v[202:205], v[64:67]
	v_mfma_f32_16x16x32_bf16 v[116:119], v[214:217], v[170:173], v[116:119]
	v_mfma_f32_16x16x32_bf16 v[112:115], v[222:225], v[170:173], v[112:115]
	v_mfma_f32_16x16x32_bf16 v[100:103], v[214:217], v[190:193], v[100:103]
	v_mfma_f32_16x16x32_bf16 v[96:99], v[222:225], v[190:193], v[96:99]
	v_mfma_f32_16x16x32_bf16 v[84:87], v[214:217], v[198:201], v[84:87]
	v_mfma_f32_16x16x32_bf16 v[80:83], v[222:225], v[198:201], v[80:83]
	v_mfma_f32_16x16x32_bf16 v[68:71], v[214:217], v[206:209], v[68:71]
	v_mfma_f32_16x16x32_bf16 v[64:67], v[222:225], v[206:209], v[64:67]
	s_barrier
	s_mov_b32 m0, s35
	v_lshl_add_u64 v[174:175], v[226:227], 0, s[4:5]
	ds_read_b128 v[166:169], v152 offset:49152
	ds_read_b128 v[170:173], v152 offset:50176
	ds_read_b128 v[182:185], v152 offset:51200
	ds_read_b128 v[190:193], v152 offset:52224
	ds_read_b128 v[194:197], v152 offset:53248
	ds_read_b128 v[198:201], v152 offset:54272
	ds_read_b128 v[202:205], v152 offset:55296
	ds_read_b128 v[206:209], v152 offset:56320
	global_load_lds_dwordx4 v[174:175], off
	v_lshl_add_u64 v[174:175], v[228:229], 0, s[4:5]
	s_mov_b32 m0, s36
	s_nop 0
	global_load_lds_dwordx4 v[174:175], off
	s_barrier
; __device__ __forceinline__ unsigned cvt_pk_bf16(float lo, float hi) { unsigned r; asm volatile("v_cvt_pk_bf16_f32 %0, %1, %2" : "=v"(r) : "v"(lo), "v"(hi)); return r; }
; #define PG8_STAGE(bufoff, gbase, voff) do { _Pragma("unroll") for (int _i = 0; _i < 2; ++_i) \
;         __builtin_amdgcn_global_load_lds((const unsigned*)((const char*)(gbase) + (voff)[_i]), (PG8_LAS unsigned*)(lds + (bufoff) + ldsw + _i * 8192), 16, 0, 0); } while (0)
; #define PG8_LDA(dst, b, h) do { _Pragma("unroll") for (int m = 0; m < 4; ++m) _Pragma("unroll") for (int k = 0; k < 2; ++k) dst[m][k] = *(const PG8_LAS bf16x8*)(lds + PG8_SA(b, h) + aoff + m * 2048 + k * 1024); } while (0)
; #define PG8_MMA(ai, bj, At, Bt) do { __builtin_amdgcn_s_setprio(1); _Pragma("unroll") for (int m = 0; m < 4; ++m) _Pragma("unroll") for (int n = 0; n < 2; ++n) _Pragma("unroll") for (int k = 0; k < 2; ++k) \
;         acc[ai][bj][m][n] = __builtin_amdgcn_mfma_f32_16x16x32_bf16(Bt[n][k], At[m][k], acc[ai][bj][m][n], 0, 0, 0); __builtin_amdgcn_s_setprio(0); } while (0)
; #define PG8_BAR __builtin_amdgcn_s_barrier()
;     __device__ __forceinline__ void operator()(const f32x4 (&acc)[2][2][4][2], const Unit& u, int wr, int wc, int fr, int fq) const {
;         const int row0 = u.pm * BM + wr * 64 + fr, col0 = u.pn * HALF + wc * 32 + 8 * fq;
; #pragma unroll
;         for (int ai = 0; ai < 2; ++ai)
; #pragma unroll
;             for (int m = 0; m < 4; ++m) { bf16_t* rowp = O + (size_t)(row0 + ai * HALF + m * 16) * ldc + col0;
;                 f32x4 v0, v1;
; #pragma unroll
;                 for (int j = 0; j < 1; ++j) { v0 = acc[ai][0][m][0] * sigmoid4(acc[ai][0][m][0]) * acc[ai][1][m][0]; v1 = acc[ai][0][m][1] * sigmoid4(acc[ai][0][m][1]) * acc[ai][1][m][1]; }
;                 u32x4 w; w.x = cvt_pk_bf16(v0[0], v0[1]); w.y = cvt_pk_bf16(v0[2], v0[3]); w.z = cvt_pk_bf16(v1[0], v1[1]); w.w = cvt_pk_bf16(v1[2], v1[3]);
;                 *(u32x4*)rowp = w; }
; template <class Epi, class Sched>
; __device__ __forceinline__ void gemm_phase(PG8_LAS unsigned char* lds, const Gemm g, const Sched& S, const Epi& E) {
;     ...
;             PG8_LDA(At, 1, 1); PG8_STAGE(PG8_SA(1, 0), a3, voffA);
;             PG8_BAR; PG8_WAIT_L(0); PG8_MMA(1, 0, At, B0); PG8_BAR; PG8_SCHED;
;             PG8_STAGE(PG8_SB(1, 1), b3 + hstep, voffB);
;             PG8_WAIT_V(6); PG8_BAR; PG8_MMA(1, 1, At, B1); PG8_BAR;
	s_waitcnt lgkmcnt(0)
	s_waitcnt lgkmcnt(0)
	v_mfma_f32_16x16x32_bf16 v[60:63], v[144:147], v[166:169], v[60:63]
	v_mfma_f32_16x16x32_bf16 v[56:59], v[158:161], v[166:169], v[56:59]
	v_mfma_f32_16x16x32_bf16 v[44:47], v[144:147], v[182:185], v[44:47]
	v_mfma_f32_16x16x32_bf16 v[40:43], v[158:161], v[182:185], v[40:43]
	v_mfma_f32_16x16x32_bf16 v[28:31], v[144:147], v[194:197], v[28:31]
	v_mfma_f32_16x16x32_bf16 v[24:27], v[158:161], v[194:197], v[24:27]
	v_mfma_f32_16x16x32_bf16 v[12:15], v[144:147], v[202:205], v[12:15]
	v_mfma_f32_16x16x32_bf16 v[8:11], v[158:161], v[202:205], v[8:11]
	v_mfma_f32_16x16x32_bf16 v[60:63], v[154:157], v[170:173], v[60:63]
	v_mfma_f32_16x16x32_bf16 v[56:59], v[162:165], v[170:173], v[56:59]
	v_mfma_f32_16x16x32_bf16 v[44:47], v[154:157], v[190:193], v[44:47]
	v_mfma_f32_16x16x32_bf16 v[40:43], v[162:165], v[190:193], v[40:43]
	v_mfma_f32_16x16x32_bf16 v[28:31], v[154:157], v[198:201], v[28:31]
	v_mfma_f32_16x16x32_bf16 v[24:27], v[162:165], v[198:201], v[24:27]
	v_mfma_f32_16x16x32_bf16 v[12:15], v[154:157], v[206:209], v[12:15]
	v_mfma_f32_16x16x32_bf16 v[8:11], v[162:165], v[206:209], v[8:11]
	s_barrier
	s_add_u32 s18, s18, 0x40080
	s_addc_u32 s19, s19, 0
	s_add_i32 s20, s20, s26
	v_lshl_add_u64 v[144:145], s[18:19], 0, v[132:133]
	s_mov_b32 m0, s20
	s_nop 0
	global_load_lds_dwordx4 v[144:145], off
	v_lshl_add_u64 v[144:145], s[18:19], 0, v[128:129]
	s_add_i32 m0, s20, 0x2000
	s_nop 0
	global_load_lds_dwordx4 v[144:145], off
	s_waitcnt vmcnt(6)
	s_barrier
	v_mfma_f32_16x16x32_bf16 v[52:55], v[210:213], v[166:169], v[52:55]
	v_mfma_f32_16x16x32_bf16 v[48:51], v[218:221], v[166:169], v[48:51]
	v_mfma_f32_16x16x32_bf16 v[36:39], v[210:213], v[182:185], v[36:39]
	v_mfma_f32_16x16x32_bf16 v[32:35], v[218:221], v[182:185], v[32:35]
	v_mfma_f32_16x16x32_bf16 v[20:23], v[210:213], v[194:197], v[20:23]
	v_mfma_f32_16x16x32_bf16 v[16:19], v[218:221], v[194:197], v[16:19]
	v_mfma_f32_16x16x32_bf16 v[4:7], v[210:213], v[202:205], v[4:7]
	v_mfma_f32_16x16x32_bf16 v[0:3], v[218:221], v[202:205], v[0:3]
	v_mfma_f32_16x16x32_bf16 v[52:55], v[214:217], v[170:173], v[52:55]
	v_mfma_f32_16x16x32_bf16 v[48:51], v[222:225], v[170:173], v[48:51]
	v_mfma_f32_16x16x32_bf16 v[36:39], v[214:217], v[190:193], v[36:39]
	v_mfma_f32_16x16x32_bf16 v[32:35], v[222:225], v[190:193], v[32:35]
	v_mfma_f32_16x16x32_bf16 v[20:23], v[214:217], v[198:201], v[20:23]
	v_mfma_f32_16x16x32_bf16 v[16:19], v[222:225], v[198:201], v[16:19]
	v_mfma_f32_16x16x32_bf16 v[4:7], v[214:217], v[206:209], v[4:7]
	v_mfma_f32_16x16x32_bf16 v[0:3], v[222:225], v[206:209], v[0:3]
	s_barrier
	s_add_i32 s46, s46, 2
	s_add_u32 s16, s16, 0x100
	s_addc_u32 s17, s17, 0
	s_add_u32 s44, s44, 0x100
	s_addc_u32 s45, s45, 0
	s_cmp_gt_u32 s46, 13
	s_cbranch_scc0 .LBB0_1202
	v_max_f32_e32 v144, v124, v124
	v_max_f32_e32 v144, 0xc1a00000, v144
	v_mul_f32_e32 v144, 0xbfb8aa3b, v144
	v_exp_f32_e32 v157, v144
	v_max_f32_e32 v144, v125, v125
	v_max_f32_e32 v144, 0xc1a00000, v144
	v_mul_f32_e32 v144, 0xbfb8aa3b, v144
	v_exp_f32_e32 v156, v144
	v_max_f32_e32 v144, v126, v126
	v_max_f32_e32 v144, 0xc1a00000, v144
	v_mul_f32_e32 v144, 0xbfb8aa3b, v144
	v_exp_f32_e32 v159, v144
	v_max_f32_e32 v144, v127, v127
	v_max_f32_e32 v144, 0xc1a00000, v144
	v_mul_f32_e32 v144, 0xbfb8aa3b, v144
	v_exp_f32_e32 v158, v144
	v_pk_add_f32 v[156:157], v[156:157], 1.0 op_sel_hi:[1,0]
	v_lshl_or_b32 v146, s41, 7, v150
	v_mov_b32_e32 v160, v157
	v_pk_add_f32 v[158:159], v[158:159], 1.0 op_sel_hi:[1,0]
	v_mov_b32_e32 v162, v156
	v_mov_b32_e32 v161, v159
	v_mov_b32_e32 v163, v158
	v_pk_mul_f32 v[160:161], v[160:161], v[162:163]
	v_lshl_add_u32 v154, s14, 8, v148
	v_mul_f32_e32 v155, v160, v161
	v_rcp_f32_e32 v155, v155
	v_ashrrev_i32_e32 v147, 31, v146
	v_mov_b64_e32 v[144:145], s[0:1]
	v_mad_i64_i32 v[162:163], s[16:17], v154, s40, v[144:145]
	v_mul_f32_e32 v164, v161, v155
	v_mul_f32_e32 v160, v160, v155
	v_max_f32_e32 v155, v120, v120
	v_max_f32_e32 v155, 0xc1a00000, v155
	v_mul_f32_e32 v155, 0xbfb8aa3b, v155
	v_pk_mul_f32 v[158:159], v[158:159], v[160:161] op_sel_hi:[1,0]
	v_exp_f32_e32 v161, v155
	v_max_f32_e32 v155, v121, v121
	v_max_f32_e32 v155, 0xc1a00000, v155
	v_mul_f32_e32 v155, 0xbfb8aa3b, v155
	v_exp_f32_e32 v160, v155
	v_max_f32_e32 v155, v122, v122
	v_max_f32_e32 v155, 0xc1a00000, v155
	v_mul_f32_e32 v155, 0xbfb8aa3b, v155
	v_exp_f32_e32 v167, v155
	v_max_f32_e32 v155, v123, v123
	v_max_f32_e32 v155, 0xc1a00000, v155
	v_mul_f32_e32 v155, 0xbfb8aa3b, v155
	v_exp_f32_e32 v166, v155
	v_pk_mul_f32 v[156:157], v[156:157], v[164:165] op_sel_hi:[1,0]
	v_pk_mul_f32 v[126:127], v[126:127], v[158:159]
	v_pk_mul_f32 v[124:125], v[124:125], v[156:157]
	v_pk_add_f32 v[156:157], v[160:161], 1.0 op_sel_hi:[1,0]
	v_pk_add_f32 v[160:161], v[166:167], 1.0 op_sel_hi:[1,0]
	v_mov_b32_e32 v164, v157
	v_mov_b32_e32 v165, v161
	v_mov_b32_e32 v166, v156
	v_mov_b32_e32 v167, v160
	v_pk_mul_f32 v[164:165], v[164:165], v[166:167]
	v_pk_mul_f32 v[118:119], v[126:127], v[118:119]
	v_mul_f32_e32 v155, v164, v165
	v_rcp_f32_e32 v155, v155
	v_pk_mul_f32 v[116:117], v[124:125], v[116:117]
	v_lshlrev_b64 v[146:147], 1, v[146:147]
	v_lshl_add_u64 v[162:163], v[162:163], 0, v[146:147]
	v_mul_f32_e32 v124, v165, v155
	v_mul_f32_e32 v126, v164, v155
	v_pk_mul_f32 v[126:127], v[160:161], v[126:127] op_sel_hi:[1,0]
	v_pk_mul_f32 v[124:125], v[156:157], v[124:125] op_sel_hi:[1,0]
	v_pk_mul_f32 v[122:123], v[122:123], v[126:127]
	v_pk_mul_f32 v[120:121], v[120:121], v[124:125]
	v_pk_mul_f32 v[122:123], v[122:123], v[114:115]
	v_pk_mul_f32 v[114:115], v[120:121], v[112:113]
	v_cvt_pk_bf16_f32 v112, v116, v117
	v_cvt_pk_bf16_f32 v113, v118, v119
; __device__ __forceinline__ unsigned cvt_pk_bf16(float lo, float hi) { unsigned r; asm volatile("v_cvt_pk_bf16_f32 %0, %1, %2" : "=v"(r) : "v"(lo), "v"(hi)); return r; }
; __device__ __forceinline__ f32x4 sigmoid4(f32x4 x) {
;     f32x4 d;
; #pragma unroll
;     for (int j = 0; j < 4; ++j) d[j] = 1.0f + __expf(-fmaxf(x[j], -20.0f));
;     const float p01 = d[0] * d[1], p23 = d[2] * d[3], r = __builtin_amdgcn_rcpf(p01 * p23), r01 = r * p23, r23 = r * p01;
;     return (f32x4){r01 * d[1], r01 * d[0], r23 * d[3], r23 * d[2]};
; }
;     __device__ __forceinline__ void operator()(const f32x4 (&acc)[2][2][4][2], const Unit& u, int wr, int wc, int fr, int fq) const {
;     ...
;         for (int ai = 0; ai < 2; ++ai)
; #pragma unroll
;             for (int m = 0; m < 4; ++m) { bf16_t* rowp = O + (size_t)(row0 + ai * HALF + m * 16) * ldc + col0;
;                 f32x4 v0, v1;
; #pragma unroll
;                 for (int j = 0; j < 1; ++j) { v0 = acc[ai][0][m][0] * sigmoid4(acc[ai][0][m][0]) * acc[ai][1][m][0]; v1 = acc[ai][0][m][1] * sigmoid4(acc[ai][0][m][1]) * acc[ai][1][m][1]; }
;                 u32x4 w; w.x = cvt_pk_bf16(v0[0], v0[1]); w.y = cvt_pk_bf16(v0[2], v0[3]); w.z = cvt_pk_bf16(v1[0], v1[1]); w.w = cvt_pk_bf16(v1[2], v1[3]);
;                 *(u32x4*)rowp = w; }
	v_max_f32_e32 v116, v108, v108
	v_max_f32_e32 v118, v110, v110
	v_max_f32_e32 v116, 0xc1a00000, v116
	v_max_f32_e32 v118, 0xc1a00000, v118
	v_mul_f32_e32 v116, 0xbfb8aa3b, v116
	v_mul_f32_e32 v118, 0xbfb8aa3b, v118
	v_exp_f32_e32 v117, v116
	v_max_f32_e32 v116, v109, v109
	v_exp_f32_e32 v119, v118
	v_max_f32_e32 v118, v111, v111
	v_max_f32_e32 v116, 0xc1a00000, v116
	v_max_f32_e32 v118, 0xc1a00000, v118
	v_mul_f32_e32 v116, 0xbfb8aa3b, v116
	v_mul_f32_e32 v118, 0xbfb8aa3b, v118
	v_exp_f32_e32 v116, v116
	v_exp_f32_e32 v118, v118
	v_cvt_pk_bf16_f32 v114, v114, v115
	v_cvt_pk_bf16_f32 v115, v122, v123
	global_store_dwordx4 v[162:163], v[112:115], off
	v_or_b32_e32 v120, 16, v154
	s_and_b64 vcc, exec, s[2:3]
	v_pk_add_f32 v[112:113], v[116:117], 1.0 op_sel_hi:[1,0]
	v_pk_add_f32 v[114:115], v[118:119], 1.0 op_sel_hi:[1,0]
	v_mov_b32_e32 v116, v113
	v_mov_b32_e32 v117, v115
	v_mov_b32_e32 v118, v112
	v_mov_b32_e32 v119, v114
	v_pk_mul_f32 v[116:117], v[116:117], v[118:119]
	s_mov_b32 s41, s6
	v_mul_f32_e32 v118, v116, v117
	v_rcp_f32_e32 v121, v118
	v_mad_i64_i32 v[118:119], s[16:17], v120, s40, v[144:145]
	v_lshl_add_u64 v[118:119], v[118:119], 0, v[146:147]
	v_mul_f32_e32 v116, v116, v121
	v_mul_f32_e32 v120, v117, v121
	v_pk_mul_f32 v[114:115], v[114:115], v[116:117] op_sel_hi:[1,0]
	v_max_f32_e32 v116, v104, v104
	v_max_f32_e32 v121, v106, v106
	v_max_f32_e32 v116, 0xc1a00000, v116
	v_max_f32_e32 v121, 0xc1a00000, v121
	v_mul_f32_e32 v116, 0xbfb8aa3b, v116
	v_mul_f32_e32 v121, 0xbfb8aa3b, v121
	v_exp_f32_e32 v117, v116
	v_max_f32_e32 v116, v105, v105
	v_exp_f32_e32 v123, v121
	v_max_f32_e32 v121, v107, v107
	v_max_f32_e32 v116, 0xc1a00000, v116
	v_max_f32_e32 v121, 0xc1a00000, v121
	v_mul_f32_e32 v116, 0xbfb8aa3b, v116
	v_mul_f32_e32 v121, 0xbfb8aa3b, v121
	v_exp_f32_e32 v116, v116
	v_exp_f32_e32 v122, v121
	v_pk_mul_f32 v[112:113], v[112:113], v[120:121] op_sel_hi:[1,0]
	v_pk_mul_f32 v[110:111], v[110:111], v[114:115]
	v_pk_mul_f32 v[108:109], v[108:109], v[112:113]
	v_pk_add_f32 v[112:113], v[116:117], 1.0 op_sel_hi:[1,0]
	v_pk_add_f32 v[116:117], v[122:123], 1.0 op_sel_hi:[1,0]
	v_mov_b32_e32 v120, v113
	v_mov_b32_e32 v121, v117
	v_mov_b32_e32 v122, v112
	v_mov_b32_e32 v123, v116
	v_pk_mul_f32 v[120:121], v[120:121], v[122:123]
	v_pk_mul_f32 v[102:103], v[110:111], v[102:103]
	v_mul_f32_e32 v122, v120, v121
	v_rcp_f32_e32 v122, v122
	v_pk_mul_f32 v[100:101], v[108:109], v[100:101]
	s_mov_b32 s14, s8
	s_mov_b64 s[18:19], s[12:13]
	v_mul_f32_e32 v108, v121, v122
	v_mul_f32_e32 v110, v120, v122
	v_pk_mul_f32 v[110:111], v[116:117], v[110:111] op_sel_hi:[1,0]
	v_pk_mul_f32 v[108:109], v[112:113], v[108:109] op_sel_hi:[1,0]
	v_pk_mul_f32 v[106:107], v[106:107], v[110:111]
	v_pk_mul_f32 v[104:105], v[104:105], v[108:109]
	v_pk_mul_f32 v[106:107], v[106:107], v[98:99]
	v_pk_mul_f32 v[98:99], v[104:105], v[96:97]
	v_cvt_pk_bf16_f32 v96, v100, v101
	v_cvt_pk_bf16_f32 v97, v102, v103
	v_max_f32_e32 v100, v92, v92
	v_max_f32_e32 v102, v94, v94
	v_max_f32_e32 v100, 0xc1a00000, v100
	v_max_f32_e32 v102, 0xc1a00000, v102
	v_mul_f32_e32 v100, 0xbfb8aa3b, v100
	v_mul_f32_e32 v102, 0xbfb8aa3b, v102
	v_exp_f32_e32 v101, v100
	v_max_f32_e32 v100, v93, v93
	v_exp_f32_e32 v103, v102
	v_max_f32_e32 v102, v95, v95
	v_max_f32_e32 v100, 0xc1a00000, v100
	v_max_f32_e32 v102, 0xc1a00000, v102
	v_mul_f32_e32 v100, 0xbfb8aa3b, v100
	v_mul_f32_e32 v102, 0xbfb8aa3b, v102
	v_exp_f32_e32 v100, v100
	v_exp_f32_e32 v102, v102
	v_cvt_pk_bf16_f32 v98, v98, v99
	v_cvt_pk_bf16_f32 v99, v106, v107
	global_store_dwordx4 v[118:119], v[96:99], off
	v_or_b32_e32 v104, 32, v154
	s_nop 0
	v_pk_add_f32 v[96:97], v[100:101], 1.0 op_sel_hi:[1,0]
	v_pk_add_f32 v[98:99], v[102:103], 1.0 op_sel_hi:[1,0]
	v_mov_b32_e32 v100, v97
	v_mov_b32_e32 v101, v99
	v_mov_b32_e32 v102, v96
	v_mov_b32_e32 v103, v98
	v_pk_mul_f32 v[100:101], v[100:101], v[102:103]
	s_nop 0
	v_mul_f32_e32 v102, v100, v101
	v_rcp_f32_e32 v105, v102
	v_mad_i64_i32 v[102:103], s[16:17], v104, s40, v[144:145]
	v_lshl_add_u64 v[102:103], v[102:103], 0, v[146:147]
	v_mul_f32_e32 v100, v100, v105
	v_mul_f32_e32 v104, v101, v105
	v_pk_mul_f32 v[98:99], v[98:99], v[100:101] op_sel_hi:[1,0]
	v_max_f32_e32 v100, v88, v88
	v_max_f32_e32 v105, v90, v90
	v_max_f32_e32 v100, 0xc1a00000, v100
	v_max_f32_e32 v105, 0xc1a00000, v105
	v_mul_f32_e32 v100, 0xbfb8aa3b, v100
	v_mul_f32_e32 v105, 0xbfb8aa3b, v105
	v_exp_f32_e32 v101, v100
	v_max_f32_e32 v100, v89, v89
	v_exp_f32_e32 v107, v105
	v_max_f32_e32 v105, v91, v91
	v_max_f32_e32 v100, 0xc1a00000, v100
	v_max_f32_e32 v105, 0xc1a00000, v105
	v_mul_f32_e32 v100, 0xbfb8aa3b, v100
	v_mul_f32_e32 v105, 0xbfb8aa3b, v105
	v_exp_f32_e32 v100, v100
	v_exp_f32_e32 v106, v105
	v_pk_mul_f32 v[96:97], v[96:97], v[104:105] op_sel_hi:[1,0]
	v_pk_mul_f32 v[94:95], v[94:95], v[98:99]
	v_pk_mul_f32 v[92:93], v[92:93], v[96:97]
	v_pk_add_f32 v[96:97], v[100:101], 1.0 op_sel_hi:[1,0]
	v_pk_add_f32 v[100:101], v[106:107], 1.0 op_sel_hi:[1,0]
	v_mov_b32_e32 v104, v97
	v_mov_b32_e32 v105, v101
	v_mov_b32_e32 v106, v96
	v_mov_b32_e32 v107, v100
	v_pk_mul_f32 v[104:105], v[104:105], v[106:107]
	v_pk_mul_f32 v[86:87], v[94:95], v[86:87]
	v_mul_f32_e32 v106, v104, v105
	v_rcp_f32_e32 v106, v106
	v_pk_mul_f32 v[84:85], v[92:93], v[84:85]
	v_mul_f32_e32 v92, v105, v106
	v_mul_f32_e32 v94, v104, v106
	v_pk_mul_f32 v[94:95], v[100:101], v[94:95] op_sel_hi:[1,0]
	v_pk_mul_f32 v[92:93], v[96:97], v[92:93] op_sel_hi:[1,0]
	v_pk_mul_f32 v[90:91], v[90:91], v[94:95]
	v_pk_mul_f32 v[88:89], v[88:89], v[92:93]
	v_pk_mul_f32 v[90:91], v[90:91], v[82:83]
	v_pk_mul_f32 v[82:83], v[88:89], v[80:81]
	v_cvt_pk_bf16_f32 v80, v84, v85
; __device__ __forceinline__ unsigned cvt_pk_bf16(float lo, float hi) { unsigned r; asm volatile("v_cvt_pk_bf16_f32 %0, %1, %2" : "=v"(r) : "v"(lo), "v"(hi)); return r; }
; __device__ __forceinline__ f32x4 sigmoid4(f32x4 x) {
;     f32x4 d;
; #pragma unroll
;     for (int j = 0; j < 4; ++j) d[j] = 1.0f + __expf(-fmaxf(x[j], -20.0f));
;     const float p01 = d[0] * d[1], p23 = d[2] * d[3], r = __builtin_amdgcn_rcpf(p01 * p23), r01 = r * p23, r23 = r * p01;
;     return (f32x4){r01 * d[1], r01 * d[0], r23 * d[3], r23 * d[2]};
; }
;     __device__ __forceinline__ void operator()(const f32x4 (&acc)[2][2][4][2], const Unit& u, int wr, int wc, int fr, int fq) const {
;     ...
;         for (int ai = 0; ai < 2; ++ai)
; #pragma unroll
;             for (int m = 0; m < 4; ++m) { bf16_t* rowp = O + (size_t)(row0 + ai * HALF + m * 16) * ldc + col0;
;                 f32x4 v0, v1;
; #pragma unroll
;                 for (int j = 0; j < 1; ++j) { v0 = acc[ai][0][m][0] * sigmoid4(acc[ai][0][m][0]) * acc[ai][1][m][0]; v1 = acc[ai][0][m][1] * sigmoid4(acc[ai][0][m][1]) * acc[ai][1][m][1]; }
;                 u32x4 w; w.x = cvt_pk_bf16(v0[0], v0[1]); w.y = cvt_pk_bf16(v0[2], v0[3]); w.z = cvt_pk_bf16(v1[0], v1[1]); w.w = cvt_pk_bf16(v1[2], v1[3]);
;                 *(u32x4*)rowp = w; }
	v_cvt_pk_bf16_f32 v81, v86, v87
	v_max_f32_e32 v84, v76, v76
	v_max_f32_e32 v86, v78, v78
	v_max_f32_e32 v84, 0xc1a00000, v84
	v_max_f32_e32 v86, 0xc1a00000, v86
	v_mul_f32_e32 v84, 0xbfb8aa3b, v84
	v_mul_f32_e32 v86, 0xbfb8aa3b, v86
	v_exp_f32_e32 v85, v84
	v_max_f32_e32 v84, v77, v77
	v_exp_f32_e32 v87, v86
	v_max_f32_e32 v86, v79, v79
	v_max_f32_e32 v84, 0xc1a00000, v84
	v_max_f32_e32 v86, 0xc1a00000, v86
	v_mul_f32_e32 v84, 0xbfb8aa3b, v84
	v_mul_f32_e32 v86, 0xbfb8aa3b, v86
	v_exp_f32_e32 v84, v84
	v_exp_f32_e32 v86, v86
	v_cvt_pk_bf16_f32 v82, v82, v83
	v_cvt_pk_bf16_f32 v83, v90, v91
	global_store_dwordx4 v[102:103], v[80:83], off
	v_or_b32_e32 v88, 48, v154
	s_nop 0
	v_pk_add_f32 v[80:81], v[84:85], 1.0 op_sel_hi:[1,0]
	v_pk_add_f32 v[82:83], v[86:87], 1.0 op_sel_hi:[1,0]
	v_mov_b32_e32 v84, v81
	v_mov_b32_e32 v85, v83
	v_mov_b32_e32 v86, v80
	v_mov_b32_e32 v87, v82
	v_pk_mul_f32 v[84:85], v[84:85], v[86:87]
	s_nop 0
	v_mul_f32_e32 v86, v84, v85
	v_rcp_f32_e32 v89, v86
	v_mad_i64_i32 v[86:87], s[16:17], v88, s40, v[144:145]
	v_lshl_add_u64 v[86:87], v[86:87], 0, v[146:147]
	v_mul_f32_e32 v84, v84, v89
	v_mul_f32_e32 v88, v85, v89
	v_pk_mul_f32 v[82:83], v[82:83], v[84:85] op_sel_hi:[1,0]
	v_max_f32_e32 v84, v72, v72
	v_max_f32_e32 v89, v74, v74
	v_max_f32_e32 v84, 0xc1a00000, v84
	v_max_f32_e32 v89, 0xc1a00000, v89
	v_mul_f32_e32 v84, 0xbfb8aa3b, v84
	v_mul_f32_e32 v89, 0xbfb8aa3b, v89
	v_exp_f32_e32 v85, v84
	v_max_f32_e32 v84, v73, v73
	v_exp_f32_e32 v91, v89
	v_max_f32_e32 v89, v75, v75
	v_max_f32_e32 v84, 0xc1a00000, v84
	v_max_f32_e32 v89, 0xc1a00000, v89
	v_mul_f32_e32 v84, 0xbfb8aa3b, v84
	v_mul_f32_e32 v89, 0xbfb8aa3b, v89
	v_exp_f32_e32 v84, v84
	v_exp_f32_e32 v90, v89
	v_pk_mul_f32 v[80:81], v[80:81], v[88:89] op_sel_hi:[1,0]
	v_pk_mul_f32 v[78:79], v[78:79], v[82:83]
	v_pk_mul_f32 v[76:77], v[76:77], v[80:81]
	v_pk_add_f32 v[80:81], v[84:85], 1.0 op_sel_hi:[1,0]
	v_pk_add_f32 v[84:85], v[90:91], 1.0 op_sel_hi:[1,0]
	v_mov_b32_e32 v88, v81
	v_mov_b32_e32 v89, v85
	v_mov_b32_e32 v90, v80
	v_mov_b32_e32 v91, v84
	v_pk_mul_f32 v[88:89], v[88:89], v[90:91]
	v_pk_mul_f32 v[70:71], v[78:79], v[70:71]
	v_mul_f32_e32 v90, v88, v89
	v_rcp_f32_e32 v90, v90
	v_pk_mul_f32 v[68:69], v[76:77], v[68:69]
	v_mul_f32_e32 v76, v89, v90
	v_mul_f32_e32 v78, v88, v90
	v_pk_mul_f32 v[78:79], v[84:85], v[78:79] op_sel_hi:[1,0]
	v_pk_mul_f32 v[76:77], v[80:81], v[76:77] op_sel_hi:[1,0]
	v_pk_mul_f32 v[74:75], v[74:75], v[78:79]
	v_pk_mul_f32 v[72:73], v[72:73], v[76:77]
	v_pk_mul_f32 v[74:75], v[74:75], v[66:67]
	v_pk_mul_f32 v[66:67], v[72:73], v[64:65]
	v_cvt_pk_bf16_f32 v64, v68, v69
	v_cvt_pk_bf16_f32 v65, v70, v71
	v_max_f32_e32 v68, v60, v60
	v_max_f32_e32 v70, v62, v62
	v_max_f32_e32 v68, 0xc1a00000, v68
	v_max_f32_e32 v70, 0xc1a00000, v70
	v_mul_f32_e32 v68, 0xbfb8aa3b, v68
	v_mul_f32_e32 v70, 0xbfb8aa3b, v70
	v_exp_f32_e32 v69, v68
	v_max_f32_e32 v68, v61, v61
	v_exp_f32_e32 v71, v70
	v_max_f32_e32 v70, v63, v63
	v_max_f32_e32 v68, 0xc1a00000, v68
	v_max_f32_e32 v70, 0xc1a00000, v70
	v_mul_f32_e32 v68, 0xbfb8aa3b, v68
	v_mul_f32_e32 v70, 0xbfb8aa3b, v70
	v_exp_f32_e32 v68, v68
	v_exp_f32_e32 v70, v70
	v_cvt_pk_bf16_f32 v66, v66, v67
	v_cvt_pk_bf16_f32 v67, v74, v75
	global_store_dwordx4 v[86:87], v[64:67], off
	v_add_u32_e32 v72, 0x80, v154
	s_nop 0
	v_pk_add_f32 v[64:65], v[68:69], 1.0 op_sel_hi:[1,0]
	v_pk_add_f32 v[66:67], v[70:71], 1.0 op_sel_hi:[1,0]
	v_mov_b32_e32 v68, v65
	v_mov_b32_e32 v69, v67
	v_mov_b32_e32 v70, v64
	v_mov_b32_e32 v71, v66
	v_pk_mul_f32 v[68:69], v[68:69], v[70:71]
	s_nop 0
	v_mul_f32_e32 v70, v68, v69
	v_rcp_f32_e32 v73, v70
	v_mad_i64_i32 v[70:71], s[16:17], v72, s40, v[144:145]
	v_lshl_add_u64 v[70:71], v[70:71], 0, v[146:147]
	v_mul_f32_e32 v68, v68, v73
	v_mul_f32_e32 v72, v69, v73
	v_pk_mul_f32 v[66:67], v[66:67], v[68:69] op_sel_hi:[1,0]
	v_max_f32_e32 v68, v56, v56
	v_max_f32_e32 v73, v58, v58
	v_max_f32_e32 v68, 0xc1a00000, v68
	v_max_f32_e32 v73, 0xc1a00000, v73
	v_mul_f32_e32 v68, 0xbfb8aa3b, v68
	v_mul_f32_e32 v73, 0xbfb8aa3b, v73
	v_exp_f32_e32 v69, v68
	v_max_f32_e32 v68, v57, v57
	v_exp_f32_e32 v75, v73
	v_max_f32_e32 v73, v59, v59
	v_max_f32_e32 v68, 0xc1a00000, v68
	v_max_f32_e32 v73, 0xc1a00000, v73
	v_mul_f32_e32 v68, 0xbfb8aa3b, v68
	v_mul_f32_e32 v73, 0xbfb8aa3b, v73
	v_exp_f32_e32 v68, v68
	v_exp_f32_e32 v74, v73
	v_pk_mul_f32 v[64:65], v[64:65], v[72:73] op_sel_hi:[1,0]
	v_pk_mul_f32 v[62:63], v[62:63], v[66:67]
	v_pk_mul_f32 v[60:61], v[60:61], v[64:65]
	v_pk_add_f32 v[64:65], v[68:69], 1.0 op_sel_hi:[1,0]
	v_pk_add_f32 v[68:69], v[74:75], 1.0 op_sel_hi:[1,0]
	v_mov_b32_e32 v72, v65
	v_mov_b32_e32 v73, v69
	v_mov_b32_e32 v74, v64
	v_mov_b32_e32 v75, v68
	v_pk_mul_f32 v[72:73], v[72:73], v[74:75]
	v_pk_mul_f32 v[54:55], v[62:63], v[54:55]
	v_mul_f32_e32 v74, v72, v73
	v_rcp_f32_e32 v74, v74
	v_pk_mul_f32 v[52:53], v[60:61], v[52:53]
	v_mul_f32_e32 v60, v73, v74
	v_mul_f32_e32 v62, v72, v74
	v_pk_mul_f32 v[62:63], v[68:69], v[62:63] op_sel_hi:[1,0]
	v_pk_mul_f32 v[60:61], v[64:65], v[60:61] op_sel_hi:[1,0]
	v_pk_mul_f32 v[58:59], v[58:59], v[62:63]
	v_pk_mul_f32 v[56:57], v[56:57], v[60:61]
	v_pk_mul_f32 v[58:59], v[58:59], v[50:51]
	v_pk_mul_f32 v[50:51], v[56:57], v[48:49]
	v_cvt_pk_bf16_f32 v48, v52, v53
	v_cvt_pk_bf16_f32 v49, v54, v55
	v_max_f32_e32 v52, v44, v44
	v_max_f32_e32 v54, v46, v46
	v_max_f32_e32 v52, 0xc1a00000, v52
	v_max_f32_e32 v54, 0xc1a00000, v54
	v_mul_f32_e32 v52, 0xbfb8aa3b, v52
	v_mul_f32_e32 v54, 0xbfb8aa3b, v54
	v_exp_f32_e32 v53, v52
	v_max_f32_e32 v52, v45, v45
	v_exp_f32_e32 v55, v54
	v_max_f32_e32 v54, v47, v47
	v_max_f32_e32 v52, 0xc1a00000, v52
; __device__ __forceinline__ unsigned cvt_pk_bf16(float lo, float hi) { unsigned r; asm volatile("v_cvt_pk_bf16_f32 %0, %1, %2" : "=v"(r) : "v"(lo), "v"(hi)); return r; }
; __device__ __forceinline__ f32x4 sigmoid4(f32x4 x) {
;     f32x4 d;
; #pragma unroll
;     for (int j = 0; j < 4; ++j) d[j] = 1.0f + __expf(-fmaxf(x[j], -20.0f));
;     const float p01 = d[0] * d[1], p23 = d[2] * d[3], r = __builtin_amdgcn_rcpf(p01 * p23), r01 = r * p23, r23 = r * p01;
;     return (f32x4){r01 * d[1], r01 * d[0], r23 * d[3], r23 * d[2]};
; }
;     __device__ __forceinline__ void operator()(const f32x4 (&acc)[2][2][4][2], const Unit& u, int wr, int wc, int fr, int fq) const {
;     ...
;         for (int ai = 0; ai < 2; ++ai)
; #pragma unroll
;             for (int m = 0; m < 4; ++m) { bf16_t* rowp = O + (size_t)(row0 + ai * HALF + m * 16) * ldc + col0;
;                 f32x4 v0, v1;
; #pragma unroll
;                 for (int j = 0; j < 1; ++j) { v0 = acc[ai][0][m][0] * sigmoid4(acc[ai][0][m][0]) * acc[ai][1][m][0]; v1 = acc[ai][0][m][1] * sigmoid4(acc[ai][0][m][1]) * acc[ai][1][m][1]; }
;                 u32x4 w; w.x = cvt_pk_bf16(v0[0], v0[1]); w.y = cvt_pk_bf16(v0[2], v0[3]); w.z = cvt_pk_bf16(v1[0], v1[1]); w.w = cvt_pk_bf16(v1[2], v1[3]);
;                 *(u32x4*)rowp = w; }
	v_max_f32_e32 v54, 0xc1a00000, v54
	v_mul_f32_e32 v52, 0xbfb8aa3b, v52
	v_mul_f32_e32 v54, 0xbfb8aa3b, v54
	v_exp_f32_e32 v52, v52
	v_exp_f32_e32 v54, v54
	v_cvt_pk_bf16_f32 v50, v50, v51
	v_cvt_pk_bf16_f32 v51, v58, v59
	global_store_dwordx4 v[70:71], v[48:51], off
	v_add_u32_e32 v56, 0x90, v154
	s_nop 0
	v_pk_add_f32 v[48:49], v[52:53], 1.0 op_sel_hi:[1,0]
	v_pk_add_f32 v[50:51], v[54:55], 1.0 op_sel_hi:[1,0]
	v_mov_b32_e32 v52, v49
	v_mov_b32_e32 v53, v51
	v_mov_b32_e32 v54, v48
	v_mov_b32_e32 v55, v50
	v_pk_mul_f32 v[52:53], v[52:53], v[54:55]
	s_nop 0
	v_mul_f32_e32 v54, v52, v53
	v_rcp_f32_e32 v57, v54
	v_mad_i64_i32 v[54:55], s[16:17], v56, s40, v[144:145]
	v_lshl_add_u64 v[54:55], v[54:55], 0, v[146:147]
	v_mul_f32_e32 v52, v52, v57
	v_mul_f32_e32 v56, v53, v57
	v_pk_mul_f32 v[50:51], v[50:51], v[52:53] op_sel_hi:[1,0]
	v_max_f32_e32 v52, v40, v40
	v_max_f32_e32 v57, v42, v42
	v_max_f32_e32 v52, 0xc1a00000, v52
	v_max_f32_e32 v57, 0xc1a00000, v57
	v_mul_f32_e32 v52, 0xbfb8aa3b, v52
	v_mul_f32_e32 v57, 0xbfb8aa3b, v57
	v_exp_f32_e32 v53, v52
	v_max_f32_e32 v52, v41, v41
	v_exp_f32_e32 v59, v57
	v_max_f32_e32 v57, v43, v43
	v_max_f32_e32 v52, 0xc1a00000, v52
	v_max_f32_e32 v57, 0xc1a00000, v57
	v_mul_f32_e32 v52, 0xbfb8aa3b, v52
	v_mul_f32_e32 v57, 0xbfb8aa3b, v57
	v_exp_f32_e32 v52, v52
	v_exp_f32_e32 v58, v57
	v_pk_mul_f32 v[48:49], v[48:49], v[56:57] op_sel_hi:[1,0]
	v_pk_mul_f32 v[46:47], v[46:47], v[50:51]
	v_pk_mul_f32 v[44:45], v[44:45], v[48:49]
	v_pk_add_f32 v[48:49], v[52:53], 1.0 op_sel_hi:[1,0]
	v_pk_add_f32 v[52:53], v[58:59], 1.0 op_sel_hi:[1,0]
	v_mov_b32_e32 v56, v49
	v_mov_b32_e32 v57, v53
	v_mov_b32_e32 v58, v48
	v_mov_b32_e32 v59, v52
	v_pk_mul_f32 v[56:57], v[56:57], v[58:59]
	v_pk_mul_f32 v[38:39], v[46:47], v[38:39]
	v_mul_f32_e32 v58, v56, v57
	v_rcp_f32_e32 v58, v58
	v_pk_mul_f32 v[36:37], v[44:45], v[36:37]
	v_mul_f32_e32 v44, v57, v58
	v_mul_f32_e32 v46, v56, v58
	v_pk_mul_f32 v[46:47], v[52:53], v[46:47] op_sel_hi:[1,0]
	v_pk_mul_f32 v[44:45], v[48:49], v[44:45] op_sel_hi:[1,0]
	v_pk_mul_f32 v[42:43], v[42:43], v[46:47]
	v_pk_mul_f32 v[40:41], v[40:41], v[44:45]
	v_pk_mul_f32 v[42:43], v[42:43], v[34:35]
	v_pk_mul_f32 v[34:35], v[40:41], v[32:33]
	v_cvt_pk_bf16_f32 v32, v36, v37
	v_cvt_pk_bf16_f32 v33, v38, v39
	v_max_f32_e32 v36, v28, v28
	v_max_f32_e32 v38, v30, v30
	v_max_f32_e32 v36, 0xc1a00000, v36
	v_max_f32_e32 v38, 0xc1a00000, v38
	v_mul_f32_e32 v36, 0xbfb8aa3b, v36
	v_mul_f32_e32 v38, 0xbfb8aa3b, v38
	v_exp_f32_e32 v37, v36
	v_max_f32_e32 v36, v29, v29
	v_exp_f32_e32 v39, v38
	v_max_f32_e32 v38, v31, v31
	v_max_f32_e32 v36, 0xc1a00000, v36
	v_max_f32_e32 v38, 0xc1a00000, v38
	v_mul_f32_e32 v36, 0xbfb8aa3b, v36
	v_mul_f32_e32 v38, 0xbfb8aa3b, v38
	v_exp_f32_e32 v36, v36
	v_exp_f32_e32 v38, v38
	v_cvt_pk_bf16_f32 v34, v34, v35
	v_cvt_pk_bf16_f32 v35, v42, v43
	global_store_dwordx4 v[54:55], v[32:35], off
	v_add_u32_e32 v40, 0xa0, v154
	s_nop 0
	v_pk_add_f32 v[32:33], v[36:37], 1.0 op_sel_hi:[1,0]
	v_pk_add_f32 v[34:35], v[38:39], 1.0 op_sel_hi:[1,0]
	v_mov_b32_e32 v36, v33
	v_mov_b32_e32 v37, v35
	v_mov_b32_e32 v38, v32
	v_mov_b32_e32 v39, v34
	v_pk_mul_f32 v[36:37], v[36:37], v[38:39]
	s_nop 0
	v_mul_f32_e32 v38, v36, v37
	v_rcp_f32_e32 v41, v38
	v_mad_i64_i32 v[38:39], s[16:17], v40, s40, v[144:145]
	v_lshl_add_u64 v[38:39], v[38:39], 0, v[146:147]
	v_mul_f32_e32 v36, v36, v41
	v_mul_f32_e32 v40, v37, v41
	v_pk_mul_f32 v[34:35], v[34:35], v[36:37] op_sel_hi:[1,0]
	v_max_f32_e32 v36, v24, v24
	v_max_f32_e32 v41, v26, v26
	v_max_f32_e32 v36, 0xc1a00000, v36
	v_max_f32_e32 v41, 0xc1a00000, v41
	v_mul_f32_e32 v36, 0xbfb8aa3b, v36
	v_mul_f32_e32 v41, 0xbfb8aa3b, v41
	v_exp_f32_e32 v37, v36
	v_max_f32_e32 v36, v25, v25
	v_exp_f32_e32 v43, v41
	v_max_f32_e32 v41, v27, v27
	v_max_f32_e32 v36, 0xc1a00000, v36
	v_max_f32_e32 v41, 0xc1a00000, v41
	v_mul_f32_e32 v36, 0xbfb8aa3b, v36
; __device__ __forceinline__ unsigned cvt_pk_bf16(float lo, float hi) { unsigned r; asm volatile("v_cvt_pk_bf16_f32 %0, %1, %2" : "=v"(r) : "v"(lo), "v"(hi)); return r; }
; __device__ __forceinline__ f32x4 sigmoid4(f32x4 x) {
;     f32x4 d;
; #pragma unroll
;     for (int j = 0; j < 4; ++j) d[j] = 1.0f + __expf(-fmaxf(x[j], -20.0f));
;     const float p01 = d[0] * d[1], p23 = d[2] * d[3], r = __builtin_amdgcn_rcpf(p01 * p23), r01 = r * p23, r23 = r * p01;
;     return (f32x4){r01 * d[1], r01 * d[0], r23 * d[3], r23 * d[2]};
; }
;     __device__ __forceinline__ void operator()(const f32x4 (&acc)[2][2][4][2], const Unit& u, int wr, int wc, int fr, int fq) const {
;     ...
;         for (int ai = 0; ai < 2; ++ai)
; #pragma unroll
;             for (int m = 0; m < 4; ++m) { bf16_t* rowp = O + (size_t)(row0 + ai * HALF + m * 16) * ldc + col0;
;                 f32x4 v0, v1;
; #pragma unroll
;                 for (int j = 0; j < 1; ++j) { v0 = acc[ai][0][m][0] * sigmoid4(acc[ai][0][m][0]) * acc[ai][1][m][0]; v1 = acc[ai][0][m][1] * sigmoid4(acc[ai][0][m][1]) * acc[ai][1][m][1]; }
;                 u32x4 w; w.x = cvt_pk_bf16(v0[0], v0[1]); w.y = cvt_pk_bf16(v0[2], v0[3]); w.z = cvt_pk_bf16(v1[0], v1[1]); w.w = cvt_pk_bf16(v1[2], v1[3]);
;                 *(u32x4*)rowp = w; }
	v_mul_f32_e32 v41, 0xbfb8aa3b, v41
	v_exp_f32_e32 v36, v36
	v_exp_f32_e32 v42, v41
	v_pk_mul_f32 v[32:33], v[32:33], v[40:41] op_sel_hi:[1,0]
	v_pk_mul_f32 v[30:31], v[30:31], v[34:35]
	v_pk_mul_f32 v[28:29], v[28:29], v[32:33]
	v_pk_add_f32 v[32:33], v[36:37], 1.0 op_sel_hi:[1,0]
	v_pk_add_f32 v[36:37], v[42:43], 1.0 op_sel_hi:[1,0]
	v_mov_b32_e32 v40, v33
	v_mov_b32_e32 v41, v37
	v_mov_b32_e32 v42, v32
	v_mov_b32_e32 v43, v36
	v_pk_mul_f32 v[40:41], v[40:41], v[42:43]
	v_pk_mul_f32 v[22:23], v[30:31], v[22:23]
	v_mul_f32_e32 v42, v40, v41
	v_rcp_f32_e32 v42, v42
	v_pk_mul_f32 v[20:21], v[28:29], v[20:21]
	v_mul_f32_e32 v28, v41, v42
	v_mul_f32_e32 v30, v40, v42
	v_pk_mul_f32 v[30:31], v[36:37], v[30:31] op_sel_hi:[1,0]
	v_pk_mul_f32 v[28:29], v[32:33], v[28:29] op_sel_hi:[1,0]
	v_pk_mul_f32 v[26:27], v[26:27], v[30:31]
	v_pk_mul_f32 v[24:25], v[24:25], v[28:29]
	v_pk_mul_f32 v[26:27], v[26:27], v[18:19]
	v_pk_mul_f32 v[18:19], v[24:25], v[16:17]
	v_cvt_pk_bf16_f32 v16, v20, v21
	v_cvt_pk_bf16_f32 v17, v22, v23
	v_max_f32_e32 v20, v12, v12
	v_max_f32_e32 v22, v14, v14
	v_max_f32_e32 v20, 0xc1a00000, v20
	v_max_f32_e32 v22, 0xc1a00000, v22
	v_mul_f32_e32 v20, 0xbfb8aa3b, v20
	v_mul_f32_e32 v22, 0xbfb8aa3b, v22
	v_exp_f32_e32 v21, v20
	v_max_f32_e32 v20, v13, v13
	v_exp_f32_e32 v23, v22
	v_max_f32_e32 v22, v15, v15
	v_max_f32_e32 v20, 0xc1a00000, v20
	v_max_f32_e32 v22, 0xc1a00000, v22
	v_mul_f32_e32 v20, 0xbfb8aa3b, v20
	v_mul_f32_e32 v22, 0xbfb8aa3b, v22
	v_exp_f32_e32 v20, v20
	v_exp_f32_e32 v22, v22
	v_cvt_pk_bf16_f32 v18, v18, v19
	v_cvt_pk_bf16_f32 v19, v26, v27
	global_store_dwordx4 v[38:39], v[16:19], off
	v_add_u32_e32 v24, 0xb0, v154
	s_nop 0
	v_pk_add_f32 v[16:17], v[20:21], 1.0 op_sel_hi:[1,0]
	v_pk_add_f32 v[18:19], v[22:23], 1.0 op_sel_hi:[1,0]
	v_mov_b32_e32 v20, v17
	v_mov_b32_e32 v21, v19
	v_mov_b32_e32 v22, v16
	v_mov_b32_e32 v23, v18
	v_pk_mul_f32 v[20:21], v[20:21], v[22:23]
	s_nop 0
	v_mul_f32_e32 v22, v20, v21
	v_rcp_f32_e32 v25, v22
	v_mad_i64_i32 v[22:23], s[16:17], v24, s40, v[144:145]
	v_lshl_add_u64 v[22:23], v[22:23], 0, v[146:147]
	v_mul_f32_e32 v20, v20, v25
	v_mul_f32_e32 v24, v21, v25
	v_pk_mul_f32 v[18:19], v[18:19], v[20:21] op_sel_hi:[1,0]
	v_max_f32_e32 v20, v8, v8
	v_max_f32_e32 v25, v10, v10
	v_max_f32_e32 v20, 0xc1a00000, v20
	v_max_f32_e32 v25, 0xc1a00000, v25
	v_mul_f32_e32 v20, 0xbfb8aa3b, v20
	v_mul_f32_e32 v25, 0xbfb8aa3b, v25
	v_exp_f32_e32 v21, v20
	v_max_f32_e32 v20, v9, v9
	v_exp_f32_e32 v27, v25
	v_max_f32_e32 v25, v11, v11
	v_max_f32_e32 v20, 0xc1a00000, v20
	v_max_f32_e32 v25, 0xc1a00000, v25
	v_mul_f32_e32 v20, 0xbfb8aa3b, v20
	v_mul_f32_e32 v25, 0xbfb8aa3b, v25
	v_exp_f32_e32 v20, v20
	v_exp_f32_e32 v26, v25
	v_pk_mul_f32 v[16:17], v[16:17], v[24:25] op_sel_hi:[1,0]
	v_pk_mul_f32 v[14:15], v[14:15], v[18:19]
	v_pk_mul_f32 v[12:13], v[12:13], v[16:17]
	v_pk_add_f32 v[16:17], v[20:21], 1.0 op_sel_hi:[1,0]
	v_pk_add_f32 v[20:21], v[26:27], 1.0 op_sel_hi:[1,0]
	v_mov_b32_e32 v24, v17
	v_mov_b32_e32 v25, v21
	v_mov_b32_e32 v26, v16
	v_mov_b32_e32 v27, v20
	v_pk_mul_f32 v[24:25], v[24:25], v[26:27]
	v_pk_mul_f32 v[6:7], v[14:15], v[6:7]
	v_mul_f32_e32 v26, v24, v25
	v_rcp_f32_e32 v26, v26
	v_pk_mul_f32 v[4:5], v[12:13], v[4:5]
	s_mov_b64 s[16:17], s[10:11]
	v_mul_f32_e32 v12, v25, v26
	v_mul_f32_e32 v14, v24, v26
	v_pk_mul_f32 v[14:15], v[20:21], v[14:15] op_sel_hi:[1,0]
	v_pk_mul_f32 v[12:13], v[16:17], v[12:13] op_sel_hi:[1,0]
	v_pk_mul_f32 v[10:11], v[10:11], v[14:15]
	v_pk_mul_f32 v[8:9], v[8:9], v[12:13]
	v_pk_mul_f32 v[10:11], v[10:11], v[2:3]
	v_pk_mul_f32 v[2:3], v[8:9], v[0:1]
	v_cvt_pk_bf16_f32 v0, v4, v5
	v_cvt_pk_bf16_f32 v1, v6, v7
	s_nop 0
	v_cvt_pk_bf16_f32 v2, v2, v3
	v_cvt_pk_bf16_f32 v3, v10, v11
	global_store_dwordx4 v[22:23], v[0:3], off
	s_cbranch_vccz .LBB0_1199
	s_waitcnt vmcnt(0)
	s_cmpk_gt_u32 s23, 0xff
	s_cbranch_scc1 .LBB0_1206
	s_barrier

; #define PG8_STAGE(bufoff, gbase, voff) do { _Pragma("unroll") for (int _i = 0; _i < 2; ++_i) \
;         __builtin_amdgcn_global_load_lds((const unsigned*)((const char*)(gbase) + (voff)[_i]), (PG8_LAS unsigned*)(lds + (bufoff) + ldsw + _i * 8192), 16, 0, 0); } while (0)
; #define PG8_LDA(dst, b, h) do { _Pragma("unroll") for (int m = 0; m < 4; ++m) _Pragma("unroll") for (int k = 0; k < 2; ++k) dst[m][k] = *(const PG8_LAS bf16x8*)(lds + PG8_SA(b, h) + aoff + m * 2048 + k * 1024); } while (0)
; #define PG8_LDB(dst, b, h) do { _Pragma("unroll") for (int n = 0; n < 2; ++n) _Pragma("unroll") for (int k = 0; k < 2; ++k) dst[n][k] = *(const PG8_LAS bf16x8*)(lds + PG8_SB(b, h) + boff + n * 2048 + k * 1024); } while (0)
; #define PG8_MMA(ai, bj, At, Bt) do { __builtin_amdgcn_s_setprio(1); _Pragma("unroll") for (int m = 0; m < 4; ++m) _Pragma("unroll") for (int n = 0; n < 2; ++n) _Pragma("unroll") for (int k = 0; k < 2; ++k) \
;         acc[ai][bj][m][n] = __builtin_amdgcn_mfma_f32_16x16x32_bf16(Bt[n][k], At[m][k], acc[ai][bj][m][n], 0, 0, 0); __builtin_amdgcn_s_setprio(0); } while (0)
; #define PG8_WAIT_V(n) asm volatile("s_waitcnt vmcnt(" #n ")" ::: "memory")
; #define PG8_WAIT_L(n) asm volatile("s_waitcnt lgkmcnt(" #n ")" ::: "memory")
; #define PG8_BAR __builtin_amdgcn_s_barrier()
; #define PG8_SCHED __builtin_amdgcn_sched_barrier(0)
; template <class Epi, class Sched>
; __device__ __forceinline__ void gemm_phase(PG8_LAS unsigned char* lds, const Gemm g, const Sched& S, const Epi& E) {
;     ...
;             PG8_LDB(B0, 0, 0); PG8_SCHED; PG8_LDA(At, 0, 0); PG8_STAGE(PG8_SA(1, 1), a1 + hstep, voffA);
;             PG8_WAIT_L(8); PG8_BAR; PG8_WAIT_L(0); PG8_MMA(0, 0, At, B0); PG8_BAR; PG8_SCHED;
;             PG8_LDB(B1, 0, 1); PG8_STAGE(PG8_SB(0, 0), b2, voffB);
;             PG8_BAR; PG8_WAIT_L(0); PG8_MMA(0, 1, At, B1); PG8_BAR;
;             PG8_LDA(At, 0, 1); PG8_STAGE(PG8_SA(0, 0), a2, voffA);
;             PG8_BAR; PG8_WAIT_L(0); PG8_MMA(1, 0, At, B0); PG8_BAR; PG8_SCHED;
;             PG8_STAGE(PG8_SB(0, 1), b2 + hstep, voffB);
;             PG8_WAIT_V(6); PG8_BAR; PG8_MMA(1, 1, At, B1); PG8_BAR;
.LBB0_1278:
	ds_read_b128 v[152:155], v149
	ds_read_b128 v[156:159], v149 offset:1024
	ds_read_b128 v[160:163], v149 offset:2048
	ds_read_b128 v[164:167], v149 offset:3072
	s_add_u32 s20, s18, 0x100
	s_addc_u32 s21, s19, 0
	s_cmp_eq_u32 s54, 40
	s_cselect_b32 s25, s1, s21
	s_cselect_b32 s24, s0, s20
	s_cselect_b32 s23, s5, s53
	s_cselect_b32 s22, s4, s52
	v_lshl_add_u64 v[144:145], s[18:19], 0, v[136:137]
	s_add_i32 m0, s34, 0xc000
	ds_read_b128 v[168:171], v150
	ds_read_b128 v[172:175], v150 offset:1024
	ds_read_b128 v[182:185], v150 offset:2048
	ds_read_b128 v[190:193], v150 offset:3072
	ds_read_b128 v[194:197], v150 offset:4096
	ds_read_b128 v[198:201], v150 offset:5120
	ds_read_b128 v[202:205], v150 offset:6144
	ds_read_b128 v[206:209], v150 offset:7168
	global_load_lds_dwordx4 v[144:145], off
	v_lshl_add_u64 v[144:145], s[18:19], 0, v[138:139]
	s_add_i32 m0, s34, 0xe000
	s_nop 0
	global_load_lds_dwordx4 v[144:145], off
	s_waitcnt lgkmcnt(8)
	s_barrier
	s_waitcnt lgkmcnt(0)
	s_waitcnt lgkmcnt(0)
	v_mfma_f32_16x16x32_bf16 v[124:127], v[152:155], v[168:171], v[124:127]
	v_mfma_f32_16x16x32_bf16 v[120:123], v[160:163], v[168:171], v[120:123]
	v_mfma_f32_16x16x32_bf16 v[108:111], v[152:155], v[182:185], v[108:111]
	v_mfma_f32_16x16x32_bf16 v[104:107], v[160:163], v[182:185], v[104:107]
	v_mfma_f32_16x16x32_bf16 v[92:95], v[152:155], v[194:197], v[92:95]
	v_mfma_f32_16x16x32_bf16 v[88:91], v[160:163], v[194:197], v[88:91]
	v_mfma_f32_16x16x32_bf16 v[76:79], v[152:155], v[202:205], v[76:79]
	v_mfma_f32_16x16x32_bf16 v[72:75], v[160:163], v[202:205], v[72:75]
	v_mfma_f32_16x16x32_bf16 v[124:127], v[156:159], v[172:175], v[124:127]
	v_mfma_f32_16x16x32_bf16 v[120:123], v[164:167], v[172:175], v[120:123]
	v_mfma_f32_16x16x32_bf16 v[108:111], v[156:159], v[190:193], v[108:111]
	v_mfma_f32_16x16x32_bf16 v[104:107], v[164:167], v[190:193], v[104:107]
	v_mfma_f32_16x16x32_bf16 v[92:95], v[156:159], v[198:201], v[92:95]
	v_mfma_f32_16x16x32_bf16 v[88:91], v[164:167], v[198:201], v[88:91]
	v_mfma_f32_16x16x32_bf16 v[76:79], v[156:159], v[206:209], v[76:79]
	v_mfma_f32_16x16x32_bf16 v[72:75], v[164:167], v[206:209], v[72:75]
	s_barrier
	s_add_i32 s18, s42, s31
	v_lshl_add_u64 v[144:145], s[22:23], 0, v[130:131]
	s_mov_b32 m0, s18
	ds_read_b128 v[210:213], v151
	ds_read_b128 v[214:217], v151 offset:1024
	ds_read_b128 v[218:221], v151 offset:2048
	ds_read_b128 v[222:225], v151 offset:3072
	global_load_lds_dwordx4 v[144:145], off
	v_lshl_add_u64 v[186:187], s[22:23], 0, v[134:135]
	s_add_i32 m0, s18, 0x2000
	s_nop 0
	global_load_lds_dwordx4 v[186:187], off
	s_barrier
	s_waitcnt lgkmcnt(0)
	s_waitcnt lgkmcnt(0)
	v_mfma_f32_16x16x32_bf16 v[116:119], v[210:213], v[168:171], v[116:119]
	v_mfma_f32_16x16x32_bf16 v[112:115], v[218:221], v[168:171], v[112:115]
	v_mfma_f32_16x16x32_bf16 v[100:103], v[210:213], v[182:185], v[100:103]
	v_mfma_f32_16x16x32_bf16 v[96:99], v[218:221], v[182:185], v[96:99]
	v_mfma_f32_16x16x32_bf16 v[84:87], v[210:213], v[194:197], v[84:87]
	v_mfma_f32_16x16x32_bf16 v[80:83], v[218:221], v[194:197], v[80:83]
	v_mfma_f32_16x16x32_bf16 v[68:71], v[210:213], v[202:205], v[68:71]
	v_mfma_f32_16x16x32_bf16 v[64:67], v[218:221], v[202:205], v[64:67]
	v_mfma_f32_16x16x32_bf16 v[116:119], v[214:217], v[172:175], v[116:119]
	v_mfma_f32_16x16x32_bf16 v[112:115], v[222:225], v[172:175], v[112:115]
	v_mfma_f32_16x16x32_bf16 v[100:103], v[214:217], v[190:193], v[100:103]
	v_mfma_f32_16x16x32_bf16 v[96:99], v[222:225], v[190:193], v[96:99]
	v_mfma_f32_16x16x32_bf16 v[84:87], v[214:217], v[198:201], v[84:87]
	v_mfma_f32_16x16x32_bf16 v[80:83], v[222:225], v[198:201], v[80:83]
	v_mfma_f32_16x16x32_bf16 v[68:71], v[214:217], v[206:209], v[68:71]
	v_mfma_f32_16x16x32_bf16 v[64:67], v[222:225], v[206:209], v[64:67]
	s_barrier
	s_mov_b32 m0, s34
	v_lshl_add_u64 v[226:227], s[24:25], 0, v[128:129]
	ds_read_b128 v[168:171], v150 offset:16384
	ds_read_b128 v[172:175], v150 offset:17408
	ds_read_b128 v[182:185], v150 offset:18432
	ds_read_b128 v[190:193], v150 offset:19456
	ds_read_b128 v[194:197], v150 offset:20480
	ds_read_b128 v[198:201], v150 offset:21504
	ds_read_b128 v[202:205], v150 offset:22528
	ds_read_b128 v[206:209], v150 offset:23552
	global_load_lds_dwordx4 v[226:227], off
	v_lshl_add_u64 v[228:229], s[24:25], 0, v[132:133]
	s_mov_b32 m0, s35
	s_nop 0
	global_load_lds_dwordx4 v[228:229], off
	s_barrier
	s_waitcnt lgkmcnt(0)
	s_waitcnt lgkmcnt(0)
	v_mfma_f32_16x16x32_bf16 v[60:63], v[152:155], v[168:171], v[60:63]
	v_mfma_f32_16x16x32_bf16 v[56:59], v[160:163], v[168:171], v[56:59]
	v_mfma_f32_16x16x32_bf16 v[48:51], v[152:155], v[182:185], v[48:51]
	v_mfma_f32_16x16x32_bf16 v[40:43], v[160:163], v[182:185], v[40:43]
	v_mfma_f32_16x16x32_bf16 v[32:35], v[152:155], v[194:197], v[32:35]
	v_mfma_f32_16x16x32_bf16 v[24:27], v[160:163], v[194:197], v[24:27]
	v_mfma_f32_16x16x32_bf16 v[16:19], v[152:155], v[202:205], v[16:19]
	v_mfma_f32_16x16x32_bf16 v[8:11], v[160:163], v[202:205], v[8:11]
	v_mfma_f32_16x16x32_bf16 v[60:63], v[156:159], v[172:175], v[60:63]
	v_mfma_f32_16x16x32_bf16 v[56:59], v[164:167], v[172:175], v[56:59]
	v_mfma_f32_16x16x32_bf16 v[48:51], v[156:159], v[190:193], v[48:51]
	v_mfma_f32_16x16x32_bf16 v[40:43], v[164:167], v[190:193], v[40:43]
	v_mfma_f32_16x16x32_bf16 v[32:35], v[156:159], v[198:201], v[32:35]
	v_mfma_f32_16x16x32_bf16 v[24:27], v[164:167], v[198:201], v[24:27]
	v_mfma_f32_16x16x32_bf16 v[16:19], v[156:159], v[206:209], v[16:19]
	v_mfma_f32_16x16x32_bf16 v[8:11], v[164:167], v[206:209], v[8:11]
	s_barrier
; #define PG8_STAGE(bufoff, gbase, voff) do { _Pragma("unroll") for (int _i = 0; _i < 2; ++_i) \
;         __builtin_amdgcn_global_load_lds((const unsigned*)((const char*)(gbase) + (voff)[_i]), (PG8_LAS unsigned*)(lds + (bufoff) + ldsw + _i * 8192), 16, 0, 0); } while (0)
; #define PG8_LDA(dst, b, h) do { _Pragma("unroll") for (int m = 0; m < 4; ++m) _Pragma("unroll") for (int k = 0; k < 2; ++k) dst[m][k] = *(const PG8_LAS bf16x8*)(lds + PG8_SA(b, h) + aoff + m * 2048 + k * 1024); } while (0)
; #define PG8_LDB(dst, b, h) do { _Pragma("unroll") for (int n = 0; n < 2; ++n) _Pragma("unroll") for (int k = 0; k < 2; ++k) dst[n][k] = *(const PG8_LAS bf16x8*)(lds + PG8_SB(b, h) + boff + n * 2048 + k * 1024); } while (0)
; #define PG8_MMA(ai, bj, At, Bt) do { __builtin_amdgcn_s_setprio(1); _Pragma("unroll") for (int m = 0; m < 4; ++m) _Pragma("unroll") for (int n = 0; n < 2; ++n) _Pragma("unroll") for (int k = 0; k < 2; ++k) \
;         acc[ai][bj][m][n] = __builtin_amdgcn_mfma_f32_16x16x32_bf16(Bt[n][k], At[m][k], acc[ai][bj][m][n], 0, 0, 0); __builtin_amdgcn_s_setprio(0); } while (0)
; #define PG8_WAIT_V(n) asm volatile("s_waitcnt vmcnt(" #n ")" ::: "memory")
; #define PG8_WAIT_L(n) asm volatile("s_waitcnt lgkmcnt(" #n ")" ::: "memory")
; #define PG8_BAR __builtin_amdgcn_s_barrier()
; #define PG8_SCHED __builtin_amdgcn_sched_barrier(0)
; template <class Epi, class Sched>
; __device__ __forceinline__ void gemm_phase(PG8_LAS unsigned char* lds, const Gemm g, const Sched& S, const Epi& E) {
;     ...
;             PG8_STAGE(PG8_SB(0, 1), b2 + hstep, voffB);
;             PG8_WAIT_V(6); PG8_BAR; PG8_MMA(1, 1, At, B1); PG8_BAR;
;             PG8_LDB(B0, 1, 0); PG8_SCHED; PG8_LDA(At, 1, 0); PG8_STAGE(PG8_SA(0, 1), a2 + hstep, voffA);
;             PG8_WAIT_L(8); PG8_BAR; PG8_WAIT_L(0); PG8_MMA(0, 0, At, B0); PG8_BAR; PG8_SCHED;
;             PG8_LDB(B1, 1, 1); PG8_STAGE(PG8_SB(1, 0), b3, voffB);
;             PG8_BAR; PG8_WAIT_L(0); PG8_MMA(0, 1, At, B1); PG8_BAR;
;             PG8_LDA(At, 1, 1); PG8_STAGE(PG8_SA(1, 0), a3, voffA);
;             PG8_BAR; PG8_WAIT_L(0); PG8_MMA(1, 0, At, B0); PG8_BAR; PG8_SCHED;
	s_add_u32 s18, s22, 0xb0000
	s_addc_u32 s19, s23, 0
	s_add_i32 s55, s43, s31
	v_lshl_add_u64 v[152:153], s[18:19], 0, v[130:131]
	s_mov_b32 m0, s55
	s_nop 0
	global_load_lds_dwordx4 v[152:153], off
	v_lshl_add_u64 v[152:153], s[18:19], 0, v[134:135]
	s_add_i32 m0, s55, 0x2000
	s_nop 0
	global_load_lds_dwordx4 v[152:153], off
	s_waitcnt vmcnt(6)
	s_barrier
	v_mfma_f32_16x16x32_bf16 v[52:55], v[210:213], v[168:171], v[52:55]
	v_mfma_f32_16x16x32_bf16 v[44:47], v[218:221], v[168:171], v[44:47]
	v_mfma_f32_16x16x32_bf16 v[36:39], v[210:213], v[182:185], v[36:39]
	v_mfma_f32_16x16x32_bf16 v[28:31], v[218:221], v[182:185], v[28:31]
	v_mfma_f32_16x16x32_bf16 v[20:23], v[210:213], v[194:197], v[20:23]
	v_mfma_f32_16x16x32_bf16 v[12:15], v[218:221], v[194:197], v[12:15]
	v_mfma_f32_16x16x32_bf16 v[4:7], v[210:213], v[202:205], v[4:7]
	v_mfma_f32_16x16x32_bf16 v[0:3], v[218:221], v[202:205], v[0:3]
	v_mfma_f32_16x16x32_bf16 v[52:55], v[214:217], v[172:175], v[52:55]
	v_mfma_f32_16x16x32_bf16 v[44:47], v[222:225], v[172:175], v[44:47]
	v_mfma_f32_16x16x32_bf16 v[36:39], v[214:217], v[190:193], v[36:39]
	v_mfma_f32_16x16x32_bf16 v[28:31], v[222:225], v[190:193], v[28:31]
	v_mfma_f32_16x16x32_bf16 v[20:23], v[214:217], v[198:201], v[20:23]
	v_mfma_f32_16x16x32_bf16 v[12:15], v[222:225], v[198:201], v[12:15]
	v_mfma_f32_16x16x32_bf16 v[4:7], v[214:217], v[206:209], v[4:7]
	v_mfma_f32_16x16x32_bf16 v[0:3], v[222:225], v[206:209], v[0:3]
	s_barrier
	s_add_i32 s55, 0, 0x18000
	v_add_u32_e32 v164, s55, v147
	ds_read_b128 v[152:155], v164
	ds_read_b128 v[156:159], v164 offset:1024
	ds_read_b128 v[160:163], v164 offset:2048
	ds_read_b128 v[164:167], v164 offset:3072
	s_add_u32 s18, s24, 0xb0000
	s_addc_u32 s19, s25, 0
	s_mov_b32 m0, s36
	v_lshl_add_u64 v[210:211], s[18:19], 0, v[128:129]
	ds_read_b128 v[168:171], v150 offset:32768
	ds_read_b128 v[172:175], v150 offset:33792
	ds_read_b128 v[182:185], v150 offset:34816
	ds_read_b128 v[190:193], v150 offset:35840
	ds_read_b128 v[194:197], v150 offset:36864
	ds_read_b128 v[198:201], v150 offset:37888
	ds_read_b128 v[202:205], v150 offset:38912
	ds_read_b128 v[206:209], v150 offset:39936
	global_load_lds_dwordx4 v[210:211], off
	v_lshl_add_u64 v[210:211], s[18:19], 0, v[132:133]
	s_mov_b32 m0, s37
	s_nop 0
	global_load_lds_dwordx4 v[210:211], off
	s_waitcnt lgkmcnt(8)
	s_barrier
	s_waitcnt lgkmcnt(0)
	s_waitcnt lgkmcnt(0)
	v_mfma_f32_16x16x32_bf16 v[124:127], v[152:155], v[168:171], v[124:127]
	v_mfma_f32_16x16x32_bf16 v[120:123], v[160:163], v[168:171], v[120:123]
	v_mfma_f32_16x16x32_bf16 v[108:111], v[152:155], v[182:185], v[108:111]
	v_mfma_f32_16x16x32_bf16 v[104:107], v[160:163], v[182:185], v[104:107]
	v_mfma_f32_16x16x32_bf16 v[92:95], v[152:155], v[194:197], v[92:95]
	v_mfma_f32_16x16x32_bf16 v[88:91], v[160:163], v[194:197], v[88:91]
	v_mfma_f32_16x16x32_bf16 v[76:79], v[152:155], v[202:205], v[76:79]
	v_mfma_f32_16x16x32_bf16 v[72:75], v[160:163], v[202:205], v[72:75]
	v_mfma_f32_16x16x32_bf16 v[124:127], v[156:159], v[172:175], v[124:127]
	v_mfma_f32_16x16x32_bf16 v[120:123], v[164:167], v[172:175], v[120:123]
	v_mfma_f32_16x16x32_bf16 v[108:111], v[156:159], v[190:193], v[108:111]
	v_mfma_f32_16x16x32_bf16 v[104:107], v[164:167], v[190:193], v[104:107]
	v_mfma_f32_16x16x32_bf16 v[92:95], v[156:159], v[198:201], v[92:95]
	v_mfma_f32_16x16x32_bf16 v[88:91], v[164:167], v[198:201], v[88:91]
	v_mfma_f32_16x16x32_bf16 v[76:79], v[156:159], v[206:209], v[76:79]
	v_mfma_f32_16x16x32_bf16 v[72:75], v[164:167], v[206:209], v[72:75]
	s_barrier
	s_add_i32 s24, 0, 0x1c000
	s_add_i32 s18, s55, s31
	v_add_u32_e32 v179, s24, v147
	v_lshl_add_u64 v[144:145], v[144:145], 0, s[8:9]
	s_mov_b32 m0, s18
	ds_read_b128 v[210:213], v179
	ds_read_b128 v[214:217], v179 offset:1024
	ds_read_b128 v[218:221], v179 offset:2048
	ds_read_b128 v[222:225], v179 offset:3072
	global_load_lds_dwordx4 v[144:145], off
	v_lshl_add_u64 v[144:145], v[186:187], 0, s[8:9]
	s_add_i32 m0, s18, 0x2000
	s_nop 0
	global_load_lds_dwordx4 v[144:145], off
	s_barrier
	s_waitcnt lgkmcnt(0)
	s_waitcnt lgkmcnt(0)
	v_mfma_f32_16x16x32_bf16 v[116:119], v[210:213], v[168:171], v[116:119]
	v_mfma_f32_16x16x32_bf16 v[112:115], v[218:221], v[168:171], v[112:115]
	v_mfma_f32_16x16x32_bf16 v[100:103], v[210:213], v[182:185], v[100:103]
	v_mfma_f32_16x16x32_bf16 v[96:99], v[218:221], v[182:185], v[96:99]
	v_mfma_f32_16x16x32_bf16 v[84:87], v[210:213], v[194:197], v[84:87]
	v_mfma_f32_16x16x32_bf16 v[80:83], v[218:221], v[194:197], v[80:83]
	v_mfma_f32_16x16x32_bf16 v[68:71], v[210:213], v[202:205], v[68:71]
	v_mfma_f32_16x16x32_bf16 v[64:67], v[218:221], v[202:205], v[64:67]
	v_mfma_f32_16x16x32_bf16 v[116:119], v[214:217], v[172:175], v[116:119]
	v_mfma_f32_16x16x32_bf16 v[112:115], v[222:225], v[172:175], v[112:115]
	v_mfma_f32_16x16x32_bf16 v[100:103], v[214:217], v[190:193], v[100:103]
	v_mfma_f32_16x16x32_bf16 v[96:99], v[222:225], v[190:193], v[96:99]
	v_mfma_f32_16x16x32_bf16 v[84:87], v[214:217], v[198:201], v[84:87]
	v_mfma_f32_16x16x32_bf16 v[80:83], v[222:225], v[198:201], v[80:83]
	v_mfma_f32_16x16x32_bf16 v[68:71], v[214:217], v[206:209], v[68:71]
	v_mfma_f32_16x16x32_bf16 v[64:67], v[222:225], v[206:209], v[64:67]
	s_barrier
	s_mov_b32 m0, s39
	v_lshl_add_u64 v[144:145], v[226:227], 0, s[8:9]
	ds_read_b128 v[168:171], v150 offset:49152
	ds_read_b128 v[172:175], v150 offset:50176
	ds_read_b128 v[182:185], v150 offset:51200
	ds_read_b128 v[190:193], v150 offset:52224
	ds_read_b128 v[194:197], v150 offset:53248
	ds_read_b128 v[198:201], v150 offset:54272
	ds_read_b128 v[202:205], v150 offset:55296
	ds_read_b128 v[206:209], v150 offset:56320
	global_load_lds_dwordx4 v[144:145], off
	v_lshl_add_u64 v[144:145], v[228:229], 0, s[8:9]
	s_mov_b32 m0, s40
	s_nop 0
	global_load_lds_dwordx4 v[144:145], off
	s_barrier
; __device__ __forceinline__ unsigned cvt_pk_bf16(float lo, float hi) { unsigned r; asm volatile("v_cvt_pk_bf16_f32 %0, %1, %2" : "=v"(r) : "v"(lo), "v"(hi)); return r; }
; __device__ __forceinline__ float flogsig16(float x) { return (fminf(x, 0.f) - __logf(1.0f + __expf(-fabsf(x)))) * 0.0625f; }
; #define PG8_STAGE(bufoff, gbase, voff) do { _Pragma("unroll") for (int _i = 0; _i < 2; ++_i) \
;         __builtin_amdgcn_global_load_lds((const unsigned*)((const char*)(gbase) + (voff)[_i]), (PG8_LAS unsigned*)(lds + (bufoff) + ldsw + _i * 8192), 16, 0, 0); } while (0)
;     __device__ __forceinline__ void operator()(const f32x4 (&acc)[2][2][4][2], const Unit& u, int wr, int wc, int fr, int fq) const {
;     ...
;         const int row0 = u.pm * BM + wr * 64 + fr, col0 = u.pn * BM + wc * 32 + 8 * fq, bcol0 = wc * 32 + 8 * fq;
;         f32x4 bv[2][2];
; #pragma unroll
;         for (int bj = 0; bj < 2; ++bj)
; #pragma unroll
;             for (int n = 0; n < 2; ++n) bv[bj][n] = bias ? *(const f32x4*)(bias + bcol0 + bj * HALF + 4 * n) : (f32x4){0.f, 0.f, 0.f, 0.f};
; #pragma unroll
;         for (int ai = 0; ai < 2; ++ai)
; #pragma unroll
;             for (int m = 0; m < 4; ++m) { bf16_t* rowp = O + (size_t)(row0 + ai * HALF + m * 16) * ldc + col0;
; #pragma unroll
;                 for (int bj = 0; bj < 2; ++bj) { f32x4 v0 = acc[ai][bj][m][0] + bv[bj][0], v1 = acc[ai][bj][m][1] + bv[bj][1];
;                     if (act == 1) {
; #pragma unroll
;                         for (int j = 0; j < 1; ++j) { v0 = v0 * sigmoid4(v0); v1 = v1 * sigmoid4(v1); } }
;                     else if (act == 2) {
; #pragma unroll
;                         for (int j = 0; j < 1; ++j) { v0 = sigmoid4(v0); v1 = sigmoid4(v1); } }
;                     else if (act == 3) {
; #pragma unroll
;                         for (int j = 0; j < 4; ++j) { v0[j] = flogsig16(v0[j]); v1[j] = flogsig16(v1[j]); } }
;                     u32x4 w; w.x = cvt_pk_bf16(v0[0], v0[1]); w.y = cvt_pk_bf16(v0[2], v0[3]); w.z = cvt_pk_bf16(v1[0], v1[1]); w.w = cvt_pk_bf16(v1[2], v1[3]);
;                     *(u32x4*)(rowp + bj * HALF) = w; } }
; template <class Epi, class Sched>
; __device__ __forceinline__ void gemm_phase(PG8_LAS unsigned char* lds, const Gemm g, const Sched& S, const Epi& E) {
;     ...
;             PG8_STAGE(PG8_SB(1, 1), b3 + hstep, voffB);
;             PG8_WAIT_V(6); PG8_BAR; PG8_MMA(1, 1, At, B1); PG8_BAR;
	s_waitcnt lgkmcnt(0)
	s_waitcnt lgkmcnt(0)
	v_mfma_f32_16x16x32_bf16 v[60:63], v[152:155], v[168:171], v[60:63]
	v_mfma_f32_16x16x32_bf16 v[56:59], v[160:163], v[168:171], v[56:59]
	v_mfma_f32_16x16x32_bf16 v[48:51], v[152:155], v[182:185], v[48:51]
	v_mfma_f32_16x16x32_bf16 v[40:43], v[160:163], v[182:185], v[40:43]
	v_mfma_f32_16x16x32_bf16 v[32:35], v[152:155], v[194:197], v[32:35]
	v_mfma_f32_16x16x32_bf16 v[24:27], v[160:163], v[194:197], v[24:27]
	v_mfma_f32_16x16x32_bf16 v[16:19], v[152:155], v[202:205], v[16:19]
	v_mfma_f32_16x16x32_bf16 v[8:11], v[160:163], v[202:205], v[8:11]
	v_mfma_f32_16x16x32_bf16 v[60:63], v[156:159], v[172:175], v[60:63]
	v_mfma_f32_16x16x32_bf16 v[56:59], v[164:167], v[172:175], v[56:59]
	v_mfma_f32_16x16x32_bf16 v[48:51], v[156:159], v[190:193], v[48:51]
	v_mfma_f32_16x16x32_bf16 v[40:43], v[164:167], v[190:193], v[40:43]
	v_mfma_f32_16x16x32_bf16 v[32:35], v[156:159], v[198:201], v[32:35]
	v_mfma_f32_16x16x32_bf16 v[24:27], v[164:167], v[198:201], v[24:27]
	v_mfma_f32_16x16x32_bf16 v[16:19], v[156:159], v[206:209], v[16:19]
	v_mfma_f32_16x16x32_bf16 v[8:11], v[164:167], v[206:209], v[8:11]
	s_barrier
	s_add_u32 s18, s22, 0xb0080
	s_addc_u32 s19, s23, 0
	s_add_i32 s22, s24, s31
	v_lshl_add_u64 v[144:145], s[18:19], 0, v[130:131]
	s_mov_b32 m0, s22
	s_nop 0
	global_load_lds_dwordx4 v[144:145], off
	v_lshl_add_u64 v[144:145], s[18:19], 0, v[134:135]
	s_add_i32 m0, s22, 0x2000
	s_nop 0
	global_load_lds_dwordx4 v[144:145], off
	s_waitcnt vmcnt(6)
	s_barrier
	v_mfma_f32_16x16x32_bf16 v[52:55], v[210:213], v[168:171], v[52:55]
	v_mfma_f32_16x16x32_bf16 v[44:47], v[218:221], v[168:171], v[44:47]
	v_mfma_f32_16x16x32_bf16 v[36:39], v[210:213], v[182:185], v[36:39]
	v_mfma_f32_16x16x32_bf16 v[28:31], v[218:221], v[182:185], v[28:31]
	v_mfma_f32_16x16x32_bf16 v[20:23], v[210:213], v[194:197], v[20:23]
	v_mfma_f32_16x16x32_bf16 v[12:15], v[218:221], v[194:197], v[12:15]
	v_mfma_f32_16x16x32_bf16 v[4:7], v[210:213], v[202:205], v[4:7]
	v_mfma_f32_16x16x32_bf16 v[0:3], v[218:221], v[202:205], v[0:3]
	v_mfma_f32_16x16x32_bf16 v[52:55], v[214:217], v[172:175], v[52:55]
	v_mfma_f32_16x16x32_bf16 v[44:47], v[222:225], v[172:175], v[44:47]
	v_mfma_f32_16x16x32_bf16 v[36:39], v[214:217], v[190:193], v[36:39]
	v_mfma_f32_16x16x32_bf16 v[28:31], v[222:225], v[190:193], v[28:31]
	v_mfma_f32_16x16x32_bf16 v[20:23], v[214:217], v[198:201], v[20:23]
	v_mfma_f32_16x16x32_bf16 v[12:15], v[222:225], v[198:201], v[12:15]
	v_mfma_f32_16x16x32_bf16 v[4:7], v[214:217], v[206:209], v[4:7]
	v_mfma_f32_16x16x32_bf16 v[0:3], v[222:225], v[206:209], v[0:3]
	s_add_i32 s54, s54, 2
	s_add_u32 s52, s52, 0x100
	s_addc_u32 s53, s53, 0
	s_cmp_gt_u32 s54, 41
	s_mov_b64 s[18:19], s[20:21]
	s_barrier
	s_cbranch_scc0 .LBB0_1278
	v_lshl_add_u32 v152, s50, 8, v146
	v_lshl_or_b32 v144, s51, 8, v148
	v_ashrrev_i32_e32 v153, 31, v152
	v_ashrrev_i32_e32 v145, 31, v144
	v_lshlrev_b64 v[154:155], 11, v[152:153]
	v_lshl_add_u64 v[154:155], s[6:7], 0, v[154:155]
	v_lshlrev_b64 v[156:157], 1, v[144:145]
	v_lshl_add_u64 v[144:145], v[154:155], 0, v[156:157]
	v_pk_add_f32 v[126:127], v[126:127], 0 op_sel_hi:[1,0]
	v_pk_add_f32 v[124:125], v[124:125], 0 op_sel_hi:[1,0]
	v_pk_add_f32 v[154:155], v[122:123], 0 op_sel_hi:[1,0]
	v_pk_add_f32 v[122:123], v[120:121], 0 op_sel_hi:[1,0]
	v_cvt_pk_bf16_f32 v120, v124, v125
	v_cvt_pk_bf16_f32 v121, v126, v127
	v_pk_add_f32 v[116:117], v[116:117], 0 op_sel_hi:[1,0]
	v_cvt_pk_bf16_f32 v122, v122, v123
	v_cvt_pk_bf16_f32 v123, v154, v155
	global_store_dwordx4 v[144:145], v[120:123], off
	v_pk_add_f32 v[118:119], v[118:119], 0 op_sel_hi:[1,0]
	v_pk_add_f32 v[110:111], v[110:111], 0 op_sel_hi:[1,0]
	v_pk_add_f32 v[120:121], v[114:115], 0 op_sel_hi:[1,0]
	v_pk_add_f32 v[114:115], v[112:113], 0 op_sel_hi:[1,0]
	v_cvt_pk_bf16_f32 v112, v116, v117
	v_cvt_pk_bf16_f32 v113, v118, v119
	v_pk_add_f32 v[108:109], v[108:109], 0 op_sel_hi:[1,0]
	v_cvt_pk_bf16_f32 v114, v114, v115
	v_cvt_pk_bf16_f32 v115, v120, v121
	global_store_dwordx4 v[144:145], v[112:115], off offset:256
	v_pk_add_f32 v[100:101], v[100:101], 0 op_sel_hi:[1,0]
	v_pk_add_f32 v[102:103], v[102:103], 0 op_sel_hi:[1,0]
	v_or_b32_e32 v112, 16, v152
	v_ashrrev_i32_e32 v113, 31, v112
	v_lshlrev_b64 v[112:113], 11, v[112:113]
	v_lshl_add_u64 v[112:113], s[6:7], 0, v[112:113]
	v_lshl_add_u64 v[112:113], v[112:113], 0, v[156:157]
	v_pk_add_f32 v[114:115], v[106:107], 0 op_sel_hi:[1,0]
	v_pk_add_f32 v[106:107], v[104:105], 0 op_sel_hi:[1,0]
	v_cvt_pk_bf16_f32 v104, v108, v109
	v_cvt_pk_bf16_f32 v105, v110, v111
	v_pk_add_f32 v[94:95], v[94:95], 0 op_sel_hi:[1,0]
	v_cvt_pk_bf16_f32 v106, v106, v107
	v_cvt_pk_bf16_f32 v107, v114, v115
	global_store_dwordx4 v[112:113], v[104:107], off
	v_pk_add_f32 v[92:93], v[92:93], 0 op_sel_hi:[1,0]
	v_pk_add_f32 v[84:85], v[84:85], 0 op_sel_hi:[1,0]
	v_pk_add_f32 v[104:105], v[98:99], 0 op_sel_hi:[1,0]
	v_pk_add_f32 v[98:99], v[96:97], 0 op_sel_hi:[1,0]
	v_cvt_pk_bf16_f32 v96, v100, v101
	v_cvt_pk_bf16_f32 v97, v102, v103
	v_pk_add_f32 v[86:87], v[86:87], 0 op_sel_hi:[1,0]
	v_cvt_pk_bf16_f32 v98, v98, v99
	v_cvt_pk_bf16_f32 v99, v104, v105
	global_store_dwordx4 v[112:113], v[96:99], off offset:256
	v_pk_add_f32 v[78:79], v[78:79], 0 op_sel_hi:[1,0]
	v_pk_add_f32 v[76:77], v[76:77], 0 op_sel_hi:[1,0]
	v_or_b32_e32 v96, 32, v152
	v_ashrrev_i32_e32 v97, 31, v96
	v_lshlrev_b64 v[96:97], 11, v[96:97]
	v_lshl_add_u64 v[96:97], s[6:7], 0, v[96:97]
; __device__ __forceinline__ unsigned cvt_pk_bf16(float lo, float hi) { unsigned r; asm volatile("v_cvt_pk_bf16_f32 %0, %1, %2" : "=v"(r) : "v"(lo), "v"(hi)); return r; }
; __device__ __forceinline__ float flogsig16(float x) { return (fminf(x, 0.f) - __logf(1.0f + __expf(-fabsf(x)))) * 0.0625f; }
;     __device__ __forceinline__ void operator()(const f32x4 (&acc)[2][2][4][2], const Unit& u, int wr, int wc, int fr, int fq) const {
;     ...
;             for (int m = 0; m < 4; ++m) { bf16_t* rowp = O + (size_t)(row0 + ai * HALF + m * 16) * ldc + col0;
; #pragma unroll
;                 for (int bj = 0; bj < 2; ++bj) { f32x4 v0 = acc[ai][bj][m][0] + bv[bj][0], v1 = acc[ai][bj][m][1] + bv[bj][1];
;                     if (act == 1) {
; #pragma unroll
;                         for (int j = 0; j < 1; ++j) { v0 = v0 * sigmoid4(v0); v1 = v1 * sigmoid4(v1); } }
;                     else if (act == 2) {
; #pragma unroll
;                         for (int j = 0; j < 1; ++j) { v0 = sigmoid4(v0); v1 = sigmoid4(v1); } }
;                     else if (act == 3) {
; #pragma unroll
;                         for (int j = 0; j < 4; ++j) { v0[j] = flogsig16(v0[j]); v1[j] = flogsig16(v1[j]); } }
;                     u32x4 w; w.x = cvt_pk_bf16(v0[0], v0[1]); w.y = cvt_pk_bf16(v0[2], v0[3]); w.z = cvt_pk_bf16(v1[0], v1[1]); w.w = cvt_pk_bf16(v1[2], v1[3]);
;                     *(u32x4*)(rowp + bj * HALF) = w; } }
	v_lshl_add_u64 v[96:97], v[96:97], 0, v[156:157]
	v_pk_add_f32 v[98:99], v[90:91], 0 op_sel_hi:[1,0]
	v_pk_add_f32 v[90:91], v[88:89], 0 op_sel_hi:[1,0]
	v_cvt_pk_bf16_f32 v88, v92, v93
	v_cvt_pk_bf16_f32 v89, v94, v95
	v_pk_add_f32 v[70:71], v[70:71], 0 op_sel_hi:[1,0]
	v_cvt_pk_bf16_f32 v90, v90, v91
	v_cvt_pk_bf16_f32 v91, v98, v99
	global_store_dwordx4 v[96:97], v[88:91], off
	v_pk_add_f32 v[68:69], v[68:69], 0 op_sel_hi:[1,0]
	v_pk_add_f32 v[60:61], v[60:61], 0 op_sel_hi:[1,0]
	v_pk_add_f32 v[88:89], v[82:83], 0 op_sel_hi:[1,0]
	v_pk_add_f32 v[82:83], v[80:81], 0 op_sel_hi:[1,0]
	v_cvt_pk_bf16_f32 v80, v84, v85
	v_cvt_pk_bf16_f32 v81, v86, v87
	v_pk_add_f32 v[62:63], v[62:63], 0 op_sel_hi:[1,0]
	v_cvt_pk_bf16_f32 v82, v82, v83
	v_cvt_pk_bf16_f32 v83, v88, v89
	global_store_dwordx4 v[96:97], v[80:83], off offset:256
	v_pk_add_f32 v[54:55], v[54:55], 0 op_sel_hi:[1,0]
	v_pk_add_f32 v[52:53], v[52:53], 0 op_sel_hi:[1,0]
	v_or_b32_e32 v80, 48, v152
	v_ashrrev_i32_e32 v81, 31, v80
	v_lshlrev_b64 v[80:81], 11, v[80:81]
	v_lshl_add_u64 v[80:81], s[6:7], 0, v[80:81]
	v_lshl_add_u64 v[80:81], v[80:81], 0, v[156:157]
	v_pk_add_f32 v[82:83], v[74:75], 0 op_sel_hi:[1,0]
	v_pk_add_f32 v[74:75], v[72:73], 0 op_sel_hi:[1,0]
	v_cvt_pk_bf16_f32 v72, v76, v77
	v_cvt_pk_bf16_f32 v73, v78, v79
	v_pk_add_f32 v[48:49], v[48:49], 0 op_sel_hi:[1,0]
	v_cvt_pk_bf16_f32 v74, v74, v75
	v_cvt_pk_bf16_f32 v75, v82, v83
	global_store_dwordx4 v[80:81], v[72:75], off
	v_pk_add_f32 v[38:39], v[38:39], 0 op_sel_hi:[1,0]
	v_pk_add_f32 v[36:37], v[36:37], 0 op_sel_hi:[1,0]
	v_pk_add_f32 v[72:73], v[66:67], 0 op_sel_hi:[1,0]
	v_pk_add_f32 v[66:67], v[64:65], 0 op_sel_hi:[1,0]
	v_cvt_pk_bf16_f32 v64, v68, v69
	v_cvt_pk_bf16_f32 v65, v70, v71
	v_pk_add_f32 v[32:33], v[32:33], 0 op_sel_hi:[1,0]
	v_cvt_pk_bf16_f32 v66, v66, v67
	v_cvt_pk_bf16_f32 v67, v72, v73
	global_store_dwordx4 v[80:81], v[64:67], off offset:256
	v_pk_add_f32 v[22:23], v[22:23], 0 op_sel_hi:[1,0]
	v_pk_add_f32 v[20:21], v[20:21], 0 op_sel_hi:[1,0]
	v_pk_add_f32 v[66:67], v[58:59], 0 op_sel_hi:[1,0]
	v_pk_add_f32 v[58:59], v[56:57], 0 op_sel_hi:[1,0]
	v_cvt_pk_bf16_f32 v56, v60, v61
	v_add_co_u32_e32 v60, vcc, s44, v144
	v_cvt_pk_bf16_f32 v57, v62, v63
	v_cvt_pk_bf16_f32 v58, v58, v59
	v_cvt_pk_bf16_f32 v59, v66, v67
	v_lshl_add_u64 v[64:65], v[144:145], 0, s[10:11]
	s_nop 0
	v_addc_co_u32_e32 v61, vcc, 0, v145, vcc
	global_store_dwordx4 v[60:61], v[56:59], off
	v_pk_add_f32 v[16:17], v[16:17], 0 op_sel_hi:[1,0]
	s_mov_b32 s51, s48
	v_pk_add_f32 v[56:57], v[46:47], 0 op_sel_hi:[1,0]
	v_pk_add_f32 v[46:47], v[44:45], 0 op_sel_hi:[1,0]
	v_cvt_pk_bf16_f32 v44, v52, v53
	v_cvt_pk_bf16_f32 v45, v54, v55
	s_mov_b32 s50, s49
	v_cvt_pk_bf16_f32 v46, v46, v47
	v_cvt_pk_bf16_f32 v47, v56, v57
	global_store_dwordx4 v[64:65], v[44:47], off offset:256
	s_mov_b64 s[20:21], s[4:5]
	s_mov_b64 s[18:19], s[0:1]
	v_pk_add_f32 v[46:47], v[50:51], 0 op_sel_hi:[1,0]
	v_pk_add_f32 v[50:51], v[42:43], 0 op_sel_hi:[1,0]
	v_pk_add_f32 v[42:43], v[40:41], 0 op_sel_hi:[1,0]
	v_cvt_pk_bf16_f32 v40, v48, v49
	v_cvt_pk_bf16_f32 v41, v46, v47
	v_add_co_u32_e32 v46, vcc, s45, v144
	v_cvt_pk_bf16_f32 v42, v42, v43
	v_cvt_pk_bf16_f32 v43, v50, v51
	v_lshl_add_u64 v[44:45], v[144:145], 0, s[12:13]
	s_nop 0
	v_addc_co_u32_e32 v47, vcc, 0, v145, vcc
	global_store_dwordx4 v[46:47], v[40:43], off
	v_pk_add_f32 v[6:7], v[6:7], 0 op_sel_hi:[1,0]
	v_pk_add_f32 v[4:5], v[4:5], 0 op_sel_hi:[1,0]
	v_pk_add_f32 v[40:41], v[30:31], 0 op_sel_hi:[1,0]
	v_pk_add_f32 v[30:31], v[28:29], 0 op_sel_hi:[1,0]
	v_cvt_pk_bf16_f32 v28, v36, v37
	v_cvt_pk_bf16_f32 v29, v38, v39
	s_nop 0
	v_cvt_pk_bf16_f32 v30, v30, v31
	v_cvt_pk_bf16_f32 v31, v40, v41
	global_store_dwordx4 v[44:45], v[28:31], off offset:256
	s_nop 1
	v_pk_add_f32 v[30:31], v[34:35], 0 op_sel_hi:[1,0]
	v_pk_add_f32 v[34:35], v[26:27], 0 op_sel_hi:[1,0]
	v_pk_add_f32 v[26:27], v[24:25], 0 op_sel_hi:[1,0]
	v_cvt_pk_bf16_f32 v24, v32, v33
	v_cvt_pk_bf16_f32 v25, v30, v31
	v_add_co_u32_e32 v30, vcc, s46, v144
	v_cvt_pk_bf16_f32 v26, v26, v27
	v_cvt_pk_bf16_f32 v27, v34, v35
	v_lshl_add_u64 v[28:29], v[144:145], 0, s[14:15]
	s_nop 0
	v_addc_co_u32_e32 v31, vcc, 0, v145, vcc
	global_store_dwordx4 v[30:31], v[24:27], off
	s_nop 1
	v_pk_add_f32 v[24:25], v[14:15], 0 op_sel_hi:[1,0]
	v_pk_add_f32 v[14:15], v[12:13], 0 op_sel_hi:[1,0]
	v_cvt_pk_bf16_f32 v12, v20, v21
	v_cvt_pk_bf16_f32 v13, v22, v23
	s_nop 0
	v_cvt_pk_bf16_f32 v14, v14, v15
	v_cvt_pk_bf16_f32 v15, v24, v25
	global_store_dwordx4 v[28:29], v[12:15], off offset:256
	s_nop 1
	v_pk_add_f32 v[14:15], v[18:19], 0 op_sel_hi:[1,0]
	v_pk_add_f32 v[18:19], v[10:11], 0 op_sel_hi:[1,0]
	v_pk_add_f32 v[10:11], v[8:9], 0 op_sel_hi:[1,0]
	v_cvt_pk_bf16_f32 v8, v16, v17
	v_cvt_pk_bf16_f32 v9, v14, v15
	v_add_co_u32_e32 v14, vcc, s47, v144
	v_lshl_add_u64 v[12:13], v[144:145], 0, s[16:17]
	s_nop 0
	v_addc_co_u32_e32 v15, vcc, 0, v145, vcc
	v_cvt_pk_bf16_f32 v10, v10, v11
	v_cvt_pk_bf16_f32 v11, v18, v19
	global_store_dwordx4 v[14:15], v[8:11], off
	s_and_b64 vcc, exec, s[2:3]
	s_nop 0
	v_pk_add_f32 v[8:9], v[2:3], 0 op_sel_hi:[1,0]
	v_pk_add_f32 v[2:3], v[0:1], 0 op_sel_hi:[1,0]
	v_cvt_pk_bf16_f32 v0, v4, v5
	v_cvt_pk_bf16_f32 v1, v6, v7
	s_nop 0
	v_cvt_pk_bf16_f32 v2, v2, v3
	v_cvt_pk_bf16_f32 v3, v8, v9
	global_store_dwordx4 v[12:13], v[0:3], off offset:256
	s_cbranch_vccz .LBB0_1267
	s_waitcnt vmcnt(0)
	s_cmpk_gt_u32 s27, 0xff
	s_cbranch_scc1 .LBB0_1282
	s_barrier
